# gemm_m0_wait_state_from_address_add_not_s_nop
# speedup vs baseline: 1.0093x; 1.0093x over previous
.LBB0_150:
	ds_read_b128 v[152:155], v148
	ds_read_b128 v[156:159], v148 offset:1024
	ds_read_b128 v[160:163], v148 offset:2048
	ds_read_b128 v[164:167], v148 offset:3072
	s_add_u32 s40, s38, 0xfffc0080
	s_addc_u32 s41, s39, -1
	s_cmp_eq_u32 s75, 12
	s_cselect_b32 s43, s13, s41
	s_cselect_b32 s42, s37, s40
	s_cselect_b32 s41, s9, s74
	s_cselect_b32 s40, s72, s73
	v_lshl_add_u64 v[200:201], s[38:39], 0, v[136:137]
	s_add_i32 m0, s51, 0xc000
	ds_read_b128 v[168:171], v149
	ds_read_b128 v[172:175], v149 offset:1024
	ds_read_b128 v[176:179], v149 offset:2048
	ds_read_b128 v[180:183], v149 offset:3072
	ds_read_b128 v[184:187], v149 offset:4096
	ds_read_b128 v[188:191], v149 offset:5120
	ds_read_b128 v[192:195], v149 offset:6144
	ds_read_b128 v[196:199], v149 offset:7168
	global_load_lds_dwordx4 v[200:201], off
	s_add_i32 m0, s51, 0xe000
	v_lshl_add_u64 v[200:201], s[38:39], 0, v[138:139]
	global_load_lds_dwordx4 v[200:201], off
	s_waitcnt lgkmcnt(8)
	s_setprio 1
	s_barrier
	s_waitcnt lgkmcnt(0)
	v_mfma_f32_16x16x32_bf16 v[124:127], v[152:155], v[168:171], v[124:127]
	v_mfma_f32_16x16x32_bf16 v[120:123], v[160:163], v[168:171], v[120:123]
	v_mfma_f32_16x16x32_bf16 v[116:119], v[152:155], v[176:179], v[116:119]
	v_mfma_f32_16x16x32_bf16 v[112:115], v[160:163], v[176:179], v[112:115]
	v_mfma_f32_16x16x32_bf16 v[108:111], v[152:155], v[184:187], v[108:111]
	v_mfma_f32_16x16x32_bf16 v[104:107], v[160:163], v[184:187], v[104:107]
	v_mfma_f32_16x16x32_bf16 v[100:103], v[152:155], v[192:195], v[100:103]
	v_mfma_f32_16x16x32_bf16 v[96:99], v[160:163], v[192:195], v[96:99]
	v_mfma_f32_16x16x32_bf16 v[124:127], v[156:159], v[172:175], v[124:127]
	v_mfma_f32_16x16x32_bf16 v[120:123], v[164:167], v[172:175], v[120:123]
	v_mfma_f32_16x16x32_bf16 v[116:119], v[156:159], v[180:183], v[116:119]
	v_mfma_f32_16x16x32_bf16 v[112:115], v[164:167], v[180:183], v[112:115]
	v_mfma_f32_16x16x32_bf16 v[108:111], v[156:159], v[188:191], v[108:111]
	v_mfma_f32_16x16x32_bf16 v[104:107], v[164:167], v[188:191], v[104:107]
	v_mfma_f32_16x16x32_bf16 v[100:103], v[156:159], v[196:199], v[100:103]
	v_mfma_f32_16x16x32_bf16 v[96:99], v[164:167], v[196:199], v[96:99]
	s_setprio 0
	s_barrier
	s_add_i32 s76, s69, s48
	v_lshl_add_u64 v[208:209], s[40:41], 0, v[132:133]
	s_mov_b32 m0, s76
	ds_read_b128 v[200:203], v150
	ds_read_b128 v[204:207], v150 offset:1024
	ds_read_b128 v[212:215], v150 offset:2048
	ds_read_b128 v[216:219], v150 offset:3072
	global_load_lds_dwordx4 v[208:209], off
	s_add_i32 m0, s76, 0x2000
	v_lshl_add_u64 v[220:221], s[40:41], 0, v[128:129]
	global_load_lds_dwordx4 v[220:221], off
	s_setprio 1
	s_barrier
	s_waitcnt lgkmcnt(0)
	v_mfma_f32_16x16x32_bf16 v[76:79], v[200:203], v[168:171], v[76:79]
	v_mfma_f32_16x16x32_bf16 v[72:75], v[212:215], v[168:171], v[72:75]
	v_mfma_f32_16x16x32_bf16 v[60:63], v[200:203], v[176:179], v[60:63]
	v_mfma_f32_16x16x32_bf16 v[56:59], v[212:215], v[176:179], v[56:59]
	v_mfma_f32_16x16x32_bf16 v[44:47], v[200:203], v[184:187], v[44:47]
	v_mfma_f32_16x16x32_bf16 v[40:43], v[212:215], v[184:187], v[40:43]
	v_mfma_f32_16x16x32_bf16 v[36:39], v[200:203], v[192:195], v[36:39]
	v_mfma_f32_16x16x32_bf16 v[32:35], v[212:215], v[192:195], v[32:35]
	v_mfma_f32_16x16x32_bf16 v[76:79], v[204:207], v[172:175], v[76:79]
	v_mfma_f32_16x16x32_bf16 v[72:75], v[216:219], v[172:175], v[72:75]
	v_mfma_f32_16x16x32_bf16 v[60:63], v[204:207], v[180:183], v[60:63]
	v_mfma_f32_16x16x32_bf16 v[56:59], v[216:219], v[180:183], v[56:59]
	v_mfma_f32_16x16x32_bf16 v[44:47], v[204:207], v[188:191], v[44:47]
	v_mfma_f32_16x16x32_bf16 v[40:43], v[216:219], v[188:191], v[40:43]
	v_mfma_f32_16x16x32_bf16 v[36:39], v[204:207], v[196:199], v[36:39]
	v_mfma_f32_16x16x32_bf16 v[32:35], v[216:219], v[196:199], v[32:35]
	s_setprio 0
	s_mov_b32 m0, s51
	v_lshl_add_u64 v[222:223], s[42:43], 0, v[134:135]
	s_barrier
	ds_read_b128 v[168:171], v149 offset:16384
	ds_read_b128 v[172:175], v149 offset:17408
	ds_read_b128 v[176:179], v149 offset:18432
	ds_read_b128 v[180:183], v149 offset:19456
	ds_read_b128 v[184:187], v149 offset:20480
	ds_read_b128 v[188:191], v149 offset:21504
	ds_read_b128 v[192:195], v149 offset:22528
	ds_read_b128 v[196:199], v149 offset:23552
	global_load_lds_dwordx4 v[222:223], off
	s_mov_b32 m0, s54
	v_lshl_add_u64 v[224:225], s[42:43], 0, v[130:131]
	global_load_lds_dwordx4 v[224:225], off
	s_setprio 1
	s_barrier
	s_waitcnt lgkmcnt(0)
	v_mfma_f32_16x16x32_bf16 v[92:95], v[152:155], v[168:171], v[92:95]
	v_mfma_f32_16x16x32_bf16 v[88:91], v[160:163], v[168:171], v[88:91]
	v_mfma_f32_16x16x32_bf16 v[84:87], v[152:155], v[176:179], v[84:87]
	v_mfma_f32_16x16x32_bf16 v[80:83], v[160:163], v[176:179], v[80:83]
	v_mfma_f32_16x16x32_bf16 v[68:71], v[152:155], v[184:187], v[68:71]
	v_mfma_f32_16x16x32_bf16 v[64:67], v[160:163], v[184:187], v[64:67]
	v_mfma_f32_16x16x32_bf16 v[52:55], v[152:155], v[192:195], v[52:55]
	v_mfma_f32_16x16x32_bf16 v[48:51], v[160:163], v[192:195], v[48:51]
	v_mfma_f32_16x16x32_bf16 v[92:95], v[156:159], v[172:175], v[92:95]
	v_mfma_f32_16x16x32_bf16 v[88:91], v[164:167], v[172:175], v[88:91]
	v_mfma_f32_16x16x32_bf16 v[84:87], v[156:159], v[180:183], v[84:87]
	v_mfma_f32_16x16x32_bf16 v[80:83], v[164:167], v[180:183], v[80:83]
	v_mfma_f32_16x16x32_bf16 v[68:71], v[156:159], v[188:191], v[68:71]
	v_mfma_f32_16x16x32_bf16 v[64:67], v[164:167], v[188:191], v[64:67]
	v_mfma_f32_16x16x32_bf16 v[52:55], v[156:159], v[196:199], v[52:55]
	v_mfma_f32_16x16x32_bf16 v[48:51], v[164:167], v[196:199], v[48:51]
	s_setprio 0
	s_barrier
	s_add_u32 s76, s40, 0x40000
	s_addc_u32 s77, s41, 0
	s_add_i32 s78, s70, s48
	s_mov_b32 m0, s78
	v_lshl_add_u64 v[152:153], s[76:77], 0, v[132:133]
	global_load_lds_dwordx4 v[152:153], off
	s_add_i32 m0, s78, 0x2000
	v_lshl_add_u64 v[152:153], s[76:77], 0, v[128:129]
	global_load_lds_dwordx4 v[152:153], off
	s_waitcnt vmcnt(6)
	s_setprio 1
	s_barrier
	v_mfma_f32_16x16x32_bf16 v[28:31], v[200:203], v[168:171], v[28:31]
	v_mfma_f32_16x16x32_bf16 v[24:27], v[212:215], v[168:171], v[24:27]
	v_mfma_f32_16x16x32_bf16 v[20:23], v[200:203], v[176:179], v[20:23]
	v_mfma_f32_16x16x32_bf16 v[16:19], v[212:215], v[176:179], v[16:19]
	v_mfma_f32_16x16x32_bf16 v[12:15], v[200:203], v[184:187], v[12:15]
	v_mfma_f32_16x16x32_bf16 v[8:11], v[212:215], v[184:187], v[8:11]
	v_mfma_f32_16x16x32_bf16 v[4:7], v[200:203], v[192:195], v[4:7]
	v_mfma_f32_16x16x32_bf16 v[0:3], v[212:215], v[192:195], v[0:3]
	v_mfma_f32_16x16x32_bf16 v[28:31], v[204:207], v[172:175], v[28:31]
	v_mfma_f32_16x16x32_bf16 v[24:27], v[216:219], v[172:175], v[24:27]
	v_mfma_f32_16x16x32_bf16 v[20:23], v[204:207], v[180:183], v[20:23]
	v_mfma_f32_16x16x32_bf16 v[16:19], v[216:219], v[180:183], v[16:19]
	v_mfma_f32_16x16x32_bf16 v[12:15], v[204:207], v[188:191], v[12:15]
	v_mfma_f32_16x16x32_bf16 v[8:11], v[216:219], v[188:191], v[8:11]
	v_mfma_f32_16x16x32_bf16 v[4:7], v[204:207], v[196:199], v[4:7]
	v_mfma_f32_16x16x32_bf16 v[0:3], v[216:219], v[196:199], v[0:3]
	s_setprio 0
	s_add_i32 s76, 0, 0x18000
	v_add_u32_e32 v151, s76, v146
	s_barrier
	ds_read_b128 v[152:155], v151
	ds_read_b128 v[156:159], v151 offset:1024
	ds_read_b128 v[160:163], v151 offset:2048
	ds_read_b128 v[164:167], v151 offset:3072
	s_add_u32 s42, s42, 0x40000
	s_addc_u32 s43, s43, 0
	s_mov_b32 m0, s55
	v_lshl_add_u64 v[200:201], s[42:43], 0, v[134:135]
	ds_read_b128 v[168:171], v149 offset:32768
	ds_read_b128 v[172:175], v149 offset:33792
	ds_read_b128 v[176:179], v149 offset:34816
	ds_read_b128 v[180:183], v149 offset:35840
	ds_read_b128 v[184:187], v149 offset:36864
	ds_read_b128 v[188:191], v149 offset:37888
	ds_read_b128 v[192:195], v149 offset:38912
	ds_read_b128 v[196:199], v149 offset:39936
	global_load_lds_dwordx4 v[200:201], off
	s_mov_b32 m0, s62
	v_lshl_add_u64 v[200:201], s[42:43], 0, v[130:131]
	global_load_lds_dwordx4 v[200:201], off
	s_waitcnt lgkmcnt(8)
	s_setprio 1
	s_barrier
	s_waitcnt lgkmcnt(0)
	v_mfma_f32_16x16x32_bf16 v[124:127], v[152:155], v[168:171], v[124:127]
	v_mfma_f32_16x16x32_bf16 v[120:123], v[160:163], v[168:171], v[120:123]
	v_mfma_f32_16x16x32_bf16 v[116:119], v[152:155], v[176:179], v[116:119]
	v_mfma_f32_16x16x32_bf16 v[112:115], v[160:163], v[176:179], v[112:115]
	v_mfma_f32_16x16x32_bf16 v[108:111], v[152:155], v[184:187], v[108:111]
	v_mfma_f32_16x16x32_bf16 v[104:107], v[160:163], v[184:187], v[104:107]
	v_mfma_f32_16x16x32_bf16 v[100:103], v[152:155], v[192:195], v[100:103]
	v_mfma_f32_16x16x32_bf16 v[96:99], v[160:163], v[192:195], v[96:99]
	v_mfma_f32_16x16x32_bf16 v[124:127], v[156:159], v[172:175], v[124:127]
	v_mfma_f32_16x16x32_bf16 v[120:123], v[164:167], v[172:175], v[120:123]
	v_mfma_f32_16x16x32_bf16 v[116:119], v[156:159], v[180:183], v[116:119]
	v_mfma_f32_16x16x32_bf16 v[112:115], v[164:167], v[180:183], v[112:115]
	v_mfma_f32_16x16x32_bf16 v[108:111], v[156:159], v[188:191], v[108:111]
	v_mfma_f32_16x16x32_bf16 v[104:107], v[164:167], v[188:191], v[104:107]
	v_mfma_f32_16x16x32_bf16 v[100:103], v[156:159], v[196:199], v[100:103]
	v_mfma_f32_16x16x32_bf16 v[96:99], v[164:167], v[196:199], v[96:99]
	s_setprio 0
	s_barrier
	s_add_i32 s42, 0, 0x1c000
	s_add_i32 s43, s76, s48
	v_add_u32_e32 v151, s42, v146
	v_lshl_add_u64 v[208:209], v[208:209], 0, s[0:1]
	s_mov_b32 m0, s43
	ds_read_b128 v[200:203], v151
	ds_read_b128 v[204:207], v151 offset:1024
	ds_read_b128 v[212:215], v151 offset:2048
	ds_read_b128 v[216:219], v151 offset:3072
	global_load_lds_dwordx4 v[208:209], off
	s_add_i32 m0, s43, 0x2000
	v_lshl_add_u64 v[208:209], v[220:221], 0, s[0:1]
	global_load_lds_dwordx4 v[208:209], off
	s_setprio 1
	s_barrier
	s_waitcnt lgkmcnt(0)
	v_mfma_f32_16x16x32_bf16 v[76:79], v[200:203], v[168:171], v[76:79]
	v_mfma_f32_16x16x32_bf16 v[72:75], v[212:215], v[168:171], v[72:75]
	v_mfma_f32_16x16x32_bf16 v[60:63], v[200:203], v[176:179], v[60:63]
	v_mfma_f32_16x16x32_bf16 v[56:59], v[212:215], v[176:179], v[56:59]
	v_mfma_f32_16x16x32_bf16 v[44:47], v[200:203], v[184:187], v[44:47]
	v_mfma_f32_16x16x32_bf16 v[40:43], v[212:215], v[184:187], v[40:43]
	v_mfma_f32_16x16x32_bf16 v[36:39], v[200:203], v[192:195], v[36:39]
	v_mfma_f32_16x16x32_bf16 v[32:35], v[212:215], v[192:195], v[32:35]
	v_mfma_f32_16x16x32_bf16 v[76:79], v[204:207], v[172:175], v[76:79]
	v_mfma_f32_16x16x32_bf16 v[72:75], v[216:219], v[172:175], v[72:75]
	v_mfma_f32_16x16x32_bf16 v[60:63], v[204:207], v[180:183], v[60:63]
	v_mfma_f32_16x16x32_bf16 v[56:59], v[216:219], v[180:183], v[56:59]
	v_mfma_f32_16x16x32_bf16 v[44:47], v[204:207], v[188:191], v[44:47]
	v_mfma_f32_16x16x32_bf16 v[40:43], v[216:219], v[188:191], v[40:43]
	v_mfma_f32_16x16x32_bf16 v[36:39], v[204:207], v[196:199], v[36:39]
	v_mfma_f32_16x16x32_bf16 v[32:35], v[216:219], v[196:199], v[32:35]
	s_setprio 0
	s_mov_b32 m0, s63
	v_lshl_add_u64 v[208:209], v[222:223], 0, s[0:1]
	s_barrier
	ds_read_b128 v[168:171], v149 offset:49152
	ds_read_b128 v[172:175], v149 offset:50176
	ds_read_b128 v[176:179], v149 offset:51200
	ds_read_b128 v[180:183], v149 offset:52224
	ds_read_b128 v[184:187], v149 offset:53248
	ds_read_b128 v[188:191], v149 offset:54272
	ds_read_b128 v[192:195], v149 offset:55296
	ds_read_b128 v[196:199], v149 offset:56320
	global_load_lds_dwordx4 v[208:209], off
	s_mov_b32 m0, s64
	v_lshl_add_u64 v[208:209], v[224:225], 0, s[0:1]
	global_load_lds_dwordx4 v[208:209], off
	s_setprio 1
	s_barrier
	s_waitcnt lgkmcnt(0)
	v_mfma_f32_16x16x32_bf16 v[92:95], v[152:155], v[168:171], v[92:95]
	v_mfma_f32_16x16x32_bf16 v[88:91], v[160:163], v[168:171], v[88:91]
	v_mfma_f32_16x16x32_bf16 v[84:87], v[152:155], v[176:179], v[84:87]
	v_mfma_f32_16x16x32_bf16 v[80:83], v[160:163], v[176:179], v[80:83]
	v_mfma_f32_16x16x32_bf16 v[68:71], v[152:155], v[184:187], v[68:71]
	v_mfma_f32_16x16x32_bf16 v[64:67], v[160:163], v[184:187], v[64:67]
	v_mfma_f32_16x16x32_bf16 v[52:55], v[152:155], v[192:195], v[52:55]
	v_mfma_f32_16x16x32_bf16 v[48:51], v[160:163], v[192:195], v[48:51]
	v_mfma_f32_16x16x32_bf16 v[92:95], v[156:159], v[172:175], v[92:95]
	v_mfma_f32_16x16x32_bf16 v[88:91], v[164:167], v[172:175], v[88:91]
	v_mfma_f32_16x16x32_bf16 v[84:87], v[156:159], v[180:183], v[84:87]
	v_mfma_f32_16x16x32_bf16 v[80:83], v[164:167], v[180:183], v[80:83]
	v_mfma_f32_16x16x32_bf16 v[68:71], v[156:159], v[188:191], v[68:71]
	v_mfma_f32_16x16x32_bf16 v[64:67], v[164:167], v[188:191], v[64:67]
	v_mfma_f32_16x16x32_bf16 v[52:55], v[156:159], v[196:199], v[52:55]
	v_mfma_f32_16x16x32_bf16 v[48:51], v[164:167], v[196:199], v[48:51]
	s_setprio 0
	s_barrier
	s_add_u32 s40, s40, 0x40080
	s_addc_u32 s41, s41, 0
	s_add_i32 s42, s42, s48
	s_mov_b32 m0, s42
	v_lshl_add_u64 v[152:153], s[40:41], 0, v[132:133]
	global_load_lds_dwordx4 v[152:153], off
	s_add_i32 m0, s42, 0x2000
	v_lshl_add_u64 v[152:153], s[40:41], 0, v[128:129]
	global_load_lds_dwordx4 v[152:153], off
	s_waitcnt vmcnt(6)
	s_setprio 1
	s_barrier
	v_mfma_f32_16x16x32_bf16 v[28:31], v[200:203], v[168:171], v[28:31]
	v_mfma_f32_16x16x32_bf16 v[24:27], v[212:215], v[168:171], v[24:27]
	v_mfma_f32_16x16x32_bf16 v[20:23], v[200:203], v[176:179], v[20:23]
	v_mfma_f32_16x16x32_bf16 v[16:19], v[212:215], v[176:179], v[16:19]
	v_mfma_f32_16x16x32_bf16 v[12:15], v[200:203], v[184:187], v[12:15]
	v_mfma_f32_16x16x32_bf16 v[8:11], v[212:215], v[184:187], v[8:11]
	v_mfma_f32_16x16x32_bf16 v[4:7], v[200:203], v[192:195], v[4:7]
	v_mfma_f32_16x16x32_bf16 v[0:3], v[212:215], v[192:195], v[0:3]
	v_mfma_f32_16x16x32_bf16 v[28:31], v[204:207], v[172:175], v[28:31]
	v_mfma_f32_16x16x32_bf16 v[24:27], v[216:219], v[172:175], v[24:27]
	v_mfma_f32_16x16x32_bf16 v[20:23], v[204:207], v[180:183], v[20:23]
	v_mfma_f32_16x16x32_bf16 v[16:19], v[216:219], v[180:183], v[16:19]
	v_mfma_f32_16x16x32_bf16 v[12:15], v[204:207], v[188:191], v[12:15]
	v_mfma_f32_16x16x32_bf16 v[8:11], v[216:219], v[188:191], v[8:11]
	v_mfma_f32_16x16x32_bf16 v[4:7], v[204:207], v[196:199], v[4:7]
	v_mfma_f32_16x16x32_bf16 v[0:3], v[216:219], v[196:199], v[0:3]
	s_setprio 0
	s_add_i32 s75, s75, 2
	s_add_u32 s38, s38, 0x100
	s_addc_u32 s39, s39, 0
	s_add_u32 s73, s73, 0x100
	s_addc_u32 s74, s74, 0
	s_cmp_gt_u32 s75, 13
	s_barrier
	s_cbranch_scc0 .LBB0_150
	v_lshl_add_u32 v151, s36, 8, v144
	s_cmp_gt_i32 s71, 11
	s_mov_b64 s[36:37], -1
	s_cbranch_scc0 .LBB0_155
	s_and_saveexec_b64 s[36:37], s[2:3]
	s_cbranch_execz .LBB0_154
	v_lshl_or_b32 v152, v151, 8, v147
	v_readlane_b32 s38, v253, 59
	v_readlane_b32 s39, v253, 60
	v_or_b32_e32 v153, 0x1000, v152
	s_nop 3
	global_store_dwordx4 v153, v[116:119], s[38:39] nt
	v_or_b32_e32 v153, 0x2000, v152
	global_store_dwordx4 v153, v[108:111], s[38:39] nt
	v_or_b32_e32 v153, 0x3000, v152
	global_store_dwordx4 v153, v[100:103], s[38:39] nt
	v_add_u32_e32 v153, 0x8000, v152
	global_store_dwordx4 v153, v[92:95], s[38:39] nt
	v_add_u32_e32 v153, 0x9000, v152
	global_store_dwordx4 v153, v[84:87], s[38:39] nt
	v_add_u32_e32 v153, 0xa000, v152
	global_store_dwordx4 v153, v[68:71], s[38:39] nt
	v_add_u32_e32 v153, 0xb000, v152
	global_store_dwordx4 v153, v[52:55], s[38:39] nt
	v_or_b32_e32 v153, 16, v152
	global_store_dwordx4 v153, v[120:123], s[38:39] nt
	v_or_b32_e32 v153, 0x1010, v152
	global_store_dwordx4 v153, v[112:115], s[38:39] nt
	v_or_b32_e32 v153, 0x2010, v152
	global_store_dwordx4 v153, v[104:107], s[38:39] nt
	v_or_b32_e32 v153, 0x3010, v152
	global_store_dwordx4 v153, v[96:99], s[38:39] nt
	v_add_u32_e32 v153, 0x8010, v152
	global_store_dwordx4 v153, v[88:91], s[38:39] nt
	v_add_u32_e32 v153, 0x9010, v152
	global_store_dwordx4 v152, v[124:127], s[38:39] nt
	global_store_dwordx4 v153, v[80:83], s[38:39] nt
	v_add_u32_e32 v153, 0xa010, v152
	v_add_u32_e32 v152, 0xb010, v152
	global_store_dwordx4 v153, v[64:67], s[38:39] nt
	global_store_dwordx4 v152, v[48:51], s[38:39] nt

.LBB0_177:
	ds_read_b128 v[152:155], v149
	ds_read_b128 v[156:159], v149 offset:1024
	ds_read_b128 v[160:163], v149 offset:2048
	ds_read_b128 v[164:167], v149 offset:3072
	s_add_u32 s36, s34, 0xfffc0080
	s_addc_u32 s37, s35, -1
	s_cmp_eq_u32 s68, 12
	s_cselect_b32 s39, s9, s37
	s_cselect_b32 s38, s64, s36
	s_cselect_b32 s37, s3, s67
	s_cselect_b32 s36, s65, s66
	v_lshl_add_u64 v[144:145], s[34:35], 0, v[136:137]
	s_add_i32 m0, s13, 0xc000
	ds_read_b128 v[168:171], v150
	ds_read_b128 v[172:175], v150 offset:1024
	ds_read_b128 v[176:179], v150 offset:2048
	ds_read_b128 v[180:183], v150 offset:3072
	ds_read_b128 v[184:187], v150 offset:4096
	ds_read_b128 v[188:191], v150 offset:5120
	ds_read_b128 v[192:195], v150 offset:6144
	ds_read_b128 v[196:199], v150 offset:7168
	global_load_lds_dwordx4 v[144:145], off
	s_add_i32 m0, s13, 0xe000
	v_lshl_add_u64 v[144:145], s[34:35], 0, v[138:139]
	global_load_lds_dwordx4 v[144:145], off
	s_waitcnt lgkmcnt(8)
	s_setprio 1
	s_barrier
	s_waitcnt lgkmcnt(0)
	v_mfma_f32_16x16x32_bf16 v[124:127], v[152:155], v[168:171], v[124:127]
	v_mfma_f32_16x16x32_bf16 v[120:123], v[160:163], v[168:171], v[120:123]
	v_mfma_f32_16x16x32_bf16 v[112:115], v[152:155], v[176:179], v[112:115]
	v_mfma_f32_16x16x32_bf16 v[104:107], v[160:163], v[176:179], v[104:107]
	v_mfma_f32_16x16x32_bf16 v[96:99], v[152:155], v[184:187], v[96:99]
	v_mfma_f32_16x16x32_bf16 v[88:91], v[160:163], v[184:187], v[88:91]
	v_mfma_f32_16x16x32_bf16 v[80:83], v[152:155], v[192:195], v[80:83]
	v_mfma_f32_16x16x32_bf16 v[72:75], v[160:163], v[192:195], v[72:75]
	v_mfma_f32_16x16x32_bf16 v[124:127], v[156:159], v[172:175], v[124:127]
	v_mfma_f32_16x16x32_bf16 v[120:123], v[164:167], v[172:175], v[120:123]
	v_mfma_f32_16x16x32_bf16 v[112:115], v[156:159], v[180:183], v[112:115]
	v_mfma_f32_16x16x32_bf16 v[104:107], v[164:167], v[180:183], v[104:107]
	v_mfma_f32_16x16x32_bf16 v[96:99], v[156:159], v[188:191], v[96:99]
	v_mfma_f32_16x16x32_bf16 v[88:91], v[164:167], v[188:191], v[88:91]
	v_mfma_f32_16x16x32_bf16 v[80:83], v[156:159], v[196:199], v[80:83]
	v_mfma_f32_16x16x32_bf16 v[72:75], v[164:167], v[196:199], v[72:75]
	s_setprio 0
	s_barrier
	s_add_i32 s69, s55, s42
	v_lshl_add_u64 v[144:145], s[36:37], 0, v[130:131]
	s_mov_b32 m0, s69
	ds_read_b128 v[200:203], v151
	ds_read_b128 v[204:207], v151 offset:1024
	ds_read_b128 v[212:215], v151 offset:2048
	ds_read_b128 v[216:219], v151 offset:3072
	global_load_lds_dwordx4 v[144:145], off
	s_add_i32 m0, s69, 0x2000
	v_lshl_add_u64 v[208:209], s[36:37], 0, v[134:135]
	global_load_lds_dwordx4 v[208:209], off
	s_setprio 1
	s_barrier
	s_waitcnt lgkmcnt(0)
	v_mfma_f32_16x16x32_bf16 v[116:119], v[200:203], v[168:171], v[116:119]
	v_mfma_f32_16x16x32_bf16 v[108:111], v[212:215], v[168:171], v[108:111]
	v_mfma_f32_16x16x32_bf16 v[100:103], v[200:203], v[176:179], v[100:103]
	v_mfma_f32_16x16x32_bf16 v[92:95], v[212:215], v[176:179], v[92:95]
	v_mfma_f32_16x16x32_bf16 v[84:87], v[200:203], v[184:187], v[84:87]
	v_mfma_f32_16x16x32_bf16 v[76:79], v[212:215], v[184:187], v[76:79]
	v_mfma_f32_16x16x32_bf16 v[68:71], v[200:203], v[192:195], v[68:71]
	v_mfma_f32_16x16x32_bf16 v[64:67], v[212:215], v[192:195], v[64:67]
	v_mfma_f32_16x16x32_bf16 v[116:119], v[204:207], v[172:175], v[116:119]
	v_mfma_f32_16x16x32_bf16 v[108:111], v[216:219], v[172:175], v[108:111]
	v_mfma_f32_16x16x32_bf16 v[100:103], v[204:207], v[180:183], v[100:103]
	v_mfma_f32_16x16x32_bf16 v[92:95], v[216:219], v[180:183], v[92:95]
	v_mfma_f32_16x16x32_bf16 v[84:87], v[204:207], v[188:191], v[84:87]
	v_mfma_f32_16x16x32_bf16 v[76:79], v[216:219], v[188:191], v[76:79]
	v_mfma_f32_16x16x32_bf16 v[68:71], v[204:207], v[196:199], v[68:71]
	v_mfma_f32_16x16x32_bf16 v[64:67], v[216:219], v[196:199], v[64:67]
	s_setprio 0
	s_mov_b32 m0, s13
	v_lshl_add_u64 v[220:221], s[38:39], 0, v[128:129]
	s_barrier
	ds_read_b128 v[168:171], v150 offset:16384
	ds_read_b128 v[172:175], v150 offset:17408
	ds_read_b128 v[176:179], v150 offset:18432
	ds_read_b128 v[180:183], v150 offset:19456
	ds_read_b128 v[184:187], v150 offset:20480
	ds_read_b128 v[188:191], v150 offset:21504
	ds_read_b128 v[192:195], v150 offset:22528
	ds_read_b128 v[196:199], v150 offset:23552
	global_load_lds_dwordx4 v[220:221], off
	s_mov_b32 m0, s43
	v_lshl_add_u64 v[222:223], s[38:39], 0, v[132:133]
	global_load_lds_dwordx4 v[222:223], off
	s_setprio 1
	s_barrier
	s_waitcnt lgkmcnt(0)
	v_mfma_f32_16x16x32_bf16 v[60:63], v[152:155], v[168:171], v[60:63]
	v_mfma_f32_16x16x32_bf16 v[56:59], v[160:163], v[168:171], v[56:59]
	v_mfma_f32_16x16x32_bf16 v[52:55], v[152:155], v[176:179], v[52:55]
	v_mfma_f32_16x16x32_bf16 v[44:47], v[160:163], v[176:179], v[44:47]
	v_mfma_f32_16x16x32_bf16 v[36:39], v[152:155], v[184:187], v[36:39]
	v_mfma_f32_16x16x32_bf16 v[28:31], v[160:163], v[184:187], v[28:31]
	v_mfma_f32_16x16x32_bf16 v[20:23], v[152:155], v[192:195], v[20:23]
	v_mfma_f32_16x16x32_bf16 v[12:15], v[160:163], v[192:195], v[12:15]
	v_mfma_f32_16x16x32_bf16 v[60:63], v[156:159], v[172:175], v[60:63]
	v_mfma_f32_16x16x32_bf16 v[56:59], v[164:167], v[172:175], v[56:59]
	v_mfma_f32_16x16x32_bf16 v[52:55], v[156:159], v[180:183], v[52:55]
	v_mfma_f32_16x16x32_bf16 v[44:47], v[164:167], v[180:183], v[44:47]
	v_mfma_f32_16x16x32_bf16 v[36:39], v[156:159], v[188:191], v[36:39]
	v_mfma_f32_16x16x32_bf16 v[28:31], v[164:167], v[188:191], v[28:31]
	v_mfma_f32_16x16x32_bf16 v[20:23], v[156:159], v[196:199], v[20:23]
	v_mfma_f32_16x16x32_bf16 v[12:15], v[164:167], v[196:199], v[12:15]
	s_setprio 0
	s_barrier
	s_add_u32 s70, s36, 0x40000
	s_addc_u32 s71, s37, 0
	s_add_i32 s69, s62, s42
	s_mov_b32 m0, s69
	v_lshl_add_u64 v[152:153], s[70:71], 0, v[130:131]
	global_load_lds_dwordx4 v[152:153], off
	s_add_i32 m0, s69, 0x2000
	v_lshl_add_u64 v[152:153], s[70:71], 0, v[134:135]
	global_load_lds_dwordx4 v[152:153], off
	s_waitcnt vmcnt(6)
	s_setprio 1
	s_barrier
	v_mfma_f32_16x16x32_bf16 v[48:51], v[200:203], v[168:171], v[48:51]
	v_mfma_f32_16x16x32_bf16 v[40:43], v[212:215], v[168:171], v[40:43]
	v_mfma_f32_16x16x32_bf16 v[32:35], v[200:203], v[176:179], v[32:35]
	v_mfma_f32_16x16x32_bf16 v[24:27], v[212:215], v[176:179], v[24:27]
	v_mfma_f32_16x16x32_bf16 v[16:19], v[200:203], v[184:187], v[16:19]
	v_mfma_f32_16x16x32_bf16 v[8:11], v[212:215], v[184:187], v[8:11]
	v_mfma_f32_16x16x32_bf16 v[4:7], v[200:203], v[192:195], v[4:7]
	v_mfma_f32_16x16x32_bf16 v[0:3], v[212:215], v[192:195], v[0:3]
	v_mfma_f32_16x16x32_bf16 v[48:51], v[204:207], v[172:175], v[48:51]
	v_mfma_f32_16x16x32_bf16 v[40:43], v[216:219], v[172:175], v[40:43]
	v_mfma_f32_16x16x32_bf16 v[32:35], v[204:207], v[180:183], v[32:35]
	v_mfma_f32_16x16x32_bf16 v[24:27], v[216:219], v[180:183], v[24:27]
	v_mfma_f32_16x16x32_bf16 v[16:19], v[204:207], v[188:191], v[16:19]
	v_mfma_f32_16x16x32_bf16 v[8:11], v[216:219], v[188:191], v[8:11]
	v_mfma_f32_16x16x32_bf16 v[4:7], v[204:207], v[196:199], v[4:7]
	v_mfma_f32_16x16x32_bf16 v[0:3], v[216:219], v[196:199], v[0:3]
	s_setprio 0
	s_add_i32 s69, 0, 0x18000
	v_add_u32_e32 v164, s69, v147
	s_barrier
	ds_read_b128 v[152:155], v164
	ds_read_b128 v[156:159], v164 offset:1024
	ds_read_b128 v[160:163], v164 offset:2048
	ds_read_b128 v[164:167], v164 offset:3072
	s_add_u32 s38, s38, 0x40000
	s_addc_u32 s39, s39, 0
	s_mov_b32 m0, s48
	v_lshl_add_u64 v[200:201], s[38:39], 0, v[128:129]
	ds_read_b128 v[168:171], v150 offset:32768
	ds_read_b128 v[172:175], v150 offset:33792
	ds_read_b128 v[176:179], v150 offset:34816
	ds_read_b128 v[180:183], v150 offset:35840
	ds_read_b128 v[184:187], v150 offset:36864
	ds_read_b128 v[188:191], v150 offset:37888
	ds_read_b128 v[192:195], v150 offset:38912
	ds_read_b128 v[196:199], v150 offset:39936
	global_load_lds_dwordx4 v[200:201], off
	s_mov_b32 m0, s49
	v_lshl_add_u64 v[200:201], s[38:39], 0, v[132:133]
	global_load_lds_dwordx4 v[200:201], off
	s_waitcnt lgkmcnt(8)
	s_setprio 1
	s_barrier
	s_waitcnt lgkmcnt(0)
	v_mfma_f32_16x16x32_bf16 v[124:127], v[152:155], v[168:171], v[124:127]
	v_mfma_f32_16x16x32_bf16 v[120:123], v[160:163], v[168:171], v[120:123]
	v_mfma_f32_16x16x32_bf16 v[112:115], v[152:155], v[176:179], v[112:115]
	v_mfma_f32_16x16x32_bf16 v[104:107], v[160:163], v[176:179], v[104:107]
	v_mfma_f32_16x16x32_bf16 v[96:99], v[152:155], v[184:187], v[96:99]
	v_mfma_f32_16x16x32_bf16 v[88:91], v[160:163], v[184:187], v[88:91]
	v_mfma_f32_16x16x32_bf16 v[80:83], v[152:155], v[192:195], v[80:83]
	v_mfma_f32_16x16x32_bf16 v[72:75], v[160:163], v[192:195], v[72:75]
	v_mfma_f32_16x16x32_bf16 v[124:127], v[156:159], v[172:175], v[124:127]
	v_mfma_f32_16x16x32_bf16 v[120:123], v[164:167], v[172:175], v[120:123]
	v_mfma_f32_16x16x32_bf16 v[112:115], v[156:159], v[180:183], v[112:115]
	v_mfma_f32_16x16x32_bf16 v[104:107], v[164:167], v[180:183], v[104:107]
	v_mfma_f32_16x16x32_bf16 v[96:99], v[156:159], v[188:191], v[96:99]
	v_mfma_f32_16x16x32_bf16 v[88:91], v[164:167], v[188:191], v[88:91]
	v_mfma_f32_16x16x32_bf16 v[80:83], v[156:159], v[196:199], v[80:83]
	v_mfma_f32_16x16x32_bf16 v[72:75], v[164:167], v[196:199], v[72:75]
	s_setprio 0
	s_barrier
	s_add_i32 s38, 0, 0x1c000
	s_add_i32 s39, s69, s42
	v_add_u32_e32 v211, s38, v147
	v_lshl_add_u64 v[144:145], v[144:145], 0, s[0:1]
	s_mov_b32 m0, s39
	ds_read_b128 v[200:203], v211
	ds_read_b128 v[204:207], v211 offset:1024
	ds_read_b128 v[212:215], v211 offset:2048
	ds_read_b128 v[216:219], v211 offset:3072
	global_load_lds_dwordx4 v[144:145], off
	s_add_i32 m0, s39, 0x2000
	v_lshl_add_u64 v[144:145], v[208:209], 0, s[0:1]
	global_load_lds_dwordx4 v[144:145], off
	s_setprio 1
	s_barrier
	s_waitcnt lgkmcnt(0)
	v_mfma_f32_16x16x32_bf16 v[116:119], v[200:203], v[168:171], v[116:119]
	v_mfma_f32_16x16x32_bf16 v[108:111], v[212:215], v[168:171], v[108:111]
	v_mfma_f32_16x16x32_bf16 v[100:103], v[200:203], v[176:179], v[100:103]
	v_mfma_f32_16x16x32_bf16 v[92:95], v[212:215], v[176:179], v[92:95]
	v_mfma_f32_16x16x32_bf16 v[84:87], v[200:203], v[184:187], v[84:87]
	v_mfma_f32_16x16x32_bf16 v[76:79], v[212:215], v[184:187], v[76:79]
	v_mfma_f32_16x16x32_bf16 v[68:71], v[200:203], v[192:195], v[68:71]
	v_mfma_f32_16x16x32_bf16 v[64:67], v[212:215], v[192:195], v[64:67]
	v_mfma_f32_16x16x32_bf16 v[116:119], v[204:207], v[172:175], v[116:119]
	v_mfma_f32_16x16x32_bf16 v[108:111], v[216:219], v[172:175], v[108:111]
	v_mfma_f32_16x16x32_bf16 v[100:103], v[204:207], v[180:183], v[100:103]
	v_mfma_f32_16x16x32_bf16 v[92:95], v[216:219], v[180:183], v[92:95]
	v_mfma_f32_16x16x32_bf16 v[84:87], v[204:207], v[188:191], v[84:87]
	v_mfma_f32_16x16x32_bf16 v[76:79], v[216:219], v[188:191], v[76:79]
	v_mfma_f32_16x16x32_bf16 v[68:71], v[204:207], v[196:199], v[68:71]
	v_mfma_f32_16x16x32_bf16 v[64:67], v[216:219], v[196:199], v[64:67]
	s_setprio 0
	s_mov_b32 m0, s51
	v_lshl_add_u64 v[144:145], v[220:221], 0, s[0:1]
	s_barrier
	ds_read_b128 v[168:171], v150 offset:49152
	ds_read_b128 v[172:175], v150 offset:50176
	ds_read_b128 v[176:179], v150 offset:51200
	ds_read_b128 v[180:183], v150 offset:52224
	ds_read_b128 v[184:187], v150 offset:53248
	ds_read_b128 v[188:191], v150 offset:54272
	ds_read_b128 v[192:195], v150 offset:55296
	ds_read_b128 v[196:199], v150 offset:56320
	global_load_lds_dwordx4 v[144:145], off
	s_mov_b32 m0, s54
	v_lshl_add_u64 v[144:145], v[222:223], 0, s[0:1]
	global_load_lds_dwordx4 v[144:145], off
	s_setprio 1
	s_barrier
	s_waitcnt lgkmcnt(0)
	v_mfma_f32_16x16x32_bf16 v[60:63], v[152:155], v[168:171], v[60:63]
	v_mfma_f32_16x16x32_bf16 v[56:59], v[160:163], v[168:171], v[56:59]
	v_mfma_f32_16x16x32_bf16 v[52:55], v[152:155], v[176:179], v[52:55]
	v_mfma_f32_16x16x32_bf16 v[44:47], v[160:163], v[176:179], v[44:47]
	v_mfma_f32_16x16x32_bf16 v[36:39], v[152:155], v[184:187], v[36:39]
	v_mfma_f32_16x16x32_bf16 v[28:31], v[160:163], v[184:187], v[28:31]
	v_mfma_f32_16x16x32_bf16 v[20:23], v[152:155], v[192:195], v[20:23]
	v_mfma_f32_16x16x32_bf16 v[12:15], v[160:163], v[192:195], v[12:15]
	v_mfma_f32_16x16x32_bf16 v[60:63], v[156:159], v[172:175], v[60:63]
	v_mfma_f32_16x16x32_bf16 v[56:59], v[164:167], v[172:175], v[56:59]
	v_mfma_f32_16x16x32_bf16 v[52:55], v[156:159], v[180:183], v[52:55]
	v_mfma_f32_16x16x32_bf16 v[44:47], v[164:167], v[180:183], v[44:47]
	v_mfma_f32_16x16x32_bf16 v[36:39], v[156:159], v[188:191], v[36:39]
	v_mfma_f32_16x16x32_bf16 v[28:31], v[164:167], v[188:191], v[28:31]
	v_mfma_f32_16x16x32_bf16 v[20:23], v[156:159], v[196:199], v[20:23]
	v_mfma_f32_16x16x32_bf16 v[12:15], v[164:167], v[196:199], v[12:15]
	s_setprio 0
	s_barrier
	s_add_u32 s36, s36, 0x40080
	s_addc_u32 s37, s37, 0
	s_add_i32 s38, s38, s42
	s_mov_b32 m0, s38
	v_lshl_add_u64 v[144:145], s[36:37], 0, v[130:131]
	global_load_lds_dwordx4 v[144:145], off
	s_add_i32 m0, s38, 0x2000
	v_lshl_add_u64 v[144:145], s[36:37], 0, v[134:135]
	global_load_lds_dwordx4 v[144:145], off
	s_waitcnt vmcnt(6)
	s_setprio 1
	s_barrier
	v_mfma_f32_16x16x32_bf16 v[48:51], v[200:203], v[168:171], v[48:51]
	v_mfma_f32_16x16x32_bf16 v[40:43], v[212:215], v[168:171], v[40:43]
	v_mfma_f32_16x16x32_bf16 v[32:35], v[200:203], v[176:179], v[32:35]
	v_mfma_f32_16x16x32_bf16 v[24:27], v[212:215], v[176:179], v[24:27]
	v_mfma_f32_16x16x32_bf16 v[16:19], v[200:203], v[184:187], v[16:19]
	v_mfma_f32_16x16x32_bf16 v[8:11], v[212:215], v[184:187], v[8:11]
	v_mfma_f32_16x16x32_bf16 v[4:7], v[200:203], v[192:195], v[4:7]
	v_mfma_f32_16x16x32_bf16 v[0:3], v[212:215], v[192:195], v[0:3]
	v_mfma_f32_16x16x32_bf16 v[48:51], v[204:207], v[172:175], v[48:51]
	v_mfma_f32_16x16x32_bf16 v[40:43], v[216:219], v[172:175], v[40:43]
	v_mfma_f32_16x16x32_bf16 v[32:35], v[204:207], v[180:183], v[32:35]
	v_mfma_f32_16x16x32_bf16 v[24:27], v[216:219], v[180:183], v[24:27]
	v_mfma_f32_16x16x32_bf16 v[16:19], v[204:207], v[188:191], v[16:19]
	v_mfma_f32_16x16x32_bf16 v[8:11], v[216:219], v[188:191], v[8:11]
	v_mfma_f32_16x16x32_bf16 v[4:7], v[204:207], v[196:199], v[4:7]
	v_mfma_f32_16x16x32_bf16 v[0:3], v[216:219], v[196:199], v[0:3]
	s_setprio 0
	s_add_i32 s68, s68, 2
	s_add_u32 s34, s34, 0x100
	s_addc_u32 s35, s35, 0
	s_add_u32 s66, s66, 0x100
	s_addc_u32 s67, s67, 0
	s_cmp_gt_u32 s68, 13
	s_barrier
	s_cbranch_scc0 .LBB0_177
	v_lshl_add_u32 v152, s12, 8, v146
	v_ashrrev_i32_e32 v153, 31, v152
	v_lshl_or_b32 v144, s63, 8, v148
	v_readlane_b32 s34, v253, 61
	v_ashrrev_i32_e32 v145, 31, v144
	v_lshlrev_b64 v[154:155], 17, v[152:153]
	v_readlane_b32 s35, v253, 62
	v_lshlrev_b64 v[156:157], 1, v[144:145]
	v_cvt_pk_bf16_f32 v124, v124, v125
	v_cvt_pk_bf16_f32 v125, v126, v127
	v_cvt_pk_bf16_f32 v126, v120, v121
	s_nop 0
	v_lshl_add_u64 v[154:155], s[34:35], 0, v[154:155]
	v_lshl_add_u64 v[144:145], v[154:155], 0, v[156:157]
	v_cvt_pk_bf16_f32 v127, v122, v123
	global_store_dwordx4 v[144:145], v[124:127], off nt
	v_cvt_pk_bf16_f32 v116, v116, v117
	v_cvt_pk_bf16_f32 v117, v118, v119
	v_cvt_pk_bf16_f32 v118, v108, v109
	v_or_b32_e32 v108, 16, v152
	v_ashrrev_i32_e32 v109, 31, v108
	v_lshlrev_b64 v[108:109], 17, v[108:109]
	v_lshl_add_u64 v[108:109], s[34:35], 0, v[108:109]
	v_cvt_pk_bf16_f32 v119, v110, v111
	global_store_dwordx4 v[144:145], v[116:119], off offset:256 nt
	s_mov_b32 s3, 0x1000000
	s_mov_b32 s63, s2
	v_lshl_add_u64 v[116:117], v[108:109], 0, v[156:157]
	v_cvt_pk_bf16_f32 v108, v112, v113
	v_cvt_pk_bf16_f32 v109, v114, v115
	v_cvt_pk_bf16_f32 v110, v104, v105
	v_cvt_pk_bf16_f32 v111, v106, v107
	global_store_dwordx4 v[116:117], v[108:111], off nt
	v_cvt_pk_bf16_f32 v100, v100, v101
	v_cvt_pk_bf16_f32 v101, v102, v103
	v_cvt_pk_bf16_f32 v102, v92, v93
	v_or_b32_e32 v92, 32, v152
	v_ashrrev_i32_e32 v93, 31, v92
	v_lshlrev_b64 v[92:93], 17, v[92:93]
	v_lshl_add_u64 v[92:93], s[34:35], 0, v[92:93]
	v_cvt_pk_bf16_f32 v103, v94, v95
	global_store_dwordx4 v[116:117], v[100:103], off offset:256 nt
	s_mov_b32 s12, s8
	s_mov_b64 s[36:37], s[30:31]
	v_lshl_add_u64 v[100:101], v[92:93], 0, v[156:157]
	v_cvt_pk_bf16_f32 v92, v96, v97
	v_cvt_pk_bf16_f32 v93, v98, v99
	v_cvt_pk_bf16_f32 v94, v88, v89
	v_cvt_pk_bf16_f32 v95, v90, v91
	global_store_dwordx4 v[100:101], v[92:95], off nt
	v_cvt_pk_bf16_f32 v84, v84, v85
	v_cvt_pk_bf16_f32 v85, v86, v87
	v_cvt_pk_bf16_f32 v86, v76, v77
	v_or_b32_e32 v76, 48, v152
	v_ashrrev_i32_e32 v77, 31, v76
	v_lshlrev_b64 v[76:77], 17, v[76:77]
	v_lshl_add_u64 v[76:77], s[34:35], 0, v[76:77]
	v_cvt_pk_bf16_f32 v87, v78, v79
	global_store_dwordx4 v[100:101], v[84:87], off offset:256 nt
	s_mov_b64 s[34:35], 0x1000000
	s_nop 0
	v_lshl_add_u64 v[84:85], v[76:77], 0, v[156:157]
	v_cvt_pk_bf16_f32 v76, v80, v81
	v_cvt_pk_bf16_f32 v77, v82, v83
	v_cvt_pk_bf16_f32 v78, v72, v73
	v_cvt_pk_bf16_f32 v79, v74, v75
	global_store_dwordx4 v[84:85], v[76:79], off nt
	v_cvt_pk_bf16_f32 v68, v68, v69
	v_cvt_pk_bf16_f32 v69, v70, v71
	v_cvt_pk_bf16_f32 v70, v64, v65
	v_cvt_pk_bf16_f32 v71, v66, v67
	global_store_dwordx4 v[84:85], v[68:71], off offset:256 nt
	v_cvt_pk_bf16_f32 v60, v60, v61
	v_cvt_pk_bf16_f32 v61, v62, v63
	v_cvt_pk_bf16_f32 v62, v56, v57
	v_add_co_u32_e32 v56, vcc, s3, v144
	v_lshl_add_u64 v[64:65], v[144:145], 0, s[34:35]
	s_nop 0
	v_addc_co_u32_e32 v57, vcc, 0, v145, vcc
	s_mov_b32 s3, 0x1200000
	v_cvt_pk_bf16_f32 v63, v58, v59
	global_store_dwordx4 v[56:57], v[60:63], off nt
	v_cvt_pk_bf16_f32 v48, v48, v49
	v_cvt_pk_bf16_f32 v49, v50, v51
	v_cvt_pk_bf16_f32 v50, v40, v41
	v_cvt_pk_bf16_f32 v51, v42, v43
	global_store_dwordx4 v[64:65], v[48:51], off offset:256 nt
	s_mov_b64 s[34:35], 0x1200000
	v_cvt_pk_bf16_f32 v40, v52, v53
	v_cvt_pk_bf16_f32 v41, v54, v55
	v_cvt_pk_bf16_f32 v42, v44, v45
	v_add_co_u32_e32 v44, vcc, s3, v144
	v_lshl_add_u64 v[48:49], v[144:145], 0, s[34:35]
	s_nop 0
	v_addc_co_u32_e32 v45, vcc, 0, v145, vcc
	s_mov_b32 s3, 0x1400000
	v_cvt_pk_bf16_f32 v43, v46, v47
	global_store_dwordx4 v[44:45], v[40:43], off nt
	v_cvt_pk_bf16_f32 v32, v32, v33
	v_cvt_pk_bf16_f32 v33, v34, v35
	v_cvt_pk_bf16_f32 v34, v24, v25
	v_cvt_pk_bf16_f32 v35, v26, v27
	global_store_dwordx4 v[48:49], v[32:35], off offset:256 nt
	s_mov_b64 s[34:35], 0x1400000
	v_cvt_pk_bf16_f32 v24, v36, v37
	v_cvt_pk_bf16_f32 v25, v38, v39
	v_cvt_pk_bf16_f32 v26, v28, v29
	v_add_co_u32_e32 v28, vcc, s3, v144
	v_lshl_add_u64 v[32:33], v[144:145], 0, s[34:35]
	s_nop 0
	v_addc_co_u32_e32 v29, vcc, 0, v145, vcc
	s_mov_b32 s3, 0x1600000
	v_cvt_pk_bf16_f32 v27, v30, v31
	global_store_dwordx4 v[28:29], v[24:27], off nt
	v_cvt_pk_bf16_f32 v16, v16, v17
	v_cvt_pk_bf16_f32 v17, v18, v19
	v_cvt_pk_bf16_f32 v18, v8, v9
	v_cvt_pk_bf16_f32 v19, v10, v11
	global_store_dwordx4 v[32:33], v[16:19], off offset:256 nt
	v_cvt_pk_bf16_f32 v8, v20, v21
	v_cvt_pk_bf16_f32 v9, v22, v23
	v_cvt_pk_bf16_f32 v10, v12, v13
	v_add_co_u32_e32 v12, vcc, s3, v144
	s_mov_b64 s[34:35], 0x1600000
	s_nop 0
	v_addc_co_u32_e32 v13, vcc, 0, v145, vcc
	v_lshl_add_u64 v[16:17], v[144:145], 0, s[34:35]
	s_and_b64 vcc, exec, s[4:5]
	s_mov_b64 s[34:35], s[14:15]
	v_cvt_pk_bf16_f32 v11, v14, v15
	global_store_dwordx4 v[12:13], v[8:11], off nt
	v_cvt_pk_bf16_f32 v4, v4, v5
	v_cvt_pk_bf16_f32 v5, v6, v7
	v_cvt_pk_bf16_f32 v6, v0, v1
	v_cvt_pk_bf16_f32 v7, v2, v3
	global_store_dwordx4 v[16:17], v[4:7], off offset:256 nt
	s_cbranch_vccz .LBB0_170
	s_waitcnt vmcnt(0)
	s_cmpk_gt_u32 s40, 0xff
	s_cbranch_scc1 .LBB0_181
	s_barrier

.LBB0_200:
	s_add_u32 s48, s42, 0xfffc0080
	s_addc_u32 s49, s43, -1
	s_add_i32 s81, 0, 0x10000
	v_add_u32_e32 v140, s81, v144
	ds_read_b128 v[148:151], v140
	ds_read_b128 v[152:155], v140 offset:1024
	ds_read_b128 v[156:159], v140 offset:2048
	ds_read_b128 v[160:163], v140 offset:3072
	s_cmp_eq_u32 s80, 12
	s_cselect_b32 s51, s35, s49
	s_cselect_b32 s50, s76, s48
	s_cselect_b32 s49, s31, s79
	s_cselect_b32 s48, s77, s78
	v_lshl_add_u64 v[140:141], s[42:43], 0, v[136:137]
	s_add_i32 m0, s37, 0xc000
	ds_read_b128 v[164:167], v146
	ds_read_b128 v[168:171], v146 offset:1024
	ds_read_b128 v[172:175], v146 offset:2048
	ds_read_b128 v[176:179], v146 offset:3072
	ds_read_b128 v[180:183], v146 offset:4096
	ds_read_b128 v[184:187], v146 offset:5120
	ds_read_b128 v[188:191], v146 offset:6144
	ds_read_b128 v[192:195], v146 offset:7168
	global_load_lds_dwordx4 v[140:141], off
	s_add_i32 m0, s37, 0xe000
	v_lshl_add_u64 v[140:141], s[42:43], 0, v[138:139]
	global_load_lds_dwordx4 v[140:141], off
	s_waitcnt lgkmcnt(8)
	s_setprio 1
	s_barrier
	s_waitcnt lgkmcnt(0)
	v_mfma_f32_16x16x32_bf16 v[124:127], v[148:151], v[164:167], v[124:127]
	v_mfma_f32_16x16x32_bf16 v[120:123], v[156:159], v[164:167], v[120:123]
	v_mfma_f32_16x16x32_bf16 v[116:119], v[148:151], v[172:175], v[116:119]
	v_mfma_f32_16x16x32_bf16 v[108:111], v[156:159], v[172:175], v[108:111]
	v_mfma_f32_16x16x32_bf16 v[100:103], v[148:151], v[180:183], v[100:103]
	v_mfma_f32_16x16x32_bf16 v[92:95], v[156:159], v[180:183], v[92:95]
	v_mfma_f32_16x16x32_bf16 v[84:87], v[148:151], v[188:191], v[84:87]
	v_mfma_f32_16x16x32_bf16 v[76:79], v[156:159], v[188:191], v[76:79]
	v_mfma_f32_16x16x32_bf16 v[124:127], v[152:155], v[168:171], v[124:127]
	v_mfma_f32_16x16x32_bf16 v[120:123], v[160:163], v[168:171], v[120:123]
	v_mfma_f32_16x16x32_bf16 v[116:119], v[152:155], v[176:179], v[116:119]
	v_mfma_f32_16x16x32_bf16 v[108:111], v[160:163], v[176:179], v[108:111]
	v_mfma_f32_16x16x32_bf16 v[100:103], v[152:155], v[184:187], v[100:103]
	v_mfma_f32_16x16x32_bf16 v[92:95], v[160:163], v[184:187], v[92:95]
	v_mfma_f32_16x16x32_bf16 v[84:87], v[152:155], v[192:195], v[84:87]
	v_mfma_f32_16x16x32_bf16 v[76:79], v[160:163], v[192:195], v[76:79]
	s_setprio 0
	s_barrier
	s_add_i32 s84, 0, 0x14000
	v_add_u32_e32 v140, s84, v144
	s_add_i32 s81, s81, s69
	ds_read_b128 v[196:199], v140
	ds_read_b128 v[200:203], v140 offset:1024
	ds_read_b128 v[204:207], v140 offset:2048
	ds_read_b128 v[212:215], v140 offset:3072
	v_lshl_add_u64 v[140:141], s[48:49], 0, v[128:129]
	s_mov_b32 m0, s81
	v_lshl_add_u64 v[208:209], s[48:49], 0, v[134:135]
	global_load_lds_dwordx4 v[140:141], off
	s_add_i32 m0, s81, 0x2000
	s_nop 0
	global_load_lds_dwordx4 v[208:209], off
	s_setprio 1
	s_barrier
	s_waitcnt lgkmcnt(0)
	v_mfma_f32_16x16x32_bf16 v[112:115], v[196:199], v[164:167], v[112:115]
	v_mfma_f32_16x16x32_bf16 v[104:107], v[204:207], v[164:167], v[104:107]
	v_mfma_f32_16x16x32_bf16 v[96:99], v[196:199], v[172:175], v[96:99]
	v_mfma_f32_16x16x32_bf16 v[88:91], v[204:207], v[172:175], v[88:91]
	v_mfma_f32_16x16x32_bf16 v[80:83], v[196:199], v[180:183], v[80:83]
	v_mfma_f32_16x16x32_bf16 v[72:75], v[204:207], v[180:183], v[72:75]
	v_mfma_f32_16x16x32_bf16 v[68:71], v[196:199], v[188:191], v[68:71]
	v_mfma_f32_16x16x32_bf16 v[64:67], v[204:207], v[188:191], v[64:67]
	v_mfma_f32_16x16x32_bf16 v[112:115], v[200:203], v[168:171], v[112:115]
	v_mfma_f32_16x16x32_bf16 v[104:107], v[212:215], v[168:171], v[104:107]
	v_mfma_f32_16x16x32_bf16 v[96:99], v[200:203], v[176:179], v[96:99]
	v_mfma_f32_16x16x32_bf16 v[88:91], v[212:215], v[176:179], v[88:91]
	v_mfma_f32_16x16x32_bf16 v[80:83], v[200:203], v[184:187], v[80:83]
	v_mfma_f32_16x16x32_bf16 v[72:75], v[212:215], v[184:187], v[72:75]
	v_mfma_f32_16x16x32_bf16 v[68:71], v[200:203], v[192:195], v[68:71]
	v_mfma_f32_16x16x32_bf16 v[64:67], v[212:215], v[192:195], v[64:67]
	s_setprio 0
	s_mov_b32 m0, s37
	v_lshl_add_u64 v[216:217], s[50:51], 0, v[130:131]
	s_barrier
	ds_read_b128 v[164:167], v146 offset:16384
	ds_read_b128 v[168:171], v146 offset:17408
	ds_read_b128 v[172:175], v146 offset:18432
	ds_read_b128 v[176:179], v146 offset:19456
	ds_read_b128 v[180:183], v146 offset:20480
	ds_read_b128 v[184:187], v146 offset:21504
	ds_read_b128 v[188:191], v146 offset:22528
	ds_read_b128 v[192:195], v146 offset:23552
	global_load_lds_dwordx4 v[216:217], off
	s_mov_b32 m0, s70
	v_lshl_add_u64 v[218:219], s[50:51], 0, v[132:133]
	global_load_lds_dwordx4 v[218:219], off
	s_setprio 1
	s_barrier
	s_waitcnt lgkmcnt(0)
	v_mfma_f32_16x16x32_bf16 v[60:63], v[148:151], v[164:167], v[60:63]
	v_mfma_f32_16x16x32_bf16 v[56:59], v[156:159], v[164:167], v[56:59]
	v_mfma_f32_16x16x32_bf16 v[52:55], v[148:151], v[172:175], v[52:55]
	v_mfma_f32_16x16x32_bf16 v[44:47], v[156:159], v[172:175], v[44:47]
	v_mfma_f32_16x16x32_bf16 v[36:39], v[148:151], v[180:183], v[36:39]
	v_mfma_f32_16x16x32_bf16 v[28:31], v[156:159], v[180:183], v[28:31]
	v_mfma_f32_16x16x32_bf16 v[20:23], v[148:151], v[188:191], v[20:23]
	v_mfma_f32_16x16x32_bf16 v[12:15], v[156:159], v[188:191], v[12:15]
	v_mfma_f32_16x16x32_bf16 v[60:63], v[152:155], v[168:171], v[60:63]
	v_mfma_f32_16x16x32_bf16 v[56:59], v[160:163], v[168:171], v[56:59]
	v_mfma_f32_16x16x32_bf16 v[52:55], v[152:155], v[176:179], v[52:55]
	v_mfma_f32_16x16x32_bf16 v[44:47], v[160:163], v[176:179], v[44:47]
	v_mfma_f32_16x16x32_bf16 v[36:39], v[152:155], v[184:187], v[36:39]
	v_mfma_f32_16x16x32_bf16 v[28:31], v[160:163], v[184:187], v[28:31]
	v_mfma_f32_16x16x32_bf16 v[20:23], v[152:155], v[192:195], v[20:23]
	v_mfma_f32_16x16x32_bf16 v[12:15], v[160:163], v[192:195], v[12:15]
	s_setprio 0
	s_barrier
	s_add_u32 s82, s48, 0x40000
	s_addc_u32 s83, s49, 0
	s_add_i32 s81, s84, s69
	s_mov_b32 m0, s81
	v_lshl_add_u64 v[148:149], s[82:83], 0, v[128:129]
	global_load_lds_dwordx4 v[148:149], off
	s_add_i32 m0, s81, 0x2000
	v_lshl_add_u64 v[148:149], s[82:83], 0, v[134:135]
	global_load_lds_dwordx4 v[148:149], off
	s_waitcnt vmcnt(6)
	s_setprio 1
	s_barrier
	v_mfma_f32_16x16x32_bf16 v[48:51], v[196:199], v[164:167], v[48:51]
	v_mfma_f32_16x16x32_bf16 v[40:43], v[204:207], v[164:167], v[40:43]
	v_mfma_f32_16x16x32_bf16 v[32:35], v[196:199], v[172:175], v[32:35]
	v_mfma_f32_16x16x32_bf16 v[24:27], v[204:207], v[172:175], v[24:27]
	v_mfma_f32_16x16x32_bf16 v[16:19], v[196:199], v[180:183], v[16:19]
	v_mfma_f32_16x16x32_bf16 v[8:11], v[204:207], v[180:183], v[8:11]
	v_mfma_f32_16x16x32_bf16 v[4:7], v[196:199], v[188:191], v[4:7]
	v_mfma_f32_16x16x32_bf16 v[0:3], v[204:207], v[188:191], v[0:3]
	v_mfma_f32_16x16x32_bf16 v[48:51], v[200:203], v[168:171], v[48:51]
	v_mfma_f32_16x16x32_bf16 v[40:43], v[212:215], v[168:171], v[40:43]
	v_mfma_f32_16x16x32_bf16 v[32:35], v[200:203], v[176:179], v[32:35]
	v_mfma_f32_16x16x32_bf16 v[24:27], v[212:215], v[176:179], v[24:27]
	v_mfma_f32_16x16x32_bf16 v[16:19], v[200:203], v[184:187], v[16:19]
	v_mfma_f32_16x16x32_bf16 v[8:11], v[212:215], v[184:187], v[8:11]
	v_mfma_f32_16x16x32_bf16 v[4:7], v[200:203], v[192:195], v[4:7]
	v_mfma_f32_16x16x32_bf16 v[0:3], v[212:215], v[192:195], v[0:3]
	s_setprio 0
	s_add_i32 s81, 0, 0x18000
	v_add_u32_e32 v147, s81, v144
	s_barrier
	ds_read_b128 v[148:151], v147
	ds_read_b128 v[152:155], v147 offset:1024
	ds_read_b128 v[156:159], v147 offset:2048
	ds_read_b128 v[160:163], v147 offset:3072
	s_add_u32 s50, s50, 0x40000
	s_addc_u32 s51, s51, 0
	s_mov_b32 m0, s71
	v_lshl_add_u64 v[196:197], s[50:51], 0, v[130:131]
	ds_read_b128 v[164:167], v146 offset:32768
	ds_read_b128 v[168:171], v146 offset:33792
	ds_read_b128 v[172:175], v146 offset:34816
	ds_read_b128 v[176:179], v146 offset:35840
	ds_read_b128 v[180:183], v146 offset:36864
	ds_read_b128 v[184:187], v146 offset:37888
	ds_read_b128 v[188:191], v146 offset:38912
	ds_read_b128 v[192:195], v146 offset:39936
	global_load_lds_dwordx4 v[196:197], off
	s_mov_b32 m0, s72
	v_lshl_add_u64 v[196:197], s[50:51], 0, v[132:133]
	global_load_lds_dwordx4 v[196:197], off
	s_waitcnt lgkmcnt(8)
	s_setprio 1
	s_barrier
	s_waitcnt lgkmcnt(0)
	v_mfma_f32_16x16x32_bf16 v[124:127], v[148:151], v[164:167], v[124:127]
	v_mfma_f32_16x16x32_bf16 v[120:123], v[156:159], v[164:167], v[120:123]
	v_mfma_f32_16x16x32_bf16 v[116:119], v[148:151], v[172:175], v[116:119]
	v_mfma_f32_16x16x32_bf16 v[108:111], v[156:159], v[172:175], v[108:111]
	v_mfma_f32_16x16x32_bf16 v[100:103], v[148:151], v[180:183], v[100:103]
	v_mfma_f32_16x16x32_bf16 v[92:95], v[156:159], v[180:183], v[92:95]
	v_mfma_f32_16x16x32_bf16 v[84:87], v[148:151], v[188:191], v[84:87]
	v_mfma_f32_16x16x32_bf16 v[76:79], v[156:159], v[188:191], v[76:79]
	v_mfma_f32_16x16x32_bf16 v[124:127], v[152:155], v[168:171], v[124:127]
	v_mfma_f32_16x16x32_bf16 v[120:123], v[160:163], v[168:171], v[120:123]
	v_mfma_f32_16x16x32_bf16 v[116:119], v[152:155], v[176:179], v[116:119]
	v_mfma_f32_16x16x32_bf16 v[108:111], v[160:163], v[176:179], v[108:111]
	v_mfma_f32_16x16x32_bf16 v[100:103], v[152:155], v[184:187], v[100:103]
	v_mfma_f32_16x16x32_bf16 v[92:95], v[160:163], v[184:187], v[92:95]
	v_mfma_f32_16x16x32_bf16 v[84:87], v[152:155], v[192:195], v[84:87]
	v_mfma_f32_16x16x32_bf16 v[76:79], v[160:163], v[192:195], v[76:79]
	s_setprio 0
	s_barrier
	s_add_i32 s50, 0, 0x1c000
	s_add_i32 s51, s81, s69
	v_add_u32_e32 v147, s50, v144
	v_lshl_add_u64 v[140:141], v[140:141], 0, s[2:3]
	s_mov_b32 m0, s51
	ds_read_b128 v[196:199], v147
	ds_read_b128 v[200:203], v147 offset:1024
	ds_read_b128 v[204:207], v147 offset:2048
	ds_read_b128 v[212:215], v147 offset:3072
	global_load_lds_dwordx4 v[140:141], off
	s_add_i32 m0, s51, 0x2000
	v_lshl_add_u64 v[140:141], v[208:209], 0, s[2:3]
	global_load_lds_dwordx4 v[140:141], off
	s_setprio 1
	s_barrier
	s_waitcnt lgkmcnt(0)
	v_mfma_f32_16x16x32_bf16 v[112:115], v[196:199], v[164:167], v[112:115]
	v_mfma_f32_16x16x32_bf16 v[104:107], v[204:207], v[164:167], v[104:107]
	v_mfma_f32_16x16x32_bf16 v[96:99], v[196:199], v[172:175], v[96:99]
	v_mfma_f32_16x16x32_bf16 v[88:91], v[204:207], v[172:175], v[88:91]
	v_mfma_f32_16x16x32_bf16 v[80:83], v[196:199], v[180:183], v[80:83]
	v_mfma_f32_16x16x32_bf16 v[72:75], v[204:207], v[180:183], v[72:75]
	v_mfma_f32_16x16x32_bf16 v[68:71], v[196:199], v[188:191], v[68:71]
	v_mfma_f32_16x16x32_bf16 v[64:67], v[204:207], v[188:191], v[64:67]
	v_mfma_f32_16x16x32_bf16 v[112:115], v[200:203], v[168:171], v[112:115]
	v_mfma_f32_16x16x32_bf16 v[104:107], v[212:215], v[168:171], v[104:107]
	v_mfma_f32_16x16x32_bf16 v[96:99], v[200:203], v[176:179], v[96:99]
	v_mfma_f32_16x16x32_bf16 v[88:91], v[212:215], v[176:179], v[88:91]
	v_mfma_f32_16x16x32_bf16 v[80:83], v[200:203], v[184:187], v[80:83]
	v_mfma_f32_16x16x32_bf16 v[72:75], v[212:215], v[184:187], v[72:75]
	v_mfma_f32_16x16x32_bf16 v[68:71], v[200:203], v[192:195], v[68:71]
	v_mfma_f32_16x16x32_bf16 v[64:67], v[212:215], v[192:195], v[64:67]
	s_setprio 0
	s_mov_b32 m0, s0
	v_lshl_add_u64 v[140:141], v[216:217], 0, s[2:3]
	s_barrier
	ds_read_b128 v[164:167], v146 offset:49152
	ds_read_b128 v[168:171], v146 offset:50176
	ds_read_b128 v[172:175], v146 offset:51200
	ds_read_b128 v[176:179], v146 offset:52224
	ds_read_b128 v[180:183], v146 offset:53248
	ds_read_b128 v[184:187], v146 offset:54272
	ds_read_b128 v[188:191], v146 offset:55296
	ds_read_b128 v[192:195], v146 offset:56320
	global_load_lds_dwordx4 v[140:141], off
	s_mov_b32 m0, s73
	v_lshl_add_u64 v[140:141], v[218:219], 0, s[2:3]
	global_load_lds_dwordx4 v[140:141], off
	s_setprio 1
	s_barrier
	s_waitcnt lgkmcnt(0)
	v_mfma_f32_16x16x32_bf16 v[60:63], v[148:151], v[164:167], v[60:63]
	v_mfma_f32_16x16x32_bf16 v[56:59], v[156:159], v[164:167], v[56:59]
	v_mfma_f32_16x16x32_bf16 v[52:55], v[148:151], v[172:175], v[52:55]
	v_mfma_f32_16x16x32_bf16 v[44:47], v[156:159], v[172:175], v[44:47]
	v_mfma_f32_16x16x32_bf16 v[36:39], v[148:151], v[180:183], v[36:39]
	v_mfma_f32_16x16x32_bf16 v[28:31], v[156:159], v[180:183], v[28:31]
	v_mfma_f32_16x16x32_bf16 v[20:23], v[148:151], v[188:191], v[20:23]
	v_mfma_f32_16x16x32_bf16 v[12:15], v[156:159], v[188:191], v[12:15]
	v_mfma_f32_16x16x32_bf16 v[60:63], v[152:155], v[168:171], v[60:63]
	v_mfma_f32_16x16x32_bf16 v[56:59], v[160:163], v[168:171], v[56:59]
	v_mfma_f32_16x16x32_bf16 v[52:55], v[152:155], v[176:179], v[52:55]
	v_mfma_f32_16x16x32_bf16 v[44:47], v[160:163], v[176:179], v[44:47]
	v_mfma_f32_16x16x32_bf16 v[36:39], v[152:155], v[184:187], v[36:39]
	v_mfma_f32_16x16x32_bf16 v[28:31], v[160:163], v[184:187], v[28:31]
	v_mfma_f32_16x16x32_bf16 v[20:23], v[152:155], v[192:195], v[20:23]
	v_mfma_f32_16x16x32_bf16 v[12:15], v[160:163], v[192:195], v[12:15]
	s_setprio 0
	s_barrier
	s_add_u32 s48, s48, 0x40080
	s_addc_u32 s49, s49, 0
	s_add_i32 s50, s50, s69
	s_mov_b32 m0, s50
	v_lshl_add_u64 v[140:141], s[48:49], 0, v[128:129]
	global_load_lds_dwordx4 v[140:141], off
	s_add_i32 m0, s50, 0x2000
	v_lshl_add_u64 v[140:141], s[48:49], 0, v[134:135]
	global_load_lds_dwordx4 v[140:141], off
	s_waitcnt vmcnt(6)
	s_setprio 1
	s_barrier
	v_mfma_f32_16x16x32_bf16 v[48:51], v[196:199], v[164:167], v[48:51]
	v_mfma_f32_16x16x32_bf16 v[40:43], v[204:207], v[164:167], v[40:43]
	v_mfma_f32_16x16x32_bf16 v[32:35], v[196:199], v[172:175], v[32:35]
	v_mfma_f32_16x16x32_bf16 v[24:27], v[204:207], v[172:175], v[24:27]
	v_mfma_f32_16x16x32_bf16 v[16:19], v[196:199], v[180:183], v[16:19]
	v_mfma_f32_16x16x32_bf16 v[8:11], v[204:207], v[180:183], v[8:11]
	v_mfma_f32_16x16x32_bf16 v[4:7], v[196:199], v[188:191], v[4:7]
	v_mfma_f32_16x16x32_bf16 v[0:3], v[204:207], v[188:191], v[0:3]
	v_mfma_f32_16x16x32_bf16 v[48:51], v[200:203], v[168:171], v[48:51]
	v_mfma_f32_16x16x32_bf16 v[40:43], v[212:215], v[168:171], v[40:43]
	v_mfma_f32_16x16x32_bf16 v[32:35], v[200:203], v[176:179], v[32:35]
	v_mfma_f32_16x16x32_bf16 v[24:27], v[212:215], v[176:179], v[24:27]
	v_mfma_f32_16x16x32_bf16 v[16:19], v[200:203], v[184:187], v[16:19]
	v_mfma_f32_16x16x32_bf16 v[8:11], v[212:215], v[184:187], v[8:11]
	v_mfma_f32_16x16x32_bf16 v[4:7], v[200:203], v[192:195], v[4:7]
	v_mfma_f32_16x16x32_bf16 v[0:3], v[212:215], v[192:195], v[0:3]
	s_setprio 0
	s_add_i32 s80, s80, 2
	s_add_u32 s42, s42, 0x100
	s_addc_u32 s43, s43, 0
	s_add_u32 s78, s78, 0x100
	s_addc_u32 s79, s79, 0
	s_cmp_gt_u32 s80, 13
	s_barrier
	s_cbranch_scc0 .LBB0_200
	v_lshl_add_u32 v148, s36, 8, v143
	v_ashrrev_i32_e32 v149, 31, v148
	v_lshl_or_b32 v140, s75, 8, v145
	v_ashrrev_i32_e32 v141, 31, v140
	v_lshlrev_b64 v[150:151], 10, v[148:149]
	v_lshl_add_u64 v[150:151], s[14:15], 0, v[150:151]
	v_lshlrev_b64 v[152:153], 1, v[140:141]
	v_lshl_add_u64 v[140:141], v[150:151], 0, v[152:153]
	v_cvt_pk_bf16_f32 v124, v124, v125
	v_cvt_pk_bf16_f32 v125, v126, v127
	v_cvt_pk_bf16_f32 v126, v120, v121
	v_cvt_pk_bf16_f32 v127, v122, v123
	global_store_dwordx4 v[140:141], v[124:127], off nt
	v_cvt_pk_bf16_f32 v112, v112, v113
	v_cvt_pk_bf16_f32 v113, v114, v115
	v_cvt_pk_bf16_f32 v114, v104, v105
	v_or_b32_e32 v104, 16, v148
	v_ashrrev_i32_e32 v105, 31, v104
	v_lshlrev_b64 v[104:105], 10, v[104:105]
	v_lshl_add_u64 v[104:105], s[14:15], 0, v[104:105]
	v_cvt_pk_bf16_f32 v115, v106, v107
	global_store_dwordx4 v[140:141], v[112:115], off offset:256 nt
	s_mov_b32 s31, 0x20000
	s_mov_b64 s[42:43], 0x20000
	v_lshl_add_u64 v[112:113], v[104:105], 0, v[152:153]
	v_cvt_pk_bf16_f32 v104, v116, v117
	v_cvt_pk_bf16_f32 v105, v118, v119
	v_cvt_pk_bf16_f32 v106, v108, v109
	v_cvt_pk_bf16_f32 v107, v110, v111
	global_store_dwordx4 v[112:113], v[104:107], off nt
	v_cvt_pk_bf16_f32 v96, v96, v97
	v_cvt_pk_bf16_f32 v97, v98, v99
	v_cvt_pk_bf16_f32 v98, v88, v89
	v_or_b32_e32 v88, 32, v148
	v_ashrrev_i32_e32 v89, 31, v88
	v_lshlrev_b64 v[88:89], 10, v[88:89]
	v_lshl_add_u64 v[88:89], s[14:15], 0, v[88:89]
	v_cvt_pk_bf16_f32 v99, v90, v91
	global_store_dwordx4 v[112:113], v[96:99], off offset:256 nt
	s_mov_b32 s75, s30
	s_mov_b32 s36, s34
	v_lshl_add_u64 v[96:97], v[88:89], 0, v[152:153]
	v_cvt_pk_bf16_f32 v88, v100, v101
	v_cvt_pk_bf16_f32 v89, v102, v103
	v_cvt_pk_bf16_f32 v90, v92, v93
	v_cvt_pk_bf16_f32 v91, v94, v95
	global_store_dwordx4 v[96:97], v[88:91], off nt
	v_cvt_pk_bf16_f32 v80, v80, v81
	v_cvt_pk_bf16_f32 v81, v82, v83
	v_cvt_pk_bf16_f32 v82, v72, v73
	v_or_b32_e32 v72, 48, v148
	v_ashrrev_i32_e32 v73, 31, v72
	v_lshlrev_b64 v[72:73], 10, v[72:73]
	v_lshl_add_u64 v[72:73], s[14:15], 0, v[72:73]
	v_cvt_pk_bf16_f32 v83, v74, v75
	global_store_dwordx4 v[96:97], v[80:83], off offset:256 nt
	s_mov_b64 s[48:49], s[40:41]
	s_nop 0
	v_lshl_add_u64 v[80:81], v[72:73], 0, v[152:153]
	v_cvt_pk_bf16_f32 v72, v84, v85
	v_cvt_pk_bf16_f32 v73, v86, v87
	v_cvt_pk_bf16_f32 v74, v76, v77
	v_cvt_pk_bf16_f32 v75, v78, v79
	global_store_dwordx4 v[80:81], v[72:75], off nt
	v_cvt_pk_bf16_f32 v68, v68, v69
	v_cvt_pk_bf16_f32 v69, v70, v71
	v_cvt_pk_bf16_f32 v70, v64, v65
	v_cvt_pk_bf16_f32 v71, v66, v67
	global_store_dwordx4 v[80:81], v[68:71], off offset:256 nt
	v_cvt_pk_bf16_f32 v60, v60, v61
	v_cvt_pk_bf16_f32 v61, v62, v63
	v_cvt_pk_bf16_f32 v62, v56, v57
	v_add_co_u32_e32 v56, vcc, s31, v140
	v_lshl_add_u64 v[64:65], v[140:141], 0, s[42:43]
	s_nop 0
	v_addc_co_u32_e32 v57, vcc, 0, v141, vcc
	s_mov_b32 s31, 0x24000
	v_cvt_pk_bf16_f32 v63, v58, v59
	global_store_dwordx4 v[56:57], v[60:63], off nt
	v_cvt_pk_bf16_f32 v48, v48, v49
	v_cvt_pk_bf16_f32 v49, v50, v51
	v_cvt_pk_bf16_f32 v50, v40, v41
	v_cvt_pk_bf16_f32 v51, v42, v43
	global_store_dwordx4 v[64:65], v[48:51], off offset:256 nt
	s_mov_b64 s[42:43], 0x24000
	v_cvt_pk_bf16_f32 v40, v52, v53
	v_cvt_pk_bf16_f32 v41, v54, v55
	v_cvt_pk_bf16_f32 v42, v44, v45
	v_add_co_u32_e32 v44, vcc, s31, v140
	v_lshl_add_u64 v[48:49], v[140:141], 0, s[42:43]
	s_nop 0
	v_addc_co_u32_e32 v45, vcc, 0, v141, vcc
	s_mov_b32 s31, 0x28000
	v_cvt_pk_bf16_f32 v43, v46, v47
	global_store_dwordx4 v[44:45], v[40:43], off nt
	v_cvt_pk_bf16_f32 v32, v32, v33
	v_cvt_pk_bf16_f32 v33, v34, v35
	v_cvt_pk_bf16_f32 v34, v24, v25
	v_cvt_pk_bf16_f32 v35, v26, v27
	global_store_dwordx4 v[48:49], v[32:35], off offset:256 nt
	s_mov_b64 s[42:43], 0x28000
	v_cvt_pk_bf16_f32 v24, v36, v37
	v_cvt_pk_bf16_f32 v25, v38, v39
	v_cvt_pk_bf16_f32 v26, v28, v29
	v_add_co_u32_e32 v28, vcc, s31, v140
	v_lshl_add_u64 v[32:33], v[140:141], 0, s[42:43]
	s_nop 0
	v_addc_co_u32_e32 v29, vcc, 0, v141, vcc
	s_mov_b32 s31, 0x2c000
	v_cvt_pk_bf16_f32 v27, v30, v31
	global_store_dwordx4 v[28:29], v[24:27], off nt
	v_cvt_pk_bf16_f32 v16, v16, v17
	v_cvt_pk_bf16_f32 v17, v18, v19
	v_cvt_pk_bf16_f32 v18, v8, v9
	v_cvt_pk_bf16_f32 v19, v10, v11
	global_store_dwordx4 v[32:33], v[16:19], off offset:256 nt
	v_cvt_pk_bf16_f32 v8, v20, v21
	v_cvt_pk_bf16_f32 v9, v22, v23
	v_cvt_pk_bf16_f32 v10, v12, v13
	v_add_co_u32_e32 v12, vcc, s31, v140
	s_mov_b64 s[42:43], 0x2c000
	s_nop 0
	v_addc_co_u32_e32 v13, vcc, 0, v141, vcc
	v_lshl_add_u64 v[16:17], v[140:141], 0, s[42:43]
	s_and_b64 vcc, exec, s[28:29]
	s_mov_b64 s[42:43], s[38:39]
	v_cvt_pk_bf16_f32 v11, v14, v15
	global_store_dwordx4 v[12:13], v[8:11], off nt
	v_cvt_pk_bf16_f32 v4, v4, v5
	v_cvt_pk_bf16_f32 v5, v6, v7
	v_cvt_pk_bf16_f32 v6, v0, v1
	v_cvt_pk_bf16_f32 v7, v2, v3
	global_store_dwordx4 v[16:17], v[4:7], off offset:256 nt
	s_cbranch_vccz .LBB0_193
	s_waitcnt vmcnt(0)
	s_cmpk_gt_u32 s65, 0xff
	s_cbranch_scc1 .LBB0_204
	s_barrier

.LBB0_220:
	s_add_u32 s40, s38, 0xfffc0080
	s_addc_u32 s41, s39, -1
	s_add_i32 s76, 0, 0x10000
	v_add_u32_e32 v140, s76, v144
	ds_read_b128 v[148:151], v140
	ds_read_b128 v[152:155], v140 offset:1024
	ds_read_b128 v[156:159], v140 offset:2048
	ds_read_b128 v[160:163], v140 offset:3072
	s_cmp_eq_u32 s75, 12
	s_cselect_b32 s43, s29, s41
	s_cselect_b32 s42, s71, s40
	s_cselect_b32 s41, s15, s74
	s_cselect_b32 s40, s72, s73
	v_lshl_add_u64 v[140:141], s[38:39], 0, v[136:137]
	s_add_i32 m0, s31, 0xc000
	ds_read_b128 v[164:167], v146
	ds_read_b128 v[168:171], v146 offset:1024
	ds_read_b128 v[172:175], v146 offset:2048
	ds_read_b128 v[176:179], v146 offset:3072
	ds_read_b128 v[180:183], v146 offset:4096
	ds_read_b128 v[184:187], v146 offset:5120
	ds_read_b128 v[188:191], v146 offset:6144
	ds_read_b128 v[192:195], v146 offset:7168
	global_load_lds_dwordx4 v[140:141], off
	s_add_i32 m0, s31, 0xe000
	v_lshl_add_u64 v[140:141], s[38:39], 0, v[138:139]
	global_load_lds_dwordx4 v[140:141], off
	s_waitcnt lgkmcnt(8)
	s_setprio 1
	s_barrier
	s_waitcnt lgkmcnt(0)
	v_mfma_f32_16x16x32_bf16 v[124:127], v[148:151], v[164:167], v[124:127]
	v_mfma_f32_16x16x32_bf16 v[120:123], v[156:159], v[164:167], v[120:123]
	v_mfma_f32_16x16x32_bf16 v[116:119], v[148:151], v[172:175], v[116:119]
	v_mfma_f32_16x16x32_bf16 v[108:111], v[156:159], v[172:175], v[108:111]
	v_mfma_f32_16x16x32_bf16 v[100:103], v[148:151], v[180:183], v[100:103]
	v_mfma_f32_16x16x32_bf16 v[92:95], v[156:159], v[180:183], v[92:95]
	v_mfma_f32_16x16x32_bf16 v[84:87], v[148:151], v[188:191], v[84:87]
	v_mfma_f32_16x16x32_bf16 v[76:79], v[156:159], v[188:191], v[76:79]
	v_mfma_f32_16x16x32_bf16 v[124:127], v[152:155], v[168:171], v[124:127]
	v_mfma_f32_16x16x32_bf16 v[120:123], v[160:163], v[168:171], v[120:123]
	v_mfma_f32_16x16x32_bf16 v[116:119], v[152:155], v[176:179], v[116:119]
	v_mfma_f32_16x16x32_bf16 v[108:111], v[160:163], v[176:179], v[108:111]
	v_mfma_f32_16x16x32_bf16 v[100:103], v[152:155], v[184:187], v[100:103]
	v_mfma_f32_16x16x32_bf16 v[92:95], v[160:163], v[184:187], v[92:95]
	v_mfma_f32_16x16x32_bf16 v[84:87], v[152:155], v[192:195], v[84:87]
	v_mfma_f32_16x16x32_bf16 v[76:79], v[160:163], v[192:195], v[76:79]
	s_setprio 0
	s_barrier
	s_add_i32 s78, 0, 0x14000
	v_add_u32_e32 v140, s78, v144
	s_add_i32 s76, s76, s64
	ds_read_b128 v[196:199], v140
	ds_read_b128 v[200:203], v140 offset:1024
	ds_read_b128 v[204:207], v140 offset:2048
	ds_read_b128 v[212:215], v140 offset:3072
	v_lshl_add_u64 v[140:141], s[40:41], 0, v[128:129]
	s_mov_b32 m0, s76
	v_lshl_add_u64 v[208:209], s[40:41], 0, v[134:135]
	global_load_lds_dwordx4 v[140:141], off
	s_add_i32 m0, s76, 0x2000
	s_nop 0
	global_load_lds_dwordx4 v[208:209], off
	s_setprio 1
	s_barrier
	s_waitcnt lgkmcnt(0)
	v_mfma_f32_16x16x32_bf16 v[112:115], v[196:199], v[164:167], v[112:115]
	v_mfma_f32_16x16x32_bf16 v[104:107], v[204:207], v[164:167], v[104:107]
	v_mfma_f32_16x16x32_bf16 v[96:99], v[196:199], v[172:175], v[96:99]
	v_mfma_f32_16x16x32_bf16 v[88:91], v[204:207], v[172:175], v[88:91]
	v_mfma_f32_16x16x32_bf16 v[80:83], v[196:199], v[180:183], v[80:83]
	v_mfma_f32_16x16x32_bf16 v[72:75], v[204:207], v[180:183], v[72:75]
	v_mfma_f32_16x16x32_bf16 v[68:71], v[196:199], v[188:191], v[68:71]
	v_mfma_f32_16x16x32_bf16 v[64:67], v[204:207], v[188:191], v[64:67]
	v_mfma_f32_16x16x32_bf16 v[112:115], v[200:203], v[168:171], v[112:115]
	v_mfma_f32_16x16x32_bf16 v[104:107], v[212:215], v[168:171], v[104:107]
	v_mfma_f32_16x16x32_bf16 v[96:99], v[200:203], v[176:179], v[96:99]
	v_mfma_f32_16x16x32_bf16 v[88:91], v[212:215], v[176:179], v[88:91]
	v_mfma_f32_16x16x32_bf16 v[80:83], v[200:203], v[184:187], v[80:83]
	v_mfma_f32_16x16x32_bf16 v[72:75], v[212:215], v[184:187], v[72:75]
	v_mfma_f32_16x16x32_bf16 v[68:71], v[200:203], v[192:195], v[68:71]
	v_mfma_f32_16x16x32_bf16 v[64:67], v[212:215], v[192:195], v[64:67]
	s_setprio 0
	s_mov_b32 m0, s31
	v_lshl_add_u64 v[216:217], s[42:43], 0, v[130:131]
	s_barrier
	ds_read_b128 v[164:167], v146 offset:16384
	ds_read_b128 v[168:171], v146 offset:17408
	ds_read_b128 v[172:175], v146 offset:18432
	ds_read_b128 v[176:179], v146 offset:19456
	ds_read_b128 v[180:183], v146 offset:20480
	ds_read_b128 v[184:187], v146 offset:21504
	ds_read_b128 v[188:191], v146 offset:22528
	ds_read_b128 v[192:195], v146 offset:23552
	global_load_lds_dwordx4 v[216:217], off
	s_mov_b32 m0, s65
	v_lshl_add_u64 v[218:219], s[42:43], 0, v[132:133]
	global_load_lds_dwordx4 v[218:219], off
	s_setprio 1
	s_barrier
	s_waitcnt lgkmcnt(0)
	v_mfma_f32_16x16x32_bf16 v[60:63], v[148:151], v[164:167], v[60:63]
	v_mfma_f32_16x16x32_bf16 v[56:59], v[156:159], v[164:167], v[56:59]
	v_mfma_f32_16x16x32_bf16 v[52:55], v[148:151], v[172:175], v[52:55]
	v_mfma_f32_16x16x32_bf16 v[44:47], v[156:159], v[172:175], v[44:47]
	v_mfma_f32_16x16x32_bf16 v[36:39], v[148:151], v[180:183], v[36:39]
	v_mfma_f32_16x16x32_bf16 v[28:31], v[156:159], v[180:183], v[28:31]
	v_mfma_f32_16x16x32_bf16 v[20:23], v[148:151], v[188:191], v[20:23]
	v_mfma_f32_16x16x32_bf16 v[12:15], v[156:159], v[188:191], v[12:15]
	v_mfma_f32_16x16x32_bf16 v[60:63], v[152:155], v[168:171], v[60:63]
	v_mfma_f32_16x16x32_bf16 v[56:59], v[160:163], v[168:171], v[56:59]
	v_mfma_f32_16x16x32_bf16 v[52:55], v[152:155], v[176:179], v[52:55]
	v_mfma_f32_16x16x32_bf16 v[44:47], v[160:163], v[176:179], v[44:47]
	v_mfma_f32_16x16x32_bf16 v[36:39], v[152:155], v[184:187], v[36:39]
	v_mfma_f32_16x16x32_bf16 v[28:31], v[160:163], v[184:187], v[28:31]
	v_mfma_f32_16x16x32_bf16 v[20:23], v[152:155], v[192:195], v[20:23]
	v_mfma_f32_16x16x32_bf16 v[12:15], v[160:163], v[192:195], v[12:15]
	s_setprio 0
	s_barrier
	s_add_u32 s76, s40, 0x40000
	s_addc_u32 s77, s41, 0
	s_add_i32 s78, s78, s64
	s_mov_b32 m0, s78
	v_lshl_add_u64 v[148:149], s[76:77], 0, v[128:129]
	global_load_lds_dwordx4 v[148:149], off
	s_add_i32 m0, s78, 0x2000
	v_lshl_add_u64 v[148:149], s[76:77], 0, v[134:135]
	global_load_lds_dwordx4 v[148:149], off
	s_waitcnt vmcnt(6)
	s_setprio 1
	s_barrier
	v_mfma_f32_16x16x32_bf16 v[48:51], v[196:199], v[164:167], v[48:51]
	v_mfma_f32_16x16x32_bf16 v[40:43], v[204:207], v[164:167], v[40:43]
	v_mfma_f32_16x16x32_bf16 v[32:35], v[196:199], v[172:175], v[32:35]
	v_mfma_f32_16x16x32_bf16 v[24:27], v[204:207], v[172:175], v[24:27]
	v_mfma_f32_16x16x32_bf16 v[16:19], v[196:199], v[180:183], v[16:19]
	v_mfma_f32_16x16x32_bf16 v[8:11], v[204:207], v[180:183], v[8:11]
	v_mfma_f32_16x16x32_bf16 v[4:7], v[196:199], v[188:191], v[4:7]
	v_mfma_f32_16x16x32_bf16 v[0:3], v[204:207], v[188:191], v[0:3]
	v_mfma_f32_16x16x32_bf16 v[48:51], v[200:203], v[168:171], v[48:51]
	v_mfma_f32_16x16x32_bf16 v[40:43], v[212:215], v[168:171], v[40:43]
	v_mfma_f32_16x16x32_bf16 v[32:35], v[200:203], v[176:179], v[32:35]
	v_mfma_f32_16x16x32_bf16 v[24:27], v[212:215], v[176:179], v[24:27]
	v_mfma_f32_16x16x32_bf16 v[16:19], v[200:203], v[184:187], v[16:19]
	v_mfma_f32_16x16x32_bf16 v[8:11], v[212:215], v[184:187], v[8:11]
	v_mfma_f32_16x16x32_bf16 v[4:7], v[200:203], v[192:195], v[4:7]
	v_mfma_f32_16x16x32_bf16 v[0:3], v[212:215], v[192:195], v[0:3]
	s_setprio 0
	s_add_i32 s76, 0, 0x18000
	v_add_u32_e32 v147, s76, v144
	s_barrier
	ds_read_b128 v[148:151], v147
	ds_read_b128 v[152:155], v147 offset:1024
	ds_read_b128 v[156:159], v147 offset:2048
	ds_read_b128 v[160:163], v147 offset:3072
	s_add_u32 s42, s42, 0x40000
	s_addc_u32 s43, s43, 0
	s_mov_b32 m0, s66
	v_lshl_add_u64 v[196:197], s[42:43], 0, v[130:131]
	ds_read_b128 v[164:167], v146 offset:32768
	ds_read_b128 v[168:171], v146 offset:33792
	ds_read_b128 v[172:175], v146 offset:34816
	ds_read_b128 v[176:179], v146 offset:35840
	ds_read_b128 v[180:183], v146 offset:36864
	ds_read_b128 v[184:187], v146 offset:37888
	ds_read_b128 v[188:191], v146 offset:38912
	ds_read_b128 v[192:195], v146 offset:39936
	global_load_lds_dwordx4 v[196:197], off
	s_mov_b32 m0, s67
	v_lshl_add_u64 v[196:197], s[42:43], 0, v[132:133]
	global_load_lds_dwordx4 v[196:197], off
	s_waitcnt lgkmcnt(8)
	s_setprio 1
	s_barrier
	s_waitcnt lgkmcnt(0)
	v_mfma_f32_16x16x32_bf16 v[124:127], v[148:151], v[164:167], v[124:127]
	v_mfma_f32_16x16x32_bf16 v[120:123], v[156:159], v[164:167], v[120:123]
	v_mfma_f32_16x16x32_bf16 v[116:119], v[148:151], v[172:175], v[116:119]
	v_mfma_f32_16x16x32_bf16 v[108:111], v[156:159], v[172:175], v[108:111]
	v_mfma_f32_16x16x32_bf16 v[100:103], v[148:151], v[180:183], v[100:103]
	v_mfma_f32_16x16x32_bf16 v[92:95], v[156:159], v[180:183], v[92:95]
	v_mfma_f32_16x16x32_bf16 v[84:87], v[148:151], v[188:191], v[84:87]
	v_mfma_f32_16x16x32_bf16 v[76:79], v[156:159], v[188:191], v[76:79]
	v_mfma_f32_16x16x32_bf16 v[124:127], v[152:155], v[168:171], v[124:127]
	v_mfma_f32_16x16x32_bf16 v[120:123], v[160:163], v[168:171], v[120:123]
	v_mfma_f32_16x16x32_bf16 v[116:119], v[152:155], v[176:179], v[116:119]
	v_mfma_f32_16x16x32_bf16 v[108:111], v[160:163], v[176:179], v[108:111]
	v_mfma_f32_16x16x32_bf16 v[100:103], v[152:155], v[184:187], v[100:103]
	v_mfma_f32_16x16x32_bf16 v[92:95], v[160:163], v[184:187], v[92:95]
	v_mfma_f32_16x16x32_bf16 v[84:87], v[152:155], v[192:195], v[84:87]
	v_mfma_f32_16x16x32_bf16 v[76:79], v[160:163], v[192:195], v[76:79]
	s_setprio 0
	s_barrier
	s_add_i32 s42, 0, 0x1c000
	s_add_i32 s43, s76, s64
	v_add_u32_e32 v147, s42, v144
	v_lshl_add_u64 v[140:141], v[140:141], 0, s[2:3]
	s_mov_b32 m0, s43
	ds_read_b128 v[196:199], v147
	ds_read_b128 v[200:203], v147 offset:1024
	ds_read_b128 v[204:207], v147 offset:2048
	ds_read_b128 v[212:215], v147 offset:3072
	global_load_lds_dwordx4 v[140:141], off
	s_add_i32 m0, s43, 0x2000
	v_lshl_add_u64 v[140:141], v[208:209], 0, s[2:3]
	global_load_lds_dwordx4 v[140:141], off
	s_setprio 1
	s_barrier
	s_waitcnt lgkmcnt(0)
	v_mfma_f32_16x16x32_bf16 v[112:115], v[196:199], v[164:167], v[112:115]
	v_mfma_f32_16x16x32_bf16 v[104:107], v[204:207], v[164:167], v[104:107]
	v_mfma_f32_16x16x32_bf16 v[96:99], v[196:199], v[172:175], v[96:99]
	v_mfma_f32_16x16x32_bf16 v[88:91], v[204:207], v[172:175], v[88:91]
	v_mfma_f32_16x16x32_bf16 v[80:83], v[196:199], v[180:183], v[80:83]
	v_mfma_f32_16x16x32_bf16 v[72:75], v[204:207], v[180:183], v[72:75]
	v_mfma_f32_16x16x32_bf16 v[68:71], v[196:199], v[188:191], v[68:71]
	v_mfma_f32_16x16x32_bf16 v[64:67], v[204:207], v[188:191], v[64:67]
	v_mfma_f32_16x16x32_bf16 v[112:115], v[200:203], v[168:171], v[112:115]
	v_mfma_f32_16x16x32_bf16 v[104:107], v[212:215], v[168:171], v[104:107]
	v_mfma_f32_16x16x32_bf16 v[96:99], v[200:203], v[176:179], v[96:99]
	v_mfma_f32_16x16x32_bf16 v[88:91], v[212:215], v[176:179], v[88:91]
	v_mfma_f32_16x16x32_bf16 v[80:83], v[200:203], v[184:187], v[80:83]
	v_mfma_f32_16x16x32_bf16 v[72:75], v[212:215], v[184:187], v[72:75]
	v_mfma_f32_16x16x32_bf16 v[68:71], v[200:203], v[192:195], v[68:71]
	v_mfma_f32_16x16x32_bf16 v[64:67], v[212:215], v[192:195], v[64:67]
	s_setprio 0
	s_mov_b32 m0, s0
	v_lshl_add_u64 v[140:141], v[216:217], 0, s[2:3]
	s_barrier
	ds_read_b128 v[164:167], v146 offset:49152
	ds_read_b128 v[168:171], v146 offset:50176
	ds_read_b128 v[172:175], v146 offset:51200
	ds_read_b128 v[176:179], v146 offset:52224
	ds_read_b128 v[180:183], v146 offset:53248
	ds_read_b128 v[184:187], v146 offset:54272
	ds_read_b128 v[188:191], v146 offset:55296
	ds_read_b128 v[192:195], v146 offset:56320
	global_load_lds_dwordx4 v[140:141], off
	s_mov_b32 m0, s68
	v_lshl_add_u64 v[140:141], v[218:219], 0, s[2:3]
	global_load_lds_dwordx4 v[140:141], off
	s_setprio 1
	s_barrier
	s_waitcnt lgkmcnt(0)
	v_mfma_f32_16x16x32_bf16 v[60:63], v[148:151], v[164:167], v[60:63]
	v_mfma_f32_16x16x32_bf16 v[56:59], v[156:159], v[164:167], v[56:59]
	v_mfma_f32_16x16x32_bf16 v[52:55], v[148:151], v[172:175], v[52:55]
	v_mfma_f32_16x16x32_bf16 v[44:47], v[156:159], v[172:175], v[44:47]
	v_mfma_f32_16x16x32_bf16 v[36:39], v[148:151], v[180:183], v[36:39]
	v_mfma_f32_16x16x32_bf16 v[28:31], v[156:159], v[180:183], v[28:31]
	v_mfma_f32_16x16x32_bf16 v[20:23], v[148:151], v[188:191], v[20:23]
	v_mfma_f32_16x16x32_bf16 v[12:15], v[156:159], v[188:191], v[12:15]
	v_mfma_f32_16x16x32_bf16 v[60:63], v[152:155], v[168:171], v[60:63]
	v_mfma_f32_16x16x32_bf16 v[56:59], v[160:163], v[168:171], v[56:59]
	v_mfma_f32_16x16x32_bf16 v[52:55], v[152:155], v[176:179], v[52:55]
	v_mfma_f32_16x16x32_bf16 v[44:47], v[160:163], v[176:179], v[44:47]
	v_mfma_f32_16x16x32_bf16 v[36:39], v[152:155], v[184:187], v[36:39]
	v_mfma_f32_16x16x32_bf16 v[28:31], v[160:163], v[184:187], v[28:31]
	v_mfma_f32_16x16x32_bf16 v[20:23], v[152:155], v[192:195], v[20:23]
	v_mfma_f32_16x16x32_bf16 v[12:15], v[160:163], v[192:195], v[12:15]
	s_setprio 0
	s_barrier
	s_add_u32 s40, s40, 0x40080
	s_addc_u32 s41, s41, 0
	s_add_i32 s42, s42, s64
	s_mov_b32 m0, s42
	v_lshl_add_u64 v[140:141], s[40:41], 0, v[128:129]
	global_load_lds_dwordx4 v[140:141], off
	s_add_i32 m0, s42, 0x2000
	v_lshl_add_u64 v[140:141], s[40:41], 0, v[134:135]
	global_load_lds_dwordx4 v[140:141], off
	s_waitcnt vmcnt(6)
	s_setprio 1
	s_barrier
	v_mfma_f32_16x16x32_bf16 v[48:51], v[196:199], v[164:167], v[48:51]
	v_mfma_f32_16x16x32_bf16 v[40:43], v[204:207], v[164:167], v[40:43]
	v_mfma_f32_16x16x32_bf16 v[32:35], v[196:199], v[172:175], v[32:35]
	v_mfma_f32_16x16x32_bf16 v[24:27], v[204:207], v[172:175], v[24:27]
	v_mfma_f32_16x16x32_bf16 v[16:19], v[196:199], v[180:183], v[16:19]
	v_mfma_f32_16x16x32_bf16 v[8:11], v[204:207], v[180:183], v[8:11]
	v_mfma_f32_16x16x32_bf16 v[4:7], v[196:199], v[188:191], v[4:7]
	v_mfma_f32_16x16x32_bf16 v[0:3], v[204:207], v[188:191], v[0:3]
	v_mfma_f32_16x16x32_bf16 v[48:51], v[200:203], v[168:171], v[48:51]
	v_mfma_f32_16x16x32_bf16 v[40:43], v[212:215], v[168:171], v[40:43]
	v_mfma_f32_16x16x32_bf16 v[32:35], v[200:203], v[176:179], v[32:35]
	v_mfma_f32_16x16x32_bf16 v[24:27], v[212:215], v[176:179], v[24:27]
	v_mfma_f32_16x16x32_bf16 v[16:19], v[200:203], v[184:187], v[16:19]
	v_mfma_f32_16x16x32_bf16 v[8:11], v[212:215], v[184:187], v[8:11]
	v_mfma_f32_16x16x32_bf16 v[4:7], v[200:203], v[192:195], v[4:7]
	v_mfma_f32_16x16x32_bf16 v[0:3], v[212:215], v[192:195], v[0:3]
	s_setprio 0
	s_add_i32 s75, s75, 2
	s_add_u32 s38, s38, 0x100
	s_addc_u32 s39, s39, 0
	s_add_u32 s73, s73, 0x100
	s_addc_u32 s74, s74, 0
	s_cmp_gt_u32 s75, 13
	s_barrier
	s_cbranch_scc0 .LBB0_220
	v_lshl_add_u32 v148, s30, 8, v143
	v_ashrrev_i32_e32 v149, 31, v148
	v_lshl_or_b32 v140, s70, 8, v145
	v_ashrrev_i32_e32 v141, 31, v140
	v_lshlrev_b64 v[150:151], 13, v[148:149]
	v_lshl_add_u64 v[150:151], s[8:9], 0, v[150:151]
	v_lshlrev_b64 v[152:153], 1, v[140:141]
	v_lshl_add_u64 v[140:141], v[150:151], 0, v[152:153]
	v_cvt_pk_bf16_f32 v124, v124, v125
	v_cvt_pk_bf16_f32 v125, v126, v127
	v_cvt_pk_bf16_f32 v126, v120, v121
	v_cvt_pk_bf16_f32 v127, v122, v123
	global_store_dwordx4 v[140:141], v[124:127], off nt
	v_cvt_pk_bf16_f32 v112, v112, v113
	v_cvt_pk_bf16_f32 v113, v114, v115
	v_cvt_pk_bf16_f32 v114, v104, v105
	v_or_b32_e32 v104, 16, v148
	v_ashrrev_i32_e32 v105, 31, v104
	v_lshlrev_b64 v[104:105], 13, v[104:105]
	v_lshl_add_u64 v[104:105], s[8:9], 0, v[104:105]
	v_cvt_pk_bf16_f32 v115, v106, v107
	global_store_dwordx4 v[140:141], v[112:115], off offset:256 nt
	s_mov_b32 s15, 0x100000
	s_mov_b64 s[38:39], 0x100000
	v_lshl_add_u64 v[112:113], v[104:105], 0, v[152:153]
	v_cvt_pk_bf16_f32 v104, v116, v117
	v_cvt_pk_bf16_f32 v105, v118, v119
	v_cvt_pk_bf16_f32 v106, v108, v109
	v_cvt_pk_bf16_f32 v107, v110, v111
	global_store_dwordx4 v[112:113], v[104:107], off nt
	v_cvt_pk_bf16_f32 v96, v96, v97
	v_cvt_pk_bf16_f32 v97, v98, v99
	v_cvt_pk_bf16_f32 v98, v88, v89
	v_or_b32_e32 v88, 32, v148
	v_ashrrev_i32_e32 v89, 31, v88
	v_lshlrev_b64 v[88:89], 13, v[88:89]
	v_lshl_add_u64 v[88:89], s[8:9], 0, v[88:89]
	v_cvt_pk_bf16_f32 v99, v90, v91
	global_store_dwordx4 v[112:113], v[96:99], off offset:256 nt
	s_mov_b32 s70, s14
	s_mov_b32 s30, s28
	v_lshl_add_u64 v[96:97], v[88:89], 0, v[152:153]
	v_cvt_pk_bf16_f32 v88, v100, v101
	v_cvt_pk_bf16_f32 v89, v102, v103
	v_cvt_pk_bf16_f32 v90, v92, v93
	v_cvt_pk_bf16_f32 v91, v94, v95
	global_store_dwordx4 v[96:97], v[88:91], off nt
	v_cvt_pk_bf16_f32 v80, v80, v81
	v_cvt_pk_bf16_f32 v81, v82, v83
	v_cvt_pk_bf16_f32 v82, v72, v73
	v_or_b32_e32 v72, 48, v148
	v_ashrrev_i32_e32 v73, 31, v72
	v_lshlrev_b64 v[72:73], 13, v[72:73]
	v_lshl_add_u64 v[72:73], s[8:9], 0, v[72:73]
	v_cvt_pk_bf16_f32 v83, v74, v75
	global_store_dwordx4 v[96:97], v[80:83], off offset:256 nt
	s_mov_b64 s[40:41], s[36:37]
	s_nop 0
	v_lshl_add_u64 v[80:81], v[72:73], 0, v[152:153]
	v_cvt_pk_bf16_f32 v72, v84, v85
	v_cvt_pk_bf16_f32 v73, v86, v87
	v_cvt_pk_bf16_f32 v74, v76, v77
	v_cvt_pk_bf16_f32 v75, v78, v79
	global_store_dwordx4 v[80:81], v[72:75], off nt
	v_cvt_pk_bf16_f32 v68, v68, v69
	v_cvt_pk_bf16_f32 v69, v70, v71
	v_cvt_pk_bf16_f32 v70, v64, v65
	v_cvt_pk_bf16_f32 v71, v66, v67
	global_store_dwordx4 v[80:81], v[68:71], off offset:256 nt
	v_cvt_pk_bf16_f32 v60, v60, v61
	v_cvt_pk_bf16_f32 v61, v62, v63
	v_cvt_pk_bf16_f32 v62, v56, v57
	v_add_co_u32_e32 v56, vcc, s15, v140
	v_lshl_add_u64 v[64:65], v[140:141], 0, s[38:39]
	s_nop 0
	v_addc_co_u32_e32 v57, vcc, 0, v141, vcc
	s_mov_b32 s15, 0x120000
	v_cvt_pk_bf16_f32 v63, v58, v59
	global_store_dwordx4 v[56:57], v[60:63], off nt
	v_cvt_pk_bf16_f32 v48, v48, v49
	v_cvt_pk_bf16_f32 v49, v50, v51
	v_cvt_pk_bf16_f32 v50, v40, v41
	v_cvt_pk_bf16_f32 v51, v42, v43
	global_store_dwordx4 v[64:65], v[48:51], off offset:256 nt
	s_mov_b64 s[38:39], 0x120000
	v_cvt_pk_bf16_f32 v40, v52, v53
	v_cvt_pk_bf16_f32 v41, v54, v55
	v_cvt_pk_bf16_f32 v42, v44, v45
	v_add_co_u32_e32 v44, vcc, s15, v140
	v_lshl_add_u64 v[48:49], v[140:141], 0, s[38:39]
	s_nop 0
	v_addc_co_u32_e32 v45, vcc, 0, v141, vcc
	s_mov_b32 s15, 0x140000
	v_cvt_pk_bf16_f32 v43, v46, v47
	global_store_dwordx4 v[44:45], v[40:43], off nt
	v_cvt_pk_bf16_f32 v32, v32, v33
	v_cvt_pk_bf16_f32 v33, v34, v35
	v_cvt_pk_bf16_f32 v34, v24, v25
	v_cvt_pk_bf16_f32 v35, v26, v27
	global_store_dwordx4 v[48:49], v[32:35], off offset:256 nt
	s_mov_b64 s[38:39], 0x140000
	v_cvt_pk_bf16_f32 v24, v36, v37
	v_cvt_pk_bf16_f32 v25, v38, v39
	v_cvt_pk_bf16_f32 v26, v28, v29
	v_add_co_u32_e32 v28, vcc, s15, v140
	v_lshl_add_u64 v[32:33], v[140:141], 0, s[38:39]
	s_nop 0
	v_addc_co_u32_e32 v29, vcc, 0, v141, vcc
	s_mov_b32 s15, 0x160000
	v_cvt_pk_bf16_f32 v27, v30, v31
	global_store_dwordx4 v[28:29], v[24:27], off nt
	v_cvt_pk_bf16_f32 v16, v16, v17
	v_cvt_pk_bf16_f32 v17, v18, v19
	v_cvt_pk_bf16_f32 v18, v8, v9
	v_cvt_pk_bf16_f32 v19, v10, v11
	global_store_dwordx4 v[32:33], v[16:19], off offset:256 nt
	v_cvt_pk_bf16_f32 v8, v20, v21
	v_cvt_pk_bf16_f32 v9, v22, v23
	v_cvt_pk_bf16_f32 v10, v12, v13
	v_add_co_u32_e32 v12, vcc, s15, v140
	s_mov_b64 s[38:39], 0x160000
	s_nop 0
	v_addc_co_u32_e32 v13, vcc, 0, v141, vcc
	v_lshl_add_u64 v[16:17], v[140:141], 0, s[38:39]
	s_and_b64 vcc, exec, s[12:13]
	s_mov_b64 s[38:39], s[34:35]
	v_cvt_pk_bf16_f32 v11, v14, v15
	global_store_dwordx4 v[12:13], v[8:11], off nt
	v_cvt_pk_bf16_f32 v4, v4, v5
	v_cvt_pk_bf16_f32 v5, v6, v7
	v_cvt_pk_bf16_f32 v6, v0, v1
	v_cvt_pk_bf16_f32 v7, v2, v3
	global_store_dwordx4 v[16:17], v[4:7], off offset:256 nt
	s_cbranch_vccz .LBB0_213
	s_waitcnt vmcnt(0)
	s_cmpk_gt_u32 s49, 0xff
	s_cbranch_scc1 .LBB0_183
	s_barrier
	s_branch .LBB0_183

.LBB0_262:
	ds_read_b128 v[128:131], v157
	ds_read_b128 v[132:135], v157 offset:1024
	ds_read_b128 v[160:163], v157 offset:2048
	ds_read_b128 v[164:167], v157 offset:3072
	s_add_u32 s34, s30, 0xfffc0080
	s_addc_u32 s35, s31, -1
	s_cmp_eq_u32 s59, 28
	s_cselect_b32 s37, s1, s35
	s_cselect_b32 s36, s2, s34
	s_cselect_b32 s35, s13, s58
	s_cselect_b32 s34, s15, s55
	v_lshl_add_u64 v[152:153], s[30:31], 0, v[148:149]
	s_add_i32 m0, s40, 0xc000
	ds_read_b128 v[168:171], v158
	ds_read_b128 v[172:175], v158 offset:1024
	ds_read_b128 v[176:179], v158 offset:2048
	ds_read_b128 v[180:183], v158 offset:3072
	ds_read_b128 v[184:187], v158 offset:4096
	ds_read_b128 v[188:191], v158 offset:5120
	ds_read_b128 v[192:195], v158 offset:6144
	ds_read_b128 v[196:199], v158 offset:7168
	global_load_lds_dwordx4 v[152:153], off
	s_add_i32 m0, s40, 0xe000
	v_lshl_add_u64 v[152:153], s[30:31], 0, v[150:151]
	global_load_lds_dwordx4 v[152:153], off
	s_waitcnt lgkmcnt(8)
	s_setprio 1
	s_barrier
	s_waitcnt lgkmcnt(0)
	v_mfma_f32_16x16x32_bf16 v[124:127], v[128:131], v[168:171], v[124:127]
	v_mfma_f32_16x16x32_bf16 v[100:103], v[160:163], v[168:171], v[100:103]
	v_mfma_f32_16x16x32_bf16 v[116:119], v[128:131], v[176:179], v[116:119]
	v_mfma_f32_16x16x32_bf16 v[96:99], v[160:163], v[176:179], v[96:99]
	v_mfma_f32_16x16x32_bf16 v[92:95], v[128:131], v[184:187], v[92:95]
	v_mfma_f32_16x16x32_bf16 v[72:75], v[160:163], v[184:187], v[72:75]
	v_mfma_f32_16x16x32_bf16 v[84:87], v[128:131], v[192:195], v[84:87]
	v_mfma_f32_16x16x32_bf16 v[60:63], v[160:163], v[192:195], v[60:63]
	v_mfma_f32_16x16x32_bf16 v[124:127], v[132:135], v[172:175], v[124:127]
	v_mfma_f32_16x16x32_bf16 v[100:103], v[164:167], v[172:175], v[100:103]
	v_mfma_f32_16x16x32_bf16 v[116:119], v[132:135], v[180:183], v[116:119]
	v_mfma_f32_16x16x32_bf16 v[96:99], v[164:167], v[180:183], v[96:99]
	v_mfma_f32_16x16x32_bf16 v[92:95], v[132:135], v[188:191], v[92:95]
	v_mfma_f32_16x16x32_bf16 v[72:75], v[164:167], v[188:191], v[72:75]
	v_mfma_f32_16x16x32_bf16 v[84:87], v[132:135], v[196:199], v[84:87]
	v_mfma_f32_16x16x32_bf16 v[60:63], v[164:167], v[196:199], v[60:63]
	s_setprio 0
	s_barrier
	s_add_i32 s60, s51, s39
	v_lshl_add_u64 v[152:153], s[34:35], 0, v[138:139]
	s_mov_b32 m0, s60
	ds_read_b128 v[200:203], v159
	ds_read_b128 v[204:207], v159 offset:1024
	ds_read_b128 v[212:215], v159 offset:2048
	ds_read_b128 v[216:219], v159 offset:3072
	global_load_lds_dwordx4 v[152:153], off
	s_add_i32 m0, s60, 0x2000
	v_lshl_add_u64 v[208:209], s[34:35], 0, v[142:143]
	global_load_lds_dwordx4 v[208:209], off
	s_setprio 1
	s_barrier
	s_waitcnt lgkmcnt(0)
	v_mfma_f32_16x16x32_bf16 v[120:123], v[200:203], v[168:171], v[120:123]
	v_mfma_f32_16x16x32_bf16 v[108:111], v[212:215], v[168:171], v[108:111]
	v_mfma_f32_16x16x32_bf16 v[112:115], v[200:203], v[176:179], v[112:115]
	v_mfma_f32_16x16x32_bf16 v[104:107], v[212:215], v[176:179], v[104:107]
	v_mfma_f32_16x16x32_bf16 v[88:91], v[200:203], v[184:187], v[88:91]
	v_mfma_f32_16x16x32_bf16 v[80:83], v[212:215], v[184:187], v[80:83]
	v_mfma_f32_16x16x32_bf16 v[76:79], v[200:203], v[192:195], v[76:79]
	v_mfma_f32_16x16x32_bf16 v[68:71], v[212:215], v[192:195], v[68:71]
	v_mfma_f32_16x16x32_bf16 v[120:123], v[204:207], v[172:175], v[120:123]
	v_mfma_f32_16x16x32_bf16 v[108:111], v[216:219], v[172:175], v[108:111]
	v_mfma_f32_16x16x32_bf16 v[112:115], v[204:207], v[180:183], v[112:115]
	v_mfma_f32_16x16x32_bf16 v[104:107], v[216:219], v[180:183], v[104:107]
	v_mfma_f32_16x16x32_bf16 v[88:91], v[204:207], v[188:191], v[88:91]
	v_mfma_f32_16x16x32_bf16 v[80:83], v[216:219], v[188:191], v[80:83]
	v_mfma_f32_16x16x32_bf16 v[76:79], v[204:207], v[196:199], v[76:79]
	v_mfma_f32_16x16x32_bf16 v[68:71], v[216:219], v[196:199], v[68:71]
	s_setprio 0
	s_mov_b32 m0, s40
	v_lshl_add_u64 v[220:221], s[36:37], 0, v[136:137]
	s_barrier
	ds_read_b128 v[168:171], v158 offset:16384
	ds_read_b128 v[172:175], v158 offset:17408
	ds_read_b128 v[176:179], v158 offset:18432
	ds_read_b128 v[180:183], v158 offset:19456
	ds_read_b128 v[184:187], v158 offset:20480
	ds_read_b128 v[188:191], v158 offset:21504
	ds_read_b128 v[192:195], v158 offset:22528
	ds_read_b128 v[196:199], v158 offset:23552
	global_load_lds_dwordx4 v[220:221], off
	s_mov_b32 m0, s41
	v_lshl_add_u64 v[222:223], s[36:37], 0, v[140:141]
	global_load_lds_dwordx4 v[222:223], off
	s_setprio 1
	s_barrier
	s_waitcnt lgkmcnt(0)
	v_mfma_f32_16x16x32_bf16 v[64:67], v[128:131], v[168:171], v[64:67]
	v_mfma_f32_16x16x32_bf16 v[48:51], v[160:163], v[168:171], v[48:51]
	v_mfma_f32_16x16x32_bf16 v[44:47], v[128:131], v[176:179], v[44:47]
	v_mfma_f32_16x16x32_bf16 v[32:35], v[160:163], v[176:179], v[32:35]
	v_mfma_f32_16x16x32_bf16 v[28:31], v[128:131], v[184:187], v[28:31]
	v_mfma_f32_16x16x32_bf16 v[16:19], v[160:163], v[184:187], v[16:19]
	v_mfma_f32_16x16x32_bf16 v[12:15], v[128:131], v[192:195], v[12:15]
	v_mfma_f32_16x16x32_bf16 v[0:3], v[160:163], v[192:195], v[0:3]
	v_mfma_f32_16x16x32_bf16 v[64:67], v[132:135], v[172:175], v[64:67]
	v_mfma_f32_16x16x32_bf16 v[48:51], v[164:167], v[172:175], v[48:51]
	v_mfma_f32_16x16x32_bf16 v[44:47], v[132:135], v[180:183], v[44:47]
	v_mfma_f32_16x16x32_bf16 v[32:35], v[164:167], v[180:183], v[32:35]
	v_mfma_f32_16x16x32_bf16 v[28:31], v[132:135], v[188:191], v[28:31]
	v_mfma_f32_16x16x32_bf16 v[16:19], v[164:167], v[188:191], v[16:19]
	v_mfma_f32_16x16x32_bf16 v[12:15], v[132:135], v[196:199], v[12:15]
	v_mfma_f32_16x16x32_bf16 v[0:3], v[164:167], v[196:199], v[0:3]
	s_setprio 0
	s_barrier
	s_add_u32 s60, s34, 0x80000
	s_addc_u32 s61, s35, 0
	s_add_i32 s62, s53, s39
	s_mov_b32 m0, s62
	v_lshl_add_u64 v[128:129], s[60:61], 0, v[138:139]
	global_load_lds_dwordx4 v[128:129], off
	s_add_i32 m0, s62, 0x2000
	v_lshl_add_u64 v[128:129], s[60:61], 0, v[142:143]
	global_load_lds_dwordx4 v[128:129], off
	s_waitcnt vmcnt(6)
	s_setprio 1
	s_barrier
	v_mfma_f32_16x16x32_bf16 v[56:59], v[200:203], v[168:171], v[56:59]
	v_mfma_f32_16x16x32_bf16 v[52:55], v[212:215], v[168:171], v[52:55]
	v_mfma_f32_16x16x32_bf16 v[40:43], v[200:203], v[176:179], v[40:43]
	v_mfma_f32_16x16x32_bf16 v[36:39], v[212:215], v[176:179], v[36:39]
	v_mfma_f32_16x16x32_bf16 v[24:27], v[200:203], v[184:187], v[24:27]
	v_mfma_f32_16x16x32_bf16 v[20:23], v[212:215], v[184:187], v[20:23]
	v_mfma_f32_16x16x32_bf16 v[8:11], v[200:203], v[192:195], v[8:11]
	v_mfma_f32_16x16x32_bf16 v[4:7], v[212:215], v[192:195], v[4:7]
	v_mfma_f32_16x16x32_bf16 v[56:59], v[204:207], v[172:175], v[56:59]
	v_mfma_f32_16x16x32_bf16 v[52:55], v[216:219], v[172:175], v[52:55]
	v_mfma_f32_16x16x32_bf16 v[40:43], v[204:207], v[180:183], v[40:43]
	v_mfma_f32_16x16x32_bf16 v[36:39], v[216:219], v[180:183], v[36:39]
	v_mfma_f32_16x16x32_bf16 v[24:27], v[204:207], v[188:191], v[24:27]
	v_mfma_f32_16x16x32_bf16 v[20:23], v[216:219], v[188:191], v[20:23]
	v_mfma_f32_16x16x32_bf16 v[8:11], v[204:207], v[196:199], v[8:11]
	v_mfma_f32_16x16x32_bf16 v[4:7], v[216:219], v[196:199], v[4:7]
	s_setprio 0
	s_add_i32 s60, 0, 0x18000
	v_add_u32_e32 v164, s60, v156
	s_barrier
	ds_read_b128 v[128:131], v164
	ds_read_b128 v[132:135], v164 offset:1024
	ds_read_b128 v[160:163], v164 offset:2048
	ds_read_b128 v[164:167], v164 offset:3072
	s_add_u32 s36, s36, 0x40000
	s_addc_u32 s37, s37, 0
	s_mov_b32 m0, s42
	v_lshl_add_u64 v[200:201], s[36:37], 0, v[136:137]
	ds_read_b128 v[168:171], v158 offset:32768
	ds_read_b128 v[172:175], v158 offset:33792
	ds_read_b128 v[176:179], v158 offset:34816
	ds_read_b128 v[180:183], v158 offset:35840
	ds_read_b128 v[184:187], v158 offset:36864
	ds_read_b128 v[188:191], v158 offset:37888
	ds_read_b128 v[192:195], v158 offset:38912
	ds_read_b128 v[196:199], v158 offset:39936
	global_load_lds_dwordx4 v[200:201], off
	s_mov_b32 m0, s43
	v_lshl_add_u64 v[200:201], s[36:37], 0, v[140:141]
	global_load_lds_dwordx4 v[200:201], off
	s_waitcnt lgkmcnt(8)
	s_setprio 1
	s_barrier
	s_waitcnt lgkmcnt(0)
	v_mfma_f32_16x16x32_bf16 v[124:127], v[128:131], v[168:171], v[124:127]
	v_mfma_f32_16x16x32_bf16 v[100:103], v[160:163], v[168:171], v[100:103]
	v_mfma_f32_16x16x32_bf16 v[116:119], v[128:131], v[176:179], v[116:119]
	v_mfma_f32_16x16x32_bf16 v[96:99], v[160:163], v[176:179], v[96:99]
	v_mfma_f32_16x16x32_bf16 v[92:95], v[128:131], v[184:187], v[92:95]
	v_mfma_f32_16x16x32_bf16 v[72:75], v[160:163], v[184:187], v[72:75]
	v_mfma_f32_16x16x32_bf16 v[84:87], v[128:131], v[192:195], v[84:87]
	v_mfma_f32_16x16x32_bf16 v[60:63], v[160:163], v[192:195], v[60:63]
	v_mfma_f32_16x16x32_bf16 v[124:127], v[132:135], v[172:175], v[124:127]
	v_mfma_f32_16x16x32_bf16 v[100:103], v[164:167], v[172:175], v[100:103]
	v_mfma_f32_16x16x32_bf16 v[116:119], v[132:135], v[180:183], v[116:119]
	v_mfma_f32_16x16x32_bf16 v[96:99], v[164:167], v[180:183], v[96:99]
	v_mfma_f32_16x16x32_bf16 v[92:95], v[132:135], v[188:191], v[92:95]
	v_mfma_f32_16x16x32_bf16 v[72:75], v[164:167], v[188:191], v[72:75]
	v_mfma_f32_16x16x32_bf16 v[84:87], v[132:135], v[196:199], v[84:87]
	v_mfma_f32_16x16x32_bf16 v[60:63], v[164:167], v[196:199], v[60:63]
	s_setprio 0
	s_barrier
	s_add_i32 s36, 0, 0x1c000
	s_add_i32 s37, s60, s39
	v_add_u32_e32 v211, s36, v156
	v_lshl_add_u64 v[152:153], v[152:153], 0, s[4:5]
	s_mov_b32 m0, s37
	ds_read_b128 v[200:203], v211
	ds_read_b128 v[204:207], v211 offset:1024
	ds_read_b128 v[212:215], v211 offset:2048
	ds_read_b128 v[216:219], v211 offset:3072
	global_load_lds_dwordx4 v[152:153], off
	s_add_i32 m0, s37, 0x2000
	v_lshl_add_u64 v[152:153], v[208:209], 0, s[4:5]
	global_load_lds_dwordx4 v[152:153], off
	s_setprio 1
	s_barrier
	s_waitcnt lgkmcnt(0)
	v_mfma_f32_16x16x32_bf16 v[120:123], v[200:203], v[168:171], v[120:123]
	v_mfma_f32_16x16x32_bf16 v[108:111], v[212:215], v[168:171], v[108:111]
	v_mfma_f32_16x16x32_bf16 v[112:115], v[200:203], v[176:179], v[112:115]
	v_mfma_f32_16x16x32_bf16 v[104:107], v[212:215], v[176:179], v[104:107]
	v_mfma_f32_16x16x32_bf16 v[88:91], v[200:203], v[184:187], v[88:91]
	v_mfma_f32_16x16x32_bf16 v[80:83], v[212:215], v[184:187], v[80:83]
	v_mfma_f32_16x16x32_bf16 v[76:79], v[200:203], v[192:195], v[76:79]
	v_mfma_f32_16x16x32_bf16 v[68:71], v[212:215], v[192:195], v[68:71]
	v_mfma_f32_16x16x32_bf16 v[120:123], v[204:207], v[172:175], v[120:123]
	v_mfma_f32_16x16x32_bf16 v[108:111], v[216:219], v[172:175], v[108:111]
	v_mfma_f32_16x16x32_bf16 v[112:115], v[204:207], v[180:183], v[112:115]
	v_mfma_f32_16x16x32_bf16 v[104:107], v[216:219], v[180:183], v[104:107]
	v_mfma_f32_16x16x32_bf16 v[88:91], v[204:207], v[188:191], v[88:91]
	v_mfma_f32_16x16x32_bf16 v[80:83], v[216:219], v[188:191], v[80:83]
	v_mfma_f32_16x16x32_bf16 v[76:79], v[204:207], v[196:199], v[76:79]
	v_mfma_f32_16x16x32_bf16 v[68:71], v[216:219], v[196:199], v[68:71]
	s_setprio 0
	s_mov_b32 m0, s48
	v_lshl_add_u64 v[152:153], v[220:221], 0, s[4:5]
	s_barrier
	ds_read_b128 v[168:171], v158 offset:49152
	ds_read_b128 v[172:175], v158 offset:50176
	ds_read_b128 v[176:179], v158 offset:51200
	ds_read_b128 v[180:183], v158 offset:52224
	ds_read_b128 v[184:187], v158 offset:53248
	ds_read_b128 v[188:191], v158 offset:54272
	ds_read_b128 v[192:195], v158 offset:55296
	ds_read_b128 v[196:199], v158 offset:56320
	global_load_lds_dwordx4 v[152:153], off
	s_mov_b32 m0, s49
	v_lshl_add_u64 v[152:153], v[222:223], 0, s[4:5]
	global_load_lds_dwordx4 v[152:153], off
	s_setprio 1
	s_barrier
	s_waitcnt lgkmcnt(0)
	v_mfma_f32_16x16x32_bf16 v[64:67], v[128:131], v[168:171], v[64:67]
	v_mfma_f32_16x16x32_bf16 v[48:51], v[160:163], v[168:171], v[48:51]
	v_mfma_f32_16x16x32_bf16 v[44:47], v[128:131], v[176:179], v[44:47]
	v_mfma_f32_16x16x32_bf16 v[32:35], v[160:163], v[176:179], v[32:35]
	v_mfma_f32_16x16x32_bf16 v[28:31], v[128:131], v[184:187], v[28:31]
	v_mfma_f32_16x16x32_bf16 v[16:19], v[160:163], v[184:187], v[16:19]
	v_mfma_f32_16x16x32_bf16 v[12:15], v[128:131], v[192:195], v[12:15]
	v_mfma_f32_16x16x32_bf16 v[0:3], v[160:163], v[192:195], v[0:3]
	v_mfma_f32_16x16x32_bf16 v[64:67], v[132:135], v[172:175], v[64:67]
	v_mfma_f32_16x16x32_bf16 v[48:51], v[164:167], v[172:175], v[48:51]
	v_mfma_f32_16x16x32_bf16 v[44:47], v[132:135], v[180:183], v[44:47]
	v_mfma_f32_16x16x32_bf16 v[32:35], v[164:167], v[180:183], v[32:35]
	v_mfma_f32_16x16x32_bf16 v[28:31], v[132:135], v[188:191], v[28:31]
	v_mfma_f32_16x16x32_bf16 v[16:19], v[164:167], v[188:191], v[16:19]
	v_mfma_f32_16x16x32_bf16 v[12:15], v[132:135], v[196:199], v[12:15]
	v_mfma_f32_16x16x32_bf16 v[0:3], v[164:167], v[196:199], v[0:3]
	s_setprio 0
	s_barrier
	s_add_u32 s34, s34, 0x80080
	s_addc_u32 s35, s35, 0
	s_add_i32 s36, s36, s39
	s_mov_b32 m0, s36
	v_lshl_add_u64 v[128:129], s[34:35], 0, v[138:139]
	global_load_lds_dwordx4 v[128:129], off
	s_add_i32 m0, s36, 0x2000
	v_lshl_add_u64 v[128:129], s[34:35], 0, v[142:143]
	global_load_lds_dwordx4 v[128:129], off
	s_waitcnt vmcnt(6)
	s_setprio 1
	s_barrier
	v_mfma_f32_16x16x32_bf16 v[56:59], v[200:203], v[168:171], v[56:59]
	v_mfma_f32_16x16x32_bf16 v[52:55], v[212:215], v[168:171], v[52:55]
	v_mfma_f32_16x16x32_bf16 v[40:43], v[200:203], v[176:179], v[40:43]
	v_mfma_f32_16x16x32_bf16 v[36:39], v[212:215], v[176:179], v[36:39]
	v_mfma_f32_16x16x32_bf16 v[24:27], v[200:203], v[184:187], v[24:27]
	v_mfma_f32_16x16x32_bf16 v[20:23], v[212:215], v[184:187], v[20:23]
	v_mfma_f32_16x16x32_bf16 v[8:11], v[200:203], v[192:195], v[8:11]
	v_mfma_f32_16x16x32_bf16 v[4:7], v[212:215], v[192:195], v[4:7]
	v_mfma_f32_16x16x32_bf16 v[56:59], v[204:207], v[172:175], v[56:59]
	v_mfma_f32_16x16x32_bf16 v[52:55], v[216:219], v[172:175], v[52:55]
	v_mfma_f32_16x16x32_bf16 v[40:43], v[204:207], v[180:183], v[40:43]
	v_mfma_f32_16x16x32_bf16 v[36:39], v[216:219], v[180:183], v[36:39]
	v_mfma_f32_16x16x32_bf16 v[24:27], v[204:207], v[188:191], v[24:27]
	v_mfma_f32_16x16x32_bf16 v[20:23], v[216:219], v[188:191], v[20:23]
	v_mfma_f32_16x16x32_bf16 v[8:11], v[204:207], v[196:199], v[8:11]
	v_mfma_f32_16x16x32_bf16 v[4:7], v[216:219], v[196:199], v[4:7]
	s_setprio 0
	s_add_i32 s59, s59, 2
	s_add_u32 s30, s30, 0x100
	s_addc_u32 s31, s31, 0
	s_add_u32 s55, s55, 0x100
	s_addc_u32 s58, s58, 0
	s_cmp_gt_u32 s59, 29
	s_barrier
	s_cbranch_scc0 .LBB0_262
	s_cmp_gt_i32 s0, 31
	s_cselect_b64 vcc, -1, 0
	s_and_b64 s[30:31], vcc, exec
	s_cselect_b32 s2, 0x200, 0
	v_lshl_add_u64 v[128:129], v[144:145], 0, s[2:3]
	global_load_dwordx4 v[132:135], v[128:129], off
	s_nop 0
	global_load_dwordx4 v[128:131], v[128:129], off offset:16
	v_cndmask_b32_e32 v121, v125, v121, vcc
	v_cndmask_b32_e32 v120, v124, v120, vcc
	v_cndmask_b32_e32 v101, v101, v109, vcc
	v_cndmask_b32_e32 v100, v100, v108, vcc
	v_cndmask_b32_e32 v123, v127, v123, vcc
	v_cndmask_b32_e32 v122, v126, v122, vcc
	v_cndmask_b32_e32 v103, v103, v111, vcc
	v_cndmask_b32_e32 v102, v102, v110, vcc
	v_cndmask_b32_e32 v111, v119, v115, vcc
	v_cndmask_b32_e32 v110, v118, v114, vcc
	v_cndmask_b32_e32 v99, v99, v107, vcc
	v_cndmask_b32_e32 v98, v98, v106, vcc
	v_cndmask_b32_e32 v109, v117, v113, vcc
	v_cndmask_b32_e32 v108, v116, v112, vcc
	v_cndmask_b32_e32 v89, v93, v89, vcc
	v_cndmask_b32_e32 v88, v92, v88, vcc
	v_cndmask_b32_e32 v73, v73, v81, vcc
	v_cndmask_b32_e32 v72, v72, v80, vcc
	v_cndmask_b32_e32 v105, v97, v105, vcc
	v_cndmask_b32_e32 v104, v96, v104, vcc
	v_cndmask_b32_e32 v74, v74, v82, vcc
	v_lshl_add_u32 v152, s0, 8, v155
	v_ashrrev_i32_e32 v153, 31, v152
	v_lshlrev_b64 v[162:163], 8, v[152:153]
	v_cndmask_b32_e32 v75, v75, v83, vcc
	v_lshl_add_u64 v[96:97], v[146:147], 0, v[162:163]
	v_cndmask_b32_e32 v91, v95, v91, vcc
	v_cndmask_b32_e32 v90, v94, v90, vcc
	v_or_b32_e32 v160, 16, v152
	v_ashrrev_i32_e32 v161, 31, v160
	v_lshlrev_b64 v[106:107], 8, v[160:161]
	v_cndmask_b32_e32 v61, v61, v69, vcc
	v_cndmask_b32_e32 v60, v60, v68, vcc
	v_cndmask_b32_e32 v57, v65, v57, vcc
	v_cndmask_b32_e32 v56, v64, v56, vcc
	v_cndmask_b32_e32 v49, v49, v53, vcc
	v_cndmask_b32_e32 v48, v48, v52, vcc
	v_cndmask_b32_e32 v62, v62, v70, vcc
	v_cndmask_b32_e32 v50, v50, v54, vcc
	v_cndmask_b32_e32 v41, v45, v41, vcc
	v_cndmask_b32_e32 v40, v44, v40, vcc
	v_cndmask_b32_e32 v33, v33, v37, vcc
	v_cndmask_b32_e32 v32, v32, v36, vcc
	v_cndmask_b32_e32 v25, v29, v25, vcc
	v_cndmask_b32_e32 v24, v28, v24, vcc
	v_cndmask_b32_e32 v17, v17, v21, vcc
	v_cndmask_b32_e32 v16, v16, v20, vcc
	v_cndmask_b32_e32 v34, v34, v38, vcc
	v_cndmask_b32_e32 v18, v18, v22, vcc
	v_cndmask_b32_e32 v9, v13, v9, vcc
	v_cndmask_b32_e32 v8, v12, v8, vcc
	v_cndmask_b32_e32 v1, v1, v5, vcc
	v_cndmask_b32_e32 v0, v0, v4, vcc
	v_cndmask_b32_e32 v63, v63, v71, vcc
	v_cndmask_b32_e32 v51, v51, v55, vcc
	v_cndmask_b32_e32 v2, v2, v6, vcc
	v_cndmask_b32_e32 v35, v35, v39, vcc
	v_cndmask_b32_e32 v59, v67, v59, vcc
	v_cndmask_b32_e32 v58, v66, v58, vcc
	v_cndmask_b32_e32 v19, v19, v23, vcc
	v_cndmask_b32_e32 v43, v47, v43, vcc
	v_cndmask_b32_e32 v42, v46, v42, vcc
	v_cndmask_b32_e32 v3, v3, v7, vcc
	v_cndmask_b32_e32 v27, v31, v27, vcc
	v_cndmask_b32_e32 v26, v30, v26, vcc
	v_cndmask_b32_e32 v11, v15, v11, vcc
	v_cndmask_b32_e32 v10, v14, v10, vcc
	s_mov_b32 s0, 0x9000
	s_mov_b64 s[34:35], s[28:29]
	s_mov_b64 s[30:31], s[26:27]
	s_waitcnt vmcnt(0)
	v_pk_add_f32 v[114:115], v[120:121], v[132:133]
	v_pk_add_f32 v[100:101], v[100:101], v[128:129]
	v_pk_add_f32 v[112:113], v[122:123], v[134:135]
	v_pk_add_f32 v[102:103], v[102:103], v[130:131]
	v_pk_add_f32 v[116:117], v[98:99], v[130:131]
	v_mul_f32_e32 v98, 0xbfb8aa3b, v114
	v_mul_f32_e32 v99, 0xbfb8aa3b, v100
	v_mul_f32_e32 v118, 0xbfb8aa3b, v115
	v_mul_f32_e32 v119, 0xbfb8aa3b, v101
	v_mul_f32_e32 v120, 0xbfb8aa3b, v112
	v_mul_f32_e32 v121, 0xbfb8aa3b, v102
	v_mul_f32_e32 v122, 0xbfb8aa3b, v113
	v_mul_f32_e32 v123, 0xbfb8aa3b, v103
	v_exp_f32_e32 v98, v98
	v_exp_f32_e32 v99, v99
	v_exp_f32_e32 v118, v118
	v_exp_f32_e32 v119, v119
	v_exp_f32_e32 v120, v120
	v_exp_f32_e32 v121, v121
	v_exp_f32_e32 v122, v122
	v_exp_f32_e32 v123, v123
	v_pk_add_f32 v[88:89], v[88:89], v[132:133]
	v_pk_add_f32 v[72:73], v[72:73], v[128:129]
	v_add_f32_e32 v98, 1.0, v98
	v_add_f32_e32 v99, 1.0, v99
	v_add_f32_e32 v118, 1.0, v118
	v_add_f32_e32 v119, 1.0, v119
	v_mul_f32_e32 v80, 0xbfb8aa3b, v88
	v_mul_f32_e32 v81, 0xbfb8aa3b, v72
	v_mul_f32_e32 v82, 0xbfb8aa3b, v89
	v_pk_add_f32 v[104:105], v[104:105], v[128:129]
	v_add_f32_e32 v120, 1.0, v120
	v_add_f32_e32 v121, 1.0, v121
	v_add_f32_e32 v122, 1.0, v122
	v_add_f32_e32 v123, 1.0, v123
	v_rcp_f32_e32 v98, v98
	v_rcp_f32_e32 v99, v99
	v_rcp_f32_e32 v118, v118
	v_rcp_f32_e32 v119, v119
	v_exp_f32_e32 v80, v80
	v_exp_f32_e32 v81, v81
	v_exp_f32_e32 v82, v82
	v_mul_f32_e32 v127, 0xbfb8aa3b, v105
	v_rcp_f32_e32 v120, v120
	v_rcp_f32_e32 v121, v121
	v_rcp_f32_e32 v122, v122
	v_rcp_f32_e32 v123, v123
	v_exp_f32_e32 v127, v127
	v_mul_f32_e32 v98, v114, v98
	v_mul_f32_e32 v100, v100, v99
	v_mul_f32_e32 v99, v115, v118
	v_mul_f32_e32 v101, v101, v119
	v_add_f32_e32 v80, 1.0, v80
	v_add_f32_e32 v81, 1.0, v81
	v_add_f32_e32 v82, 1.0, v82
	v_mul_f32_e32 v83, 0xbfb8aa3b, v73
	v_pk_add_f32 v[110:111], v[110:111], v[134:135]
	v_mul_f32_e32 v112, v112, v120
	v_mul_f32_e32 v102, v102, v121
	v_mul_f32_e32 v113, v113, v122
	v_mul_f32_e32 v103, v103, v123
	v_cvt_pk_bf16_f32 v98, v98, v99
	v_cvt_pk_bf16_f32 v99, v112, v113
	v_cvt_pk_bf16_f32 v100, v100, v101
	v_cvt_pk_bf16_f32 v101, v102, v103
	v_rcp_f32_e32 v80, v80
	v_rcp_f32_e32 v81, v81
	v_rcp_f32_e32 v82, v82
	v_exp_f32_e32 v83, v83
	global_store_dwordx4 v[96:97], v[98:101], off
	v_pk_add_f32 v[90:91], v[90:91], v[134:135]
	v_pk_add_f32 v[74:75], v[74:75], v[130:131]
	v_add_f32_e32 v99, 1.0, v127
	v_mul_f32_e32 v100, 0xbfb8aa3b, v110
	v_mul_f32_e32 v101, 0xbfb8aa3b, v116
	v_rcp_f32_e32 v99, v99
	v_exp_f32_e32 v100, v100
	v_exp_f32_e32 v101, v101
	v_pk_add_f32 v[108:109], v[108:109], v[132:133]
	v_mul_f32_e32 v88, v88, v80
	v_mul_f32_e32 v92, v72, v81
	v_mul_f32_e32 v72, v89, v82
	v_add_f32_e32 v80, 1.0, v83
	v_mul_f32_e32 v81, 0xbfb8aa3b, v90
	v_mul_f32_e32 v82, 0xbfb8aa3b, v74
	v_mul_f32_e32 v126, 0xbfb8aa3b, v109
	v_rcp_f32_e32 v80, v80
	v_exp_f32_e32 v81, v81
	v_exp_f32_e32 v82, v82
	v_mul_f32_e32 v124, 0xbfb8aa3b, v108
	v_exp_f32_e32 v126, v126
	v_mul_f32_e32 v105, v105, v99
	v_add_f32_e32 v99, 1.0, v100
	v_add_f32_e32 v100, 1.0, v101
	v_mul_f32_e32 v101, 0xbfb8aa3b, v111
	v_mul_f32_e32 v102, 0xbfb8aa3b, v117
	v_mul_f32_e32 v125, 0xbfb8aa3b, v104
	v_exp_f32_e32 v124, v124
	v_exp_f32_e32 v101, v101
	v_exp_f32_e32 v102, v102
	v_exp_f32_e32 v125, v125
	v_mul_f32_e32 v83, v73, v80
	v_add_f32_e32 v73, 1.0, v81
	v_add_f32_e32 v80, 1.0, v82
	v_mul_f32_e32 v81, 0xbfb8aa3b, v91
	v_mul_f32_e32 v82, 0xbfb8aa3b, v75
	v_add_f32_e32 v126, 1.0, v126
	v_exp_f32_e32 v81, v81
	v_exp_f32_e32 v82, v82
	v_add_f32_e32 v124, 1.0, v124
	v_rcp_f32_e32 v126, v126
	v_add_f32_e32 v101, 1.0, v101
	v_add_f32_e32 v102, 1.0, v102
	v_add_f32_e32 v125, 1.0, v125
	v_rcp_f32_e32 v124, v124
	v_rcp_f32_e32 v99, v99
	v_rcp_f32_e32 v100, v100
	v_rcp_f32_e32 v101, v101
	v_rcp_f32_e32 v102, v102
	v_rcp_f32_e32 v125, v125
	v_add_f32_e32 v81, 1.0, v81
	v_add_f32_e32 v82, 1.0, v82
	v_mul_f32_e32 v98, v109, v126
	v_rcp_f32_e32 v73, v73
	v_rcp_f32_e32 v80, v80
	v_rcp_f32_e32 v81, v81
	v_rcp_f32_e32 v82, v82
	v_mul_f32_e32 v108, v108, v124
	v_mul_f32_e32 v99, v110, v99
	v_mul_f32_e32 v109, v116, v100
	v_mul_f32_e32 v100, v111, v101
	v_mul_f32_e32 v101, v117, v102
	v_lshl_add_u64 v[102:103], v[146:147], 0, v[106:107]
	v_cvt_pk_bf16_f32 v98, v108, v98
	v_mul_f32_e32 v104, v104, v125
	v_cvt_pk_bf16_f32 v99, v99, v100
	v_cvt_pk_bf16_f32 v100, v104, v105
	v_cvt_pk_bf16_f32 v101, v109, v101
	global_store_dwordx4 v[102:103], v[98:101], off
	v_mul_f32_e32 v73, v90, v73
	v_mul_f32_e32 v89, v74, v80
	v_or_b32_e32 v98, 32, v152
	v_ashrrev_i32_e32 v99, 31, v98
	v_lshlrev_b64 v[98:99], 8, v[98:99]
	v_mul_f32_e32 v74, v91, v81
	v_mul_f32_e32 v75, v75, v82
	v_lshl_add_u64 v[80:81], v[146:147], 0, v[98:99]
	v_cvt_pk_bf16_f32 v72, v88, v72
	v_cvt_pk_bf16_f32 v73, v73, v74
	v_cvt_pk_bf16_f32 v74, v92, v83
	v_cvt_pk_bf16_f32 v75, v89, v75
	global_store_dwordx4 v[80:81], v[72:75], off
	v_pk_add_f32 v[60:61], v[60:61], v[128:129]
	v_pk_add_f32 v[56:57], v[56:57], v[132:133]
	v_cndmask_b32_e32 v75, v85, v77, vcc
	v_cndmask_b32_e32 v74, v84, v76, vcc
	v_pk_add_f32 v[74:75], v[74:75], v[132:133]
	v_mul_f32_e32 v69, 0xbfb8aa3b, v60
	v_mul_f32_e32 v68, 0xbfb8aa3b, v74
	v_mul_f32_e32 v70, 0xbfb8aa3b, v75
	v_pk_add_f32 v[48:49], v[48:49], v[128:129]
	v_exp_f32_e32 v68, v68
	v_exp_f32_e32 v69, v69
	v_exp_f32_e32 v70, v70
	v_mul_f32_e32 v52, 0xbfb8aa3b, v56
	v_mul_f32_e32 v53, 0xbfb8aa3b, v48
	v_mul_f32_e32 v54, 0xbfb8aa3b, v57
	v_exp_f32_e32 v52, v52
	v_exp_f32_e32 v53, v53
	v_exp_f32_e32 v54, v54
	v_pk_add_f32 v[40:41], v[40:41], v[132:133]
	v_pk_add_f32 v[32:33], v[32:33], v[128:129]
	v_mul_f32_e32 v36, 0xbfb8aa3b, v40
	v_mul_f32_e32 v37, 0xbfb8aa3b, v32
	v_mul_f32_e32 v38, 0xbfb8aa3b, v41
	v_pk_add_f32 v[24:25], v[24:25], v[132:133]
	v_pk_add_f32 v[16:17], v[16:17], v[128:129]
	v_exp_f32_e32 v36, v36
	v_exp_f32_e32 v37, v37
	v_exp_f32_e32 v38, v38
	v_mul_f32_e32 v20, 0xbfb8aa3b, v24
	v_mul_f32_e32 v21, 0xbfb8aa3b, v16
	v_mul_f32_e32 v22, 0xbfb8aa3b, v25
	v_add_f32_e32 v68, 1.0, v68
	v_add_f32_e32 v69, 1.0, v69
	v_add_f32_e32 v70, 1.0, v70
	v_mul_f32_e32 v71, 0xbfb8aa3b, v61
	v_exp_f32_e32 v20, v20
	v_exp_f32_e32 v21, v21
	v_exp_f32_e32 v22, v22
	v_pk_add_f32 v[8:9], v[8:9], v[132:133]
	v_pk_add_f32 v[0:1], v[0:1], v[128:129]
	v_rcp_f32_e32 v68, v68
	v_rcp_f32_e32 v69, v69
	v_rcp_f32_e32 v70, v70
	v_exp_f32_e32 v71, v71
	v_add_f32_e32 v52, 1.0, v52
	v_add_f32_e32 v53, 1.0, v53
	v_add_f32_e32 v54, 1.0, v54
	v_mul_f32_e32 v55, 0xbfb8aa3b, v49
	v_mul_f32_e32 v4, 0xbfb8aa3b, v8
	v_mul_f32_e32 v5, 0xbfb8aa3b, v0
	v_mul_f32_e32 v6, 0xbfb8aa3b, v9
	v_rcp_f32_e32 v52, v52
	v_rcp_f32_e32 v53, v53
	v_rcp_f32_e32 v54, v54
	v_exp_f32_e32 v55, v55
	v_exp_f32_e32 v4, v4
	v_exp_f32_e32 v5, v5
	v_exp_f32_e32 v6, v6
	v_cndmask_b32_e32 v77, v87, v79, vcc
	v_cndmask_b32_e32 v76, v86, v78, vcc
	v_add_f32_e32 v36, 1.0, v36
	v_add_f32_e32 v37, 1.0, v37
	v_add_f32_e32 v38, 1.0, v38
	v_mul_f32_e32 v39, 0xbfb8aa3b, v33
	v_pk_add_f32 v[76:77], v[76:77], v[134:135]
	v_pk_add_f32 v[62:63], v[62:63], v[130:131]
	v_rcp_f32_e32 v36, v36
	v_rcp_f32_e32 v37, v37
	v_rcp_f32_e32 v38, v38
	v_exp_f32_e32 v39, v39
	v_add_f32_e32 v20, 1.0, v20
	v_add_f32_e32 v21, 1.0, v21
	v_add_f32_e32 v22, 1.0, v22
	v_mul_f32_e32 v23, 0xbfb8aa3b, v17
	v_mul_f32_e32 v74, v74, v68
	v_mul_f32_e32 v78, v60, v69
	v_mul_f32_e32 v60, v75, v70
	v_add_f32_e32 v68, 1.0, v71
	v_mul_f32_e32 v69, 0xbfb8aa3b, v76
	v_mul_f32_e32 v70, 0xbfb8aa3b, v62
	v_pk_add_f32 v[58:59], v[58:59], v[134:135]
	v_pk_add_f32 v[50:51], v[50:51], v[130:131]
	v_rcp_f32_e32 v20, v20
	v_rcp_f32_e32 v21, v21
	v_rcp_f32_e32 v22, v22
	v_exp_f32_e32 v23, v23
	v_rcp_f32_e32 v68, v68
	v_exp_f32_e32 v69, v69
	v_exp_f32_e32 v70, v70
	v_mul_f32_e32 v52, v56, v52
	v_mul_f32_e32 v53, v48, v53
	v_mul_f32_e32 v48, v57, v54
	v_add_f32_e32 v54, 1.0, v55
	v_mul_f32_e32 v55, 0xbfb8aa3b, v58
	v_mul_f32_e32 v56, 0xbfb8aa3b, v50
	v_add_f32_e32 v4, 1.0, v4
	v_add_f32_e32 v5, 1.0, v5
	v_add_f32_e32 v6, 1.0, v6
	v_mul_f32_e32 v7, 0xbfb8aa3b, v1
	v_rcp_f32_e32 v54, v54
	v_exp_f32_e32 v55, v55
	v_exp_f32_e32 v56, v56
	v_pk_add_f32 v[42:43], v[42:43], v[134:135]
	v_pk_add_f32 v[34:35], v[34:35], v[130:131]
	v_rcp_f32_e32 v4, v4
	v_rcp_f32_e32 v5, v5
	v_rcp_f32_e32 v6, v6
	v_exp_f32_e32 v7, v7
	v_mul_f32_e32 v36, v40, v36
	v_mul_f32_e32 v37, v32, v37
	v_mul_f32_e32 v32, v41, v38
	v_add_f32_e32 v38, 1.0, v39
	v_mul_f32_e32 v39, 0xbfb8aa3b, v42
	v_mul_f32_e32 v40, 0xbfb8aa3b, v34
	v_pk_add_f32 v[26:27], v[26:27], v[134:135]
	v_pk_add_f32 v[18:19], v[18:19], v[130:131]
	v_rcp_f32_e32 v38, v38
	v_exp_f32_e32 v39, v39
	v_exp_f32_e32 v40, v40
	v_mul_f32_e32 v20, v24, v20
	v_mul_f32_e32 v21, v16, v21
	v_mul_f32_e32 v16, v25, v22
	v_add_f32_e32 v22, 1.0, v23
	v_mul_f32_e32 v23, 0xbfb8aa3b, v26
	v_mul_f32_e32 v24, 0xbfb8aa3b, v18
	v_mul_f32_e32 v71, v61, v68
	v_add_f32_e32 v61, 1.0, v69
	v_add_f32_e32 v68, 1.0, v70
	v_mul_f32_e32 v69, 0xbfb8aa3b, v77
	v_mul_f32_e32 v70, 0xbfb8aa3b, v63
	v_rcp_f32_e32 v22, v22
	v_exp_f32_e32 v23, v23
	v_exp_f32_e32 v24, v24
	v_pk_add_f32 v[10:11], v[10:11], v[134:135]
	v_pk_add_f32 v[2:3], v[2:3], v[130:131]
	v_exp_f32_e32 v69, v69
	v_exp_f32_e32 v70, v70
	v_mul_f32_e32 v54, v49, v54
	v_add_f32_e32 v49, 1.0, v55
	v_add_f32_e32 v55, 1.0, v56
	v_mul_f32_e32 v56, 0xbfb8aa3b, v59
	v_mul_f32_e32 v4, v8, v4
	v_mul_f32_e32 v5, v0, v5
	v_mul_f32_e32 v0, v9, v6
	v_add_f32_e32 v6, 1.0, v7
	v_mul_f32_e32 v7, 0xbfb8aa3b, v10
	v_mul_f32_e32 v8, 0xbfb8aa3b, v2
	v_exp_f32_e32 v56, v56
	v_rcp_f32_e32 v6, v6
	v_exp_f32_e32 v7, v7
	v_exp_f32_e32 v8, v8
	v_mul_f32_e32 v57, 0xbfb8aa3b, v51
	v_mul_f32_e32 v38, v33, v38
	v_add_f32_e32 v33, 1.0, v39
	v_add_f32_e32 v39, 1.0, v40
	v_mul_f32_e32 v40, 0xbfb8aa3b, v43
	v_mul_f32_e32 v41, 0xbfb8aa3b, v35
	v_exp_f32_e32 v57, v57
	v_exp_f32_e32 v40, v40
	v_exp_f32_e32 v41, v41
	v_mul_f32_e32 v22, v17, v22
	v_add_f32_e32 v17, 1.0, v23
	v_add_f32_e32 v23, 1.0, v24
	v_mul_f32_e32 v24, 0xbfb8aa3b, v27
	v_add_f32_e32 v69, 1.0, v69
	v_add_f32_e32 v70, 1.0, v70
	v_exp_f32_e32 v24, v24
	v_mul_f32_e32 v25, 0xbfb8aa3b, v19
	v_rcp_f32_e32 v61, v61
	v_rcp_f32_e32 v68, v68
	v_rcp_f32_e32 v69, v69
	v_rcp_f32_e32 v70, v70
	v_add_f32_e32 v56, 1.0, v56
	v_exp_f32_e32 v25, v25
	v_mul_f32_e32 v6, v1, v6
	v_add_f32_e32 v1, 1.0, v7
	v_add_f32_e32 v7, 1.0, v8
	v_mul_f32_e32 v8, 0xbfb8aa3b, v11
	v_or_b32_e32 v72, 48, v152
	v_rcp_f32_e32 v49, v49
	v_rcp_f32_e32 v55, v55
	v_rcp_f32_e32 v56, v56
	v_exp_f32_e32 v8, v8
	v_ashrrev_i32_e32 v73, 31, v72
	v_add_f32_e32 v57, 1.0, v57
	v_add_f32_e32 v40, 1.0, v40
	v_add_f32_e32 v41, 1.0, v41
	v_mul_f32_e32 v9, 0xbfb8aa3b, v3
	v_lshlrev_b64 v[72:73], 8, v[72:73]
	v_rcp_f32_e32 v57, v57
	v_rcp_f32_e32 v33, v33
	v_rcp_f32_e32 v39, v39
	v_rcp_f32_e32 v40, v40
	v_rcp_f32_e32 v41, v41
	v_add_f32_e32 v24, 1.0, v24
	v_exp_f32_e32 v9, v9
	v_mul_f32_e32 v61, v76, v61
	v_mul_f32_e32 v75, v62, v68
	v_mul_f32_e32 v62, v77, v69
	v_mul_f32_e32 v63, v63, v70
	v_lshl_add_u64 v[68:69], v[146:147], 0, v[72:73]
	v_rcp_f32_e32 v17, v17
	v_rcp_f32_e32 v23, v23
	v_rcp_f32_e32 v24, v24
	v_add_f32_e32 v25, 1.0, v25
	v_cvt_pk_bf16_f32 v60, v74, v60
	v_cvt_pk_bf16_f32 v61, v61, v62
	v_cvt_pk_bf16_f32 v62, v78, v71
	v_cvt_pk_bf16_f32 v63, v75, v63
	global_store_dwordx4 v[68:69], v[60:63], off
	v_mul_f32_e32 v49, v58, v49
	v_mul_f32_e32 v55, v50, v55
	v_mul_f32_e32 v50, v59, v56
	v_cvt_pk_bf16_f32 v48, v52, v48
	v_add_co_u32_e64 v52, s[0:1], s0, v96
	v_rcp_f32_e32 v25, v25
	v_add_f32_e32 v8, 1.0, v8
	v_cvt_pk_bf16_f32 v49, v49, v50
	v_cvt_pk_bf16_f32 v50, v53, v54
	v_addc_co_u32_e64 v53, s[0:1], 0, v97, s[0:1]
	v_rcp_f32_e32 v1, v1
	v_rcp_f32_e32 v7, v7
	v_rcp_f32_e32 v8, v8
	v_mul_f32_e32 v51, v51, v57
	v_mul_f32_e32 v33, v42, v33
	v_mul_f32_e32 v39, v34, v39
	v_mul_f32_e32 v34, v43, v40
	v_mul_f32_e32 v35, v35, v41
	s_mov_b32 s0, 0xa000
	v_add_f32_e32 v9, 1.0, v9
	v_cvt_pk_bf16_f32 v51, v55, v51
	global_store_dwordx4 v[52:53], v[48:51], off offset:-4096
	v_cvt_pk_bf16_f32 v32, v36, v32
	v_cvt_pk_bf16_f32 v33, v33, v34
	v_cvt_pk_bf16_f32 v34, v37, v38
	v_cvt_pk_bf16_f32 v35, v39, v35
	global_store_dwordx4 v[52:53], v[32:35], off
	v_mul_f32_e32 v17, v26, v17
	v_mul_f32_e32 v23, v18, v23
	v_mul_f32_e32 v18, v27, v24
	v_cvt_pk_bf16_f32 v16, v20, v16
	v_add_co_u32_e64 v20, s[0:1], s0, v96
	v_rcp_f32_e32 v9, v9
	v_mul_f32_e32 v19, v19, v25
	v_cvt_pk_bf16_f32 v17, v17, v18
	v_cvt_pk_bf16_f32 v18, v21, v22
	v_addc_co_u32_e64 v21, s[0:1], 0, v97, s[0:1]
	v_cvt_pk_bf16_f32 v19, v23, v19
	global_store_dwordx4 v[20:21], v[16:19], off
	v_mul_f32_e32 v1, v10, v1
	v_mul_f32_e32 v7, v2, v7
	v_mul_f32_e32 v2, v11, v8
	v_cvt_pk_bf16_f32 v0, v4, v0
	v_add_co_u32_e32 v4, vcc, 0xb000, v96
	v_cvt_pk_bf16_f32 v1, v1, v2
	v_cvt_pk_bf16_f32 v2, v5, v6
	v_mul_f32_e32 v3, v3, v9
	s_nop 0
	v_addc_co_u32_e32 v5, vcc, 0, v97, vcc
	s_and_b64 vcc, exec, s[8:9]
	s_mov_b32 s0, s14
	v_cvt_pk_bf16_f32 v3, v7, v3
	global_store_dwordx4 v[4:5], v[0:3], off
	s_cbranch_vccz .LBB0_255
	s_waitcnt vmcnt(0)
	s_cmpk_gt_u32 s33, 0xff
	s_cbranch_scc1 .LBB0_266
	s_barrier

.LBB0_654:
	ds_read_b128 v[144:147], v157
	ds_read_b128 v[148:151], v157 offset:1024
	ds_read_b128 v[160:163], v157 offset:2048
	ds_read_b128 v[164:167], v157 offset:3072
	s_add_u32 s24, s22, 0xfffc0080
	s_addc_u32 s25, s23, -1
	s_cmp_eq_u32 s49, 12
	s_cselect_b32 s27, s13, s25
	s_cselect_b32 s26, s19, s24
	s_cselect_b32 s25, s3, s48
	s_cselect_b32 s24, s42, s43
	v_lshl_add_u64 v[152:153], s[22:23], 0, v[136:137]
	s_add_i32 m0, s21, 0xc000
	ds_read_b128 v[168:171], v158
	ds_read_b128 v[176:179], v158 offset:1024
	ds_read_b128 v[180:183], v158 offset:2048
	ds_read_b128 v[184:187], v158 offset:3072
	ds_read_b128 v[188:191], v158 offset:4096
	ds_read_b128 v[192:195], v158 offset:5120
	ds_read_b128 v[196:199], v158 offset:6144
	ds_read_b128 v[200:203], v158 offset:7168
	global_load_lds_dwordx4 v[152:153], off
	s_add_i32 m0, s21, 0xe000
	v_lshl_add_u64 v[152:153], s[22:23], 0, v[138:139]
	global_load_lds_dwordx4 v[152:153], off
	s_waitcnt lgkmcnt(8)
	s_setprio 1
	s_barrier
	s_waitcnt lgkmcnt(0)
	v_mfma_f32_16x16x32_bf16 v[124:127], v[144:147], v[168:171], v[124:127]
	v_mfma_f32_16x16x32_bf16 v[120:123], v[160:163], v[168:171], v[120:123]
	v_mfma_f32_16x16x32_bf16 v[116:119], v[144:147], v[180:183], v[116:119]
	v_mfma_f32_16x16x32_bf16 v[112:115], v[160:163], v[180:183], v[112:115]
	v_mfma_f32_16x16x32_bf16 v[96:99], v[144:147], v[188:191], v[96:99]
	v_mfma_f32_16x16x32_bf16 v[88:91], v[160:163], v[188:191], v[88:91]
	v_mfma_f32_16x16x32_bf16 v[80:83], v[144:147], v[196:199], v[80:83]
	v_mfma_f32_16x16x32_bf16 v[72:75], v[160:163], v[196:199], v[72:75]
	v_mfma_f32_16x16x32_bf16 v[124:127], v[148:151], v[176:179], v[124:127]
	v_mfma_f32_16x16x32_bf16 v[120:123], v[164:167], v[176:179], v[120:123]
	v_mfma_f32_16x16x32_bf16 v[116:119], v[148:151], v[184:187], v[116:119]
	v_mfma_f32_16x16x32_bf16 v[112:115], v[164:167], v[184:187], v[112:115]
	v_mfma_f32_16x16x32_bf16 v[96:99], v[148:151], v[192:195], v[96:99]
	v_mfma_f32_16x16x32_bf16 v[88:91], v[164:167], v[192:195], v[88:91]
	v_mfma_f32_16x16x32_bf16 v[80:83], v[148:151], v[200:203], v[80:83]
	v_mfma_f32_16x16x32_bf16 v[72:75], v[164:167], v[200:203], v[72:75]
	s_setprio 0
	s_barrier
	s_add_i32 s50, s40, s29
	v_lshl_add_u64 v[152:153], s[24:25], 0, v[130:131]
	s_mov_b32 m0, s50
	ds_read_b128 v[204:207], v159
	ds_read_b128 v[212:215], v159 offset:1024
	ds_read_b128 v[216:219], v159 offset:2048
	ds_read_b128 v[220:223], v159 offset:3072
	global_load_lds_dwordx4 v[152:153], off
	s_add_i32 m0, s50, 0x2000
	v_lshl_add_u64 v[172:173], s[24:25], 0, v[134:135]
	global_load_lds_dwordx4 v[172:173], off
	s_setprio 1
	s_barrier
	s_waitcnt lgkmcnt(0)
	v_mfma_f32_16x16x32_bf16 v[108:111], v[204:207], v[168:171], v[108:111]
	v_mfma_f32_16x16x32_bf16 v[104:107], v[216:219], v[168:171], v[104:107]
	v_mfma_f32_16x16x32_bf16 v[100:103], v[204:207], v[180:183], v[100:103]
	v_mfma_f32_16x16x32_bf16 v[92:95], v[216:219], v[180:183], v[92:95]
	v_mfma_f32_16x16x32_bf16 v[84:87], v[204:207], v[188:191], v[84:87]
	v_mfma_f32_16x16x32_bf16 v[76:79], v[216:219], v[188:191], v[76:79]
	v_mfma_f32_16x16x32_bf16 v[68:71], v[204:207], v[196:199], v[68:71]
	v_mfma_f32_16x16x32_bf16 v[64:67], v[216:219], v[196:199], v[64:67]
	v_mfma_f32_16x16x32_bf16 v[108:111], v[212:215], v[176:179], v[108:111]
	v_mfma_f32_16x16x32_bf16 v[104:107], v[220:223], v[176:179], v[104:107]
	v_mfma_f32_16x16x32_bf16 v[100:103], v[212:215], v[184:187], v[100:103]
	v_mfma_f32_16x16x32_bf16 v[92:95], v[220:223], v[184:187], v[92:95]
	v_mfma_f32_16x16x32_bf16 v[84:87], v[212:215], v[192:195], v[84:87]
	v_mfma_f32_16x16x32_bf16 v[76:79], v[220:223], v[192:195], v[76:79]
	v_mfma_f32_16x16x32_bf16 v[68:71], v[212:215], v[200:203], v[68:71]
	v_mfma_f32_16x16x32_bf16 v[64:67], v[220:223], v[200:203], v[64:67]
	s_setprio 0
	s_mov_b32 m0, s21
	v_lshl_add_u64 v[208:209], s[26:27], 0, v[128:129]
	s_barrier
	ds_read_b128 v[168:171], v158 offset:16384
	ds_read_b128 v[176:179], v158 offset:17408
	ds_read_b128 v[180:183], v158 offset:18432
	ds_read_b128 v[184:187], v158 offset:19456
	ds_read_b128 v[188:191], v158 offset:20480
	ds_read_b128 v[192:195], v158 offset:21504
	ds_read_b128 v[196:199], v158 offset:22528
	ds_read_b128 v[200:203], v158 offset:23552
	global_load_lds_dwordx4 v[208:209], off
	s_mov_b32 m0, s30
	v_lshl_add_u64 v[224:225], s[26:27], 0, v[132:133]
	global_load_lds_dwordx4 v[224:225], off
	s_setprio 1
	s_barrier
	s_waitcnt lgkmcnt(0)
	v_mfma_f32_16x16x32_bf16 v[60:63], v[144:147], v[168:171], v[60:63]
	v_mfma_f32_16x16x32_bf16 v[56:59], v[160:163], v[168:171], v[56:59]
	v_mfma_f32_16x16x32_bf16 v[52:55], v[144:147], v[180:183], v[52:55]
	v_mfma_f32_16x16x32_bf16 v[48:51], v[160:163], v[180:183], v[48:51]
	v_mfma_f32_16x16x32_bf16 v[32:35], v[144:147], v[188:191], v[32:35]
	v_mfma_f32_16x16x32_bf16 v[24:27], v[160:163], v[188:191], v[24:27]
	v_mfma_f32_16x16x32_bf16 v[16:19], v[144:147], v[196:199], v[16:19]
	v_mfma_f32_16x16x32_bf16 v[8:11], v[160:163], v[196:199], v[8:11]
	v_mfma_f32_16x16x32_bf16 v[60:63], v[148:151], v[176:179], v[60:63]
	v_mfma_f32_16x16x32_bf16 v[56:59], v[164:167], v[176:179], v[56:59]
	v_mfma_f32_16x16x32_bf16 v[52:55], v[148:151], v[184:187], v[52:55]
	v_mfma_f32_16x16x32_bf16 v[48:51], v[164:167], v[184:187], v[48:51]
	v_mfma_f32_16x16x32_bf16 v[32:35], v[148:151], v[192:195], v[32:35]
	v_mfma_f32_16x16x32_bf16 v[24:27], v[164:167], v[192:195], v[24:27]
	v_mfma_f32_16x16x32_bf16 v[16:19], v[148:151], v[200:203], v[16:19]
	v_mfma_f32_16x16x32_bf16 v[8:11], v[164:167], v[200:203], v[8:11]
	s_setprio 0
	s_barrier
	s_add_u32 s50, s24, 0x40000
	s_addc_u32 s51, s25, 0
	s_add_i32 s52, s41, s29
	s_mov_b32 m0, s52
	v_lshl_add_u64 v[144:145], s[50:51], 0, v[130:131]
	global_load_lds_dwordx4 v[144:145], off
	s_add_i32 m0, s52, 0x2000
	v_lshl_add_u64 v[144:145], s[50:51], 0, v[134:135]
	global_load_lds_dwordx4 v[144:145], off
	s_waitcnt vmcnt(6)
	s_setprio 1
	s_barrier
	v_mfma_f32_16x16x32_bf16 v[44:47], v[204:207], v[168:171], v[44:47]
	v_mfma_f32_16x16x32_bf16 v[40:43], v[216:219], v[168:171], v[40:43]
	v_mfma_f32_16x16x32_bf16 v[36:39], v[204:207], v[180:183], v[36:39]
	v_mfma_f32_16x16x32_bf16 v[28:31], v[216:219], v[180:183], v[28:31]
	v_mfma_f32_16x16x32_bf16 v[20:23], v[204:207], v[188:191], v[20:23]
	v_mfma_f32_16x16x32_bf16 v[12:15], v[216:219], v[188:191], v[12:15]
	v_mfma_f32_16x16x32_bf16 v[4:7], v[204:207], v[196:199], v[4:7]
	v_mfma_f32_16x16x32_bf16 v[0:3], v[216:219], v[196:199], v[0:3]
	v_mfma_f32_16x16x32_bf16 v[44:47], v[212:215], v[176:179], v[44:47]
	v_mfma_f32_16x16x32_bf16 v[40:43], v[220:223], v[176:179], v[40:43]
	v_mfma_f32_16x16x32_bf16 v[36:39], v[212:215], v[184:187], v[36:39]
	v_mfma_f32_16x16x32_bf16 v[28:31], v[220:223], v[184:187], v[28:31]
	v_mfma_f32_16x16x32_bf16 v[20:23], v[212:215], v[192:195], v[20:23]
	v_mfma_f32_16x16x32_bf16 v[12:15], v[220:223], v[192:195], v[12:15]
	v_mfma_f32_16x16x32_bf16 v[4:7], v[212:215], v[200:203], v[4:7]
	v_mfma_f32_16x16x32_bf16 v[0:3], v[220:223], v[200:203], v[0:3]
	s_setprio 0
	s_add_i32 s50, 0, 0x18000
	v_add_u32_e32 v164, s50, v155
	s_barrier
	ds_read_b128 v[144:147], v164
	ds_read_b128 v[148:151], v164 offset:1024
	ds_read_b128 v[160:163], v164 offset:2048
	ds_read_b128 v[164:167], v164 offset:3072
	s_add_u32 s26, s26, 0x40000
	s_addc_u32 s27, s27, 0
	s_mov_b32 m0, s31
	v_lshl_add_u64 v[204:205], s[26:27], 0, v[128:129]
	ds_read_b128 v[168:171], v158 offset:32768
	ds_read_b128 v[176:179], v158 offset:33792
	ds_read_b128 v[180:183], v158 offset:34816
	ds_read_b128 v[184:187], v158 offset:35840
	ds_read_b128 v[188:191], v158 offset:36864
	ds_read_b128 v[192:195], v158 offset:37888
	ds_read_b128 v[196:199], v158 offset:38912
	ds_read_b128 v[200:203], v158 offset:39936
	global_load_lds_dwordx4 v[204:205], off
	s_mov_b32 m0, s33
	v_lshl_add_u64 v[204:205], s[26:27], 0, v[132:133]
	global_load_lds_dwordx4 v[204:205], off
	s_waitcnt lgkmcnt(8)
	s_setprio 1
	s_barrier
	s_waitcnt lgkmcnt(0)
	v_mfma_f32_16x16x32_bf16 v[124:127], v[144:147], v[168:171], v[124:127]
	v_mfma_f32_16x16x32_bf16 v[120:123], v[160:163], v[168:171], v[120:123]
	v_mfma_f32_16x16x32_bf16 v[116:119], v[144:147], v[180:183], v[116:119]
	v_mfma_f32_16x16x32_bf16 v[112:115], v[160:163], v[180:183], v[112:115]
	v_mfma_f32_16x16x32_bf16 v[96:99], v[144:147], v[188:191], v[96:99]
	v_mfma_f32_16x16x32_bf16 v[88:91], v[160:163], v[188:191], v[88:91]
	v_mfma_f32_16x16x32_bf16 v[80:83], v[144:147], v[196:199], v[80:83]
	v_mfma_f32_16x16x32_bf16 v[72:75], v[160:163], v[196:199], v[72:75]
	v_mfma_f32_16x16x32_bf16 v[124:127], v[148:151], v[176:179], v[124:127]
	v_mfma_f32_16x16x32_bf16 v[120:123], v[164:167], v[176:179], v[120:123]
	v_mfma_f32_16x16x32_bf16 v[116:119], v[148:151], v[184:187], v[116:119]
	v_mfma_f32_16x16x32_bf16 v[112:115], v[164:167], v[184:187], v[112:115]
	v_mfma_f32_16x16x32_bf16 v[96:99], v[148:151], v[192:195], v[96:99]
	v_mfma_f32_16x16x32_bf16 v[88:91], v[164:167], v[192:195], v[88:91]
	v_mfma_f32_16x16x32_bf16 v[80:83], v[148:151], v[200:203], v[80:83]
	v_mfma_f32_16x16x32_bf16 v[72:75], v[164:167], v[200:203], v[72:75]
	s_setprio 0
	s_barrier
	s_add_i32 s26, 0, 0x1c000
	s_add_i32 s27, s50, s29
	v_add_u32_e32 v175, s26, v155
	v_lshl_add_u64 v[152:153], v[152:153], 0, s[0:1]
	s_mov_b32 m0, s27
	ds_read_b128 v[204:207], v175
	ds_read_b128 v[212:215], v175 offset:1024
	ds_read_b128 v[216:219], v175 offset:2048
	ds_read_b128 v[220:223], v175 offset:3072
	global_load_lds_dwordx4 v[152:153], off
	s_add_i32 m0, s27, 0x2000
	v_lshl_add_u64 v[152:153], v[172:173], 0, s[0:1]
	global_load_lds_dwordx4 v[152:153], off
	s_setprio 1
	s_barrier
	s_waitcnt lgkmcnt(0)
	v_mfma_f32_16x16x32_bf16 v[108:111], v[204:207], v[168:171], v[108:111]
	v_mfma_f32_16x16x32_bf16 v[104:107], v[216:219], v[168:171], v[104:107]
	v_mfma_f32_16x16x32_bf16 v[100:103], v[204:207], v[180:183], v[100:103]
	v_mfma_f32_16x16x32_bf16 v[92:95], v[216:219], v[180:183], v[92:95]
	v_mfma_f32_16x16x32_bf16 v[84:87], v[204:207], v[188:191], v[84:87]
	v_mfma_f32_16x16x32_bf16 v[76:79], v[216:219], v[188:191], v[76:79]
	v_mfma_f32_16x16x32_bf16 v[68:71], v[204:207], v[196:199], v[68:71]
	v_mfma_f32_16x16x32_bf16 v[64:67], v[216:219], v[196:199], v[64:67]
	v_mfma_f32_16x16x32_bf16 v[108:111], v[212:215], v[176:179], v[108:111]
	v_mfma_f32_16x16x32_bf16 v[104:107], v[220:223], v[176:179], v[104:107]
	v_mfma_f32_16x16x32_bf16 v[100:103], v[212:215], v[184:187], v[100:103]
	v_mfma_f32_16x16x32_bf16 v[92:95], v[220:223], v[184:187], v[92:95]
	v_mfma_f32_16x16x32_bf16 v[84:87], v[212:215], v[192:195], v[84:87]
	v_mfma_f32_16x16x32_bf16 v[76:79], v[220:223], v[192:195], v[76:79]
	v_mfma_f32_16x16x32_bf16 v[68:71], v[212:215], v[200:203], v[68:71]
	v_mfma_f32_16x16x32_bf16 v[64:67], v[220:223], v[200:203], v[64:67]
	s_setprio 0
	s_mov_b32 m0, s35
	v_lshl_add_u64 v[152:153], v[208:209], 0, s[0:1]
	s_barrier
	ds_read_b128 v[168:171], v158 offset:49152
	ds_read_b128 v[176:179], v158 offset:50176
	ds_read_b128 v[180:183], v158 offset:51200
	ds_read_b128 v[184:187], v158 offset:52224
	ds_read_b128 v[188:191], v158 offset:53248
	ds_read_b128 v[192:195], v158 offset:54272
	ds_read_b128 v[196:199], v158 offset:55296
	ds_read_b128 v[200:203], v158 offset:56320
	global_load_lds_dwordx4 v[152:153], off
	s_mov_b32 m0, s36
	v_lshl_add_u64 v[152:153], v[224:225], 0, s[0:1]
	global_load_lds_dwordx4 v[152:153], off
	s_setprio 1
	s_barrier
	s_waitcnt lgkmcnt(0)
	v_mfma_f32_16x16x32_bf16 v[60:63], v[144:147], v[168:171], v[60:63]
	v_mfma_f32_16x16x32_bf16 v[56:59], v[160:163], v[168:171], v[56:59]
	v_mfma_f32_16x16x32_bf16 v[52:55], v[144:147], v[180:183], v[52:55]
	v_mfma_f32_16x16x32_bf16 v[48:51], v[160:163], v[180:183], v[48:51]
	v_mfma_f32_16x16x32_bf16 v[32:35], v[144:147], v[188:191], v[32:35]
	v_mfma_f32_16x16x32_bf16 v[24:27], v[160:163], v[188:191], v[24:27]
	v_mfma_f32_16x16x32_bf16 v[16:19], v[144:147], v[196:199], v[16:19]
	v_mfma_f32_16x16x32_bf16 v[8:11], v[160:163], v[196:199], v[8:11]
	v_mfma_f32_16x16x32_bf16 v[60:63], v[148:151], v[176:179], v[60:63]
	v_mfma_f32_16x16x32_bf16 v[56:59], v[164:167], v[176:179], v[56:59]
	v_mfma_f32_16x16x32_bf16 v[52:55], v[148:151], v[184:187], v[52:55]
	v_mfma_f32_16x16x32_bf16 v[48:51], v[164:167], v[184:187], v[48:51]
	v_mfma_f32_16x16x32_bf16 v[32:35], v[148:151], v[192:195], v[32:35]
	v_mfma_f32_16x16x32_bf16 v[24:27], v[164:167], v[192:195], v[24:27]
	v_mfma_f32_16x16x32_bf16 v[16:19], v[148:151], v[200:203], v[16:19]
	v_mfma_f32_16x16x32_bf16 v[8:11], v[164:167], v[200:203], v[8:11]
	s_setprio 0
	s_barrier
	s_add_u32 s24, s24, 0x40080
	s_addc_u32 s25, s25, 0
	s_add_i32 s26, s26, s29
	s_mov_b32 m0, s26
	v_lshl_add_u64 v[144:145], s[24:25], 0, v[130:131]
	global_load_lds_dwordx4 v[144:145], off
	s_add_i32 m0, s26, 0x2000
	v_lshl_add_u64 v[144:145], s[24:25], 0, v[134:135]
	global_load_lds_dwordx4 v[144:145], off
	s_waitcnt vmcnt(6)
	s_setprio 1
	s_barrier
	v_mfma_f32_16x16x32_bf16 v[44:47], v[204:207], v[168:171], v[44:47]
	v_mfma_f32_16x16x32_bf16 v[40:43], v[216:219], v[168:171], v[40:43]
	v_mfma_f32_16x16x32_bf16 v[36:39], v[204:207], v[180:183], v[36:39]
	v_mfma_f32_16x16x32_bf16 v[28:31], v[216:219], v[180:183], v[28:31]
	v_mfma_f32_16x16x32_bf16 v[20:23], v[204:207], v[188:191], v[20:23]
	v_mfma_f32_16x16x32_bf16 v[12:15], v[216:219], v[188:191], v[12:15]
	v_mfma_f32_16x16x32_bf16 v[4:7], v[204:207], v[196:199], v[4:7]
	v_mfma_f32_16x16x32_bf16 v[0:3], v[216:219], v[196:199], v[0:3]
	v_mfma_f32_16x16x32_bf16 v[44:47], v[212:215], v[176:179], v[44:47]
	v_mfma_f32_16x16x32_bf16 v[40:43], v[220:223], v[176:179], v[40:43]
	v_mfma_f32_16x16x32_bf16 v[36:39], v[212:215], v[184:187], v[36:39]
	v_mfma_f32_16x16x32_bf16 v[28:31], v[220:223], v[184:187], v[28:31]
	v_mfma_f32_16x16x32_bf16 v[20:23], v[212:215], v[192:195], v[20:23]
	v_mfma_f32_16x16x32_bf16 v[12:15], v[220:223], v[192:195], v[12:15]
	v_mfma_f32_16x16x32_bf16 v[4:7], v[212:215], v[200:203], v[4:7]
	v_mfma_f32_16x16x32_bf16 v[0:3], v[220:223], v[200:203], v[0:3]
	s_setprio 0
	s_add_i32 s49, s49, 2
	s_add_u32 s22, s22, 0x100
	s_addc_u32 s23, s23, 0
	s_add_u32 s43, s43, 0x100
	s_addc_u32 s48, s48, 0
	s_cmp_gt_u32 s49, 13
	s_barrier
	s_cbranch_scc0 .LBB0_654
	v_lshl_add_u32 v148, s18, 8, v154
	v_lshl_or_b32 v144, s20, 8, v156
	v_readlane_b32 s48, v253, 12
	v_ashrrev_i32_e32 v145, 31, v144
	v_ashrrev_i32_e32 v149, 31, v148
	v_readlane_b32 s49, v253, 13
	v_lshlrev_b64 v[150:151], 12, v[148:149]
	v_or_b32_e32 v172, 16, v148
	v_lshl_add_u64 v[146:147], v[144:145], 2, s[48:49]
	v_lshl_add_u64 v[150:151], v[146:147], 0, v[150:151]
	v_ashrrev_i32_e32 v173, 31, v172
	global_load_dwordx4 v[160:163], v[150:151], off
	global_load_dwordx4 v[164:167], v[150:151], off offset:16
	global_load_dwordx4 v[168:171], v[150:151], off offset:512
	global_load_dwordx4 v[176:179], v[150:151], off offset:528
	v_lshlrev_b64 v[150:151], 12, v[172:173]
	v_or_b32_e32 v152, 32, v148
	v_lshl_add_u64 v[150:151], v[146:147], 0, v[150:151]
	v_ashrrev_i32_e32 v153, 31, v152
	global_load_dwordx4 v[180:183], v[150:151], off
	global_load_dwordx4 v[184:187], v[150:151], off offset:16
	global_load_dwordx4 v[188:191], v[150:151], off offset:512
	global_load_dwordx4 v[192:195], v[150:151], off offset:528
	v_lshlrev_b64 v[150:151], 12, v[152:153]
	v_lshl_add_u64 v[208:209], v[146:147], 0, v[150:151]
	v_or_b32_e32 v150, 48, v148
	global_load_dwordx4 v[196:199], v[208:209], off
	global_load_dwordx4 v[200:203], v[208:209], off offset:16
	v_ashrrev_i32_e32 v151, 31, v150
	v_lshlrev_b64 v[204:205], 11, v[148:149]
	v_lshlrev_b64 v[216:217], 12, v[150:151]
	v_lshl_add_u64 v[218:219], s[10:11], 0, v[204:205]
	global_load_dwordx4 v[204:207], v[208:209], off offset:528
	global_load_dwordx4 v[212:215], v[208:209], off offset:512
	v_lshlrev_b64 v[144:145], 1, v[144:145]
	v_lshl_add_u64 v[208:209], v[146:147], 0, v[216:217]
	v_lshl_add_u64 v[232:233], v[218:219], 0, v[144:145]
	global_load_dwordx4 v[216:219], v[208:209], off offset:16
	global_load_dwordx4 v[220:223], v[208:209], off
	global_load_dwordx4 v[224:227], v[208:209], off offset:528
	global_load_dwordx4 v[228:231], v[208:209], off offset:512
	v_lshlrev_b64 v[172:173], 11, v[172:173]
	v_lshl_add_u64 v[172:173], s[10:11], 0, v[172:173]
	v_lshl_add_u64 v[172:173], v[172:173], 0, v[144:145]
	v_readlane_b32 s50, v253, 14
	v_readlane_b32 s51, v253, 15
	v_readlane_b32 s52, v253, 16
	v_readlane_b32 s53, v253, 17
	v_readlane_b32 s54, v253, 18
	v_readlane_b32 s55, v253, 19
	v_readlane_b32 s56, v253, 20
	v_readlane_b32 s57, v253, 21
	v_readlane_b32 s58, v253, 22
	v_readlane_b32 s59, v253, 23
	v_readlane_b32 s60, v253, 24
	v_readlane_b32 s61, v253, 25
	v_readlane_b32 s62, v253, 26
	v_readlane_b32 s63, v253, 27
	s_waitcnt vmcnt(0)
	v_pk_add_f32 v[126:127], v[126:127], v[162:163]
	v_pk_add_f32 v[124:125], v[124:125], v[160:161]
	v_pk_add_f32 v[160:161], v[122:123], v[166:167]
	v_pk_add_f32 v[162:163], v[120:121], v[164:165]
	v_pk_add_f32 v[164:165], v[110:111], v[170:171]
	v_pk_add_f32 v[166:167], v[108:109], v[168:169]
	v_pk_add_f32 v[168:169], v[106:107], v[178:179]
	v_cvt_pk_bf16_f32 v120, v124, v125
	v_cvt_pk_bf16_f32 v121, v126, v127
	v_cvt_pk_bf16_f32 v122, v162, v163
	v_cvt_pk_bf16_f32 v123, v160, v161
	v_pk_add_f32 v[106:107], v[112:113], v[184:185]
	global_store_dwordx4 v[232:233], v[120:123], off
	v_cvt_pk_bf16_f32 v112, v166, v167
	v_cvt_pk_bf16_f32 v113, v164, v165
	v_pk_add_f32 v[170:171], v[104:105], v[176:177]
	v_pk_add_f32 v[108:109], v[118:119], v[182:183]
	v_pk_add_f32 v[110:111], v[116:117], v[180:181]
	v_pk_add_f32 v[104:105], v[114:115], v[186:187]
	v_cvt_pk_bf16_f32 v114, v170, v171
	v_cvt_pk_bf16_f32 v115, v168, v169
	global_store_dwordx4 v[232:233], v[112:115], off offset:256
	v_mul_f32_e32 v175, v125, v125
	v_mul_f32_e32 v176, v127, v127
	v_cvt_pk_bf16_f32 v112, v110, v111
	v_cvt_pk_bf16_f32 v113, v108, v109
	v_mul_f32_e32 v125, v167, v167
	v_mul_f32_e32 v127, v165, v165
	v_cvt_pk_bf16_f32 v114, v106, v107
	v_cvt_pk_bf16_f32 v115, v104, v105
	global_store_dwordx4 v[172:173], v[112:115], off
	v_mul_f32_e32 v177, v163, v163
	v_mul_f32_e32 v178, v161, v161
	v_pk_add_f32 v[112:113], v[100:101], v[188:189]
	v_pk_add_f32 v[100:101], v[92:93], v[192:193]
	v_pk_add_f32 v[92:93], v[98:99], v[198:199]
	v_lshlrev_b64 v[98:99], 11, v[152:153]
	v_mul_f32_e32 v161, v171, v171
	v_fmac_f32_e32 v175, v124, v124
	v_fmac_f32_e32 v176, v126, v126
	v_fmac_f32_e32 v125, v166, v166
	v_fmac_f32_e32 v127, v164, v164
	v_lshl_add_u64 v[98:99], s[10:11], 0, v[98:99]
	v_mul_f32_e32 v163, v169, v169
	v_fmac_f32_e32 v177, v162, v162
	v_fmac_f32_e32 v161, v170, v170
	v_add_f32_e32 v116, v175, v176
	v_add_f32_e32 v117, v125, v127
	v_lshl_add_u64 v[118:119], v[98:99], 0, v[144:145]
	v_pk_add_f32 v[98:99], v[84:85], v[212:213]
	v_pk_add_f32 v[84:85], v[76:77], v[204:205]
	v_pk_add_f32 v[76:77], v[82:83], v[222:223]
	v_lshlrev_b64 v[82:83], 11, v[150:151]
	v_fmac_f32_e32 v178, v160, v160
	v_fmac_f32_e32 v163, v168, v168
	v_add_f32_e32 v116, v116, v177
	v_add_f32_e32 v117, v117, v161
	v_lshl_add_u64 v[82:83], s[10:11], 0, v[82:83]
	v_add_f32_e32 v116, v178, v116
	v_add_f32_e32 v117, v163, v117
	v_cvt_pk_bf16_f32 v114, v112, v113
	v_lshl_add_u64 v[122:123], v[82:83], 0, v[144:145]
	v_pk_add_f32 v[82:83], v[68:69], v[228:229]
	v_pk_add_f32 v[68:69], v[64:65], v[224:225]
	v_and_b32_e32 v65, 64, v174
	v_add_f32_e32 v120, v116, v117
	v_pk_add_f32 v[102:103], v[102:103], v[190:191]
	v_pk_add_f32 v[94:95], v[94:95], v[194:195]
	v_cvt_pk_bf16_f32 v115, v102, v103
	v_cvt_pk_bf16_f32 v116, v100, v101
	v_pk_add_f32 v[96:97], v[96:97], v[196:197]
	v_cvt_pk_bf16_f32 v117, v94, v95
	global_store_dwordx4 v[172:173], v[114:117], off offset:256
	v_xor_b32_e32 v64, 16, v174
	v_add_u32_e32 v65, 64, v65
	v_cvt_pk_bf16_f32 v114, v96, v97
	v_pk_add_f32 v[90:91], v[90:91], v[202:203]
	v_pk_add_f32 v[88:89], v[88:89], v[200:201]
	v_cvt_pk_bf16_f32 v115, v92, v93
	v_cmp_lt_i32_e32 vcc, v64, v65
	v_cvt_pk_bf16_f32 v116, v88, v89
	v_cvt_pk_bf16_f32 v117, v90, v91
	global_store_dwordx4 v[118:119], v[114:117], off
	v_pk_add_f32 v[86:87], v[86:87], v[214:215]
	v_pk_add_f32 v[78:79], v[78:79], v[206:207]
	v_cvt_pk_bf16_f32 v114, v98, v99
	v_cvt_pk_bf16_f32 v115, v86, v87
	v_cvt_pk_bf16_f32 v116, v84, v85
	v_pk_add_f32 v[80:81], v[80:81], v[220:221]
	v_cvt_pk_bf16_f32 v117, v78, v79
	global_store_dwordx4 v[118:119], v[114:117], off offset:256
	v_cndmask_b32_e32 v64, v174, v64, vcc
	v_pk_add_f32 v[74:75], v[74:75], v[218:219]
	v_cvt_pk_bf16_f32 v114, v80, v81
	v_pk_add_f32 v[72:73], v[72:73], v[216:217]
	v_cvt_pk_bf16_f32 v115, v76, v77
	v_pk_add_f32 v[70:71], v[70:71], v[230:231]
	v_cvt_pk_bf16_f32 v116, v72, v73
	v_cvt_pk_bf16_f32 v117, v74, v75
	global_store_dwordx4 v[122:123], v[114:117], off
	v_pk_add_f32 v[66:67], v[66:67], v[226:227]
	v_cvt_pk_bf16_f32 v118, v82, v83
	v_cvt_pk_bf16_f32 v119, v70, v71
	s_nop 0
	v_lshlrev_b32_e32 v114, 2, v64
	ds_bpermute_b32 v64, v114, v120
	v_xor_b32_e32 v115, 32, v174
	v_cmp_lt_i32_e32 vcc, v115, v65
	s_waitcnt lgkmcnt(0)
	v_add_f32_e32 v116, v120, v64
	v_cndmask_b32_e32 v65, v174, v115, vcc
	v_lshlrev_b32_e32 v115, 2, v65
	ds_bpermute_b32 v117, v115, v116
	v_lshl_add_u64 v[64:65], v[148:149], 2, s[66:67]
	v_cvt_pk_bf16_f32 v120, v68, v69
	v_cvt_pk_bf16_f32 v121, v66, v67
	global_store_dwordx4 v[122:123], v[118:121], off offset:256
	s_and_saveexec_b64 s[18:19], s[6:7]
	s_cbranch_execz .LBB0_657
	s_waitcnt lgkmcnt(0)
	v_add_f32_e32 v116, v116, v117
	global_atomic_add_f32 v[64:65], v116, off

.LBB0_712:
	ds_read_b128 v[144:147], v151
	ds_read_b128 v[156:159], v151 offset:1024
	ds_read_b128 v[160:163], v151 offset:2048
	ds_read_b128 v[164:167], v151 offset:3072
	s_add_u32 s26, s2, 0xfffc0080
	s_addc_u32 s27, s3, -1
	s_cmp_eq_u32 s56, 12
	s_cselect_b32 s29, s21, s27
	s_cselect_b32 s28, s52, s26
	s_cselect_b32 s27, s19, s55
	s_cselect_b32 s26, s53, s54
	v_lshl_add_u64 v[172:173], s[2:3], 0, v[136:137]
	s_add_i32 m0, s34, 0xc000
	ds_read_b128 v[168:171], v152
	ds_read_b128 v[176:179], v152 offset:1024
	ds_read_b128 v[180:183], v152 offset:2048
	ds_read_b128 v[184:187], v152 offset:3072
	ds_read_b128 v[188:191], v152 offset:4096
	ds_read_b128 v[192:195], v152 offset:5120
	ds_read_b128 v[196:199], v152 offset:6144
	ds_read_b128 v[200:203], v152 offset:7168
	global_load_lds_dwordx4 v[172:173], off
	s_add_i32 m0, s34, 0xe000
	v_lshl_add_u64 v[172:173], s[2:3], 0, v[138:139]
	global_load_lds_dwordx4 v[172:173], off
	s_waitcnt lgkmcnt(8)
	s_setprio 1
	s_barrier
	s_waitcnt lgkmcnt(0)
	v_mfma_f32_16x16x32_bf16 v[124:127], v[144:147], v[168:171], v[124:127]
	v_mfma_f32_16x16x32_bf16 v[120:123], v[160:163], v[168:171], v[120:123]
	v_mfma_f32_16x16x32_bf16 v[116:119], v[144:147], v[180:183], v[116:119]
	v_mfma_f32_16x16x32_bf16 v[112:115], v[160:163], v[180:183], v[112:115]
	v_mfma_f32_16x16x32_bf16 v[104:107], v[144:147], v[188:191], v[104:107]
	v_mfma_f32_16x16x32_bf16 v[96:99], v[160:163], v[188:191], v[96:99]
	v_mfma_f32_16x16x32_bf16 v[76:79], v[144:147], v[196:199], v[76:79]
	v_mfma_f32_16x16x32_bf16 v[72:75], v[160:163], v[196:199], v[72:75]
	v_mfma_f32_16x16x32_bf16 v[124:127], v[156:159], v[176:179], v[124:127]
	v_mfma_f32_16x16x32_bf16 v[120:123], v[164:167], v[176:179], v[120:123]
	v_mfma_f32_16x16x32_bf16 v[116:119], v[156:159], v[184:187], v[116:119]
	v_mfma_f32_16x16x32_bf16 v[112:115], v[164:167], v[184:187], v[112:115]
	v_mfma_f32_16x16x32_bf16 v[104:107], v[156:159], v[192:195], v[104:107]
	v_mfma_f32_16x16x32_bf16 v[96:99], v[164:167], v[192:195], v[96:99]
	v_mfma_f32_16x16x32_bf16 v[76:79], v[156:159], v[200:203], v[76:79]
	v_mfma_f32_16x16x32_bf16 v[72:75], v[164:167], v[200:203], v[72:75]
	s_setprio 0
	s_barrier
	s_add_i32 s57, s43, s33
	v_lshl_add_u64 v[172:173], s[26:27], 0, v[130:131]
	s_mov_b32 m0, s57
	ds_read_b128 v[204:207], v153
	ds_read_b128 v[212:215], v153 offset:1024
	ds_read_b128 v[216:219], v153 offset:2048
	ds_read_b128 v[220:223], v153 offset:3072
	global_load_lds_dwordx4 v[172:173], off
	s_add_i32 m0, s57, 0x2000
	v_lshl_add_u64 v[208:209], s[26:27], 0, v[134:135]
	global_load_lds_dwordx4 v[208:209], off
	s_setprio 1
	s_barrier
	s_waitcnt lgkmcnt(0)
	v_mfma_f32_16x16x32_bf16 v[108:111], v[204:207], v[168:171], v[108:111]
	v_mfma_f32_16x16x32_bf16 v[100:103], v[216:219], v[168:171], v[100:103]
	v_mfma_f32_16x16x32_bf16 v[92:95], v[204:207], v[180:183], v[92:95]
	v_mfma_f32_16x16x32_bf16 v[88:91], v[216:219], v[180:183], v[88:91]
	v_mfma_f32_16x16x32_bf16 v[84:87], v[204:207], v[188:191], v[84:87]
	v_mfma_f32_16x16x32_bf16 v[80:83], v[216:219], v[188:191], v[80:83]
	v_mfma_f32_16x16x32_bf16 v[68:71], v[204:207], v[196:199], v[68:71]
	v_mfma_f32_16x16x32_bf16 v[64:67], v[216:219], v[196:199], v[64:67]
	v_mfma_f32_16x16x32_bf16 v[108:111], v[212:215], v[176:179], v[108:111]
	v_mfma_f32_16x16x32_bf16 v[100:103], v[220:223], v[176:179], v[100:103]
	v_mfma_f32_16x16x32_bf16 v[92:95], v[212:215], v[184:187], v[92:95]
	v_mfma_f32_16x16x32_bf16 v[88:91], v[220:223], v[184:187], v[88:91]
	v_mfma_f32_16x16x32_bf16 v[84:87], v[212:215], v[192:195], v[84:87]
	v_mfma_f32_16x16x32_bf16 v[80:83], v[220:223], v[192:195], v[80:83]
	v_mfma_f32_16x16x32_bf16 v[68:71], v[212:215], v[200:203], v[68:71]
	v_mfma_f32_16x16x32_bf16 v[64:67], v[220:223], v[200:203], v[64:67]
	s_setprio 0
	s_mov_b32 m0, s34
	v_lshl_add_u64 v[224:225], s[28:29], 0, v[128:129]
	s_barrier
	ds_read_b128 v[168:171], v152 offset:16384
	ds_read_b128 v[176:179], v152 offset:17408
	ds_read_b128 v[180:183], v152 offset:18432
	ds_read_b128 v[184:187], v152 offset:19456
	ds_read_b128 v[188:191], v152 offset:20480
	ds_read_b128 v[192:195], v152 offset:21504
	ds_read_b128 v[196:199], v152 offset:22528
	ds_read_b128 v[200:203], v152 offset:23552
	global_load_lds_dwordx4 v[224:225], off
	s_mov_b32 m0, s35
	v_lshl_add_u64 v[226:227], s[28:29], 0, v[132:133]
	global_load_lds_dwordx4 v[226:227], off
	s_setprio 1
	s_barrier
	s_waitcnt lgkmcnt(0)
	v_mfma_f32_16x16x32_bf16 v[60:63], v[144:147], v[168:171], v[60:63]
	v_mfma_f32_16x16x32_bf16 v[56:59], v[160:163], v[168:171], v[56:59]
	v_mfma_f32_16x16x32_bf16 v[44:47], v[144:147], v[180:183], v[44:47]
	v_mfma_f32_16x16x32_bf16 v[40:43], v[160:163], v[180:183], v[40:43]
	v_mfma_f32_16x16x32_bf16 v[28:31], v[144:147], v[188:191], v[28:31]
	v_mfma_f32_16x16x32_bf16 v[24:27], v[160:163], v[188:191], v[24:27]
	v_mfma_f32_16x16x32_bf16 v[12:15], v[144:147], v[196:199], v[12:15]
	v_mfma_f32_16x16x32_bf16 v[8:11], v[160:163], v[196:199], v[8:11]
	v_mfma_f32_16x16x32_bf16 v[60:63], v[156:159], v[176:179], v[60:63]
	v_mfma_f32_16x16x32_bf16 v[56:59], v[164:167], v[176:179], v[56:59]
	v_mfma_f32_16x16x32_bf16 v[44:47], v[156:159], v[184:187], v[44:47]
	v_mfma_f32_16x16x32_bf16 v[40:43], v[164:167], v[184:187], v[40:43]
	v_mfma_f32_16x16x32_bf16 v[28:31], v[156:159], v[192:195], v[28:31]
	v_mfma_f32_16x16x32_bf16 v[24:27], v[164:167], v[192:195], v[24:27]
	v_mfma_f32_16x16x32_bf16 v[12:15], v[156:159], v[200:203], v[12:15]
	v_mfma_f32_16x16x32_bf16 v[8:11], v[164:167], v[200:203], v[8:11]
	s_setprio 0
	s_barrier
	s_add_u32 s58, s26, 0x40000
	s_addc_u32 s59, s27, 0
	s_add_i32 s57, s48, s33
	s_mov_b32 m0, s57
	v_lshl_add_u64 v[144:145], s[58:59], 0, v[130:131]
	global_load_lds_dwordx4 v[144:145], off
	s_add_i32 m0, s57, 0x2000
	v_lshl_add_u64 v[144:145], s[58:59], 0, v[134:135]
	global_load_lds_dwordx4 v[144:145], off
	s_waitcnt vmcnt(6)
	s_setprio 1
	s_barrier
	v_mfma_f32_16x16x32_bf16 v[52:55], v[204:207], v[168:171], v[52:55]
	v_mfma_f32_16x16x32_bf16 v[48:51], v[216:219], v[168:171], v[48:51]
	v_mfma_f32_16x16x32_bf16 v[36:39], v[204:207], v[180:183], v[36:39]
	v_mfma_f32_16x16x32_bf16 v[32:35], v[216:219], v[180:183], v[32:35]
	v_mfma_f32_16x16x32_bf16 v[20:23], v[204:207], v[188:191], v[20:23]
	v_mfma_f32_16x16x32_bf16 v[16:19], v[216:219], v[188:191], v[16:19]
	v_mfma_f32_16x16x32_bf16 v[4:7], v[204:207], v[196:199], v[4:7]
	v_mfma_f32_16x16x32_bf16 v[0:3], v[216:219], v[196:199], v[0:3]
	v_mfma_f32_16x16x32_bf16 v[52:55], v[212:215], v[176:179], v[52:55]
	v_mfma_f32_16x16x32_bf16 v[48:51], v[220:223], v[176:179], v[48:51]
	v_mfma_f32_16x16x32_bf16 v[36:39], v[212:215], v[184:187], v[36:39]
	v_mfma_f32_16x16x32_bf16 v[32:35], v[220:223], v[184:187], v[32:35]
	v_mfma_f32_16x16x32_bf16 v[20:23], v[212:215], v[192:195], v[20:23]
	v_mfma_f32_16x16x32_bf16 v[16:19], v[220:223], v[192:195], v[16:19]
	v_mfma_f32_16x16x32_bf16 v[4:7], v[212:215], v[200:203], v[4:7]
	v_mfma_f32_16x16x32_bf16 v[0:3], v[220:223], v[200:203], v[0:3]
	s_setprio 0
	s_add_i32 s57, 0, 0x18000
	v_add_u32_e32 v155, s57, v149
	s_barrier
	ds_read_b128 v[144:147], v155
	ds_read_b128 v[156:159], v155 offset:1024
	ds_read_b128 v[160:163], v155 offset:2048
	ds_read_b128 v[164:167], v155 offset:3072
	s_add_u32 s28, s28, 0x40000
	s_addc_u32 s29, s29, 0
	s_mov_b32 m0, s36
	v_lshl_add_u64 v[204:205], s[28:29], 0, v[128:129]
	ds_read_b128 v[168:171], v152 offset:32768
	ds_read_b128 v[176:179], v152 offset:33792
	ds_read_b128 v[180:183], v152 offset:34816
	ds_read_b128 v[184:187], v152 offset:35840
	ds_read_b128 v[188:191], v152 offset:36864
	ds_read_b128 v[192:195], v152 offset:37888
	ds_read_b128 v[196:199], v152 offset:38912
	ds_read_b128 v[200:203], v152 offset:39936
	global_load_lds_dwordx4 v[204:205], off
	s_mov_b32 m0, s37
	v_lshl_add_u64 v[204:205], s[28:29], 0, v[132:133]
	global_load_lds_dwordx4 v[204:205], off
	s_waitcnt lgkmcnt(8)
	s_setprio 1
	s_barrier
	s_waitcnt lgkmcnt(0)
	v_mfma_f32_16x16x32_bf16 v[124:127], v[144:147], v[168:171], v[124:127]
	v_mfma_f32_16x16x32_bf16 v[120:123], v[160:163], v[168:171], v[120:123]
	v_mfma_f32_16x16x32_bf16 v[116:119], v[144:147], v[180:183], v[116:119]
	v_mfma_f32_16x16x32_bf16 v[112:115], v[160:163], v[180:183], v[112:115]
	v_mfma_f32_16x16x32_bf16 v[104:107], v[144:147], v[188:191], v[104:107]
	v_mfma_f32_16x16x32_bf16 v[96:99], v[160:163], v[188:191], v[96:99]
	v_mfma_f32_16x16x32_bf16 v[76:79], v[144:147], v[196:199], v[76:79]
	v_mfma_f32_16x16x32_bf16 v[72:75], v[160:163], v[196:199], v[72:75]
	v_mfma_f32_16x16x32_bf16 v[124:127], v[156:159], v[176:179], v[124:127]
	v_mfma_f32_16x16x32_bf16 v[120:123], v[164:167], v[176:179], v[120:123]
	v_mfma_f32_16x16x32_bf16 v[116:119], v[156:159], v[184:187], v[116:119]
	v_mfma_f32_16x16x32_bf16 v[112:115], v[164:167], v[184:187], v[112:115]
	v_mfma_f32_16x16x32_bf16 v[104:107], v[156:159], v[192:195], v[104:107]
	v_mfma_f32_16x16x32_bf16 v[96:99], v[164:167], v[192:195], v[96:99]
	v_mfma_f32_16x16x32_bf16 v[76:79], v[156:159], v[200:203], v[76:79]
	v_mfma_f32_16x16x32_bf16 v[72:75], v[164:167], v[200:203], v[72:75]
	s_setprio 0
	s_barrier
	s_add_i32 s28, 0, 0x1c000
	s_add_i32 s29, s57, s33
	v_add_u32_e32 v155, s28, v149
	v_lshl_add_u64 v[172:173], v[172:173], 0, s[8:9]
	s_mov_b32 m0, s29
	ds_read_b128 v[204:207], v155
	ds_read_b128 v[212:215], v155 offset:1024
	ds_read_b128 v[216:219], v155 offset:2048
	ds_read_b128 v[220:223], v155 offset:3072
	global_load_lds_dwordx4 v[172:173], off
	s_add_i32 m0, s29, 0x2000
	v_lshl_add_u64 v[172:173], v[208:209], 0, s[8:9]
	global_load_lds_dwordx4 v[172:173], off
	s_setprio 1
	s_barrier
	s_waitcnt lgkmcnt(0)
	v_mfma_f32_16x16x32_bf16 v[108:111], v[204:207], v[168:171], v[108:111]
	v_mfma_f32_16x16x32_bf16 v[100:103], v[216:219], v[168:171], v[100:103]
	v_mfma_f32_16x16x32_bf16 v[92:95], v[204:207], v[180:183], v[92:95]
	v_mfma_f32_16x16x32_bf16 v[88:91], v[216:219], v[180:183], v[88:91]
	v_mfma_f32_16x16x32_bf16 v[84:87], v[204:207], v[188:191], v[84:87]
	v_mfma_f32_16x16x32_bf16 v[80:83], v[216:219], v[188:191], v[80:83]
	v_mfma_f32_16x16x32_bf16 v[68:71], v[204:207], v[196:199], v[68:71]
	v_mfma_f32_16x16x32_bf16 v[64:67], v[216:219], v[196:199], v[64:67]
	v_mfma_f32_16x16x32_bf16 v[108:111], v[212:215], v[176:179], v[108:111]
	v_mfma_f32_16x16x32_bf16 v[100:103], v[220:223], v[176:179], v[100:103]
	v_mfma_f32_16x16x32_bf16 v[92:95], v[212:215], v[184:187], v[92:95]
	v_mfma_f32_16x16x32_bf16 v[88:91], v[220:223], v[184:187], v[88:91]
	v_mfma_f32_16x16x32_bf16 v[84:87], v[212:215], v[192:195], v[84:87]
	v_mfma_f32_16x16x32_bf16 v[80:83], v[220:223], v[192:195], v[80:83]
	v_mfma_f32_16x16x32_bf16 v[68:71], v[212:215], v[200:203], v[68:71]
	v_mfma_f32_16x16x32_bf16 v[64:67], v[220:223], v[200:203], v[64:67]
	s_setprio 0
	s_mov_b32 m0, s39
	v_lshl_add_u64 v[172:173], v[224:225], 0, s[8:9]
	s_barrier
	ds_read_b128 v[168:171], v152 offset:49152
	ds_read_b128 v[176:179], v152 offset:50176
	ds_read_b128 v[180:183], v152 offset:51200
	ds_read_b128 v[184:187], v152 offset:52224
	ds_read_b128 v[188:191], v152 offset:53248
	ds_read_b128 v[192:195], v152 offset:54272
	ds_read_b128 v[196:199], v152 offset:55296
	ds_read_b128 v[200:203], v152 offset:56320
	global_load_lds_dwordx4 v[172:173], off
	s_mov_b32 m0, s40
	v_lshl_add_u64 v[172:173], v[226:227], 0, s[8:9]
	global_load_lds_dwordx4 v[172:173], off
	s_setprio 1
	s_barrier
	s_waitcnt lgkmcnt(0)
	v_mfma_f32_16x16x32_bf16 v[60:63], v[144:147], v[168:171], v[60:63]
	v_mfma_f32_16x16x32_bf16 v[56:59], v[160:163], v[168:171], v[56:59]
	v_mfma_f32_16x16x32_bf16 v[44:47], v[144:147], v[180:183], v[44:47]
	v_mfma_f32_16x16x32_bf16 v[40:43], v[160:163], v[180:183], v[40:43]
	v_mfma_f32_16x16x32_bf16 v[28:31], v[144:147], v[188:191], v[28:31]
	v_mfma_f32_16x16x32_bf16 v[24:27], v[160:163], v[188:191], v[24:27]
	v_mfma_f32_16x16x32_bf16 v[12:15], v[144:147], v[196:199], v[12:15]
	v_mfma_f32_16x16x32_bf16 v[8:11], v[160:163], v[196:199], v[8:11]
	v_mfma_f32_16x16x32_bf16 v[60:63], v[156:159], v[176:179], v[60:63]
	v_mfma_f32_16x16x32_bf16 v[56:59], v[164:167], v[176:179], v[56:59]
	v_mfma_f32_16x16x32_bf16 v[44:47], v[156:159], v[184:187], v[44:47]
	v_mfma_f32_16x16x32_bf16 v[40:43], v[164:167], v[184:187], v[40:43]
	v_mfma_f32_16x16x32_bf16 v[28:31], v[156:159], v[192:195], v[28:31]
	v_mfma_f32_16x16x32_bf16 v[24:27], v[164:167], v[192:195], v[24:27]
	v_mfma_f32_16x16x32_bf16 v[12:15], v[156:159], v[200:203], v[12:15]
	v_mfma_f32_16x16x32_bf16 v[8:11], v[164:167], v[200:203], v[8:11]
	s_setprio 0
	s_barrier
	s_add_u32 s26, s26, 0x40080
	s_addc_u32 s27, s27, 0
	s_add_i32 s28, s28, s33
	s_mov_b32 m0, s28
	v_lshl_add_u64 v[144:145], s[26:27], 0, v[130:131]
	global_load_lds_dwordx4 v[144:145], off
	s_add_i32 m0, s28, 0x2000
	v_lshl_add_u64 v[144:145], s[26:27], 0, v[134:135]
	global_load_lds_dwordx4 v[144:145], off
	s_waitcnt vmcnt(6)
	s_setprio 1
	s_barrier
	v_mfma_f32_16x16x32_bf16 v[52:55], v[204:207], v[168:171], v[52:55]
	v_mfma_f32_16x16x32_bf16 v[48:51], v[216:219], v[168:171], v[48:51]
	v_mfma_f32_16x16x32_bf16 v[36:39], v[204:207], v[180:183], v[36:39]
	v_mfma_f32_16x16x32_bf16 v[32:35], v[216:219], v[180:183], v[32:35]
	v_mfma_f32_16x16x32_bf16 v[20:23], v[204:207], v[188:191], v[20:23]
	v_mfma_f32_16x16x32_bf16 v[16:19], v[216:219], v[188:191], v[16:19]
	v_mfma_f32_16x16x32_bf16 v[4:7], v[204:207], v[196:199], v[4:7]
	v_mfma_f32_16x16x32_bf16 v[0:3], v[216:219], v[196:199], v[0:3]
	v_mfma_f32_16x16x32_bf16 v[52:55], v[212:215], v[176:179], v[52:55]
	v_mfma_f32_16x16x32_bf16 v[48:51], v[220:223], v[176:179], v[48:51]
	v_mfma_f32_16x16x32_bf16 v[36:39], v[212:215], v[184:187], v[36:39]
	v_mfma_f32_16x16x32_bf16 v[32:35], v[220:223], v[184:187], v[32:35]
	v_mfma_f32_16x16x32_bf16 v[20:23], v[212:215], v[192:195], v[20:23]
	v_mfma_f32_16x16x32_bf16 v[16:19], v[220:223], v[192:195], v[16:19]
	v_mfma_f32_16x16x32_bf16 v[4:7], v[212:215], v[200:203], v[4:7]
	v_mfma_f32_16x16x32_bf16 v[0:3], v[220:223], v[200:203], v[0:3]
	s_setprio 0
	s_add_i32 s56, s56, 2
	s_add_u32 s2, s2, 0x100
	s_addc_u32 s3, s3, 0
	s_add_u32 s54, s54, 0x100
	s_addc_u32 s55, s55, 0
	s_cmp_gt_u32 s56, 13
	s_barrier
	s_cbranch_scc0 .LBB0_712
	v_lshl_add_u32 v146, s0, 8, v148
	v_ashrrev_i32_e32 v147, 31, v146
	v_lshl_add_u64 v[144:145], v[146:147], 2, s[66:67]
	global_load_dword v155, v[144:145], off
	global_load_dword v164, v[144:145], off offset:64
	global_load_dword v165, v[144:145], off offset:128
	global_load_dword v166, v[144:145], off offset:192
	global_load_dword v167, v[144:145], off offset:512
	global_load_dword v168, v[144:145], off offset:576
	global_load_dword v169, v[144:145], off offset:640
	global_load_dword v170, v[144:145], off offset:704
	v_lshl_or_b32 v144, s1, 8, v150
	v_ashrrev_i32_e32 v145, 31, v144
	v_lshlrev_b64 v[160:161], 10, v[146:147]
	v_lshlrev_b64 v[162:163], 1, v[144:145]
	v_lshl_add_u64 v[144:145], s[92:93], 0, v[160:161]
	v_or_b32_e32 v156, 16, v146
	v_ashrrev_i32_e32 v157, 31, v156
	v_or_b32_e32 v158, 32, v146
	v_lshlrev_b64 v[156:157], 10, v[156:157]
	v_lshl_add_u64 v[144:145], v[144:145], 0, v[162:163]
	v_ashrrev_i32_e32 v159, 31, v158
	v_lshl_add_u64 v[156:157], s[92:93], 0, v[156:157]
	v_lshlrev_b64 v[158:159], 10, v[158:159]
	v_lshl_add_u64 v[156:157], v[156:157], 0, v[162:163]
	v_lshl_add_u64 v[158:159], s[92:93], 0, v[158:159]
	v_lshl_add_u64 v[158:159], v[158:159], 0, v[162:163]
	s_mov_b64 s[26:27], s[24:25]
	s_waitcnt vmcnt(0)
	v_fmamk_f32 v147, v155, 0x3a800000, v154
	v_fmamk_f32 v155, v164, 0x3a800000, v154
	v_fmamk_f32 v160, v165, 0x3a800000, v154
	v_mul_f32_e32 v161, 0x4b800000, v147
	v_mul_f32_e32 v164, 0x4b800000, v155
	v_cmp_gt_f32_e32 vcc, s49, v147
	v_cmp_gt_f32_e64 s[0:1], s49, v155
	v_mul_f32_e32 v165, 0x4b800000, v160
	v_cndmask_b32_e32 v147, v147, v161, vcc
	v_cndmask_b32_e64 v155, v155, v164, s[0:1]
	v_cmp_gt_f32_e64 s[2:3], s49, v160
	v_rsq_f32_e32 v147, v147
	v_rsq_f32_e32 v155, v155
	v_cndmask_b32_e64 v160, v160, v165, s[2:3]
	v_rsq_f32_e32 v160, v160
	v_mul_f32_e32 v161, 0x45800000, v147
	v_mul_f32_e32 v164, 0x45800000, v155
	v_cndmask_b32_e32 v147, v147, v161, vcc
	v_mul_f32_e32 v165, 0x45800000, v160
	v_cndmask_b32_e64 v155, v155, v164, s[0:1]
	v_cndmask_b32_e64 v161, v160, v165, s[2:3]
	v_mul_f32_e32 v160, 0x3e0293ee, v147
	v_mul_f32_e32 v164, 0x3e0293ee, v155
	v_fmamk_f32 v171, v166, 0x3a800000, v154
	v_mul_f32_e32 v166, 0x3e0293ee, v161
	v_pk_mul_f32 v[126:127], v[126:127], v[160:161] op_sel_hi:[1,0]
	v_pk_mul_f32 v[124:125], v[124:125], v[160:161] op_sel_hi:[1,0]
	v_pk_mul_f32 v[122:123], v[122:123], v[160:161] op_sel_hi:[1,0]
	v_pk_mul_f32 v[120:121], v[120:121], v[160:161] op_sel_hi:[1,0]
	v_pk_mul_f32 v[110:111], v[110:111], v[160:161] op_sel_hi:[1,0]
	v_pk_mul_f32 v[108:109], v[108:109], v[160:161] op_sel_hi:[1,0]
	v_pk_mul_f32 v[102:103], v[102:103], v[160:161] op_sel_hi:[1,0]
	v_pk_mul_f32 v[100:101], v[100:101], v[160:161] op_sel_hi:[1,0]
	v_pk_mul_f32 v[118:119], v[118:119], v[164:165] op_sel_hi:[1,0]
	v_pk_mul_f32 v[116:117], v[116:117], v[164:165] op_sel_hi:[1,0]
	v_pk_mul_f32 v[114:115], v[114:115], v[164:165] op_sel_hi:[1,0]
	v_pk_mul_f32 v[112:113], v[112:113], v[164:165] op_sel_hi:[1,0]
	v_pk_mul_f32 v[94:95], v[94:95], v[164:165] op_sel_hi:[1,0]
	v_pk_mul_f32 v[92:93], v[92:93], v[164:165] op_sel_hi:[1,0]
	v_pk_mul_f32 v[160:161], v[90:91], v[164:165] op_sel_hi:[1,0]
	v_pk_mul_f32 v[164:165], v[88:89], v[164:165] op_sel_hi:[1,0]
	v_cvt_pk_bf16_f32 v88, v124, v125
	v_cvt_pk_bf16_f32 v89, v126, v127
	v_cvt_pk_bf16_f32 v90, v120, v121
	v_cvt_pk_bf16_f32 v91, v122, v123
	global_store_dwordx4 v[144:145], v[88:91], off
	v_fmamk_f32 v167, v167, 0x3a800000, v154
	v_pk_mul_f32 v[106:107], v[106:107], v[166:167] op_sel_hi:[1,0]
	v_cvt_pk_bf16_f32 v88, v108, v109
	v_cvt_pk_bf16_f32 v89, v110, v111
	v_cvt_pk_bf16_f32 v90, v100, v101
	v_cvt_pk_bf16_f32 v91, v102, v103
	global_store_dwordx4 v[144:145], v[88:91], off offset:256
	v_pk_mul_f32 v[104:105], v[104:105], v[166:167] op_sel_hi:[1,0]
	v_pk_mul_f32 v[98:99], v[98:99], v[166:167] op_sel_hi:[1,0]
	v_cvt_pk_bf16_f32 v88, v116, v117
	v_cvt_pk_bf16_f32 v89, v118, v119
	v_cvt_pk_bf16_f32 v90, v112, v113
	v_cvt_pk_bf16_f32 v91, v114, v115
	global_store_dwordx4 v[156:157], v[88:91], off
	v_pk_mul_f32 v[96:97], v[96:97], v[166:167] op_sel_hi:[1,0]
	v_pk_mul_f32 v[86:87], v[86:87], v[166:167] op_sel_hi:[1,0]
	v_cvt_pk_bf16_f32 v88, v92, v93
	v_cvt_pk_bf16_f32 v89, v94, v95
	v_cvt_pk_bf16_f32 v90, v164, v165
	v_cvt_pk_bf16_f32 v91, v160, v161
	global_store_dwordx4 v[156:157], v[88:91], off offset:256
	v_pk_mul_f32 v[84:85], v[84:85], v[166:167] op_sel_hi:[1,0]
	v_cmp_gt_f32_e32 vcc, s49, v171
	v_cvt_pk_bf16_f32 v88, v104, v105
	v_cvt_pk_bf16_f32 v89, v106, v107
	v_cvt_pk_bf16_f32 v90, v96, v97
	v_cvt_pk_bf16_f32 v91, v98, v99
	global_store_dwordx4 v[158:159], v[88:91], off
	s_mov_b64 s[0:1], 0x20000
	v_fmamk_f32 v168, v168, 0x3a800000, v154
	v_pk_mul_f32 v[88:89], v[82:83], v[166:167] op_sel_hi:[1,0]
	v_pk_mul_f32 v[82:83], v[80:81], v[166:167] op_sel_hi:[1,0]
	v_cvt_pk_bf16_f32 v80, v84, v85
	v_cvt_pk_bf16_f32 v81, v86, v87
	v_fmamk_f32 v169, v169, 0x3a800000, v154
	v_cvt_pk_bf16_f32 v82, v82, v83
	v_cvt_pk_bf16_f32 v83, v88, v89
	global_store_dwordx4 v[158:159], v[80:83], off offset:256
	v_fmamk_f32 v170, v170, 0x3a800000, v154
	s_mov_b64 s[2:3], s[22:23]
	v_mul_f32_e32 v82, 0x4b800000, v171
	v_cndmask_b32_e32 v82, v171, v82, vcc
	v_rsq_f32_e32 v82, v82
	v_or_b32_e32 v80, 48, v146
	v_ashrrev_i32_e32 v81, 31, v80
	v_lshlrev_b64 v[80:81], 10, v[80:81]
	v_mul_f32_e32 v83, 0x45800000, v82
	v_cndmask_b32_e32 v82, v82, v83, vcc
	v_lshl_add_u64 v[80:81], s[92:93], 0, v[80:81]
	v_mul_f32_e32 v82, 0x3e0293ee, v82
	v_lshl_add_u64 v[80:81], v[80:81], 0, v[162:163]
	v_pk_mul_f32 v[78:79], v[78:79], v[82:83] op_sel_hi:[1,0]
	v_pk_mul_f32 v[76:77], v[76:77], v[82:83] op_sel_hi:[1,0]
	v_pk_mul_f32 v[84:85], v[74:75], v[82:83] op_sel_hi:[1,0]
	v_pk_mul_f32 v[74:75], v[72:73], v[82:83] op_sel_hi:[1,0]
	v_cvt_pk_bf16_f32 v72, v76, v77
	v_cvt_pk_bf16_f32 v73, v78, v79
	v_pk_mul_f32 v[70:71], v[70:71], v[82:83] op_sel_hi:[1,0]
	v_cvt_pk_bf16_f32 v74, v74, v75
	v_cvt_pk_bf16_f32 v75, v84, v85
	global_store_dwordx4 v[80:81], v[72:75], off
	v_pk_mul_f32 v[68:69], v[68:69], v[82:83] op_sel_hi:[1,0]
	v_cmp_gt_f32_e32 vcc, s49, v167
	v_pk_mul_f32 v[72:73], v[66:67], v[82:83] op_sel_hi:[1,0]
	v_pk_mul_f32 v[66:67], v[64:65], v[82:83] op_sel_hi:[1,0]
	v_cvt_pk_bf16_f32 v64, v68, v69
	v_cvt_pk_bf16_f32 v65, v70, v71
	s_nop 0
	v_cvt_pk_bf16_f32 v66, v66, v67
	v_mul_f32_e32 v67, 0x4b800000, v167
	v_cndmask_b32_e32 v67, v167, v67, vcc
	v_rsq_f32_e32 v68, v67
	v_cvt_pk_bf16_f32 v67, v72, v73
	global_store_dwordx4 v[80:81], v[64:67], off offset:256
	s_nop 1
	v_mul_f32_e32 v66, 0x45800000, v68
	v_cndmask_b32_e32 v66, v68, v66, vcc
	v_mul_f32_e32 v66, 0x3e0293ee, v66
	v_lshl_add_u64 v[64:65], v[144:145], 0, s[0:1]
	v_pk_mul_f32 v[60:61], v[60:61], v[66:67] op_sel_hi:[1,0]
	s_mov_b32 s0, 0x20000
	v_pk_mul_f32 v[68:69], v[58:59], v[66:67] op_sel_hi:[1,0]
	v_pk_mul_f32 v[58:59], v[56:57], v[66:67] op_sel_hi:[1,0]
	v_cvt_pk_bf16_f32 v56, v60, v61
	v_add_co_u32_e32 v60, vcc, s0, v144
	v_pk_mul_f32 v[62:63], v[62:63], v[66:67] op_sel_hi:[1,0]
	s_nop 0
	v_addc_co_u32_e32 v61, vcc, 0, v145, vcc
	v_cvt_pk_bf16_f32 v57, v62, v63
	v_cvt_pk_bf16_f32 v58, v58, v59
	v_cvt_pk_bf16_f32 v59, v68, v69
	global_store_dwordx4 v[60:61], v[56:59], off
	v_pk_mul_f32 v[54:55], v[54:55], v[66:67] op_sel_hi:[1,0]
	v_pk_mul_f32 v[52:53], v[52:53], v[66:67] op_sel_hi:[1,0]
	v_pk_mul_f32 v[56:57], v[50:51], v[66:67] op_sel_hi:[1,0]
	v_pk_mul_f32 v[50:51], v[48:49], v[66:67] op_sel_hi:[1,0]
	v_cvt_pk_bf16_f32 v48, v52, v53
	v_cvt_pk_bf16_f32 v49, v54, v55
	v_cmp_gt_f32_e32 vcc, s49, v168
	v_cvt_pk_bf16_f32 v50, v50, v51
	v_mul_f32_e32 v51, 0x4b800000, v168
	s_mov_b64 s[0:1], 0x24000
	v_cndmask_b32_e32 v51, v168, v51, vcc
	v_rsq_f32_e32 v52, v51
	v_cvt_pk_bf16_f32 v51, v56, v57
	global_store_dwordx4 v[64:65], v[48:51], off offset:256
	s_nop 1
	v_mul_f32_e32 v50, 0x45800000, v52
	v_cndmask_b32_e32 v50, v52, v50, vcc
	v_mul_f32_e32 v50, 0x3e0293ee, v50
	v_lshl_add_u64 v[48:49], v[144:145], 0, s[0:1]
	v_pk_mul_f32 v[44:45], v[44:45], v[50:51] op_sel_hi:[1,0]
	s_mov_b32 s0, 0x24000
	v_pk_mul_f32 v[52:53], v[42:43], v[50:51] op_sel_hi:[1,0]
	v_pk_mul_f32 v[42:43], v[40:41], v[50:51] op_sel_hi:[1,0]
	v_cvt_pk_bf16_f32 v40, v44, v45
	v_add_co_u32_e32 v44, vcc, s0, v144
	v_pk_mul_f32 v[46:47], v[46:47], v[50:51] op_sel_hi:[1,0]
	s_nop 0
	v_addc_co_u32_e32 v45, vcc, 0, v145, vcc
	v_cvt_pk_bf16_f32 v41, v46, v47
	v_cvt_pk_bf16_f32 v42, v42, v43
	v_cvt_pk_bf16_f32 v43, v52, v53
	global_store_dwordx4 v[44:45], v[40:43], off
	v_pk_mul_f32 v[38:39], v[38:39], v[50:51] op_sel_hi:[1,0]
	v_pk_mul_f32 v[36:37], v[36:37], v[50:51] op_sel_hi:[1,0]
	v_pk_mul_f32 v[40:41], v[34:35], v[50:51] op_sel_hi:[1,0]
	v_pk_mul_f32 v[34:35], v[32:33], v[50:51] op_sel_hi:[1,0]
	v_cvt_pk_bf16_f32 v32, v36, v37
	v_cvt_pk_bf16_f32 v33, v38, v39
	v_cmp_gt_f32_e32 vcc, s49, v169
	v_cvt_pk_bf16_f32 v34, v34, v35
	v_mul_f32_e32 v35, 0x4b800000, v169
	s_mov_b32 s1, s18
	v_cndmask_b32_e32 v35, v169, v35, vcc
	v_rsq_f32_e32 v36, v35
	v_cvt_pk_bf16_f32 v35, v40, v41
	global_store_dwordx4 v[48:49], v[32:35], off offset:256
	s_mov_b32 s0, s20
	s_nop 0
	v_mul_f32_e32 v34, 0x45800000, v36
	v_cndmask_b32_e32 v34, v36, v34, vcc
	v_mul_f32_e32 v34, 0x3e0293ee, v34
	v_pk_mul_f32 v[28:29], v[28:29], v[34:35] op_sel_hi:[1,0]
	v_pk_mul_f32 v[36:37], v[26:27], v[34:35] op_sel_hi:[1,0]
	v_pk_mul_f32 v[26:27], v[24:25], v[34:35] op_sel_hi:[1,0]
	v_cvt_pk_bf16_f32 v24, v28, v29
	v_add_co_u32_e32 v28, vcc, s50, v144
	v_pk_mul_f32 v[30:31], v[30:31], v[34:35] op_sel_hi:[1,0]
	s_nop 0
	v_addc_co_u32_e32 v29, vcc, 0, v145, vcc
	v_cvt_pk_bf16_f32 v25, v30, v31
	v_cvt_pk_bf16_f32 v26, v26, v27
	v_cvt_pk_bf16_f32 v27, v36, v37
	global_store_dwordx4 v[28:29], v[24:27], off
	v_pk_mul_f32 v[22:23], v[22:23], v[34:35] op_sel_hi:[1,0]
	v_pk_mul_f32 v[20:21], v[20:21], v[34:35] op_sel_hi:[1,0]
	v_pk_mul_f32 v[24:25], v[18:19], v[34:35] op_sel_hi:[1,0]
	v_pk_mul_f32 v[18:19], v[16:17], v[34:35] op_sel_hi:[1,0]
	v_cvt_pk_bf16_f32 v16, v20, v21
	v_cvt_pk_bf16_f32 v17, v22, v23
	v_cmp_gt_f32_e32 vcc, s49, v170
	v_cvt_pk_bf16_f32 v18, v18, v19
	v_mul_f32_e32 v19, 0x4b800000, v170
	v_lshl_add_u64 v[32:33], v[144:145], 0, s[12:13]
	v_cndmask_b32_e32 v19, v170, v19, vcc
	v_rsq_f32_e32 v20, v19
	v_cvt_pk_bf16_f32 v19, v24, v25
	global_store_dwordx4 v[32:33], v[16:19], off offset:256
	s_nop 1
	v_mul_f32_e32 v18, 0x45800000, v20
	v_cndmask_b32_e32 v18, v20, v18, vcc
	v_mul_f32_e32 v18, 0x3e0293ee, v18
	v_pk_mul_f32 v[12:13], v[12:13], v[18:19] op_sel_hi:[1,0]
	v_pk_mul_f32 v[20:21], v[10:11], v[18:19] op_sel_hi:[1,0]
	v_pk_mul_f32 v[10:11], v[8:9], v[18:19] op_sel_hi:[1,0]
	v_cvt_pk_bf16_f32 v8, v12, v13
	v_add_co_u32_e32 v12, vcc, s51, v144
	v_pk_mul_f32 v[14:15], v[14:15], v[18:19] op_sel_hi:[1,0]
	s_nop 0
	v_addc_co_u32_e32 v13, vcc, 0, v145, vcc
	v_cvt_pk_bf16_f32 v9, v14, v15
	v_lshl_add_u64 v[16:17], v[144:145], 0, s[16:17]
	v_cvt_pk_bf16_f32 v10, v10, v11
	v_cvt_pk_bf16_f32 v11, v20, v21
	global_store_dwordx4 v[12:13], v[8:11], off
	s_and_b64 vcc, exec, s[6:7]
	v_pk_mul_f32 v[6:7], v[6:7], v[18:19] op_sel_hi:[1,0]
	v_pk_mul_f32 v[8:9], v[2:3], v[18:19] op_sel_hi:[1,0]
	v_pk_mul_f32 v[2:3], v[0:1], v[18:19] op_sel_hi:[1,0]
	v_pk_mul_f32 v[4:5], v[4:5], v[18:19] op_sel_hi:[1,0]
	s_nop 0
	v_cvt_pk_bf16_f32 v0, v4, v5
	v_cvt_pk_bf16_f32 v1, v6, v7
	v_cvt_pk_bf16_f32 v2, v2, v3
	v_cvt_pk_bf16_f32 v3, v8, v9
	global_store_dwordx4 v[16:17], v[0:3], off offset:256
	s_cbranch_vccz .LBB0_705
	s_waitcnt vmcnt(0)
	s_cmpk_gt_u32 s30, 0xff
	s_cbranch_scc1 .LBB0_716
	s_barrier

.LBB0_792:
	ds_read_b128 v[144:147], v178
	ds_read_b128 v[148:151], v178 offset:1024
	ds_read_b128 v[152:155], v178 offset:2048
	ds_read_b128 v[156:159], v178 offset:3072
	s_add_u32 s40, s38, 0xfffe0080
	s_addc_u32 s41, s39, -1
	s_cmp_eq_u32 s63, 4
	s_cselect_b32 s43, s27, s41
	s_cselect_b32 s42, s35, s40
	s_cselect_b32 s41, s25, s62
	s_cselect_b32 s40, s60, s61
	v_lshl_add_u64 v[172:173], s[38:39], 0, v[136:137]
	s_add_i32 m0, s37, 0xc000
	ds_read_b128 v[160:163], v179
	ds_read_b128 v[164:167], v179 offset:1024
	ds_read_b128 v[168:171], v179 offset:2048
	ds_read_b128 v[182:185], v179 offset:3072
	ds_read_b128 v[186:189], v179 offset:4096
	ds_read_b128 v[190:193], v179 offset:5120
	ds_read_b128 v[194:197], v179 offset:6144
	ds_read_b128 v[198:201], v179 offset:7168
	global_load_lds_dwordx4 v[172:173], off
	s_add_i32 m0, s37, 0xe000
	v_lshl_add_u64 v[172:173], s[38:39], 0, v[138:139]
	global_load_lds_dwordx4 v[172:173], off
	s_waitcnt lgkmcnt(8)
	s_setprio 1
	s_barrier
	s_waitcnt lgkmcnt(0)
	v_mfma_f32_16x16x32_bf16 v[124:127], v[144:147], v[160:163], v[124:127]
	v_mfma_f32_16x16x32_bf16 v[120:123], v[152:155], v[160:163], v[120:123]
	v_mfma_f32_16x16x32_bf16 v[108:111], v[144:147], v[168:171], v[108:111]
	v_mfma_f32_16x16x32_bf16 v[104:107], v[152:155], v[168:171], v[104:107]
	v_mfma_f32_16x16x32_bf16 v[96:99], v[144:147], v[186:189], v[96:99]
	v_mfma_f32_16x16x32_bf16 v[88:91], v[152:155], v[186:189], v[88:91]
	v_mfma_f32_16x16x32_bf16 v[80:83], v[144:147], v[194:197], v[80:83]
	v_mfma_f32_16x16x32_bf16 v[72:75], v[152:155], v[194:197], v[72:75]
	v_mfma_f32_16x16x32_bf16 v[124:127], v[148:151], v[164:167], v[124:127]
	v_mfma_f32_16x16x32_bf16 v[120:123], v[156:159], v[164:167], v[120:123]
	v_mfma_f32_16x16x32_bf16 v[108:111], v[148:151], v[182:185], v[108:111]
	v_mfma_f32_16x16x32_bf16 v[104:107], v[156:159], v[182:185], v[104:107]
	v_mfma_f32_16x16x32_bf16 v[96:99], v[148:151], v[190:193], v[96:99]
	v_mfma_f32_16x16x32_bf16 v[88:91], v[156:159], v[190:193], v[88:91]
	v_mfma_f32_16x16x32_bf16 v[80:83], v[148:151], v[198:201], v[80:83]
	v_mfma_f32_16x16x32_bf16 v[72:75], v[156:159], v[198:201], v[72:75]
	s_setprio 0
	s_barrier
	s_add_i32 s64, s58, s48
	v_lshl_add_u64 v[172:173], s[40:41], 0, v[130:131]
	s_mov_b32 m0, s64
	ds_read_b128 v[202:205], v180
	ds_read_b128 v[206:209], v180 offset:1024
	ds_read_b128 v[212:215], v180 offset:2048
	ds_read_b128 v[216:219], v180 offset:3072
	global_load_lds_dwordx4 v[172:173], off
	s_add_i32 m0, s64, 0x2000
	v_lshl_add_u64 v[220:221], s[40:41], 0, v[134:135]
	global_load_lds_dwordx4 v[220:221], off
	s_setprio 1
	s_barrier
	s_waitcnt lgkmcnt(0)
	v_mfma_f32_16x16x32_bf16 v[116:119], v[202:205], v[160:163], v[116:119]
	v_mfma_f32_16x16x32_bf16 v[112:115], v[212:215], v[160:163], v[112:115]
	v_mfma_f32_16x16x32_bf16 v[100:103], v[202:205], v[168:171], v[100:103]
	v_mfma_f32_16x16x32_bf16 v[92:95], v[212:215], v[168:171], v[92:95]
	v_mfma_f32_16x16x32_bf16 v[84:87], v[202:205], v[186:189], v[84:87]
	v_mfma_f32_16x16x32_bf16 v[76:79], v[212:215], v[186:189], v[76:79]
	v_mfma_f32_16x16x32_bf16 v[68:71], v[202:205], v[194:197], v[68:71]
	v_mfma_f32_16x16x32_bf16 v[64:67], v[212:215], v[194:197], v[64:67]
	v_mfma_f32_16x16x32_bf16 v[116:119], v[206:209], v[164:167], v[116:119]
	v_mfma_f32_16x16x32_bf16 v[112:115], v[216:219], v[164:167], v[112:115]
	v_mfma_f32_16x16x32_bf16 v[100:103], v[206:209], v[182:185], v[100:103]
	v_mfma_f32_16x16x32_bf16 v[92:95], v[216:219], v[182:185], v[92:95]
	v_mfma_f32_16x16x32_bf16 v[84:87], v[206:209], v[190:193], v[84:87]
	v_mfma_f32_16x16x32_bf16 v[76:79], v[216:219], v[190:193], v[76:79]
	v_mfma_f32_16x16x32_bf16 v[68:71], v[206:209], v[198:201], v[68:71]
	v_mfma_f32_16x16x32_bf16 v[64:67], v[216:219], v[198:201], v[64:67]
	s_setprio 0
	s_mov_b32 m0, s37
	v_lshl_add_u64 v[222:223], s[42:43], 0, v[128:129]
	s_barrier
	ds_read_b128 v[160:163], v179 offset:16384
	ds_read_b128 v[164:167], v179 offset:17408
	ds_read_b128 v[168:171], v179 offset:18432
	ds_read_b128 v[182:185], v179 offset:19456
	ds_read_b128 v[186:189], v179 offset:20480
	ds_read_b128 v[190:193], v179 offset:21504
	ds_read_b128 v[194:197], v179 offset:22528
	ds_read_b128 v[198:201], v179 offset:23552
	global_load_lds_dwordx4 v[222:223], off
	s_mov_b32 m0, s49
	v_lshl_add_u64 v[224:225], s[42:43], 0, v[132:133]
	global_load_lds_dwordx4 v[224:225], off
	s_setprio 1
	s_barrier
	s_waitcnt lgkmcnt(0)
	v_mfma_f32_16x16x32_bf16 v[60:63], v[144:147], v[160:163], v[60:63]
	v_mfma_f32_16x16x32_bf16 v[56:59], v[152:155], v[160:163], v[56:59]
	v_mfma_f32_16x16x32_bf16 v[44:47], v[144:147], v[168:171], v[44:47]
	v_mfma_f32_16x16x32_bf16 v[40:43], v[152:155], v[168:171], v[40:43]
	v_mfma_f32_16x16x32_bf16 v[32:35], v[144:147], v[186:189], v[32:35]
	v_mfma_f32_16x16x32_bf16 v[24:27], v[152:155], v[186:189], v[24:27]
	v_mfma_f32_16x16x32_bf16 v[16:19], v[144:147], v[194:197], v[16:19]
	v_mfma_f32_16x16x32_bf16 v[8:11], v[152:155], v[194:197], v[8:11]
	v_mfma_f32_16x16x32_bf16 v[60:63], v[148:151], v[164:167], v[60:63]
	v_mfma_f32_16x16x32_bf16 v[56:59], v[156:159], v[164:167], v[56:59]
	v_mfma_f32_16x16x32_bf16 v[44:47], v[148:151], v[182:185], v[44:47]
	v_mfma_f32_16x16x32_bf16 v[40:43], v[156:159], v[182:185], v[40:43]
	v_mfma_f32_16x16x32_bf16 v[32:35], v[148:151], v[190:193], v[32:35]
	v_mfma_f32_16x16x32_bf16 v[24:27], v[156:159], v[190:193], v[24:27]
	v_mfma_f32_16x16x32_bf16 v[16:19], v[148:151], v[198:201], v[16:19]
	v_mfma_f32_16x16x32_bf16 v[8:11], v[156:159], v[198:201], v[8:11]
	s_setprio 0
	s_barrier
	s_add_u32 s64, s40, 0x20000
	s_addc_u32 s65, s41, 0
	s_add_i32 s66, s59, s48
	s_mov_b32 m0, s66
	v_lshl_add_u64 v[144:145], s[64:65], 0, v[130:131]
	global_load_lds_dwordx4 v[144:145], off
	s_add_i32 m0, s66, 0x2000
	v_lshl_add_u64 v[144:145], s[64:65], 0, v[134:135]
	global_load_lds_dwordx4 v[144:145], off
	s_waitcnt vmcnt(6)
	s_setprio 1
	s_barrier
	v_mfma_f32_16x16x32_bf16 v[52:55], v[202:205], v[160:163], v[52:55]
	v_mfma_f32_16x16x32_bf16 v[48:51], v[212:215], v[160:163], v[48:51]
	v_mfma_f32_16x16x32_bf16 v[36:39], v[202:205], v[168:171], v[36:39]
	v_mfma_f32_16x16x32_bf16 v[28:31], v[212:215], v[168:171], v[28:31]
	v_mfma_f32_16x16x32_bf16 v[20:23], v[202:205], v[186:189], v[20:23]
	v_mfma_f32_16x16x32_bf16 v[12:15], v[212:215], v[186:189], v[12:15]
	v_mfma_f32_16x16x32_bf16 v[4:7], v[202:205], v[194:197], v[4:7]
	v_mfma_f32_16x16x32_bf16 v[0:3], v[212:215], v[194:197], v[0:3]
	v_mfma_f32_16x16x32_bf16 v[52:55], v[206:209], v[164:167], v[52:55]
	v_mfma_f32_16x16x32_bf16 v[48:51], v[216:219], v[164:167], v[48:51]
	v_mfma_f32_16x16x32_bf16 v[36:39], v[206:209], v[182:185], v[36:39]
	v_mfma_f32_16x16x32_bf16 v[28:31], v[216:219], v[182:185], v[28:31]
	v_mfma_f32_16x16x32_bf16 v[20:23], v[206:209], v[190:193], v[20:23]
	v_mfma_f32_16x16x32_bf16 v[12:15], v[216:219], v[190:193], v[12:15]
	v_mfma_f32_16x16x32_bf16 v[4:7], v[206:209], v[198:201], v[4:7]
	v_mfma_f32_16x16x32_bf16 v[0:3], v[216:219], v[198:201], v[0:3]
	s_setprio 0
	s_add_i32 s64, 0, 0x18000
	v_add_u32_e32 v156, s64, v176
	s_barrier
	ds_read_b128 v[144:147], v156
	ds_read_b128 v[148:151], v156 offset:1024
	ds_read_b128 v[152:155], v156 offset:2048
	ds_read_b128 v[156:159], v156 offset:3072
	s_add_u32 s42, s42, 0x20000
	s_addc_u32 s43, s43, 0
	s_mov_b32 m0, s50
	v_lshl_add_u64 v[202:203], s[42:43], 0, v[128:129]
	ds_read_b128 v[160:163], v179 offset:32768
	ds_read_b128 v[164:167], v179 offset:33792
	ds_read_b128 v[168:171], v179 offset:34816
	ds_read_b128 v[182:185], v179 offset:35840
	ds_read_b128 v[186:189], v179 offset:36864
	ds_read_b128 v[190:193], v179 offset:37888
	ds_read_b128 v[194:197], v179 offset:38912
	ds_read_b128 v[198:201], v179 offset:39936
	global_load_lds_dwordx4 v[202:203], off
	s_mov_b32 m0, s51
	v_lshl_add_u64 v[202:203], s[42:43], 0, v[132:133]
	global_load_lds_dwordx4 v[202:203], off
	s_waitcnt lgkmcnt(8)
	s_setprio 1
	s_barrier
	s_waitcnt lgkmcnt(0)
	v_mfma_f32_16x16x32_bf16 v[124:127], v[144:147], v[160:163], v[124:127]
	v_mfma_f32_16x16x32_bf16 v[120:123], v[152:155], v[160:163], v[120:123]
	v_mfma_f32_16x16x32_bf16 v[108:111], v[144:147], v[168:171], v[108:111]
	v_mfma_f32_16x16x32_bf16 v[104:107], v[152:155], v[168:171], v[104:107]
	v_mfma_f32_16x16x32_bf16 v[96:99], v[144:147], v[186:189], v[96:99]
	v_mfma_f32_16x16x32_bf16 v[88:91], v[152:155], v[186:189], v[88:91]
	v_mfma_f32_16x16x32_bf16 v[80:83], v[144:147], v[194:197], v[80:83]
	v_mfma_f32_16x16x32_bf16 v[72:75], v[152:155], v[194:197], v[72:75]
	v_mfma_f32_16x16x32_bf16 v[124:127], v[148:151], v[164:167], v[124:127]
	v_mfma_f32_16x16x32_bf16 v[120:123], v[156:159], v[164:167], v[120:123]
	v_mfma_f32_16x16x32_bf16 v[108:111], v[148:151], v[182:185], v[108:111]
	v_mfma_f32_16x16x32_bf16 v[104:107], v[156:159], v[182:185], v[104:107]
	v_mfma_f32_16x16x32_bf16 v[96:99], v[148:151], v[190:193], v[96:99]
	v_mfma_f32_16x16x32_bf16 v[88:91], v[156:159], v[190:193], v[88:91]
	v_mfma_f32_16x16x32_bf16 v[80:83], v[148:151], v[198:201], v[80:83]
	v_mfma_f32_16x16x32_bf16 v[72:75], v[156:159], v[198:201], v[72:75]
	s_setprio 0
	s_barrier
	s_add_i32 s42, 0, 0x1c000
	s_add_i32 s43, s64, s48
	v_add_u32_e32 v181, s42, v176
	v_lshl_add_u64 v[172:173], v[172:173], 0, s[0:1]
	s_mov_b32 m0, s43
	ds_read_b128 v[202:205], v181
	ds_read_b128 v[206:209], v181 offset:1024
	ds_read_b128 v[212:215], v181 offset:2048
	ds_read_b128 v[216:219], v181 offset:3072
	global_load_lds_dwordx4 v[172:173], off
	s_add_i32 m0, s43, 0x2000
	v_lshl_add_u64 v[172:173], v[220:221], 0, s[0:1]
	global_load_lds_dwordx4 v[172:173], off
	s_setprio 1
	s_barrier
	s_waitcnt lgkmcnt(0)
	v_mfma_f32_16x16x32_bf16 v[116:119], v[202:205], v[160:163], v[116:119]
	v_mfma_f32_16x16x32_bf16 v[112:115], v[212:215], v[160:163], v[112:115]
	v_mfma_f32_16x16x32_bf16 v[100:103], v[202:205], v[168:171], v[100:103]
	v_mfma_f32_16x16x32_bf16 v[92:95], v[212:215], v[168:171], v[92:95]
	v_mfma_f32_16x16x32_bf16 v[84:87], v[202:205], v[186:189], v[84:87]
	v_mfma_f32_16x16x32_bf16 v[76:79], v[212:215], v[186:189], v[76:79]
	v_mfma_f32_16x16x32_bf16 v[68:71], v[202:205], v[194:197], v[68:71]
	v_mfma_f32_16x16x32_bf16 v[64:67], v[212:215], v[194:197], v[64:67]
	v_mfma_f32_16x16x32_bf16 v[116:119], v[206:209], v[164:167], v[116:119]
	v_mfma_f32_16x16x32_bf16 v[112:115], v[216:219], v[164:167], v[112:115]
	v_mfma_f32_16x16x32_bf16 v[100:103], v[206:209], v[182:185], v[100:103]
	v_mfma_f32_16x16x32_bf16 v[92:95], v[216:219], v[182:185], v[92:95]
	v_mfma_f32_16x16x32_bf16 v[84:87], v[206:209], v[190:193], v[84:87]
	v_mfma_f32_16x16x32_bf16 v[76:79], v[216:219], v[190:193], v[76:79]
	v_mfma_f32_16x16x32_bf16 v[68:71], v[206:209], v[198:201], v[68:71]
	v_mfma_f32_16x16x32_bf16 v[64:67], v[216:219], v[198:201], v[64:67]
	s_setprio 0
	s_mov_b32 m0, s53
	v_lshl_add_u64 v[172:173], v[222:223], 0, s[0:1]
	s_barrier
	ds_read_b128 v[160:163], v179 offset:49152
	ds_read_b128 v[164:167], v179 offset:50176
	ds_read_b128 v[168:171], v179 offset:51200
	ds_read_b128 v[182:185], v179 offset:52224
	ds_read_b128 v[186:189], v179 offset:53248
	ds_read_b128 v[190:193], v179 offset:54272
	ds_read_b128 v[194:197], v179 offset:55296
	ds_read_b128 v[198:201], v179 offset:56320
	global_load_lds_dwordx4 v[172:173], off
	s_mov_b32 m0, s54
	v_lshl_add_u64 v[172:173], v[224:225], 0, s[0:1]
	global_load_lds_dwordx4 v[172:173], off
	s_setprio 1
	s_barrier
	s_waitcnt lgkmcnt(0)
	v_mfma_f32_16x16x32_bf16 v[60:63], v[144:147], v[160:163], v[60:63]
	v_mfma_f32_16x16x32_bf16 v[56:59], v[152:155], v[160:163], v[56:59]
	v_mfma_f32_16x16x32_bf16 v[44:47], v[144:147], v[168:171], v[44:47]
	v_mfma_f32_16x16x32_bf16 v[40:43], v[152:155], v[168:171], v[40:43]
	v_mfma_f32_16x16x32_bf16 v[32:35], v[144:147], v[186:189], v[32:35]
	v_mfma_f32_16x16x32_bf16 v[24:27], v[152:155], v[186:189], v[24:27]
	v_mfma_f32_16x16x32_bf16 v[16:19], v[144:147], v[194:197], v[16:19]
	v_mfma_f32_16x16x32_bf16 v[8:11], v[152:155], v[194:197], v[8:11]
	v_mfma_f32_16x16x32_bf16 v[60:63], v[148:151], v[164:167], v[60:63]
	v_mfma_f32_16x16x32_bf16 v[56:59], v[156:159], v[164:167], v[56:59]
	v_mfma_f32_16x16x32_bf16 v[44:47], v[148:151], v[182:185], v[44:47]
	v_mfma_f32_16x16x32_bf16 v[40:43], v[156:159], v[182:185], v[40:43]
	v_mfma_f32_16x16x32_bf16 v[32:35], v[148:151], v[190:193], v[32:35]
	v_mfma_f32_16x16x32_bf16 v[24:27], v[156:159], v[190:193], v[24:27]
	v_mfma_f32_16x16x32_bf16 v[16:19], v[148:151], v[198:201], v[16:19]
	v_mfma_f32_16x16x32_bf16 v[8:11], v[156:159], v[198:201], v[8:11]
	s_setprio 0
	s_barrier
	s_add_u32 s40, s40, 0x20080
	s_addc_u32 s41, s41, 0
	s_add_i32 s42, s42, s48
	s_mov_b32 m0, s42
	v_lshl_add_u64 v[144:145], s[40:41], 0, v[130:131]
	global_load_lds_dwordx4 v[144:145], off
	s_add_i32 m0, s42, 0x2000
	v_lshl_add_u64 v[144:145], s[40:41], 0, v[134:135]
	global_load_lds_dwordx4 v[144:145], off
	s_waitcnt vmcnt(6)
	s_setprio 1
	s_barrier
	v_mfma_f32_16x16x32_bf16 v[52:55], v[202:205], v[160:163], v[52:55]
	v_mfma_f32_16x16x32_bf16 v[48:51], v[212:215], v[160:163], v[48:51]
	v_mfma_f32_16x16x32_bf16 v[36:39], v[202:205], v[168:171], v[36:39]
	v_mfma_f32_16x16x32_bf16 v[28:31], v[212:215], v[168:171], v[28:31]
	v_mfma_f32_16x16x32_bf16 v[20:23], v[202:205], v[186:189], v[20:23]
	v_mfma_f32_16x16x32_bf16 v[12:15], v[212:215], v[186:189], v[12:15]
	v_mfma_f32_16x16x32_bf16 v[4:7], v[202:205], v[194:197], v[4:7]
	v_mfma_f32_16x16x32_bf16 v[0:3], v[212:215], v[194:197], v[0:3]
	v_mfma_f32_16x16x32_bf16 v[52:55], v[206:209], v[164:167], v[52:55]
	v_mfma_f32_16x16x32_bf16 v[48:51], v[216:219], v[164:167], v[48:51]
	v_mfma_f32_16x16x32_bf16 v[36:39], v[206:209], v[182:185], v[36:39]
	v_mfma_f32_16x16x32_bf16 v[28:31], v[216:219], v[182:185], v[28:31]
	v_mfma_f32_16x16x32_bf16 v[20:23], v[206:209], v[190:193], v[20:23]
	v_mfma_f32_16x16x32_bf16 v[12:15], v[216:219], v[190:193], v[12:15]
	v_mfma_f32_16x16x32_bf16 v[4:7], v[206:209], v[198:201], v[4:7]
	v_mfma_f32_16x16x32_bf16 v[0:3], v[216:219], v[198:201], v[0:3]
	s_setprio 0
	s_add_i32 s63, s63, 2
	s_add_u32 s38, s38, 0x100
	s_addc_u32 s39, s39, 0
	s_add_u32 s61, s61, 0x100
	s_addc_u32 s62, s62, 0
	s_cmp_gt_u32 s63, 5
	s_barrier
	s_cbranch_scc0 .LBB0_792
	v_lshl_or_b32 v144, s36, 8, v177
	v_lshl_add_u32 v150, s34, 8, v175
	v_ashrrev_i32_e32 v145, 31, v144
	v_ashrrev_i32_e32 v151, 31, v150
	v_lshlrev_b64 v[144:145], 1, v[144:145]
	v_lshl_add_u64 v[146:147], s[10:11], 0, v[144:145]
	v_lshlrev_b64 v[148:149], 11, v[150:151]
	v_lshl_add_u64 v[152:153], v[146:147], 0, v[148:149]
	global_load_dwordx4 v[156:159], v[152:153], off
	global_load_dwordx4 v[160:163], v[152:153], off offset:256
	v_or_b32_e32 v152, 16, v150
	v_ashrrev_i32_e32 v153, 31, v152
	v_lshlrev_b64 v[170:171], 11, v[152:153]
	v_lshl_add_u64 v[152:153], v[146:147], 0, v[170:171]
	global_load_dwordx4 v[164:167], v[152:153], off
	global_load_dwordx4 v[182:185], v[152:153], off offset:256
	v_or_b32_e32 v152, 32, v150
	v_ashrrev_i32_e32 v153, 31, v152
	v_lshlrev_b64 v[154:155], 11, v[152:153]
	v_lshl_add_u64 v[152:153], v[146:147], 0, v[154:155]
	global_load_dwordx4 v[186:189], v[152:153], off
	global_load_dwordx4 v[190:193], v[152:153], off offset:256
	v_or_b32_e32 v152, 48, v150
	v_ashrrev_i32_e32 v153, 31, v152
	v_lshlrev_b64 v[152:153], 11, v[152:153]
	v_lshl_add_u64 v[168:169], v[146:147], 0, v[152:153]
	global_load_dwordx4 v[194:197], v[168:169], off
	global_load_dwordx4 v[198:201], v[168:169], off offset:256
	s_waitcnt vmcnt(0)
	v_lshlrev_b32_e32 v202, 16, v156
	v_and_b32_e32 v203, 0xffff0000, v156
	v_lshlrev_b32_e32 v204, 16, v157
	v_and_b32_e32 v205, 0xffff0000, v157
	v_lshlrev_b32_e32 v206, 16, v158
	v_and_b32_e32 v207, 0xffff0000, v158
	v_lshlrev_b32_e32 v208, 16, v159
	v_and_b32_e32 v209, 0xffff0000, v159
	v_pk_add_f32 v[126:127], v[126:127], v[204:205]
	v_pk_add_f32 v[124:125], v[124:125], v[202:203]
	v_lshlrev_b32_e32 v224, 16, v166
	v_and_b32_e32 v225, 0xffff0000, v166
	v_lshlrev_b32_e32 v226, 16, v167
	v_and_b32_e32 v227, 0xffff0000, v167
	v_lshlrev_b32_e32 v212, 16, v160
	v_lshlrev_b32_e32 v166, 16, v194
	v_and_b32_e32 v167, 0xffff0000, v194
	v_lshlrev_b32_e32 v172, 16, v195
	v_and_b32_e32 v173, 0xffff0000, v195
	v_pk_add_f32 v[194:195], v[122:123], v[208:209]
	v_pk_add_f32 v[122:123], v[120:121], v[206:207]
	v_mul_f32_e32 v120, v125, v125
	v_mul_f32_e32 v121, v127, v127
	v_fmac_f32_e32 v120, v124, v124
	v_fmac_f32_e32 v121, v126, v126
	v_add_f32_e32 v120, v120, v121
	v_mul_f32_e32 v121, v123, v123
	v_fmac_f32_e32 v121, v122, v122
	v_add_f32_e32 v120, v121, v120
	v_mul_f32_e32 v121, v195, v195
	v_fmac_f32_e32 v121, v194, v194
	v_and_b32_e32 v213, 0xffff0000, v160
	v_lshlrev_b32_e32 v214, 16, v161
	v_and_b32_e32 v215, 0xffff0000, v161
	v_add_f32_e32 v181, v121, v120
	v_cvt_pk_bf16_f32 v120, v124, v125
	v_lshl_add_u64 v[124:125], s[90:91], 0, v[148:149]
	v_lshlrev_b32_e32 v216, 16, v162
	v_and_b32_e32 v217, 0xffff0000, v162
	v_lshlrev_b32_e32 v218, 16, v163
	v_and_b32_e32 v219, 0xffff0000, v163
	v_cvt_pk_bf16_f32 v121, v126, v127
	v_lshl_add_u64 v[124:125], v[124:125], 0, v[144:145]
	v_pk_add_f32 v[118:119], v[118:119], v[214:215]
	v_pk_add_f32 v[116:117], v[116:117], v[212:213]
	v_cvt_pk_bf16_f32 v122, v122, v123
	v_cvt_pk_bf16_f32 v123, v194, v195
	global_store_dwordx4 v[124:125], v[120:123], off
	v_lshlrev_b32_e32 v220, 16, v164
	v_and_b32_e32 v221, 0xffff0000, v164
	v_pk_add_f32 v[120:121], v[114:115], v[218:219]
	v_pk_add_f32 v[114:115], v[112:113], v[216:217]
	v_mul_f32_e32 v112, v117, v117
	v_mul_f32_e32 v113, v119, v119
	v_fmac_f32_e32 v112, v116, v116
	v_fmac_f32_e32 v113, v118, v118
	v_add_f32_e32 v112, v112, v113
	v_mul_f32_e32 v113, v115, v115
	v_fmac_f32_e32 v113, v114, v114
	v_add_f32_e32 v112, v113, v112
	v_mul_f32_e32 v113, v121, v121
	v_fmac_f32_e32 v113, v120, v120
	v_add_f32_e32 v112, v113, v112
	v_lshlrev_b32_e32 v222, 16, v165
	v_and_b32_e32 v223, 0xffff0000, v165
	v_add_f32_e32 v126, v181, v112
	v_cvt_pk_bf16_f32 v112, v116, v117
	v_cvt_pk_bf16_f32 v113, v118, v119
	v_lshl_add_u64 v[116:117], s[90:91], 0, v[170:171]
	v_lshlrev_b32_e32 v230, 16, v184
	v_and_b32_e32 v231, 0xffff0000, v184
	v_lshlrev_b32_e32 v232, 16, v186
	v_and_b32_e32 v233, 0xffff0000, v186
	v_lshlrev_b32_e32 v186, 16, v187
	v_and_b32_e32 v187, 0xffff0000, v187
	v_cvt_pk_bf16_f32 v114, v114, v115
	v_cvt_pk_bf16_f32 v115, v120, v121
	global_store_dwordx4 v[124:125], v[112:115], off offset:256
	v_pk_add_f32 v[110:111], v[110:111], v[222:223]
	v_pk_add_f32 v[108:109], v[108:109], v[220:221]
	v_lshl_add_u64 v[118:119], v[116:117], 0, v[144:145]
	v_cvt_pk_bf16_f32 v112, v108, v109
	v_cvt_pk_bf16_f32 v113, v110, v111
	v_lshlrev_b32_e32 v228, 16, v182
	v_and_b32_e32 v229, 0xffff0000, v182
	v_lshlrev_b32_e32 v182, 16, v183
	v_and_b32_e32 v183, 0xffff0000, v183
	v_lshlrev_b32_e32 v184, 16, v185
	v_and_b32_e32 v185, 0xffff0000, v185
	v_lshlrev_b32_e32 v238, 16, v192
	v_and_b32_e32 v239, 0xffff0000, v192
	v_pk_add_f32 v[106:107], v[106:107], v[226:227]
	v_pk_add_f32 v[104:105], v[104:105], v[224:225]
	v_lshlrev_b32_e32 v156, 16, v200
	v_cvt_pk_bf16_f32 v114, v104, v105
	v_cvt_pk_bf16_f32 v115, v106, v107
	global_store_dwordx4 v[118:119], v[112:115], off
	v_and_b32_e32 v157, 0xffff0000, v200
	v_pk_add_f32 v[102:103], v[102:103], v[182:183]
	v_pk_add_f32 v[112:113], v[92:93], v[230:231]
	v_pk_add_f32 v[92:93], v[98:99], v[186:187]
	v_lshl_add_u64 v[98:99], s[90:91], 0, v[154:155]
	v_pk_add_f32 v[100:101], v[100:101], v[228:229]
	v_pk_add_f32 v[94:95], v[94:95], v[184:185]
	v_cvt_pk_bf16_f32 v114, v100, v101
	v_cvt_pk_bf16_f32 v115, v102, v103
	v_cvt_pk_bf16_f32 v116, v112, v113
	v_lshlrev_b32_e32 v234, 16, v188
	v_cvt_pk_bf16_f32 v117, v94, v95
	global_store_dwordx4 v[118:119], v[114:117], off offset:256
	v_lshl_add_u64 v[118:119], v[98:99], 0, v[144:145]
	v_pk_add_f32 v[98:99], v[76:77], v[238:239]
	v_pk_add_f32 v[76:77], v[82:83], v[172:173]
	v_lshl_add_u64 v[82:83], s[90:91], 0, v[152:153]
	v_lshl_add_u64 v[122:123], v[82:83], 0, v[144:145]
	v_pk_add_f32 v[82:83], v[64:65], v[156:157]
	v_and_b32_e32 v65, 64, v174
	v_and_b32_e32 v235, 0xffff0000, v188
	v_lshlrev_b32_e32 v188, 16, v189
	v_and_b32_e32 v189, 0xffff0000, v189
	v_lshlrev_b32_e32 v236, 16, v190
	v_and_b32_e32 v237, 0xffff0000, v190
	v_pk_add_f32 v[96:97], v[96:97], v[232:233]
	v_xor_b32_e32 v64, 16, v174
	v_cvt_pk_bf16_f32 v114, v96, v97
	v_add_u32_e32 v65, 64, v65
	v_lshlrev_b32_e32 v190, 16, v191
	v_and_b32_e32 v191, 0xffff0000, v191
	v_lshlrev_b32_e32 v192, 16, v193
	v_and_b32_e32 v193, 0xffff0000, v193
	v_pk_add_f32 v[90:91], v[90:91], v[188:189]
	v_pk_add_f32 v[88:89], v[88:89], v[234:235]
	v_cvt_pk_bf16_f32 v115, v92, v93
	v_pk_add_f32 v[84:85], v[84:85], v[236:237]
	v_cvt_pk_bf16_f32 v116, v88, v89
	v_cvt_pk_bf16_f32 v117, v90, v91
	global_store_dwordx4 v[118:119], v[114:117], off
	v_cmp_lt_i32_e32 vcc, v64, v65
	v_lshlrev_b32_e32 v164, 16, v196
	v_cvt_pk_bf16_f32 v114, v84, v85
	v_and_b32_e32 v165, 0xffff0000, v196
	v_lshlrev_b32_e32 v168, 16, v197
	v_and_b32_e32 v169, 0xffff0000, v197
	v_pk_add_f32 v[86:87], v[86:87], v[190:191]
	v_pk_add_f32 v[78:79], v[78:79], v[192:193]
	v_cvt_pk_bf16_f32 v115, v86, v87
	v_cvt_pk_bf16_f32 v116, v98, v99
	v_pk_add_f32 v[80:81], v[80:81], v[166:167]
	v_cvt_pk_bf16_f32 v117, v78, v79
	global_store_dwordx4 v[118:119], v[114:117], off offset:256
	v_cndmask_b32_e32 v64, v174, v64, vcc
	v_pk_add_f32 v[74:75], v[74:75], v[168:169]
	v_cvt_pk_bf16_f32 v114, v80, v81
	v_pk_add_f32 v[72:73], v[72:73], v[164:165]
	v_cvt_pk_bf16_f32 v115, v76, v77
	v_lshlrev_b32_e32 v158, 16, v198
	v_cvt_pk_bf16_f32 v116, v72, v73
	v_cvt_pk_bf16_f32 v117, v74, v75
	global_store_dwordx4 v[122:123], v[114:117], off
	v_and_b32_e32 v159, 0xffff0000, v198
	v_lshlrev_b32_e32 v162, 16, v199
	v_lshlrev_b32_e32 v114, 2, v64
	ds_bpermute_b32 v64, v114, v126
	v_xor_b32_e32 v115, 32, v174
	v_cmp_lt_i32_e32 vcc, v115, v65
	v_and_b32_e32 v163, 0xffff0000, v199
	v_lshlrev_b32_e32 v160, 16, v201
	v_cndmask_b32_e32 v65, v174, v115, vcc
	v_lshlrev_b32_e32 v115, 2, v65
	s_waitcnt lgkmcnt(0)
	v_add_f32_e32 v116, v126, v64
	ds_bpermute_b32 v117, v115, v116
	v_and_b32_e32 v161, 0xffff0000, v201
	v_pk_add_f32 v[70:71], v[70:71], v[162:163]
	v_pk_add_f32 v[68:69], v[68:69], v[158:159]
	v_pk_add_f32 v[66:67], v[66:67], v[160:161]
	v_lshl_add_u64 v[64:65], v[150:151], 2, s[2:3]
	v_cvt_pk_bf16_f32 v118, v68, v69
	v_cvt_pk_bf16_f32 v119, v70, v71
	v_cvt_pk_bf16_f32 v120, v82, v83
	v_cvt_pk_bf16_f32 v121, v66, v67
	global_store_dwordx4 v[122:123], v[118:121], off offset:256
	s_and_saveexec_b64 s[34:35], s[6:7]
	s_cbranch_execz .LBB0_795
	s_waitcnt lgkmcnt(0)
	v_add_f32_e32 v116, v116, v117
	global_atomic_add_f32 v[64:65], v116, off

.LBB0_850:
	ds_read_b128 v[144:147], v151
	ds_read_b128 v[156:159], v151 offset:1024
	ds_read_b128 v[160:163], v151 offset:2048
	ds_read_b128 v[164:167], v151 offset:3072
	s_add_u32 s36, s34, 0xfffc0080
	s_addc_u32 s37, s35, -1
	s_cmp_eq_u32 s66, 12
	s_cselect_b32 s39, s27, s37
	s_cselect_b32 s38, s62, s36
	s_cselect_b32 s37, s25, s65
	s_cselect_b32 s36, s63, s64
	v_lshl_add_u64 v[172:173], s[34:35], 0, v[136:137]
	s_add_i32 m0, s42, 0xc000
	ds_read_b128 v[168:171], v152
	ds_read_b128 v[176:179], v152 offset:1024
	ds_read_b128 v[180:183], v152 offset:2048
	ds_read_b128 v[184:187], v152 offset:3072
	ds_read_b128 v[188:191], v152 offset:4096
	ds_read_b128 v[192:195], v152 offset:5120
	ds_read_b128 v[196:199], v152 offset:6144
	ds_read_b128 v[200:203], v152 offset:7168
	global_load_lds_dwordx4 v[172:173], off
	s_add_i32 m0, s42, 0xe000
	v_lshl_add_u64 v[172:173], s[34:35], 0, v[138:139]
	global_load_lds_dwordx4 v[172:173], off
	s_waitcnt lgkmcnt(8)
	s_setprio 1
	s_barrier
	s_waitcnt lgkmcnt(0)
	v_mfma_f32_16x16x32_bf16 v[124:127], v[144:147], v[168:171], v[124:127]
	v_mfma_f32_16x16x32_bf16 v[120:123], v[160:163], v[168:171], v[120:123]
	v_mfma_f32_16x16x32_bf16 v[116:119], v[144:147], v[180:183], v[116:119]
	v_mfma_f32_16x16x32_bf16 v[112:115], v[160:163], v[180:183], v[112:115]
	v_mfma_f32_16x16x32_bf16 v[92:95], v[144:147], v[188:191], v[92:95]
	v_mfma_f32_16x16x32_bf16 v[88:91], v[160:163], v[188:191], v[88:91]
	v_mfma_f32_16x16x32_bf16 v[76:79], v[144:147], v[196:199], v[76:79]
	v_mfma_f32_16x16x32_bf16 v[72:75], v[160:163], v[196:199], v[72:75]
	v_mfma_f32_16x16x32_bf16 v[124:127], v[156:159], v[176:179], v[124:127]
	v_mfma_f32_16x16x32_bf16 v[120:123], v[164:167], v[176:179], v[120:123]
	v_mfma_f32_16x16x32_bf16 v[116:119], v[156:159], v[184:187], v[116:119]
	v_mfma_f32_16x16x32_bf16 v[112:115], v[164:167], v[184:187], v[112:115]
	v_mfma_f32_16x16x32_bf16 v[92:95], v[156:159], v[192:195], v[92:95]
	v_mfma_f32_16x16x32_bf16 v[88:91], v[164:167], v[192:195], v[88:91]
	v_mfma_f32_16x16x32_bf16 v[76:79], v[156:159], v[200:203], v[76:79]
	v_mfma_f32_16x16x32_bf16 v[72:75], v[164:167], v[200:203], v[72:75]
	s_setprio 0
	s_barrier
	s_add_i32 s67, s55, s41
	v_lshl_add_u64 v[172:173], s[36:37], 0, v[130:131]
	s_mov_b32 m0, s67
	ds_read_b128 v[204:207], v153
	ds_read_b128 v[212:215], v153 offset:1024
	ds_read_b128 v[216:219], v153 offset:2048
	ds_read_b128 v[220:223], v153 offset:3072
	global_load_lds_dwordx4 v[172:173], off
	s_add_i32 m0, s67, 0x2000
	v_lshl_add_u64 v[208:209], s[36:37], 0, v[134:135]
	global_load_lds_dwordx4 v[208:209], off
	s_setprio 1
	s_barrier
	s_waitcnt lgkmcnt(0)
	v_mfma_f32_16x16x32_bf16 v[108:111], v[204:207], v[168:171], v[108:111]
	v_mfma_f32_16x16x32_bf16 v[104:107], v[216:219], v[168:171], v[104:107]
	v_mfma_f32_16x16x32_bf16 v[100:103], v[204:207], v[180:183], v[100:103]
	v_mfma_f32_16x16x32_bf16 v[96:99], v[216:219], v[180:183], v[96:99]
	v_mfma_f32_16x16x32_bf16 v[84:87], v[204:207], v[188:191], v[84:87]
	v_mfma_f32_16x16x32_bf16 v[80:83], v[216:219], v[188:191], v[80:83]
	v_mfma_f32_16x16x32_bf16 v[68:71], v[204:207], v[196:199], v[68:71]
	v_mfma_f32_16x16x32_bf16 v[64:67], v[216:219], v[196:199], v[64:67]
	v_mfma_f32_16x16x32_bf16 v[108:111], v[212:215], v[176:179], v[108:111]
	v_mfma_f32_16x16x32_bf16 v[104:107], v[220:223], v[176:179], v[104:107]
	v_mfma_f32_16x16x32_bf16 v[100:103], v[212:215], v[184:187], v[100:103]
	v_mfma_f32_16x16x32_bf16 v[96:99], v[220:223], v[184:187], v[96:99]
	v_mfma_f32_16x16x32_bf16 v[84:87], v[212:215], v[192:195], v[84:87]
	v_mfma_f32_16x16x32_bf16 v[80:83], v[220:223], v[192:195], v[80:83]
	v_mfma_f32_16x16x32_bf16 v[68:71], v[212:215], v[200:203], v[68:71]
	v_mfma_f32_16x16x32_bf16 v[64:67], v[220:223], v[200:203], v[64:67]
	s_setprio 0
	s_mov_b32 m0, s42
	v_lshl_add_u64 v[224:225], s[38:39], 0, v[128:129]
	s_barrier
	ds_read_b128 v[168:171], v152 offset:16384
	ds_read_b128 v[176:179], v152 offset:17408
	ds_read_b128 v[180:183], v152 offset:18432
	ds_read_b128 v[184:187], v152 offset:19456
	ds_read_b128 v[188:191], v152 offset:20480
	ds_read_b128 v[192:195], v152 offset:21504
	ds_read_b128 v[196:199], v152 offset:22528
	ds_read_b128 v[200:203], v152 offset:23552
	global_load_lds_dwordx4 v[224:225], off
	s_mov_b32 m0, s43
	v_lshl_add_u64 v[226:227], s[38:39], 0, v[132:133]
	global_load_lds_dwordx4 v[226:227], off
	s_setprio 1
	s_barrier
	s_waitcnt lgkmcnt(0)
	v_mfma_f32_16x16x32_bf16 v[60:63], v[144:147], v[168:171], v[60:63]
	v_mfma_f32_16x16x32_bf16 v[56:59], v[160:163], v[168:171], v[56:59]
	v_mfma_f32_16x16x32_bf16 v[44:47], v[144:147], v[180:183], v[44:47]
	v_mfma_f32_16x16x32_bf16 v[40:43], v[160:163], v[180:183], v[40:43]
	v_mfma_f32_16x16x32_bf16 v[28:31], v[144:147], v[188:191], v[28:31]
	v_mfma_f32_16x16x32_bf16 v[24:27], v[160:163], v[188:191], v[24:27]
	v_mfma_f32_16x16x32_bf16 v[12:15], v[144:147], v[196:199], v[12:15]
	v_mfma_f32_16x16x32_bf16 v[8:11], v[160:163], v[196:199], v[8:11]
	v_mfma_f32_16x16x32_bf16 v[60:63], v[156:159], v[176:179], v[60:63]
	v_mfma_f32_16x16x32_bf16 v[56:59], v[164:167], v[176:179], v[56:59]
	v_mfma_f32_16x16x32_bf16 v[44:47], v[156:159], v[184:187], v[44:47]
	v_mfma_f32_16x16x32_bf16 v[40:43], v[164:167], v[184:187], v[40:43]
	v_mfma_f32_16x16x32_bf16 v[28:31], v[156:159], v[192:195], v[28:31]
	v_mfma_f32_16x16x32_bf16 v[24:27], v[164:167], v[192:195], v[24:27]
	v_mfma_f32_16x16x32_bf16 v[12:15], v[156:159], v[200:203], v[12:15]
	v_mfma_f32_16x16x32_bf16 v[8:11], v[164:167], v[200:203], v[8:11]
	s_setprio 0
	s_barrier
	s_add_u32 s68, s36, 0x40000
	s_addc_u32 s69, s37, 0
	s_add_i32 s67, s56, s41
	s_mov_b32 m0, s67
	v_lshl_add_u64 v[144:145], s[68:69], 0, v[130:131]
	global_load_lds_dwordx4 v[144:145], off
	s_add_i32 m0, s67, 0x2000
	v_lshl_add_u64 v[144:145], s[68:69], 0, v[134:135]
	global_load_lds_dwordx4 v[144:145], off
	s_waitcnt vmcnt(6)
	s_setprio 1
	s_barrier
	v_mfma_f32_16x16x32_bf16 v[52:55], v[204:207], v[168:171], v[52:55]
	v_mfma_f32_16x16x32_bf16 v[48:51], v[216:219], v[168:171], v[48:51]
	v_mfma_f32_16x16x32_bf16 v[36:39], v[204:207], v[180:183], v[36:39]
	v_mfma_f32_16x16x32_bf16 v[32:35], v[216:219], v[180:183], v[32:35]
	v_mfma_f32_16x16x32_bf16 v[20:23], v[204:207], v[188:191], v[20:23]
	v_mfma_f32_16x16x32_bf16 v[16:19], v[216:219], v[188:191], v[16:19]
	v_mfma_f32_16x16x32_bf16 v[4:7], v[204:207], v[196:199], v[4:7]
	v_mfma_f32_16x16x32_bf16 v[0:3], v[216:219], v[196:199], v[0:3]
	v_mfma_f32_16x16x32_bf16 v[52:55], v[212:215], v[176:179], v[52:55]
	v_mfma_f32_16x16x32_bf16 v[48:51], v[220:223], v[176:179], v[48:51]
	v_mfma_f32_16x16x32_bf16 v[36:39], v[212:215], v[184:187], v[36:39]
	v_mfma_f32_16x16x32_bf16 v[32:35], v[220:223], v[184:187], v[32:35]
	v_mfma_f32_16x16x32_bf16 v[20:23], v[212:215], v[192:195], v[20:23]
	v_mfma_f32_16x16x32_bf16 v[16:19], v[220:223], v[192:195], v[16:19]
	v_mfma_f32_16x16x32_bf16 v[4:7], v[212:215], v[200:203], v[4:7]
	v_mfma_f32_16x16x32_bf16 v[0:3], v[220:223], v[200:203], v[0:3]
	s_setprio 0
	s_add_i32 s67, 0, 0x18000
	v_add_u32_e32 v155, s67, v149
	s_barrier
	ds_read_b128 v[144:147], v155
	ds_read_b128 v[156:159], v155 offset:1024
	ds_read_b128 v[160:163], v155 offset:2048
	ds_read_b128 v[164:167], v155 offset:3072
	s_add_u32 s38, s38, 0x40000
	s_addc_u32 s39, s39, 0
	s_mov_b32 m0, s48
	v_lshl_add_u64 v[204:205], s[38:39], 0, v[128:129]
	ds_read_b128 v[168:171], v152 offset:32768
	ds_read_b128 v[176:179], v152 offset:33792
	ds_read_b128 v[180:183], v152 offset:34816
	ds_read_b128 v[184:187], v152 offset:35840
	ds_read_b128 v[188:191], v152 offset:36864
	ds_read_b128 v[192:195], v152 offset:37888
	ds_read_b128 v[196:199], v152 offset:38912
	ds_read_b128 v[200:203], v152 offset:39936
	global_load_lds_dwordx4 v[204:205], off
	s_mov_b32 m0, s49
	v_lshl_add_u64 v[204:205], s[38:39], 0, v[132:133]
	global_load_lds_dwordx4 v[204:205], off
	s_waitcnt lgkmcnt(8)
	s_setprio 1
	s_barrier
	s_waitcnt lgkmcnt(0)
	v_mfma_f32_16x16x32_bf16 v[124:127], v[144:147], v[168:171], v[124:127]
	v_mfma_f32_16x16x32_bf16 v[120:123], v[160:163], v[168:171], v[120:123]
	v_mfma_f32_16x16x32_bf16 v[116:119], v[144:147], v[180:183], v[116:119]
	v_mfma_f32_16x16x32_bf16 v[112:115], v[160:163], v[180:183], v[112:115]
	v_mfma_f32_16x16x32_bf16 v[92:95], v[144:147], v[188:191], v[92:95]
	v_mfma_f32_16x16x32_bf16 v[88:91], v[160:163], v[188:191], v[88:91]
	v_mfma_f32_16x16x32_bf16 v[76:79], v[144:147], v[196:199], v[76:79]
	v_mfma_f32_16x16x32_bf16 v[72:75], v[160:163], v[196:199], v[72:75]
	v_mfma_f32_16x16x32_bf16 v[124:127], v[156:159], v[176:179], v[124:127]
	v_mfma_f32_16x16x32_bf16 v[120:123], v[164:167], v[176:179], v[120:123]
	v_mfma_f32_16x16x32_bf16 v[116:119], v[156:159], v[184:187], v[116:119]
	v_mfma_f32_16x16x32_bf16 v[112:115], v[164:167], v[184:187], v[112:115]
	v_mfma_f32_16x16x32_bf16 v[92:95], v[156:159], v[192:195], v[92:95]
	v_mfma_f32_16x16x32_bf16 v[88:91], v[164:167], v[192:195], v[88:91]
	v_mfma_f32_16x16x32_bf16 v[76:79], v[156:159], v[200:203], v[76:79]
	v_mfma_f32_16x16x32_bf16 v[72:75], v[164:167], v[200:203], v[72:75]
	s_setprio 0
	s_barrier
	s_add_i32 s38, 0, 0x1c000
	s_add_i32 s39, s67, s41
	v_add_u32_e32 v155, s38, v149
	v_lshl_add_u64 v[172:173], v[172:173], 0, s[8:9]
	s_mov_b32 m0, s39
	ds_read_b128 v[204:207], v155
	ds_read_b128 v[212:215], v155 offset:1024
	ds_read_b128 v[216:219], v155 offset:2048
	ds_read_b128 v[220:223], v155 offset:3072
	global_load_lds_dwordx4 v[172:173], off
	s_add_i32 m0, s39, 0x2000
	v_lshl_add_u64 v[172:173], v[208:209], 0, s[8:9]
	global_load_lds_dwordx4 v[172:173], off
	s_setprio 1
	s_barrier
	s_waitcnt lgkmcnt(0)
	v_mfma_f32_16x16x32_bf16 v[108:111], v[204:207], v[168:171], v[108:111]
	v_mfma_f32_16x16x32_bf16 v[104:107], v[216:219], v[168:171], v[104:107]
	v_mfma_f32_16x16x32_bf16 v[100:103], v[204:207], v[180:183], v[100:103]
	v_mfma_f32_16x16x32_bf16 v[96:99], v[216:219], v[180:183], v[96:99]
	v_mfma_f32_16x16x32_bf16 v[84:87], v[204:207], v[188:191], v[84:87]
	v_mfma_f32_16x16x32_bf16 v[80:83], v[216:219], v[188:191], v[80:83]
	v_mfma_f32_16x16x32_bf16 v[68:71], v[204:207], v[196:199], v[68:71]
	v_mfma_f32_16x16x32_bf16 v[64:67], v[216:219], v[196:199], v[64:67]
	v_mfma_f32_16x16x32_bf16 v[108:111], v[212:215], v[176:179], v[108:111]
	v_mfma_f32_16x16x32_bf16 v[104:107], v[220:223], v[176:179], v[104:107]
	v_mfma_f32_16x16x32_bf16 v[100:103], v[212:215], v[184:187], v[100:103]
	v_mfma_f32_16x16x32_bf16 v[96:99], v[220:223], v[184:187], v[96:99]
	v_mfma_f32_16x16x32_bf16 v[84:87], v[212:215], v[192:195], v[84:87]
	v_mfma_f32_16x16x32_bf16 v[80:83], v[220:223], v[192:195], v[80:83]
	v_mfma_f32_16x16x32_bf16 v[68:71], v[212:215], v[200:203], v[68:71]
	v_mfma_f32_16x16x32_bf16 v[64:67], v[220:223], v[200:203], v[64:67]
	s_setprio 0
	s_mov_b32 m0, s51
	v_lshl_add_u64 v[172:173], v[224:225], 0, s[8:9]
	s_barrier
	ds_read_b128 v[168:171], v152 offset:49152
	ds_read_b128 v[176:179], v152 offset:50176
	ds_read_b128 v[180:183], v152 offset:51200
	ds_read_b128 v[184:187], v152 offset:52224
	ds_read_b128 v[188:191], v152 offset:53248
	ds_read_b128 v[192:195], v152 offset:54272
	ds_read_b128 v[196:199], v152 offset:55296
	ds_read_b128 v[200:203], v152 offset:56320
	global_load_lds_dwordx4 v[172:173], off
	s_mov_b32 m0, s52
	v_lshl_add_u64 v[172:173], v[226:227], 0, s[8:9]
	global_load_lds_dwordx4 v[172:173], off
	s_setprio 1
	s_barrier
	s_waitcnt lgkmcnt(0)
	v_mfma_f32_16x16x32_bf16 v[60:63], v[144:147], v[168:171], v[60:63]
	v_mfma_f32_16x16x32_bf16 v[56:59], v[160:163], v[168:171], v[56:59]
	v_mfma_f32_16x16x32_bf16 v[44:47], v[144:147], v[180:183], v[44:47]
	v_mfma_f32_16x16x32_bf16 v[40:43], v[160:163], v[180:183], v[40:43]
	v_mfma_f32_16x16x32_bf16 v[28:31], v[144:147], v[188:191], v[28:31]
	v_mfma_f32_16x16x32_bf16 v[24:27], v[160:163], v[188:191], v[24:27]
	v_mfma_f32_16x16x32_bf16 v[12:15], v[144:147], v[196:199], v[12:15]
	v_mfma_f32_16x16x32_bf16 v[8:11], v[160:163], v[196:199], v[8:11]
	v_mfma_f32_16x16x32_bf16 v[60:63], v[156:159], v[176:179], v[60:63]
	v_mfma_f32_16x16x32_bf16 v[56:59], v[164:167], v[176:179], v[56:59]
	v_mfma_f32_16x16x32_bf16 v[44:47], v[156:159], v[184:187], v[44:47]
	v_mfma_f32_16x16x32_bf16 v[40:43], v[164:167], v[184:187], v[40:43]
	v_mfma_f32_16x16x32_bf16 v[28:31], v[156:159], v[192:195], v[28:31]
	v_mfma_f32_16x16x32_bf16 v[24:27], v[164:167], v[192:195], v[24:27]
	v_mfma_f32_16x16x32_bf16 v[12:15], v[156:159], v[200:203], v[12:15]
	v_mfma_f32_16x16x32_bf16 v[8:11], v[164:167], v[200:203], v[8:11]
	s_setprio 0
	s_barrier
	s_add_u32 s36, s36, 0x40080
	s_addc_u32 s37, s37, 0
	s_add_i32 s38, s38, s41
	s_mov_b32 m0, s38
	v_lshl_add_u64 v[144:145], s[36:37], 0, v[130:131]
	global_load_lds_dwordx4 v[144:145], off
	s_add_i32 m0, s38, 0x2000
	v_lshl_add_u64 v[144:145], s[36:37], 0, v[134:135]
	global_load_lds_dwordx4 v[144:145], off
	s_waitcnt vmcnt(6)
	s_setprio 1
	s_barrier
	v_mfma_f32_16x16x32_bf16 v[52:55], v[204:207], v[168:171], v[52:55]
	v_mfma_f32_16x16x32_bf16 v[48:51], v[216:219], v[168:171], v[48:51]
	v_mfma_f32_16x16x32_bf16 v[36:39], v[204:207], v[180:183], v[36:39]
	v_mfma_f32_16x16x32_bf16 v[32:35], v[216:219], v[180:183], v[32:35]
	v_mfma_f32_16x16x32_bf16 v[20:23], v[204:207], v[188:191], v[20:23]
	v_mfma_f32_16x16x32_bf16 v[16:19], v[216:219], v[188:191], v[16:19]
	v_mfma_f32_16x16x32_bf16 v[4:7], v[204:207], v[196:199], v[4:7]
	v_mfma_f32_16x16x32_bf16 v[0:3], v[216:219], v[196:199], v[0:3]
	v_mfma_f32_16x16x32_bf16 v[52:55], v[212:215], v[176:179], v[52:55]
	v_mfma_f32_16x16x32_bf16 v[48:51], v[220:223], v[176:179], v[48:51]
	v_mfma_f32_16x16x32_bf16 v[36:39], v[212:215], v[184:187], v[36:39]
	v_mfma_f32_16x16x32_bf16 v[32:35], v[220:223], v[184:187], v[32:35]
	v_mfma_f32_16x16x32_bf16 v[20:23], v[212:215], v[192:195], v[20:23]
	v_mfma_f32_16x16x32_bf16 v[16:19], v[220:223], v[192:195], v[16:19]
	v_mfma_f32_16x16x32_bf16 v[4:7], v[212:215], v[200:203], v[4:7]
	v_mfma_f32_16x16x32_bf16 v[0:3], v[220:223], v[200:203], v[0:3]
	s_setprio 0
	s_add_i32 s66, s66, 2
	s_add_u32 s34, s34, 0x100
	s_addc_u32 s35, s35, 0
	s_add_u32 s64, s64, 0x100
	s_addc_u32 s65, s65, 0
	s_cmp_gt_u32 s66, 13
	s_barrier
	s_cbranch_scc0 .LBB0_850
	v_lshl_add_u32 v146, s0, 8, v148
	v_ashrrev_i32_e32 v147, 31, v146
	v_lshl_add_u64 v[144:145], v[146:147], 2, s[2:3]
	global_load_dword v155, v[144:145], off
	global_load_dword v162, v[144:145], off offset:64
	global_load_dword v163, v[144:145], off offset:128
	global_load_dword v164, v[144:145], off offset:192
	global_load_dword v165, v[144:145], off offset:512
	global_load_dword v166, v[144:145], off offset:576
	global_load_dword v167, v[144:145], off offset:640
	global_load_dword v168, v[144:145], off offset:704
	v_lshl_or_b32 v144, s1, 8, v150
	v_ashrrev_i32_e32 v145, 31, v144
	v_lshlrev_b64 v[158:159], 13, v[146:147]
	v_lshlrev_b64 v[160:161], 1, v[144:145]
	v_lshl_add_u64 v[144:145], s[92:93], 0, v[158:159]
	v_lshl_add_u64 v[144:145], v[144:145], 0, v[160:161]
	v_or_b32_e32 v156, 16, v146
	v_ashrrev_i32_e32 v157, 31, v156
	v_lshlrev_b64 v[156:157], 13, v[156:157]
	v_lshl_add_u64 v[156:157], s[92:93], 0, v[156:157]
	v_lshl_add_u64 v[156:157], v[156:157], 0, v[160:161]
	s_mov_b64 s[36:37], s[30:31]
	s_mov_b64 s[34:35], s[28:29]
	s_waitcnt vmcnt(0)
	v_fmamk_f32 v147, v155, 0x3a800000, v154
	v_mul_f32_e32 v158, 0x4b800000, v147
	v_cmp_gt_f32_e32 vcc, s57, v147
	v_fmamk_f32 v155, v162, 0x3a800000, v154
	v_mul_f32_e32 v162, 0x4b800000, v155
	v_cndmask_b32_e32 v147, v147, v158, vcc
	v_rsq_f32_e32 v158, v147
	v_cmp_gt_f32_e64 s[0:1], s57, v155
	v_fmamk_f32 v159, v163, 0x3a800000, v154
	v_fmamk_f32 v163, v164, 0x3a800000, v154
	v_cndmask_b32_e64 v155, v155, v162, s[0:1]
	v_rsq_f32_e32 v155, v155
	v_mul_f32_e32 v162, 0x45800000, v158
	v_cndmask_b32_e32 v158, v158, v162, vcc
	v_pk_mul_f32 v[124:125], v[124:125], v[158:159] op_sel_hi:[1,0]
	v_pk_mul_f32 v[104:105], v[104:105], v[158:159] op_sel_hi:[1,0]
	v_fmamk_f32 v164, v165, 0x3a800000, v154
	v_fmamk_f32 v165, v166, 0x3a800000, v154
	v_fmamk_f32 v166, v167, 0x3a800000, v154
	v_mul_f32_e32 v167, 0x45800000, v155
	v_pk_mul_f32 v[126:127], v[126:127], v[158:159] op_sel_hi:[1,0]
	v_pk_mul_f32 v[122:123], v[122:123], v[158:159] op_sel_hi:[1,0]
	v_pk_mul_f32 v[120:121], v[120:121], v[158:159] op_sel_hi:[1,0]
	v_pk_mul_f32 v[108:109], v[108:109], v[158:159] op_sel_hi:[1,0]
	v_pk_mul_f32 v[106:107], v[106:107], v[158:159] op_sel_hi:[1,0]
	v_max_f32_e32 v124, 0, v124
	v_max_f32_e32 v125, 0, v125
	v_max_f32_e32 v104, 0, v104
	v_cndmask_b32_e64 v162, v155, v167, s[0:1]
	v_pk_mul_f32 v[110:111], v[110:111], v[158:159] op_sel_hi:[1,0]
	v_max_f32_e32 v120, 0, v120
	v_max_f32_e32 v121, 0, v121
	v_max_f32_e32 v126, 0, v126
	v_max_f32_e32 v122, 0, v122
	v_max_f32_e32 v127, 0, v127
	v_max_f32_e32 v123, 0, v123
	v_max_f32_e32 v108, 0, v108
	v_max_f32_e32 v109, 0, v109
	v_max_f32_e32 v105, 0, v105
	v_max_f32_e32 v106, 0, v106
	v_max_f32_e32 v107, 0, v107
	v_mul_f32_e32 v124, v124, v124
	v_mul_f32_e32 v125, v125, v125
	v_mul_f32_e32 v155, v104, v104
	v_cvt_pk_bf16_f32 v104, v124, v125
	v_fmamk_f32 v147, v168, 0x3a800000, v154
	v_pk_mul_f32 v[112:113], v[112:113], v[162:163] op_sel_hi:[1,0]
	v_max_f32_e32 v110, 0, v110
	v_max_f32_e32 v111, 0, v111
	v_mul_f32_e32 v120, v120, v120
	v_mul_f32_e32 v121, v121, v121
	v_mul_f32_e32 v126, v126, v126
	v_mul_f32_e32 v122, v122, v122
	v_mul_f32_e32 v127, v127, v127
	v_mul_f32_e32 v123, v123, v123
	v_mul_f32_e32 v108, v108, v108
	v_mul_f32_e32 v109, v109, v109
	v_mul_f32_e32 v158, v105, v105
	v_mul_f32_e32 v167, v106, v106
	v_mul_f32_e32 v168, v107, v107
	v_cvt_pk_bf16_f32 v105, v126, v127
	v_cvt_pk_bf16_f32 v106, v120, v121
	v_cvt_pk_bf16_f32 v107, v122, v123
	global_store_dwordx4 v[144:145], v[104:107], off nt
	v_pk_mul_f32 v[116:117], v[116:117], v[162:163] op_sel_hi:[1,0]
	v_mul_f32_e32 v110, v110, v110
	v_cvt_pk_bf16_f32 v104, v108, v109
	v_mul_f32_e32 v111, v111, v111
	v_cvt_pk_bf16_f32 v105, v110, v111
	v_cvt_pk_bf16_f32 v106, v155, v158
	v_cvt_pk_bf16_f32 v107, v167, v168
	global_store_dwordx4 v[144:145], v[104:107], off offset:256 nt
	v_pk_mul_f32 v[118:119], v[118:119], v[162:163] op_sel_hi:[1,0]
	v_pk_mul_f32 v[114:115], v[114:115], v[162:163] op_sel_hi:[1,0]
	v_max_f32_e32 v104, 0, v112
	v_mul_f32_e32 v106, v104, v104
	v_max_f32_e32 v104, 0, v117
	v_max_f32_e32 v116, 0, v116
	v_max_f32_e32 v107, 0, v113
	v_mul_f32_e32 v104, v104, v104
	v_pk_mul_f32 v[98:99], v[98:99], v[162:163] op_sel_hi:[1,0]
	v_pk_mul_f32 v[96:97], v[96:97], v[162:163] op_sel_hi:[1,0]
	v_mul_f32_e32 v105, v116, v116
	v_mul_f32_e32 v107, v107, v107
	v_max_f32_e32 v108, 0, v118
	v_max_f32_e32 v109, 0, v114
	v_max_f32_e32 v110, 0, v119
	v_max_f32_e32 v111, 0, v115
	v_cvt_pk_bf16_f32 v104, v105, v104
	v_pk_mul_f32 v[102:103], v[102:103], v[162:163] op_sel_hi:[1,0]
	v_pk_mul_f32 v[100:101], v[100:101], v[162:163] op_sel_hi:[1,0]
	v_max_f32_e32 v96, 0, v96
	v_max_f32_e32 v97, 0, v97
	v_max_f32_e32 v98, 0, v98
	v_mul_f32_e32 v108, v108, v108
	v_mul_f32_e32 v109, v109, v109
	v_mul_f32_e32 v110, v110, v110
	v_mul_f32_e32 v111, v111, v111
	v_cvt_pk_bf16_f32 v105, v108, v110
	v_cvt_pk_bf16_f32 v106, v106, v107
	v_cvt_pk_bf16_f32 v107, v109, v111
	global_store_dwordx4 v[156:157], v[104:107], off nt
	v_max_f32_e32 v100, 0, v100
	v_max_f32_e32 v99, 0, v99
	v_mul_f32_e32 v104, v96, v96
	v_max_f32_e32 v96, 0, v101
	v_mul_f32_e32 v101, v97, v97
	v_max_f32_e32 v97, 0, v102
	v_mul_f32_e32 v102, v98, v98
	v_max_f32_e32 v98, 0, v103
	v_mul_f32_e32 v96, v96, v96
	v_mul_f32_e32 v97, v97, v97
	v_mul_f32_e32 v98, v98, v98
	v_mul_f32_e32 v100, v100, v100
	v_mul_f32_e32 v99, v99, v99
	v_cvt_pk_bf16_f32 v96, v100, v96
	v_cvt_pk_bf16_f32 v97, v97, v98
	v_cvt_pk_bf16_f32 v98, v104, v101
	v_cvt_pk_bf16_f32 v99, v102, v99
	global_store_dwordx4 v[156:157], v[96:99], off offset:256 nt
	v_cmp_gt_f32_e32 vcc, s57, v159
	s_mov_b64 s[0:1], 0x100000
	v_mul_f32_e32 v98, 0x4b800000, v159
	v_cndmask_b32_e32 v98, v159, v98, vcc
	v_rsq_f32_e32 v98, v98
	v_or_b32_e32 v96, 32, v146
	v_ashrrev_i32_e32 v97, 31, v96
	v_lshlrev_b64 v[96:97], 13, v[96:97]
	v_mul_f32_e32 v99, 0x45800000, v98
	v_cndmask_b32_e32 v98, v98, v99, vcc
	v_pk_mul_f32 v[88:89], v[88:89], v[98:99] op_sel_hi:[1,0]
	v_pk_mul_f32 v[92:93], v[92:93], v[98:99] op_sel_hi:[1,0]
	v_pk_mul_f32 v[90:91], v[90:91], v[98:99] op_sel_hi:[1,0]
	v_max_f32_e32 v88, 0, v88
	v_pk_mul_f32 v[94:95], v[94:95], v[98:99] op_sel_hi:[1,0]
	v_mul_f32_e32 v99, v88, v88
	v_max_f32_e32 v88, 0, v93
	v_max_f32_e32 v89, 0, v89
	v_max_f32_e32 v90, 0, v90
	v_lshl_add_u64 v[96:97], s[92:93], 0, v[96:97]
	v_max_f32_e32 v92, 0, v92
	v_mul_f32_e32 v88, v88, v88
	v_mul_f32_e32 v93, v89, v89
	v_max_f32_e32 v89, 0, v94
	v_mul_f32_e32 v94, v90, v90
	v_max_f32_e32 v90, 0, v95
	v_max_f32_e32 v91, 0, v91
	v_pk_mul_f32 v[82:83], v[82:83], v[98:99] op_sel_hi:[1,0]
	v_pk_mul_f32 v[80:81], v[80:81], v[98:99] op_sel_hi:[1,0]
	v_lshl_add_u64 v[96:97], v[96:97], 0, v[160:161]
	v_mul_f32_e32 v92, v92, v92
	v_mul_f32_e32 v89, v89, v89
	v_mul_f32_e32 v90, v90, v90
	v_mul_f32_e32 v91, v91, v91
	v_cvt_pk_bf16_f32 v88, v92, v88
	v_pk_mul_f32 v[86:87], v[86:87], v[98:99] op_sel_hi:[1,0]
	v_pk_mul_f32 v[84:85], v[84:85], v[98:99] op_sel_hi:[1,0]
	v_max_f32_e32 v80, 0, v80
	v_max_f32_e32 v81, 0, v81
	v_max_f32_e32 v82, 0, v82
	v_cvt_pk_bf16_f32 v89, v89, v90
	v_cvt_pk_bf16_f32 v90, v99, v93
	v_cvt_pk_bf16_f32 v91, v94, v91
	global_store_dwordx4 v[96:97], v[88:91], off nt
	v_max_f32_e32 v84, 0, v84
	v_max_f32_e32 v83, 0, v83
	v_mul_f32_e32 v88, v80, v80
	v_max_f32_e32 v80, 0, v85
	v_mul_f32_e32 v85, v81, v81
	v_max_f32_e32 v81, 0, v86
	v_mul_f32_e32 v86, v82, v82
	v_max_f32_e32 v82, 0, v87
	v_mul_f32_e32 v80, v80, v80
	v_mul_f32_e32 v81, v81, v81
	v_mul_f32_e32 v82, v82, v82
	v_mul_f32_e32 v84, v84, v84
	v_mul_f32_e32 v83, v83, v83
	v_cvt_pk_bf16_f32 v80, v84, v80
	v_cvt_pk_bf16_f32 v81, v81, v82
	v_cvt_pk_bf16_f32 v82, v88, v85
	v_cvt_pk_bf16_f32 v83, v86, v83
	global_store_dwordx4 v[96:97], v[80:83], off offset:256 nt
	v_cmp_gt_f32_e32 vcc, s57, v163
	s_nop 0
	v_mul_f32_e32 v82, 0x4b800000, v163
	v_cndmask_b32_e32 v82, v163, v82, vcc
	v_rsq_f32_e32 v82, v82
	v_or_b32_e32 v80, 48, v146
	v_ashrrev_i32_e32 v81, 31, v80
	v_lshlrev_b64 v[80:81], 13, v[80:81]
	v_mul_f32_e32 v83, 0x45800000, v82
	v_cndmask_b32_e32 v82, v82, v83, vcc
	v_pk_mul_f32 v[72:73], v[72:73], v[82:83] op_sel_hi:[1,0]
	v_pk_mul_f32 v[76:77], v[76:77], v[82:83] op_sel_hi:[1,0]
	v_pk_mul_f32 v[74:75], v[74:75], v[82:83] op_sel_hi:[1,0]
	v_max_f32_e32 v72, 0, v72
	v_pk_mul_f32 v[78:79], v[78:79], v[82:83] op_sel_hi:[1,0]
	v_mul_f32_e32 v83, v72, v72
	v_max_f32_e32 v72, 0, v77
	v_max_f32_e32 v73, 0, v73
	v_max_f32_e32 v74, 0, v74
	v_lshl_add_u64 v[80:81], s[92:93], 0, v[80:81]
	v_max_f32_e32 v76, 0, v76
	v_mul_f32_e32 v72, v72, v72
	v_mul_f32_e32 v77, v73, v73
	v_max_f32_e32 v73, 0, v78
	v_mul_f32_e32 v78, v74, v74
	v_max_f32_e32 v74, 0, v79
	v_max_f32_e32 v75, 0, v75
	v_pk_mul_f32 v[64:65], v[64:65], v[82:83] op_sel_hi:[1,0]
	v_lshl_add_u64 v[80:81], v[80:81], 0, v[160:161]
	v_mul_f32_e32 v76, v76, v76
	v_mul_f32_e32 v73, v73, v73
	v_mul_f32_e32 v74, v74, v74
	v_mul_f32_e32 v75, v75, v75
	v_cvt_pk_bf16_f32 v72, v76, v72
	v_pk_mul_f32 v[68:69], v[68:69], v[82:83] op_sel_hi:[1,0]
	v_max_f32_e32 v64, 0, v64
	v_cvt_pk_bf16_f32 v73, v73, v74
	v_cvt_pk_bf16_f32 v74, v83, v77
	v_cvt_pk_bf16_f32 v75, v78, v75
	global_store_dwordx4 v[80:81], v[72:75], off nt
	v_max_f32_e32 v68, 0, v68
	v_mul_f32_e32 v68, v68, v68
	v_mul_f32_e32 v72, v64, v64
	v_max_f32_e32 v64, 0, v69
	v_mul_f32_e32 v64, v64, v64
	v_cvt_pk_bf16_f32 v64, v68, v64
	v_mul_f32_e32 v68, 0x4b800000, v164
	v_cmp_gt_f32_e32 vcc, s57, v164
	v_pk_mul_f32 v[66:67], v[66:67], v[82:83] op_sel_hi:[1,0]
	v_pk_mul_f32 v[70:71], v[70:71], v[82:83] op_sel_hi:[1,0]
	v_cndmask_b32_e32 v68, v164, v68, vcc
	v_max_f32_e32 v65, 0, v65
	v_max_f32_e32 v66, 0, v66
	v_rsq_f32_e32 v68, v68
	v_mul_f32_e32 v69, v65, v65
	v_max_f32_e32 v65, 0, v70
	v_mul_f32_e32 v70, v66, v66
	v_max_f32_e32 v66, 0, v71
	v_mul_f32_e32 v65, v65, v65
	v_max_f32_e32 v67, 0, v67
	v_mul_f32_e32 v66, v66, v66
	v_mul_f32_e32 v67, v67, v67
	v_cvt_pk_bf16_f32 v65, v65, v66
	v_cvt_pk_bf16_f32 v66, v72, v69
	v_cvt_pk_bf16_f32 v67, v70, v67
	global_store_dwordx4 v[80:81], v[64:67], off offset:256 nt
	s_nop 1
	v_mul_f32_e32 v66, 0x45800000, v68
	v_cndmask_b32_e32 v66, v68, v66, vcc
	v_pk_mul_f32 v[56:57], v[56:57], v[66:67] op_sel_hi:[1,0]
	v_pk_mul_f32 v[60:61], v[60:61], v[66:67] op_sel_hi:[1,0]
	v_pk_mul_f32 v[58:59], v[58:59], v[66:67] op_sel_hi:[1,0]
	v_max_f32_e32 v56, 0, v56
	v_pk_mul_f32 v[62:63], v[62:63], v[66:67] op_sel_hi:[1,0]
	v_max_f32_e32 v60, 0, v60
	v_mul_f32_e32 v67, v56, v56
	v_max_f32_e32 v56, 0, v61
	v_max_f32_e32 v57, 0, v57
	v_max_f32_e32 v58, 0, v58
	v_mul_f32_e32 v60, v60, v60
	v_mul_f32_e32 v56, v56, v56
	v_mul_f32_e32 v61, v57, v57
	v_max_f32_e32 v57, 0, v62
	v_mul_f32_e32 v62, v58, v58
	v_max_f32_e32 v58, 0, v63
	v_mul_f32_e32 v57, v57, v57
	v_max_f32_e32 v59, 0, v59
	v_mul_f32_e32 v58, v58, v58
	v_cvt_pk_bf16_f32 v56, v60, v56
	v_add_co_u32_e32 v60, vcc, s58, v144
	v_pk_mul_f32 v[48:49], v[48:49], v[66:67] op_sel_hi:[1,0]
	v_mul_f32_e32 v59, v59, v59
	v_cvt_pk_bf16_f32 v57, v57, v58
	v_cvt_pk_bf16_f32 v58, v67, v61
	v_addc_co_u32_e32 v61, vcc, 0, v145, vcc
	v_pk_mul_f32 v[52:53], v[52:53], v[66:67] op_sel_hi:[1,0]
	v_max_f32_e32 v48, 0, v48
	v_cvt_pk_bf16_f32 v59, v62, v59
	global_store_dwordx4 v[60:61], v[56:59], off nt
	v_max_f32_e32 v52, 0, v52
	v_mul_f32_e32 v52, v52, v52
	v_mul_f32_e32 v56, v48, v48
	v_max_f32_e32 v48, 0, v53
	v_mul_f32_e32 v48, v48, v48
	v_cvt_pk_bf16_f32 v48, v52, v48
	v_mul_f32_e32 v52, 0x4b800000, v165
	v_cmp_gt_f32_e32 vcc, s57, v165
	v_pk_mul_f32 v[50:51], v[50:51], v[66:67] op_sel_hi:[1,0]
	v_pk_mul_f32 v[54:55], v[54:55], v[66:67] op_sel_hi:[1,0]
	v_cndmask_b32_e32 v52, v165, v52, vcc
	v_max_f32_e32 v49, 0, v49
	v_max_f32_e32 v50, 0, v50
	v_rsq_f32_e32 v52, v52
	v_mul_f32_e32 v53, v49, v49
	v_max_f32_e32 v49, 0, v54
	v_mul_f32_e32 v54, v50, v50
	v_max_f32_e32 v50, 0, v55
	v_mul_f32_e32 v49, v49, v49
	v_max_f32_e32 v51, 0, v51
	v_mul_f32_e32 v50, v50, v50
	v_lshl_add_u64 v[64:65], v[144:145], 0, s[0:1]
	v_mul_f32_e32 v51, v51, v51
	v_cvt_pk_bf16_f32 v49, v49, v50
	v_cvt_pk_bf16_f32 v50, v56, v53
	v_cvt_pk_bf16_f32 v51, v54, v51
	global_store_dwordx4 v[64:65], v[48:51], off offset:256 nt
	s_mov_b32 s1, s24
	s_mov_b32 s0, s26
	v_mul_f32_e32 v50, 0x45800000, v52
	v_cndmask_b32_e32 v50, v52, v50, vcc
	v_pk_mul_f32 v[40:41], v[40:41], v[50:51] op_sel_hi:[1,0]
	v_pk_mul_f32 v[44:45], v[44:45], v[50:51] op_sel_hi:[1,0]
	v_pk_mul_f32 v[42:43], v[42:43], v[50:51] op_sel_hi:[1,0]
	v_max_f32_e32 v40, 0, v40
	v_pk_mul_f32 v[46:47], v[46:47], v[50:51] op_sel_hi:[1,0]
	v_max_f32_e32 v44, 0, v44
	v_mul_f32_e32 v51, v40, v40
	v_max_f32_e32 v40, 0, v45
	v_max_f32_e32 v41, 0, v41
	v_max_f32_e32 v42, 0, v42
	v_mul_f32_e32 v44, v44, v44
	v_mul_f32_e32 v40, v40, v40
	v_mul_f32_e32 v45, v41, v41
	v_max_f32_e32 v41, 0, v46
	v_mul_f32_e32 v46, v42, v42
	v_max_f32_e32 v42, 0, v47
	v_mul_f32_e32 v41, v41, v41
	v_max_f32_e32 v43, 0, v43
	v_mul_f32_e32 v42, v42, v42
	v_cvt_pk_bf16_f32 v40, v44, v40
	v_add_co_u32_e32 v44, vcc, s59, v144
	v_pk_mul_f32 v[32:33], v[32:33], v[50:51] op_sel_hi:[1,0]
	v_mul_f32_e32 v43, v43, v43
	v_cvt_pk_bf16_f32 v41, v41, v42
	v_cvt_pk_bf16_f32 v42, v51, v45
	v_addc_co_u32_e32 v45, vcc, 0, v145, vcc
	v_pk_mul_f32 v[36:37], v[36:37], v[50:51] op_sel_hi:[1,0]
	v_max_f32_e32 v32, 0, v32
	v_cvt_pk_bf16_f32 v43, v46, v43
	global_store_dwordx4 v[44:45], v[40:43], off nt
	v_max_f32_e32 v36, 0, v36
	v_mul_f32_e32 v36, v36, v36
	v_mul_f32_e32 v40, v32, v32
	v_max_f32_e32 v32, 0, v37
	v_mul_f32_e32 v32, v32, v32
	v_cvt_pk_bf16_f32 v32, v36, v32
	v_mul_f32_e32 v36, 0x4b800000, v166
	v_cmp_gt_f32_e32 vcc, s57, v166
	v_pk_mul_f32 v[34:35], v[34:35], v[50:51] op_sel_hi:[1,0]
	v_pk_mul_f32 v[38:39], v[38:39], v[50:51] op_sel_hi:[1,0]
	v_cndmask_b32_e32 v36, v166, v36, vcc
	v_max_f32_e32 v33, 0, v33
	v_max_f32_e32 v34, 0, v34
	v_rsq_f32_e32 v36, v36
	v_mul_f32_e32 v37, v33, v33
	v_max_f32_e32 v33, 0, v38
	v_mul_f32_e32 v38, v34, v34
	v_max_f32_e32 v34, 0, v39
	v_mul_f32_e32 v33, v33, v33
	v_max_f32_e32 v35, 0, v35
	v_mul_f32_e32 v34, v34, v34
	v_lshl_add_u64 v[48:49], v[144:145], 0, s[18:19]
	v_mul_f32_e32 v35, v35, v35
	v_cvt_pk_bf16_f32 v33, v33, v34
	v_cvt_pk_bf16_f32 v34, v40, v37
	v_cvt_pk_bf16_f32 v35, v38, v35
	global_store_dwordx4 v[48:49], v[32:35], off offset:256 nt
	s_nop 1
	v_mul_f32_e32 v34, 0x45800000, v36
	v_cndmask_b32_e32 v34, v36, v34, vcc
	v_pk_mul_f32 v[24:25], v[24:25], v[34:35] op_sel_hi:[1,0]
	v_pk_mul_f32 v[28:29], v[28:29], v[34:35] op_sel_hi:[1,0]
	v_pk_mul_f32 v[26:27], v[26:27], v[34:35] op_sel_hi:[1,0]
	v_max_f32_e32 v24, 0, v24
	v_pk_mul_f32 v[30:31], v[30:31], v[34:35] op_sel_hi:[1,0]
	v_max_f32_e32 v28, 0, v28
	v_mul_f32_e32 v35, v24, v24
	v_max_f32_e32 v24, 0, v29
	v_max_f32_e32 v25, 0, v25
	v_max_f32_e32 v26, 0, v26
	v_mul_f32_e32 v28, v28, v28
	v_mul_f32_e32 v24, v24, v24
	v_mul_f32_e32 v29, v25, v25
	v_max_f32_e32 v25, 0, v30
	v_mul_f32_e32 v30, v26, v26
	v_max_f32_e32 v26, 0, v31
	v_mul_f32_e32 v25, v25, v25
	v_max_f32_e32 v27, 0, v27
	v_mul_f32_e32 v26, v26, v26
	v_cvt_pk_bf16_f32 v24, v28, v24
	v_add_co_u32_e32 v28, vcc, s60, v144
	v_pk_mul_f32 v[16:17], v[16:17], v[34:35] op_sel_hi:[1,0]
	v_mul_f32_e32 v27, v27, v27
	v_cvt_pk_bf16_f32 v25, v25, v26
	v_cvt_pk_bf16_f32 v26, v35, v29
	v_addc_co_u32_e32 v29, vcc, 0, v145, vcc
	v_pk_mul_f32 v[20:21], v[20:21], v[34:35] op_sel_hi:[1,0]
	v_max_f32_e32 v16, 0, v16
	v_cvt_pk_bf16_f32 v27, v30, v27
	global_store_dwordx4 v[28:29], v[24:27], off nt
	v_max_f32_e32 v20, 0, v20
	v_mul_f32_e32 v20, v20, v20
	v_mul_f32_e32 v24, v16, v16
	v_max_f32_e32 v16, 0, v21
	v_mul_f32_e32 v16, v16, v16
	v_cvt_pk_bf16_f32 v16, v20, v16
	v_mul_f32_e32 v20, 0x4b800000, v147
	v_cmp_gt_f32_e32 vcc, s57, v147
	v_pk_mul_f32 v[18:19], v[18:19], v[34:35] op_sel_hi:[1,0]
	v_pk_mul_f32 v[22:23], v[22:23], v[34:35] op_sel_hi:[1,0]
	v_cndmask_b32_e32 v20, v147, v20, vcc
	v_max_f32_e32 v17, 0, v17
	v_max_f32_e32 v18, 0, v18
	v_rsq_f32_e32 v20, v20
	v_mul_f32_e32 v21, v17, v17
	v_max_f32_e32 v17, 0, v22
	v_mul_f32_e32 v22, v18, v18
	v_max_f32_e32 v18, 0, v23
	v_mul_f32_e32 v17, v17, v17
	v_max_f32_e32 v19, 0, v19
	v_mul_f32_e32 v18, v18, v18
	v_lshl_add_u64 v[32:33], v[144:145], 0, s[20:21]
	v_mul_f32_e32 v19, v19, v19
	v_cvt_pk_bf16_f32 v17, v17, v18
	v_cvt_pk_bf16_f32 v18, v24, v21
	v_cvt_pk_bf16_f32 v19, v22, v19
	global_store_dwordx4 v[32:33], v[16:19], off offset:256 nt
	s_nop 1
	v_mul_f32_e32 v18, 0x45800000, v20
	v_cndmask_b32_e32 v18, v20, v18, vcc
	v_pk_mul_f32 v[8:9], v[8:9], v[18:19] op_sel_hi:[1,0]
	v_pk_mul_f32 v[12:13], v[12:13], v[18:19] op_sel_hi:[1,0]
	v_pk_mul_f32 v[10:11], v[10:11], v[18:19] op_sel_hi:[1,0]
	v_max_f32_e32 v8, 0, v8
	v_pk_mul_f32 v[14:15], v[14:15], v[18:19] op_sel_hi:[1,0]
	v_max_f32_e32 v12, 0, v12
	v_mul_f32_e32 v19, v8, v8
	v_max_f32_e32 v8, 0, v13
	v_max_f32_e32 v9, 0, v9
	v_max_f32_e32 v10, 0, v10
	v_mul_f32_e32 v12, v12, v12
	v_mul_f32_e32 v8, v8, v8
	v_mul_f32_e32 v13, v9, v9
	v_max_f32_e32 v9, 0, v14
	v_mul_f32_e32 v14, v10, v10
	v_max_f32_e32 v10, 0, v15
	v_mul_f32_e32 v9, v9, v9
	v_max_f32_e32 v11, 0, v11
	v_mul_f32_e32 v10, v10, v10
	v_cvt_pk_bf16_f32 v8, v12, v8
	v_add_co_u32_e32 v12, vcc, s61, v144
	v_pk_mul_f32 v[2:3], v[2:3], v[18:19] op_sel_hi:[1,0]
	v_pk_mul_f32 v[0:1], v[0:1], v[18:19] op_sel_hi:[1,0]
	v_mul_f32_e32 v11, v11, v11
	v_cvt_pk_bf16_f32 v9, v9, v10
	v_cvt_pk_bf16_f32 v10, v19, v13
	v_addc_co_u32_e32 v13, vcc, 0, v145, vcc
	v_pk_mul_f32 v[6:7], v[6:7], v[18:19] op_sel_hi:[1,0]
	v_pk_mul_f32 v[4:5], v[4:5], v[18:19] op_sel_hi:[1,0]
	v_max_f32_e32 v0, 0, v0
	v_max_f32_e32 v1, 0, v1
	v_max_f32_e32 v2, 0, v2
	v_cvt_pk_bf16_f32 v11, v14, v11
	global_store_dwordx4 v[12:13], v[8:11], off nt
	v_max_f32_e32 v3, 0, v3
	v_lshl_add_u64 v[16:17], v[144:145], 0, s[22:23]
	v_mul_f32_e32 v8, v0, v0
	v_max_f32_e32 v0, 0, v5
	v_mul_f32_e32 v5, v1, v1
	v_max_f32_e32 v1, 0, v6
	v_mul_f32_e32 v6, v2, v2
	v_max_f32_e32 v2, 0, v7
	v_max_f32_e32 v4, 0, v4
	v_mul_f32_e32 v0, v0, v0
	v_mul_f32_e32 v1, v1, v1
	v_mul_f32_e32 v2, v2, v2
	v_mul_f32_e32 v3, v3, v3
	s_and_b64 vcc, exec, s[6:7]
	v_mul_f32_e32 v4, v4, v4
	v_cvt_pk_bf16_f32 v0, v4, v0
	v_cvt_pk_bf16_f32 v1, v1, v2
	v_cvt_pk_bf16_f32 v2, v8, v5
	v_cvt_pk_bf16_f32 v3, v6, v3
	global_store_dwordx4 v[16:17], v[0:3], off offset:256 nt
	s_cbranch_vccz .LBB0_843
	s_waitcnt vmcnt(0)
	s_cmpk_gt_u32 s33, 0xff
	s_cbranch_scc1 .LBB0_854
	s_barrier

.LBB0_896:
	ds_read_b128 v[144:147], v178
	ds_read_b128 v[148:151], v178 offset:1024
	ds_read_b128 v[152:155], v178 offset:2048
	ds_read_b128 v[156:159], v178 offset:3072
	s_add_u32 s42, s40, 0xfff00080
	s_addc_u32 s43, s41, -1
	s_cmp_eq_u32 s65, 60
	s_cselect_b32 s49, s29, s43
	s_cselect_b32 s48, s37, s42
	s_cselect_b32 s43, s27, s64
	s_cselect_b32 s42, s62, s63
	v_lshl_add_u64 v[172:173], s[40:41], 0, v[136:137]
	s_add_i32 m0, s39, 0xc000
	ds_read_b128 v[160:163], v179
	ds_read_b128 v[164:167], v179 offset:1024
	ds_read_b128 v[168:171], v179 offset:2048
	ds_read_b128 v[182:185], v179 offset:3072
	ds_read_b128 v[186:189], v179 offset:4096
	ds_read_b128 v[190:193], v179 offset:5120
	ds_read_b128 v[194:197], v179 offset:6144
	ds_read_b128 v[198:201], v179 offset:7168
	global_load_lds_dwordx4 v[172:173], off
	s_add_i32 m0, s39, 0xe000
	v_lshl_add_u64 v[172:173], s[40:41], 0, v[138:139]
	global_load_lds_dwordx4 v[172:173], off
	s_waitcnt lgkmcnt(8)
	s_setprio 1
	s_barrier
	s_waitcnt lgkmcnt(0)
	v_mfma_f32_16x16x32_bf16 v[124:127], v[144:147], v[160:163], v[124:127]
	v_mfma_f32_16x16x32_bf16 v[120:123], v[152:155], v[160:163], v[120:123]
	v_mfma_f32_16x16x32_bf16 v[108:111], v[144:147], v[168:171], v[108:111]
	v_mfma_f32_16x16x32_bf16 v[104:107], v[152:155], v[168:171], v[104:107]
	v_mfma_f32_16x16x32_bf16 v[96:99], v[144:147], v[186:189], v[96:99]
	v_mfma_f32_16x16x32_bf16 v[88:91], v[152:155], v[186:189], v[88:91]
	v_mfma_f32_16x16x32_bf16 v[80:83], v[144:147], v[194:197], v[80:83]
	v_mfma_f32_16x16x32_bf16 v[72:75], v[152:155], v[194:197], v[72:75]
	v_mfma_f32_16x16x32_bf16 v[124:127], v[148:151], v[164:167], v[124:127]
	v_mfma_f32_16x16x32_bf16 v[120:123], v[156:159], v[164:167], v[120:123]
	v_mfma_f32_16x16x32_bf16 v[108:111], v[148:151], v[182:185], v[108:111]
	v_mfma_f32_16x16x32_bf16 v[104:107], v[156:159], v[182:185], v[104:107]
	v_mfma_f32_16x16x32_bf16 v[96:99], v[148:151], v[190:193], v[96:99]
	v_mfma_f32_16x16x32_bf16 v[88:91], v[156:159], v[190:193], v[88:91]
	v_mfma_f32_16x16x32_bf16 v[80:83], v[148:151], v[198:201], v[80:83]
	v_mfma_f32_16x16x32_bf16 v[72:75], v[156:159], v[198:201], v[72:75]
	s_setprio 0
	s_barrier
	s_add_i32 s66, s60, s50
	v_lshl_add_u64 v[172:173], s[42:43], 0, v[130:131]
	s_mov_b32 m0, s66
	ds_read_b128 v[202:205], v180
	ds_read_b128 v[206:209], v180 offset:1024
	ds_read_b128 v[212:215], v180 offset:2048
	ds_read_b128 v[216:219], v180 offset:3072
	global_load_lds_dwordx4 v[172:173], off
	s_add_i32 m0, s66, 0x2000
	v_lshl_add_u64 v[220:221], s[42:43], 0, v[134:135]
	global_load_lds_dwordx4 v[220:221], off
	s_setprio 1
	s_barrier
	s_waitcnt lgkmcnt(0)
	v_mfma_f32_16x16x32_bf16 v[116:119], v[202:205], v[160:163], v[116:119]
	v_mfma_f32_16x16x32_bf16 v[112:115], v[212:215], v[160:163], v[112:115]
	v_mfma_f32_16x16x32_bf16 v[100:103], v[202:205], v[168:171], v[100:103]
	v_mfma_f32_16x16x32_bf16 v[92:95], v[212:215], v[168:171], v[92:95]
	v_mfma_f32_16x16x32_bf16 v[84:87], v[202:205], v[186:189], v[84:87]
	v_mfma_f32_16x16x32_bf16 v[76:79], v[212:215], v[186:189], v[76:79]
	v_mfma_f32_16x16x32_bf16 v[68:71], v[202:205], v[194:197], v[68:71]
	v_mfma_f32_16x16x32_bf16 v[64:67], v[212:215], v[194:197], v[64:67]
	v_mfma_f32_16x16x32_bf16 v[116:119], v[206:209], v[164:167], v[116:119]
	v_mfma_f32_16x16x32_bf16 v[112:115], v[216:219], v[164:167], v[112:115]
	v_mfma_f32_16x16x32_bf16 v[100:103], v[206:209], v[182:185], v[100:103]
	v_mfma_f32_16x16x32_bf16 v[92:95], v[216:219], v[182:185], v[92:95]
	v_mfma_f32_16x16x32_bf16 v[84:87], v[206:209], v[190:193], v[84:87]
	v_mfma_f32_16x16x32_bf16 v[76:79], v[216:219], v[190:193], v[76:79]
	v_mfma_f32_16x16x32_bf16 v[68:71], v[206:209], v[198:201], v[68:71]
	v_mfma_f32_16x16x32_bf16 v[64:67], v[216:219], v[198:201], v[64:67]
	s_setprio 0
	s_mov_b32 m0, s39
	v_lshl_add_u64 v[222:223], s[48:49], 0, v[128:129]
	s_barrier
	ds_read_b128 v[160:163], v179 offset:16384
	ds_read_b128 v[164:167], v179 offset:17408
	ds_read_b128 v[168:171], v179 offset:18432
	ds_read_b128 v[182:185], v179 offset:19456
	ds_read_b128 v[186:189], v179 offset:20480
	ds_read_b128 v[190:193], v179 offset:21504
	ds_read_b128 v[194:197], v179 offset:22528
	ds_read_b128 v[198:201], v179 offset:23552
	global_load_lds_dwordx4 v[222:223], off
	s_mov_b32 m0, s51
	v_lshl_add_u64 v[224:225], s[48:49], 0, v[132:133]
	global_load_lds_dwordx4 v[224:225], off
	s_setprio 1
	s_barrier
	s_waitcnt lgkmcnt(0)
	v_mfma_f32_16x16x32_bf16 v[60:63], v[144:147], v[160:163], v[60:63]
	v_mfma_f32_16x16x32_bf16 v[56:59], v[152:155], v[160:163], v[56:59]
	v_mfma_f32_16x16x32_bf16 v[44:47], v[144:147], v[168:171], v[44:47]
	v_mfma_f32_16x16x32_bf16 v[40:43], v[152:155], v[168:171], v[40:43]
	v_mfma_f32_16x16x32_bf16 v[32:35], v[144:147], v[186:189], v[32:35]
	v_mfma_f32_16x16x32_bf16 v[24:27], v[152:155], v[186:189], v[24:27]
	v_mfma_f32_16x16x32_bf16 v[16:19], v[144:147], v[194:197], v[16:19]
	v_mfma_f32_16x16x32_bf16 v[8:11], v[152:155], v[194:197], v[8:11]
	v_mfma_f32_16x16x32_bf16 v[60:63], v[148:151], v[164:167], v[60:63]
	v_mfma_f32_16x16x32_bf16 v[56:59], v[156:159], v[164:167], v[56:59]
	v_mfma_f32_16x16x32_bf16 v[44:47], v[148:151], v[182:185], v[44:47]
	v_mfma_f32_16x16x32_bf16 v[40:43], v[156:159], v[182:185], v[40:43]
	v_mfma_f32_16x16x32_bf16 v[32:35], v[148:151], v[190:193], v[32:35]
	v_mfma_f32_16x16x32_bf16 v[24:27], v[156:159], v[190:193], v[24:27]
	v_mfma_f32_16x16x32_bf16 v[16:19], v[148:151], v[198:201], v[16:19]
	v_mfma_f32_16x16x32_bf16 v[8:11], v[156:159], v[198:201], v[8:11]
	s_setprio 0
	s_barrier
	s_add_u32 s66, s42, 0x100000
	s_addc_u32 s67, s43, 0
	s_add_i32 s68, s61, s50
	s_mov_b32 m0, s68
	v_lshl_add_u64 v[144:145], s[66:67], 0, v[130:131]
	global_load_lds_dwordx4 v[144:145], off
	s_add_i32 m0, s68, 0x2000
	v_lshl_add_u64 v[144:145], s[66:67], 0, v[134:135]
	global_load_lds_dwordx4 v[144:145], off
	s_waitcnt vmcnt(6)
	s_setprio 1
	s_barrier
	v_mfma_f32_16x16x32_bf16 v[52:55], v[202:205], v[160:163], v[52:55]
	v_mfma_f32_16x16x32_bf16 v[48:51], v[212:215], v[160:163], v[48:51]
	v_mfma_f32_16x16x32_bf16 v[36:39], v[202:205], v[168:171], v[36:39]
	v_mfma_f32_16x16x32_bf16 v[28:31], v[212:215], v[168:171], v[28:31]
	v_mfma_f32_16x16x32_bf16 v[20:23], v[202:205], v[186:189], v[20:23]
	v_mfma_f32_16x16x32_bf16 v[12:15], v[212:215], v[186:189], v[12:15]
	v_mfma_f32_16x16x32_bf16 v[4:7], v[202:205], v[194:197], v[4:7]
	v_mfma_f32_16x16x32_bf16 v[0:3], v[212:215], v[194:197], v[0:3]
	v_mfma_f32_16x16x32_bf16 v[52:55], v[206:209], v[164:167], v[52:55]
	v_mfma_f32_16x16x32_bf16 v[48:51], v[216:219], v[164:167], v[48:51]
	v_mfma_f32_16x16x32_bf16 v[36:39], v[206:209], v[182:185], v[36:39]
	v_mfma_f32_16x16x32_bf16 v[28:31], v[216:219], v[182:185], v[28:31]
	v_mfma_f32_16x16x32_bf16 v[20:23], v[206:209], v[190:193], v[20:23]
	v_mfma_f32_16x16x32_bf16 v[12:15], v[216:219], v[190:193], v[12:15]
	v_mfma_f32_16x16x32_bf16 v[4:7], v[206:209], v[198:201], v[4:7]
	v_mfma_f32_16x16x32_bf16 v[0:3], v[216:219], v[198:201], v[0:3]
	s_setprio 0
	s_add_i32 s66, 0, 0x18000
	v_add_u32_e32 v156, s66, v176
	s_barrier
	ds_read_b128 v[144:147], v156
	ds_read_b128 v[148:151], v156 offset:1024
	ds_read_b128 v[152:155], v156 offset:2048
	ds_read_b128 v[156:159], v156 offset:3072
	s_add_u32 s48, s48, 0x100000
	s_addc_u32 s49, s49, 0
	s_mov_b32 m0, s52
	v_lshl_add_u64 v[202:203], s[48:49], 0, v[128:129]
	ds_read_b128 v[160:163], v179 offset:32768
	ds_read_b128 v[164:167], v179 offset:33792
	ds_read_b128 v[168:171], v179 offset:34816
	ds_read_b128 v[182:185], v179 offset:35840
	ds_read_b128 v[186:189], v179 offset:36864
	ds_read_b128 v[190:193], v179 offset:37888
	ds_read_b128 v[194:197], v179 offset:38912
	ds_read_b128 v[198:201], v179 offset:39936
	global_load_lds_dwordx4 v[202:203], off
	s_mov_b32 m0, s53
	v_lshl_add_u64 v[202:203], s[48:49], 0, v[132:133]
	global_load_lds_dwordx4 v[202:203], off
	s_waitcnt lgkmcnt(8)
	s_setprio 1
	s_barrier
	s_waitcnt lgkmcnt(0)
	v_mfma_f32_16x16x32_bf16 v[124:127], v[144:147], v[160:163], v[124:127]
	v_mfma_f32_16x16x32_bf16 v[120:123], v[152:155], v[160:163], v[120:123]
	v_mfma_f32_16x16x32_bf16 v[108:111], v[144:147], v[168:171], v[108:111]
	v_mfma_f32_16x16x32_bf16 v[104:107], v[152:155], v[168:171], v[104:107]
	v_mfma_f32_16x16x32_bf16 v[96:99], v[144:147], v[186:189], v[96:99]
	v_mfma_f32_16x16x32_bf16 v[88:91], v[152:155], v[186:189], v[88:91]
	v_mfma_f32_16x16x32_bf16 v[80:83], v[144:147], v[194:197], v[80:83]
	v_mfma_f32_16x16x32_bf16 v[72:75], v[152:155], v[194:197], v[72:75]
	v_mfma_f32_16x16x32_bf16 v[124:127], v[148:151], v[164:167], v[124:127]
	v_mfma_f32_16x16x32_bf16 v[120:123], v[156:159], v[164:167], v[120:123]
	v_mfma_f32_16x16x32_bf16 v[108:111], v[148:151], v[182:185], v[108:111]
	v_mfma_f32_16x16x32_bf16 v[104:107], v[156:159], v[182:185], v[104:107]
	v_mfma_f32_16x16x32_bf16 v[96:99], v[148:151], v[190:193], v[96:99]
	v_mfma_f32_16x16x32_bf16 v[88:91], v[156:159], v[190:193], v[88:91]
	v_mfma_f32_16x16x32_bf16 v[80:83], v[148:151], v[198:201], v[80:83]
	v_mfma_f32_16x16x32_bf16 v[72:75], v[156:159], v[198:201], v[72:75]
	s_setprio 0
	s_barrier
	s_add_i32 s48, 0, 0x1c000
	s_add_i32 s49, s66, s50
	v_add_u32_e32 v181, s48, v176
	v_lshl_add_u64 v[172:173], v[172:173], 0, s[0:1]
	s_mov_b32 m0, s49
	ds_read_b128 v[202:205], v181
	ds_read_b128 v[206:209], v181 offset:1024
	ds_read_b128 v[212:215], v181 offset:2048
	ds_read_b128 v[216:219], v181 offset:3072
	global_load_lds_dwordx4 v[172:173], off
	s_add_i32 m0, s49, 0x2000
	v_lshl_add_u64 v[172:173], v[220:221], 0, s[0:1]
	global_load_lds_dwordx4 v[172:173], off
	s_setprio 1
	s_barrier
	s_waitcnt lgkmcnt(0)
	v_mfma_f32_16x16x32_bf16 v[116:119], v[202:205], v[160:163], v[116:119]
	v_mfma_f32_16x16x32_bf16 v[112:115], v[212:215], v[160:163], v[112:115]
	v_mfma_f32_16x16x32_bf16 v[100:103], v[202:205], v[168:171], v[100:103]
	v_mfma_f32_16x16x32_bf16 v[92:95], v[212:215], v[168:171], v[92:95]
	v_mfma_f32_16x16x32_bf16 v[84:87], v[202:205], v[186:189], v[84:87]
	v_mfma_f32_16x16x32_bf16 v[76:79], v[212:215], v[186:189], v[76:79]
	v_mfma_f32_16x16x32_bf16 v[68:71], v[202:205], v[194:197], v[68:71]
	v_mfma_f32_16x16x32_bf16 v[64:67], v[212:215], v[194:197], v[64:67]
	v_mfma_f32_16x16x32_bf16 v[116:119], v[206:209], v[164:167], v[116:119]
	v_mfma_f32_16x16x32_bf16 v[112:115], v[216:219], v[164:167], v[112:115]
	v_mfma_f32_16x16x32_bf16 v[100:103], v[206:209], v[182:185], v[100:103]
	v_mfma_f32_16x16x32_bf16 v[92:95], v[216:219], v[182:185], v[92:95]
	v_mfma_f32_16x16x32_bf16 v[84:87], v[206:209], v[190:193], v[84:87]
	v_mfma_f32_16x16x32_bf16 v[76:79], v[216:219], v[190:193], v[76:79]
	v_mfma_f32_16x16x32_bf16 v[68:71], v[206:209], v[198:201], v[68:71]
	v_mfma_f32_16x16x32_bf16 v[64:67], v[216:219], v[198:201], v[64:67]
	s_setprio 0
	s_mov_b32 m0, s55
	v_lshl_add_u64 v[172:173], v[222:223], 0, s[0:1]
	s_barrier
	ds_read_b128 v[160:163], v179 offset:49152
	ds_read_b128 v[164:167], v179 offset:50176
	ds_read_b128 v[168:171], v179 offset:51200
	ds_read_b128 v[182:185], v179 offset:52224
	ds_read_b128 v[186:189], v179 offset:53248
	ds_read_b128 v[190:193], v179 offset:54272
	ds_read_b128 v[194:197], v179 offset:55296
	ds_read_b128 v[198:201], v179 offset:56320
	global_load_lds_dwordx4 v[172:173], off
	s_mov_b32 m0, s56
	v_lshl_add_u64 v[172:173], v[224:225], 0, s[0:1]
	global_load_lds_dwordx4 v[172:173], off
	s_setprio 1
	s_barrier
	s_waitcnt lgkmcnt(0)
	v_mfma_f32_16x16x32_bf16 v[60:63], v[144:147], v[160:163], v[60:63]
	v_mfma_f32_16x16x32_bf16 v[56:59], v[152:155], v[160:163], v[56:59]
	v_mfma_f32_16x16x32_bf16 v[44:47], v[144:147], v[168:171], v[44:47]
	v_mfma_f32_16x16x32_bf16 v[40:43], v[152:155], v[168:171], v[40:43]
	v_mfma_f32_16x16x32_bf16 v[32:35], v[144:147], v[186:189], v[32:35]
	v_mfma_f32_16x16x32_bf16 v[24:27], v[152:155], v[186:189], v[24:27]
	v_mfma_f32_16x16x32_bf16 v[16:19], v[144:147], v[194:197], v[16:19]
	v_mfma_f32_16x16x32_bf16 v[8:11], v[152:155], v[194:197], v[8:11]
	v_mfma_f32_16x16x32_bf16 v[60:63], v[148:151], v[164:167], v[60:63]
	v_mfma_f32_16x16x32_bf16 v[56:59], v[156:159], v[164:167], v[56:59]
	v_mfma_f32_16x16x32_bf16 v[44:47], v[148:151], v[182:185], v[44:47]
	v_mfma_f32_16x16x32_bf16 v[40:43], v[156:159], v[182:185], v[40:43]
	v_mfma_f32_16x16x32_bf16 v[32:35], v[148:151], v[190:193], v[32:35]
	v_mfma_f32_16x16x32_bf16 v[24:27], v[156:159], v[190:193], v[24:27]
	v_mfma_f32_16x16x32_bf16 v[16:19], v[148:151], v[198:201], v[16:19]
	v_mfma_f32_16x16x32_bf16 v[8:11], v[156:159], v[198:201], v[8:11]
	s_setprio 0
	s_barrier
	s_add_u32 s42, s42, 0x100080
	s_addc_u32 s43, s43, 0
	s_add_i32 s48, s48, s50
	s_mov_b32 m0, s48
	v_lshl_add_u64 v[144:145], s[42:43], 0, v[130:131]
	global_load_lds_dwordx4 v[144:145], off
	s_add_i32 m0, s48, 0x2000
	v_lshl_add_u64 v[144:145], s[42:43], 0, v[134:135]
	global_load_lds_dwordx4 v[144:145], off
	s_waitcnt vmcnt(6)
	s_setprio 1
	s_barrier
	v_mfma_f32_16x16x32_bf16 v[52:55], v[202:205], v[160:163], v[52:55]
	v_mfma_f32_16x16x32_bf16 v[48:51], v[212:215], v[160:163], v[48:51]
	v_mfma_f32_16x16x32_bf16 v[36:39], v[202:205], v[168:171], v[36:39]
	v_mfma_f32_16x16x32_bf16 v[28:31], v[212:215], v[168:171], v[28:31]
	v_mfma_f32_16x16x32_bf16 v[20:23], v[202:205], v[186:189], v[20:23]
	v_mfma_f32_16x16x32_bf16 v[12:15], v[212:215], v[186:189], v[12:15]
	v_mfma_f32_16x16x32_bf16 v[4:7], v[202:205], v[194:197], v[4:7]
	v_mfma_f32_16x16x32_bf16 v[0:3], v[212:215], v[194:197], v[0:3]
	v_mfma_f32_16x16x32_bf16 v[52:55], v[206:209], v[164:167], v[52:55]
	v_mfma_f32_16x16x32_bf16 v[48:51], v[216:219], v[164:167], v[48:51]
	v_mfma_f32_16x16x32_bf16 v[36:39], v[206:209], v[182:185], v[36:39]
	v_mfma_f32_16x16x32_bf16 v[28:31], v[216:219], v[182:185], v[28:31]
	v_mfma_f32_16x16x32_bf16 v[20:23], v[206:209], v[190:193], v[20:23]
	v_mfma_f32_16x16x32_bf16 v[12:15], v[216:219], v[190:193], v[12:15]
	v_mfma_f32_16x16x32_bf16 v[4:7], v[206:209], v[198:201], v[4:7]
	v_mfma_f32_16x16x32_bf16 v[0:3], v[216:219], v[198:201], v[0:3]
	s_setprio 0
	s_add_i32 s65, s65, 2
	s_add_u32 s40, s40, 0x100
	s_addc_u32 s41, s41, 0
	s_add_u32 s63, s63, 0x100
	s_addc_u32 s64, s64, 0
	s_cmp_gt_u32 s65, 61
	s_barrier
	s_cbranch_scc0 .LBB0_896
	v_lshl_or_b32 v144, s38, 8, v177
	v_lshl_add_u32 v150, s36, 8, v175
	v_ashrrev_i32_e32 v145, 31, v144
	v_ashrrev_i32_e32 v151, 31, v150
	v_lshlrev_b64 v[144:145], 1, v[144:145]
	v_lshl_add_u64 v[146:147], s[90:91], 0, v[144:145]
	v_lshlrev_b64 v[148:149], 11, v[150:151]
	v_lshl_add_u64 v[152:153], v[146:147], 0, v[148:149]
	global_load_dwordx4 v[156:159], v[152:153], off
	global_load_dwordx4 v[160:163], v[152:153], off offset:256
	v_or_b32_e32 v152, 16, v150
	v_ashrrev_i32_e32 v153, 31, v152
	v_lshlrev_b64 v[170:171], 11, v[152:153]
	v_lshl_add_u64 v[152:153], v[146:147], 0, v[170:171]
	global_load_dwordx4 v[164:167], v[152:153], off
	global_load_dwordx4 v[182:185], v[152:153], off offset:256
	v_or_b32_e32 v152, 32, v150
	v_ashrrev_i32_e32 v153, 31, v152
	v_lshlrev_b64 v[154:155], 11, v[152:153]
	v_lshl_add_u64 v[152:153], v[146:147], 0, v[154:155]
	global_load_dwordx4 v[186:189], v[152:153], off
	global_load_dwordx4 v[190:193], v[152:153], off offset:256
	v_or_b32_e32 v152, 48, v150
	v_ashrrev_i32_e32 v153, 31, v152
	v_lshlrev_b64 v[152:153], 11, v[152:153]
	v_lshl_add_u64 v[168:169], v[146:147], 0, v[152:153]
	global_load_dwordx4 v[194:197], v[168:169], off
	global_load_dwordx4 v[198:201], v[168:169], off offset:256
	s_waitcnt vmcnt(0)
	v_lshlrev_b32_e32 v202, 16, v156
	v_and_b32_e32 v203, 0xffff0000, v156
	v_lshlrev_b32_e32 v204, 16, v157
	v_and_b32_e32 v205, 0xffff0000, v157
	v_lshlrev_b32_e32 v206, 16, v158
	v_and_b32_e32 v207, 0xffff0000, v158
	v_lshlrev_b32_e32 v208, 16, v159
	v_and_b32_e32 v209, 0xffff0000, v159
	v_pk_add_f32 v[126:127], v[126:127], v[204:205]
	v_pk_add_f32 v[124:125], v[124:125], v[202:203]
	v_lshlrev_b32_e32 v224, 16, v166
	v_and_b32_e32 v225, 0xffff0000, v166
	v_lshlrev_b32_e32 v226, 16, v167
	v_and_b32_e32 v227, 0xffff0000, v167
	v_lshlrev_b32_e32 v212, 16, v160
	v_lshlrev_b32_e32 v166, 16, v194
	v_and_b32_e32 v167, 0xffff0000, v194
	v_lshlrev_b32_e32 v172, 16, v195
	v_and_b32_e32 v173, 0xffff0000, v195
	v_pk_add_f32 v[194:195], v[122:123], v[208:209]
	v_pk_add_f32 v[122:123], v[120:121], v[206:207]
	v_mul_f32_e32 v120, v125, v125
	v_mul_f32_e32 v121, v127, v127
	v_fmac_f32_e32 v120, v124, v124
	v_fmac_f32_e32 v121, v126, v126
	v_add_f32_e32 v120, v120, v121
	v_mul_f32_e32 v121, v123, v123
	v_fmac_f32_e32 v121, v122, v122
	v_add_f32_e32 v120, v121, v120
	v_mul_f32_e32 v121, v195, v195
	v_fmac_f32_e32 v121, v194, v194
	v_and_b32_e32 v213, 0xffff0000, v160
	v_lshlrev_b32_e32 v214, 16, v161
	v_and_b32_e32 v215, 0xffff0000, v161
	v_add_f32_e32 v181, v121, v120
	v_cvt_pk_bf16_f32 v120, v124, v125
	v_lshl_add_u64 v[124:125], s[10:11], 0, v[148:149]
	v_lshlrev_b32_e32 v216, 16, v162
	v_and_b32_e32 v217, 0xffff0000, v162
	v_lshlrev_b32_e32 v218, 16, v163
	v_and_b32_e32 v219, 0xffff0000, v163
	v_cvt_pk_bf16_f32 v121, v126, v127
	v_lshl_add_u64 v[124:125], v[124:125], 0, v[144:145]
	v_pk_add_f32 v[118:119], v[118:119], v[214:215]
	v_pk_add_f32 v[116:117], v[116:117], v[212:213]
	v_cvt_pk_bf16_f32 v122, v122, v123
	v_cvt_pk_bf16_f32 v123, v194, v195
	global_store_dwordx4 v[124:125], v[120:123], off
	v_lshlrev_b32_e32 v220, 16, v164
	v_and_b32_e32 v221, 0xffff0000, v164
	v_pk_add_f32 v[120:121], v[114:115], v[218:219]
	v_pk_add_f32 v[114:115], v[112:113], v[216:217]
	v_mul_f32_e32 v112, v117, v117
	v_mul_f32_e32 v113, v119, v119
	v_fmac_f32_e32 v112, v116, v116
	v_fmac_f32_e32 v113, v118, v118
	v_add_f32_e32 v112, v112, v113
	v_mul_f32_e32 v113, v115, v115
	v_fmac_f32_e32 v113, v114, v114
	v_add_f32_e32 v112, v113, v112
	v_mul_f32_e32 v113, v121, v121
	v_fmac_f32_e32 v113, v120, v120
	v_add_f32_e32 v112, v113, v112
	v_lshlrev_b32_e32 v222, 16, v165
	v_and_b32_e32 v223, 0xffff0000, v165
	v_add_f32_e32 v126, v181, v112
	v_cvt_pk_bf16_f32 v112, v116, v117
	v_cvt_pk_bf16_f32 v113, v118, v119
	v_lshl_add_u64 v[116:117], s[10:11], 0, v[170:171]
	v_lshlrev_b32_e32 v230, 16, v184
	v_and_b32_e32 v231, 0xffff0000, v184
	v_lshlrev_b32_e32 v232, 16, v186
	v_and_b32_e32 v233, 0xffff0000, v186
	v_lshlrev_b32_e32 v186, 16, v187
	v_and_b32_e32 v187, 0xffff0000, v187
	v_cvt_pk_bf16_f32 v114, v114, v115
	v_cvt_pk_bf16_f32 v115, v120, v121
	global_store_dwordx4 v[124:125], v[112:115], off offset:256
	v_pk_add_f32 v[110:111], v[110:111], v[222:223]
	v_pk_add_f32 v[108:109], v[108:109], v[220:221]
	v_lshl_add_u64 v[118:119], v[116:117], 0, v[144:145]
	v_cvt_pk_bf16_f32 v112, v108, v109
	v_cvt_pk_bf16_f32 v113, v110, v111
	v_lshlrev_b32_e32 v228, 16, v182
	v_and_b32_e32 v229, 0xffff0000, v182
	v_lshlrev_b32_e32 v182, 16, v183
	v_and_b32_e32 v183, 0xffff0000, v183
	v_lshlrev_b32_e32 v184, 16, v185
	v_and_b32_e32 v185, 0xffff0000, v185
	v_lshlrev_b32_e32 v238, 16, v192
	v_and_b32_e32 v239, 0xffff0000, v192
	v_pk_add_f32 v[106:107], v[106:107], v[226:227]
	v_pk_add_f32 v[104:105], v[104:105], v[224:225]
	v_lshlrev_b32_e32 v156, 16, v200
	v_cvt_pk_bf16_f32 v114, v104, v105
	v_cvt_pk_bf16_f32 v115, v106, v107
	global_store_dwordx4 v[118:119], v[112:115], off
	v_and_b32_e32 v157, 0xffff0000, v200
	v_pk_add_f32 v[102:103], v[102:103], v[182:183]
	v_pk_add_f32 v[112:113], v[92:93], v[230:231]
	v_pk_add_f32 v[92:93], v[98:99], v[186:187]
	v_lshl_add_u64 v[98:99], s[10:11], 0, v[154:155]
	v_pk_add_f32 v[100:101], v[100:101], v[228:229]
	v_pk_add_f32 v[94:95], v[94:95], v[184:185]
	v_cvt_pk_bf16_f32 v114, v100, v101
	v_cvt_pk_bf16_f32 v115, v102, v103
	v_cvt_pk_bf16_f32 v116, v112, v113
	v_lshlrev_b32_e32 v234, 16, v188
	v_cvt_pk_bf16_f32 v117, v94, v95
	global_store_dwordx4 v[118:119], v[114:117], off offset:256
	v_lshl_add_u64 v[118:119], v[98:99], 0, v[144:145]
	v_pk_add_f32 v[98:99], v[76:77], v[238:239]
	v_pk_add_f32 v[76:77], v[82:83], v[172:173]
	v_lshl_add_u64 v[82:83], s[10:11], 0, v[152:153]
	v_lshl_add_u64 v[122:123], v[82:83], 0, v[144:145]
	v_pk_add_f32 v[82:83], v[64:65], v[156:157]
	v_and_b32_e32 v65, 64, v174
	v_and_b32_e32 v235, 0xffff0000, v188
	v_lshlrev_b32_e32 v188, 16, v189
	v_and_b32_e32 v189, 0xffff0000, v189
	v_lshlrev_b32_e32 v236, 16, v190
	v_and_b32_e32 v237, 0xffff0000, v190
	v_pk_add_f32 v[96:97], v[96:97], v[232:233]
	v_xor_b32_e32 v64, 16, v174
	v_cvt_pk_bf16_f32 v114, v96, v97
	v_add_u32_e32 v65, 64, v65
	v_lshlrev_b32_e32 v190, 16, v191
	v_and_b32_e32 v191, 0xffff0000, v191
	v_lshlrev_b32_e32 v192, 16, v193
	v_and_b32_e32 v193, 0xffff0000, v193
	v_pk_add_f32 v[90:91], v[90:91], v[188:189]
	v_pk_add_f32 v[88:89], v[88:89], v[234:235]
	v_cvt_pk_bf16_f32 v115, v92, v93
	v_pk_add_f32 v[84:85], v[84:85], v[236:237]
	v_cvt_pk_bf16_f32 v116, v88, v89
	v_cvt_pk_bf16_f32 v117, v90, v91
	global_store_dwordx4 v[118:119], v[114:117], off
	v_cmp_lt_i32_e32 vcc, v64, v65
	v_lshlrev_b32_e32 v164, 16, v196
	v_cvt_pk_bf16_f32 v114, v84, v85
	v_and_b32_e32 v165, 0xffff0000, v196
	v_lshlrev_b32_e32 v168, 16, v197
	v_and_b32_e32 v169, 0xffff0000, v197
	v_pk_add_f32 v[86:87], v[86:87], v[190:191]
	v_pk_add_f32 v[78:79], v[78:79], v[192:193]
	v_cvt_pk_bf16_f32 v115, v86, v87
	v_cvt_pk_bf16_f32 v116, v98, v99
	v_pk_add_f32 v[80:81], v[80:81], v[166:167]
	v_cvt_pk_bf16_f32 v117, v78, v79
	global_store_dwordx4 v[118:119], v[114:117], off offset:256
	v_cndmask_b32_e32 v64, v174, v64, vcc
	v_pk_add_f32 v[74:75], v[74:75], v[168:169]
	v_cvt_pk_bf16_f32 v114, v80, v81
	v_pk_add_f32 v[72:73], v[72:73], v[164:165]
	v_cvt_pk_bf16_f32 v115, v76, v77
	v_lshlrev_b32_e32 v158, 16, v198
	v_cvt_pk_bf16_f32 v116, v72, v73
	v_cvt_pk_bf16_f32 v117, v74, v75
	global_store_dwordx4 v[122:123], v[114:117], off
	v_and_b32_e32 v159, 0xffff0000, v198
	v_lshlrev_b32_e32 v162, 16, v199
	v_lshlrev_b32_e32 v114, 2, v64
	ds_bpermute_b32 v64, v114, v126
	v_xor_b32_e32 v115, 32, v174
	v_cmp_lt_i32_e32 vcc, v115, v65
	v_and_b32_e32 v163, 0xffff0000, v199
	v_lshlrev_b32_e32 v160, 16, v201
	v_cndmask_b32_e32 v65, v174, v115, vcc
	v_lshlrev_b32_e32 v115, 2, v65
	s_waitcnt lgkmcnt(0)
	v_add_f32_e32 v116, v126, v64
	ds_bpermute_b32 v117, v115, v116
	v_and_b32_e32 v161, 0xffff0000, v201
	v_pk_add_f32 v[70:71], v[70:71], v[162:163]
	v_pk_add_f32 v[68:69], v[68:69], v[158:159]
	v_pk_add_f32 v[66:67], v[66:67], v[160:161]
	v_lshl_add_u64 v[64:65], v[150:151], 2, s[18:19]
	v_cvt_pk_bf16_f32 v118, v68, v69
	v_cvt_pk_bf16_f32 v119, v70, v71
	v_cvt_pk_bf16_f32 v120, v82, v83
	v_cvt_pk_bf16_f32 v121, v66, v67
	global_store_dwordx4 v[122:123], v[118:121], off offset:256
	s_and_saveexec_b64 s[36:37], s[6:7]
	s_cbranch_execz .LBB0_899
	s_waitcnt lgkmcnt(0)
	v_add_f32_e32 v116, v116, v117
	global_atomic_add_f32 v[64:65], v116, off

.LBB0_946:
	ds_read_b128 v[144:147], v153
	ds_read_b128 v[158:161], v153 offset:1024
	ds_read_b128 v[162:165], v153 offset:2048
	ds_read_b128 v[166:169], v153 offset:3072
	s_add_u32 s28, s2, 0xfffc0080
	s_addc_u32 s29, s3, -1
	s_cmp_eq_u32 s58, 12
	s_cselect_b32 s31, s23, s29
	s_cselect_b32 s30, s54, s28
	s_cselect_b32 s29, s21, s57
	s_cselect_b32 s28, s55, s56
	v_lshl_add_u64 v[148:149], s[2:3], 0, v[136:137]
	s_add_i32 m0, s37, 0xc000
	ds_read_b128 v[170:173], v154
	ds_read_b128 v[176:179], v154 offset:1024
	ds_read_b128 v[180:183], v154 offset:2048
	ds_read_b128 v[184:187], v154 offset:3072
	ds_read_b128 v[188:191], v154 offset:4096
	ds_read_b128 v[192:195], v154 offset:5120
	ds_read_b128 v[196:199], v154 offset:6144
	ds_read_b128 v[200:203], v154 offset:7168
	global_load_lds_dwordx4 v[148:149], off
	s_add_i32 m0, s37, 0xe000
	v_lshl_add_u64 v[148:149], s[2:3], 0, v[138:139]
	global_load_lds_dwordx4 v[148:149], off
	s_waitcnt lgkmcnt(8)
	s_setprio 1
	s_barrier
	s_waitcnt lgkmcnt(0)
	v_mfma_f32_16x16x32_bf16 v[124:127], v[144:147], v[170:173], v[124:127]
	v_mfma_f32_16x16x32_bf16 v[120:123], v[162:165], v[170:173], v[120:123]
	v_mfma_f32_16x16x32_bf16 v[116:119], v[144:147], v[180:183], v[116:119]
	v_mfma_f32_16x16x32_bf16 v[112:115], v[162:165], v[180:183], v[112:115]
	v_mfma_f32_16x16x32_bf16 v[104:107], v[144:147], v[188:191], v[104:107]
	v_mfma_f32_16x16x32_bf16 v[96:99], v[162:165], v[188:191], v[96:99]
	v_mfma_f32_16x16x32_bf16 v[76:79], v[144:147], v[196:199], v[76:79]
	v_mfma_f32_16x16x32_bf16 v[72:75], v[162:165], v[196:199], v[72:75]
	v_mfma_f32_16x16x32_bf16 v[124:127], v[158:161], v[176:179], v[124:127]
	v_mfma_f32_16x16x32_bf16 v[120:123], v[166:169], v[176:179], v[120:123]
	v_mfma_f32_16x16x32_bf16 v[116:119], v[158:161], v[184:187], v[116:119]
	v_mfma_f32_16x16x32_bf16 v[112:115], v[166:169], v[184:187], v[112:115]
	v_mfma_f32_16x16x32_bf16 v[104:107], v[158:161], v[192:195], v[104:107]
	v_mfma_f32_16x16x32_bf16 v[96:99], v[166:169], v[192:195], v[96:99]
	v_mfma_f32_16x16x32_bf16 v[76:79], v[158:161], v[200:203], v[76:79]
	v_mfma_f32_16x16x32_bf16 v[72:75], v[166:169], v[200:203], v[72:75]
	s_setprio 0
	s_barrier
	s_add_i32 s59, s50, s34
	v_lshl_add_u64 v[148:149], s[28:29], 0, v[132:133]
	s_mov_b32 m0, s59
	ds_read_b128 v[204:207], v155
	ds_read_b128 v[212:215], v155 offset:1024
	ds_read_b128 v[216:219], v155 offset:2048
	ds_read_b128 v[220:223], v155 offset:3072
	global_load_lds_dwordx4 v[148:149], off
	s_add_i32 m0, s59, 0x2000
	v_lshl_add_u64 v[208:209], s[28:29], 0, v[128:129]
	global_load_lds_dwordx4 v[208:209], off
	s_setprio 1
	s_barrier
	s_waitcnt lgkmcnt(0)
	v_mfma_f32_16x16x32_bf16 v[108:111], v[204:207], v[170:173], v[108:111]
	v_mfma_f32_16x16x32_bf16 v[100:103], v[216:219], v[170:173], v[100:103]
	v_mfma_f32_16x16x32_bf16 v[92:95], v[204:207], v[180:183], v[92:95]
	v_mfma_f32_16x16x32_bf16 v[88:91], v[216:219], v[180:183], v[88:91]
	v_mfma_f32_16x16x32_bf16 v[84:87], v[204:207], v[188:191], v[84:87]
	v_mfma_f32_16x16x32_bf16 v[80:83], v[216:219], v[188:191], v[80:83]
	v_mfma_f32_16x16x32_bf16 v[68:71], v[204:207], v[196:199], v[68:71]
	v_mfma_f32_16x16x32_bf16 v[64:67], v[216:219], v[196:199], v[64:67]
	v_mfma_f32_16x16x32_bf16 v[108:111], v[212:215], v[176:179], v[108:111]
	v_mfma_f32_16x16x32_bf16 v[100:103], v[220:223], v[176:179], v[100:103]
	v_mfma_f32_16x16x32_bf16 v[92:95], v[212:215], v[184:187], v[92:95]
	v_mfma_f32_16x16x32_bf16 v[88:91], v[220:223], v[184:187], v[88:91]
	v_mfma_f32_16x16x32_bf16 v[84:87], v[212:215], v[192:195], v[84:87]
	v_mfma_f32_16x16x32_bf16 v[80:83], v[220:223], v[192:195], v[80:83]
	v_mfma_f32_16x16x32_bf16 v[68:71], v[212:215], v[200:203], v[68:71]
	v_mfma_f32_16x16x32_bf16 v[64:67], v[220:223], v[200:203], v[64:67]
	s_setprio 0
	s_mov_b32 m0, s37
	v_lshl_add_u64 v[224:225], s[30:31], 0, v[134:135]
	s_barrier
	ds_read_b128 v[170:173], v154 offset:16384
	ds_read_b128 v[176:179], v154 offset:17408
	ds_read_b128 v[180:183], v154 offset:18432
	ds_read_b128 v[184:187], v154 offset:19456
	ds_read_b128 v[188:191], v154 offset:20480
	ds_read_b128 v[192:195], v154 offset:21504
	ds_read_b128 v[196:199], v154 offset:22528
	ds_read_b128 v[200:203], v154 offset:23552
	global_load_lds_dwordx4 v[224:225], off
	s_mov_b32 m0, s38
	v_lshl_add_u64 v[226:227], s[30:31], 0, v[130:131]
	global_load_lds_dwordx4 v[226:227], off
	s_setprio 1
	s_barrier
	s_waitcnt lgkmcnt(0)
	v_mfma_f32_16x16x32_bf16 v[60:63], v[144:147], v[170:173], v[60:63]
	v_mfma_f32_16x16x32_bf16 v[56:59], v[162:165], v[170:173], v[56:59]
	v_mfma_f32_16x16x32_bf16 v[44:47], v[144:147], v[180:183], v[44:47]
	v_mfma_f32_16x16x32_bf16 v[40:43], v[162:165], v[180:183], v[40:43]
	v_mfma_f32_16x16x32_bf16 v[28:31], v[144:147], v[188:191], v[28:31]
	v_mfma_f32_16x16x32_bf16 v[24:27], v[162:165], v[188:191], v[24:27]
	v_mfma_f32_16x16x32_bf16 v[12:15], v[144:147], v[196:199], v[12:15]
	v_mfma_f32_16x16x32_bf16 v[8:11], v[162:165], v[196:199], v[8:11]
	v_mfma_f32_16x16x32_bf16 v[60:63], v[158:161], v[176:179], v[60:63]
	v_mfma_f32_16x16x32_bf16 v[56:59], v[166:169], v[176:179], v[56:59]
	v_mfma_f32_16x16x32_bf16 v[44:47], v[158:161], v[184:187], v[44:47]
	v_mfma_f32_16x16x32_bf16 v[40:43], v[166:169], v[184:187], v[40:43]
	v_mfma_f32_16x16x32_bf16 v[28:31], v[158:161], v[192:195], v[28:31]
	v_mfma_f32_16x16x32_bf16 v[24:27], v[166:169], v[192:195], v[24:27]
	v_mfma_f32_16x16x32_bf16 v[12:15], v[158:161], v[200:203], v[12:15]
	v_mfma_f32_16x16x32_bf16 v[8:11], v[166:169], v[200:203], v[8:11]
	s_setprio 0
	s_barrier
	s_add_u32 s60, s28, 0x40000
	s_addc_u32 s61, s29, 0
	s_add_i32 s59, s51, s34
	s_mov_b32 m0, s59
	v_lshl_add_u64 v[144:145], s[60:61], 0, v[132:133]
	global_load_lds_dwordx4 v[144:145], off
	s_add_i32 m0, s59, 0x2000
	v_lshl_add_u64 v[144:145], s[60:61], 0, v[128:129]
	global_load_lds_dwordx4 v[144:145], off
	s_waitcnt vmcnt(6)
	s_setprio 1
	s_barrier
	v_mfma_f32_16x16x32_bf16 v[52:55], v[204:207], v[170:173], v[52:55]
	v_mfma_f32_16x16x32_bf16 v[48:51], v[216:219], v[170:173], v[48:51]
	v_mfma_f32_16x16x32_bf16 v[36:39], v[204:207], v[180:183], v[36:39]
	v_mfma_f32_16x16x32_bf16 v[32:35], v[216:219], v[180:183], v[32:35]
	v_mfma_f32_16x16x32_bf16 v[20:23], v[204:207], v[188:191], v[20:23]
	v_mfma_f32_16x16x32_bf16 v[16:19], v[216:219], v[188:191], v[16:19]
	v_mfma_f32_16x16x32_bf16 v[4:7], v[204:207], v[196:199], v[4:7]
	v_mfma_f32_16x16x32_bf16 v[0:3], v[216:219], v[196:199], v[0:3]
	v_mfma_f32_16x16x32_bf16 v[52:55], v[212:215], v[176:179], v[52:55]
	v_mfma_f32_16x16x32_bf16 v[48:51], v[220:223], v[176:179], v[48:51]
	v_mfma_f32_16x16x32_bf16 v[36:39], v[212:215], v[184:187], v[36:39]
	v_mfma_f32_16x16x32_bf16 v[32:35], v[220:223], v[184:187], v[32:35]
	v_mfma_f32_16x16x32_bf16 v[20:23], v[212:215], v[192:195], v[20:23]
	v_mfma_f32_16x16x32_bf16 v[16:19], v[220:223], v[192:195], v[16:19]
	v_mfma_f32_16x16x32_bf16 v[4:7], v[212:215], v[200:203], v[4:7]
	v_mfma_f32_16x16x32_bf16 v[0:3], v[220:223], v[200:203], v[0:3]
	s_setprio 0
	s_add_i32 s59, 0, 0x18000
	v_add_u32_e32 v157, s59, v151
	s_barrier
	ds_read_b128 v[144:147], v157
	ds_read_b128 v[158:161], v157 offset:1024
	ds_read_b128 v[162:165], v157 offset:2048
	ds_read_b128 v[166:169], v157 offset:3072
	s_add_u32 s30, s30, 0x40000
	s_addc_u32 s31, s31, 0
	s_mov_b32 m0, s39
	v_lshl_add_u64 v[204:205], s[30:31], 0, v[134:135]
	ds_read_b128 v[170:173], v154 offset:32768
	ds_read_b128 v[176:179], v154 offset:33792
	ds_read_b128 v[180:183], v154 offset:34816
	ds_read_b128 v[184:187], v154 offset:35840
	ds_read_b128 v[188:191], v154 offset:36864
	ds_read_b128 v[192:195], v154 offset:37888
	ds_read_b128 v[196:199], v154 offset:38912
	ds_read_b128 v[200:203], v154 offset:39936
	global_load_lds_dwordx4 v[204:205], off
	s_mov_b32 m0, s40
	v_lshl_add_u64 v[204:205], s[30:31], 0, v[130:131]
	global_load_lds_dwordx4 v[204:205], off
	s_waitcnt lgkmcnt(8)
	s_setprio 1
	s_barrier
	s_waitcnt lgkmcnt(0)
	v_mfma_f32_16x16x32_bf16 v[124:127], v[144:147], v[170:173], v[124:127]
	v_mfma_f32_16x16x32_bf16 v[120:123], v[162:165], v[170:173], v[120:123]
	v_mfma_f32_16x16x32_bf16 v[116:119], v[144:147], v[180:183], v[116:119]
	v_mfma_f32_16x16x32_bf16 v[112:115], v[162:165], v[180:183], v[112:115]
	v_mfma_f32_16x16x32_bf16 v[104:107], v[144:147], v[188:191], v[104:107]
	v_mfma_f32_16x16x32_bf16 v[96:99], v[162:165], v[188:191], v[96:99]
	v_mfma_f32_16x16x32_bf16 v[76:79], v[144:147], v[196:199], v[76:79]
	v_mfma_f32_16x16x32_bf16 v[72:75], v[162:165], v[196:199], v[72:75]
	v_mfma_f32_16x16x32_bf16 v[124:127], v[158:161], v[176:179], v[124:127]
	v_mfma_f32_16x16x32_bf16 v[120:123], v[166:169], v[176:179], v[120:123]
	v_mfma_f32_16x16x32_bf16 v[116:119], v[158:161], v[184:187], v[116:119]
	v_mfma_f32_16x16x32_bf16 v[112:115], v[166:169], v[184:187], v[112:115]
	v_mfma_f32_16x16x32_bf16 v[104:107], v[158:161], v[192:195], v[104:107]
	v_mfma_f32_16x16x32_bf16 v[96:99], v[166:169], v[192:195], v[96:99]
	v_mfma_f32_16x16x32_bf16 v[76:79], v[158:161], v[200:203], v[76:79]
	v_mfma_f32_16x16x32_bf16 v[72:75], v[166:169], v[200:203], v[72:75]
	s_setprio 0
	s_barrier
	s_add_i32 s30, 0, 0x1c000
	s_add_i32 s31, s59, s34
	v_add_u32_e32 v157, s30, v151
	v_lshl_add_u64 v[148:149], v[148:149], 0, s[8:9]
	s_mov_b32 m0, s31
	ds_read_b128 v[204:207], v157
	ds_read_b128 v[212:215], v157 offset:1024
	ds_read_b128 v[216:219], v157 offset:2048
	ds_read_b128 v[220:223], v157 offset:3072
	global_load_lds_dwordx4 v[148:149], off
	s_add_i32 m0, s31, 0x2000
	v_lshl_add_u64 v[148:149], v[208:209], 0, s[8:9]
	global_load_lds_dwordx4 v[148:149], off
	s_setprio 1
	s_barrier
	s_waitcnt lgkmcnt(0)
	v_mfma_f32_16x16x32_bf16 v[108:111], v[204:207], v[170:173], v[108:111]
	v_mfma_f32_16x16x32_bf16 v[100:103], v[216:219], v[170:173], v[100:103]
	v_mfma_f32_16x16x32_bf16 v[92:95], v[204:207], v[180:183], v[92:95]
	v_mfma_f32_16x16x32_bf16 v[88:91], v[216:219], v[180:183], v[88:91]
	v_mfma_f32_16x16x32_bf16 v[84:87], v[204:207], v[188:191], v[84:87]
	v_mfma_f32_16x16x32_bf16 v[80:83], v[216:219], v[188:191], v[80:83]
	v_mfma_f32_16x16x32_bf16 v[68:71], v[204:207], v[196:199], v[68:71]
	v_mfma_f32_16x16x32_bf16 v[64:67], v[216:219], v[196:199], v[64:67]
	v_mfma_f32_16x16x32_bf16 v[108:111], v[212:215], v[176:179], v[108:111]
	v_mfma_f32_16x16x32_bf16 v[100:103], v[220:223], v[176:179], v[100:103]
	v_mfma_f32_16x16x32_bf16 v[92:95], v[212:215], v[184:187], v[92:95]
	v_mfma_f32_16x16x32_bf16 v[88:91], v[220:223], v[184:187], v[88:91]
	v_mfma_f32_16x16x32_bf16 v[84:87], v[212:215], v[192:195], v[84:87]
	v_mfma_f32_16x16x32_bf16 v[80:83], v[220:223], v[192:195], v[80:83]
	v_mfma_f32_16x16x32_bf16 v[68:71], v[212:215], v[200:203], v[68:71]
	v_mfma_f32_16x16x32_bf16 v[64:67], v[220:223], v[200:203], v[64:67]
	s_setprio 0
	s_mov_b32 m0, s42
	v_lshl_add_u64 v[148:149], v[224:225], 0, s[8:9]
	s_barrier
	ds_read_b128 v[170:173], v154 offset:49152
	ds_read_b128 v[176:179], v154 offset:50176
	ds_read_b128 v[180:183], v154 offset:51200
	ds_read_b128 v[184:187], v154 offset:52224
	ds_read_b128 v[188:191], v154 offset:53248
	ds_read_b128 v[192:195], v154 offset:54272
	ds_read_b128 v[196:199], v154 offset:55296
	ds_read_b128 v[200:203], v154 offset:56320
	global_load_lds_dwordx4 v[148:149], off
	s_mov_b32 m0, s43
	v_lshl_add_u64 v[148:149], v[226:227], 0, s[8:9]
	global_load_lds_dwordx4 v[148:149], off
	s_setprio 1
	s_barrier
	s_waitcnt lgkmcnt(0)
	v_mfma_f32_16x16x32_bf16 v[60:63], v[144:147], v[170:173], v[60:63]
	v_mfma_f32_16x16x32_bf16 v[56:59], v[162:165], v[170:173], v[56:59]
	v_mfma_f32_16x16x32_bf16 v[44:47], v[144:147], v[180:183], v[44:47]
	v_mfma_f32_16x16x32_bf16 v[40:43], v[162:165], v[180:183], v[40:43]
	v_mfma_f32_16x16x32_bf16 v[28:31], v[144:147], v[188:191], v[28:31]
	v_mfma_f32_16x16x32_bf16 v[24:27], v[162:165], v[188:191], v[24:27]
	v_mfma_f32_16x16x32_bf16 v[12:15], v[144:147], v[196:199], v[12:15]
	v_mfma_f32_16x16x32_bf16 v[8:11], v[162:165], v[196:199], v[8:11]
	v_mfma_f32_16x16x32_bf16 v[60:63], v[158:161], v[176:179], v[60:63]
	v_mfma_f32_16x16x32_bf16 v[56:59], v[166:169], v[176:179], v[56:59]
	v_mfma_f32_16x16x32_bf16 v[44:47], v[158:161], v[184:187], v[44:47]
	v_mfma_f32_16x16x32_bf16 v[40:43], v[166:169], v[184:187], v[40:43]
	v_mfma_f32_16x16x32_bf16 v[28:31], v[158:161], v[192:195], v[28:31]
	v_mfma_f32_16x16x32_bf16 v[24:27], v[166:169], v[192:195], v[24:27]
	v_mfma_f32_16x16x32_bf16 v[12:15], v[158:161], v[200:203], v[12:15]
	v_mfma_f32_16x16x32_bf16 v[8:11], v[166:169], v[200:203], v[8:11]
	s_setprio 0
	s_barrier
	s_add_u32 s28, s28, 0x40080
	s_addc_u32 s29, s29, 0
	s_add_i32 s30, s30, s34
	s_mov_b32 m0, s30
	v_lshl_add_u64 v[144:145], s[28:29], 0, v[132:133]
	global_load_lds_dwordx4 v[144:145], off
	s_add_i32 m0, s30, 0x2000
	v_lshl_add_u64 v[144:145], s[28:29], 0, v[128:129]
	global_load_lds_dwordx4 v[144:145], off
	s_waitcnt vmcnt(6)
	s_setprio 1
	s_barrier
	v_mfma_f32_16x16x32_bf16 v[52:55], v[204:207], v[170:173], v[52:55]
	v_mfma_f32_16x16x32_bf16 v[48:51], v[216:219], v[170:173], v[48:51]
	v_mfma_f32_16x16x32_bf16 v[36:39], v[204:207], v[180:183], v[36:39]
	v_mfma_f32_16x16x32_bf16 v[32:35], v[216:219], v[180:183], v[32:35]
	v_mfma_f32_16x16x32_bf16 v[20:23], v[204:207], v[188:191], v[20:23]
	v_mfma_f32_16x16x32_bf16 v[16:19], v[216:219], v[188:191], v[16:19]
	v_mfma_f32_16x16x32_bf16 v[4:7], v[204:207], v[196:199], v[4:7]
	v_mfma_f32_16x16x32_bf16 v[0:3], v[216:219], v[196:199], v[0:3]
	v_mfma_f32_16x16x32_bf16 v[52:55], v[212:215], v[176:179], v[52:55]
	v_mfma_f32_16x16x32_bf16 v[48:51], v[220:223], v[176:179], v[48:51]
	v_mfma_f32_16x16x32_bf16 v[36:39], v[212:215], v[184:187], v[36:39]
	v_mfma_f32_16x16x32_bf16 v[32:35], v[220:223], v[184:187], v[32:35]
	v_mfma_f32_16x16x32_bf16 v[20:23], v[212:215], v[192:195], v[20:23]
	v_mfma_f32_16x16x32_bf16 v[16:19], v[220:223], v[192:195], v[16:19]
	v_mfma_f32_16x16x32_bf16 v[4:7], v[212:215], v[200:203], v[4:7]
	v_mfma_f32_16x16x32_bf16 v[0:3], v[220:223], v[200:203], v[0:3]
	s_setprio 0
	s_add_i32 s58, s58, 2
	s_add_u32 s2, s2, 0x100
	s_addc_u32 s3, s3, 0
	s_add_u32 s56, s56, 0x100
	s_addc_u32 s57, s57, 0
	s_cmp_gt_u32 s58, 13
	s_barrier
	s_cbranch_scc0 .LBB0_946
	v_lshl_add_u32 v144, s0, 8, v150
	v_ashrrev_i32_e32 v145, 31, v144
	v_lshl_add_u64 v[146:147], v[144:145], 2, s[18:19]
	global_load_dword v145, v[146:147], off
	global_load_dword v157, v[146:147], off offset:64
	global_load_dword v164, v[146:147], off offset:128
	global_load_dword v165, v[146:147], off offset:192
	global_load_dword v166, v[146:147], off offset:512
	global_load_dword v167, v[146:147], off offset:576
	global_load_dword v168, v[146:147], off offset:640
	global_load_dword v169, v[146:147], off offset:704
	v_mov_b64_e32 v[146:147], s[92:93]
	v_or_b32_e32 v160, 16, v144
	v_or_b32_e32 v162, 32, v144
	v_lshl_or_b32 v148, s1, 8, v152
	v_mad_i64_i32 v[158:159], s[0:1], v144, s52, v[146:147]
	v_mad_i64_i32 v[160:161], s[0:1], v160, s52, v[146:147]
	v_mad_i64_i32 v[162:163], s[0:1], v162, s52, v[146:147]
	v_ashrrev_i32_e32 v149, 31, v148
	v_lshlrev_b64 v[148:149], 1, v[148:149]
	v_lshl_add_u64 v[158:159], v[158:159], 0, v[148:149]
	v_lshl_add_u64 v[160:161], v[160:161], 0, v[148:149]
	v_lshl_add_u64 v[162:163], v[162:163], 0, v[148:149]
	v_add_u32_e32 v170, 0x80, v144
	s_mov_b64 s[28:29], s[26:27]
	s_waitcnt vmcnt(0)
	v_fmamk_f32 v145, v145, 0x3a800000, v156
	v_fmamk_f32 v157, v157, 0x3a800000, v156
	v_fmamk_f32 v164, v164, 0x3a800000, v156
	v_fmamk_f32 v171, v165, 0x3a800000, v156
	v_fmamk_f32 v172, v166, 0x3a800000, v156
	v_mul_f32_e32 v165, 0x4b800000, v145
	v_mul_f32_e32 v166, 0x4b800000, v157
	v_cmp_gt_f32_e32 vcc, s53, v145
	v_cmp_gt_f32_e64 s[0:1], s53, v157
	v_fmamk_f32 v173, v167, 0x3a800000, v156
	v_mul_f32_e32 v167, 0x4b800000, v164
	v_cndmask_b32_e32 v145, v145, v165, vcc
	v_cndmask_b32_e64 v157, v157, v166, s[0:1]
	v_cmp_gt_f32_e64 s[2:3], s53, v164
	v_rsq_f32_e32 v145, v145
	v_rsq_f32_e32 v157, v157
	v_cndmask_b32_e64 v164, v164, v167, s[2:3]
	v_rsq_f32_e32 v165, v164
	v_mul_f32_e32 v164, 0x45800000, v145
	v_mul_f32_e32 v166, 0x45800000, v157
	v_cndmask_b32_e32 v164, v145, v164, vcc
	v_mul_f32_e32 v167, 0x45800000, v165
	v_cndmask_b32_e64 v166, v157, v166, s[0:1]
	v_fmamk_f32 v175, v168, 0x3a800000, v156
	v_cndmask_b32_e64 v168, v165, v167, s[2:3]
	v_pk_mul_f32 v[126:127], v[126:127], v[164:165] op_sel_hi:[1,0]
	v_pk_mul_f32 v[124:125], v[124:125], v[164:165] op_sel_hi:[1,0]
	v_pk_mul_f32 v[122:123], v[122:123], v[164:165] op_sel_hi:[1,0]
	v_pk_mul_f32 v[120:121], v[120:121], v[164:165] op_sel_hi:[1,0]
	v_pk_mul_f32 v[110:111], v[110:111], v[164:165] op_sel_hi:[1,0]
	v_pk_mul_f32 v[108:109], v[108:109], v[164:165] op_sel_hi:[1,0]
	v_pk_mul_f32 v[102:103], v[102:103], v[164:165] op_sel_hi:[1,0]
	v_pk_mul_f32 v[100:101], v[100:101], v[164:165] op_sel_hi:[1,0]
	v_pk_mul_f32 v[118:119], v[118:119], v[166:167] op_sel_hi:[1,0]
	v_pk_mul_f32 v[116:117], v[116:117], v[166:167] op_sel_hi:[1,0]
	v_pk_mul_f32 v[114:115], v[114:115], v[166:167] op_sel_hi:[1,0]
	v_pk_mul_f32 v[112:113], v[112:113], v[166:167] op_sel_hi:[1,0]
	v_pk_mul_f32 v[94:95], v[94:95], v[166:167] op_sel_hi:[1,0]
	v_pk_mul_f32 v[92:93], v[92:93], v[166:167] op_sel_hi:[1,0]
	v_pk_mul_f32 v[164:165], v[90:91], v[166:167] op_sel_hi:[1,0]
	v_pk_mul_f32 v[166:167], v[88:89], v[166:167] op_sel_hi:[1,0]
	v_cvt_pk_bf16_f32 v88, v124, v125
	v_cvt_pk_bf16_f32 v89, v126, v127
	v_cvt_pk_bf16_f32 v90, v120, v121
	v_cvt_pk_bf16_f32 v91, v122, v123
	global_store_dwordx4 v[158:159], v[88:91], off nt
	v_fmamk_f32 v169, v169, 0x3a800000, v156
	v_pk_mul_f32 v[106:107], v[106:107], v[168:169] op_sel_hi:[1,0]
	v_cvt_pk_bf16_f32 v88, v108, v109
	v_cvt_pk_bf16_f32 v89, v110, v111
	v_cvt_pk_bf16_f32 v90, v100, v101
	v_cvt_pk_bf16_f32 v91, v102, v103
	global_store_dwordx4 v[158:159], v[88:91], off offset:256 nt
	v_pk_mul_f32 v[104:105], v[104:105], v[168:169] op_sel_hi:[1,0]
	v_pk_mul_f32 v[98:99], v[98:99], v[168:169] op_sel_hi:[1,0]
	v_cvt_pk_bf16_f32 v88, v116, v117
	v_cvt_pk_bf16_f32 v89, v118, v119
	v_cvt_pk_bf16_f32 v90, v112, v113
	v_cvt_pk_bf16_f32 v91, v114, v115
	global_store_dwordx4 v[160:161], v[88:91], off nt
	v_pk_mul_f32 v[96:97], v[96:97], v[168:169] op_sel_hi:[1,0]
	v_pk_mul_f32 v[86:87], v[86:87], v[168:169] op_sel_hi:[1,0]
	v_cvt_pk_bf16_f32 v88, v92, v93
	v_cvt_pk_bf16_f32 v89, v94, v95
	v_cvt_pk_bf16_f32 v90, v166, v167
	v_cvt_pk_bf16_f32 v91, v164, v165
	global_store_dwordx4 v[160:161], v[88:91], off offset:256 nt
	v_pk_mul_f32 v[84:85], v[84:85], v[168:169] op_sel_hi:[1,0]
	v_cmp_gt_f32_e32 vcc, s53, v171
	v_cvt_pk_bf16_f32 v88, v104, v105
	v_cvt_pk_bf16_f32 v89, v106, v107
	v_cvt_pk_bf16_f32 v90, v96, v97
	v_cvt_pk_bf16_f32 v91, v98, v99
	global_store_dwordx4 v[162:163], v[88:91], off nt
	s_mov_b64 s[2:3], s[24:25]
	s_nop 0
	v_pk_mul_f32 v[88:89], v[82:83], v[168:169] op_sel_hi:[1,0]
	v_pk_mul_f32 v[82:83], v[80:81], v[168:169] op_sel_hi:[1,0]
	v_cvt_pk_bf16_f32 v80, v84, v85
	v_cvt_pk_bf16_f32 v81, v86, v87
	s_nop 0
	v_cvt_pk_bf16_f32 v82, v82, v83
	v_cvt_pk_bf16_f32 v83, v88, v89
	global_store_dwordx4 v[162:163], v[80:83], off offset:256 nt
	s_nop 1
	v_mul_f32_e32 v81, 0x4b800000, v171
	v_cndmask_b32_e32 v81, v171, v81, vcc
	v_rsq_f32_e32 v82, v81
	v_or_b32_e32 v80, 48, v144
	v_mad_i64_i32 v[80:81], s[0:1], v80, s52, v[146:147]
	v_mul_f32_e32 v83, 0x45800000, v82
	v_cndmask_b32_e32 v82, v82, v83, vcc
	v_lshl_add_u64 v[80:81], v[80:81], 0, v[148:149]
	v_pk_mul_f32 v[78:79], v[78:79], v[82:83] op_sel_hi:[1,0]
	v_pk_mul_f32 v[76:77], v[76:77], v[82:83] op_sel_hi:[1,0]
	v_pk_mul_f32 v[84:85], v[74:75], v[82:83] op_sel_hi:[1,0]
	v_pk_mul_f32 v[74:75], v[72:73], v[82:83] op_sel_hi:[1,0]
	v_cvt_pk_bf16_f32 v72, v76, v77
	v_cvt_pk_bf16_f32 v73, v78, v79
	v_pk_mul_f32 v[68:69], v[68:69], v[82:83] op_sel_hi:[1,0]
	v_cvt_pk_bf16_f32 v74, v74, v75
	v_cvt_pk_bf16_f32 v75, v84, v85
	global_store_dwordx4 v[80:81], v[72:75], off nt
	v_pk_mul_f32 v[70:71], v[70:71], v[82:83] op_sel_hi:[1,0]
	v_cmp_gt_f32_e32 vcc, s53, v172
	v_pk_mul_f32 v[72:73], v[66:67], v[82:83] op_sel_hi:[1,0]
	v_pk_mul_f32 v[66:67], v[64:65], v[82:83] op_sel_hi:[1,0]
	v_cvt_pk_bf16_f32 v64, v68, v69
	v_cvt_pk_bf16_f32 v65, v70, v71
	s_nop 0
	v_cvt_pk_bf16_f32 v66, v66, v67
	v_cvt_pk_bf16_f32 v67, v72, v73
	global_store_dwordx4 v[80:81], v[64:67], off offset:256 nt
	s_nop 1
	v_mul_f32_e32 v64, 0x4b800000, v172
	v_cndmask_b32_e32 v64, v172, v64, vcc
	v_rsq_f32_e32 v66, v64
	v_mad_i64_i32 v[64:65], s[0:1], v170, s52, v[146:147]
	v_lshl_add_u64 v[64:65], v[64:65], 0, v[148:149]
	v_mul_f32_e32 v67, 0x45800000, v66
	v_cndmask_b32_e32 v66, v66, v67, vcc
	v_pk_mul_f32 v[62:63], v[62:63], v[66:67] op_sel_hi:[1,0]
	v_pk_mul_f32 v[60:61], v[60:61], v[66:67] op_sel_hi:[1,0]
	v_pk_mul_f32 v[68:69], v[58:59], v[66:67] op_sel_hi:[1,0]
	v_pk_mul_f32 v[58:59], v[56:57], v[66:67] op_sel_hi:[1,0]
	v_cvt_pk_bf16_f32 v56, v60, v61
	v_cvt_pk_bf16_f32 v57, v62, v63
	v_pk_mul_f32 v[54:55], v[54:55], v[66:67] op_sel_hi:[1,0]
	v_cvt_pk_bf16_f32 v58, v58, v59
	v_cvt_pk_bf16_f32 v59, v68, v69
	global_store_dwordx4 v[64:65], v[56:59], off nt
	v_pk_mul_f32 v[52:53], v[52:53], v[66:67] op_sel_hi:[1,0]
	v_cmp_gt_f32_e32 vcc, s53, v173
	v_pk_mul_f32 v[56:57], v[50:51], v[66:67] op_sel_hi:[1,0]
	v_pk_mul_f32 v[50:51], v[48:49], v[66:67] op_sel_hi:[1,0]
	v_cvt_pk_bf16_f32 v48, v52, v53
	v_cvt_pk_bf16_f32 v49, v54, v55
	s_nop 0
	v_cvt_pk_bf16_f32 v50, v50, v51
	v_cvt_pk_bf16_f32 v51, v56, v57
	global_store_dwordx4 v[64:65], v[48:51], off offset:256 nt
	s_nop 1
	v_mul_f32_e32 v49, 0x4b800000, v173
	v_cndmask_b32_e32 v49, v173, v49, vcc
	v_rsq_f32_e32 v50, v49
	v_add_u32_e32 v48, 0x90, v144
	v_mad_i64_i32 v[48:49], s[0:1], v48, s52, v[146:147]
	v_mul_f32_e32 v51, 0x45800000, v50
	v_cndmask_b32_e32 v50, v50, v51, vcc
	v_lshl_add_u64 v[48:49], v[48:49], 0, v[148:149]
	v_pk_mul_f32 v[46:47], v[46:47], v[50:51] op_sel_hi:[1,0]
	v_pk_mul_f32 v[44:45], v[44:45], v[50:51] op_sel_hi:[1,0]
	v_pk_mul_f32 v[52:53], v[42:43], v[50:51] op_sel_hi:[1,0]
	v_pk_mul_f32 v[42:43], v[40:41], v[50:51] op_sel_hi:[1,0]
	v_cvt_pk_bf16_f32 v40, v44, v45
	v_cvt_pk_bf16_f32 v41, v46, v47
	v_pk_mul_f32 v[38:39], v[38:39], v[50:51] op_sel_hi:[1,0]
	v_cvt_pk_bf16_f32 v42, v42, v43
	v_cvt_pk_bf16_f32 v43, v52, v53
	global_store_dwordx4 v[48:49], v[40:43], off nt
	v_pk_mul_f32 v[36:37], v[36:37], v[50:51] op_sel_hi:[1,0]
	v_cmp_gt_f32_e32 vcc, s53, v175
	v_pk_mul_f32 v[40:41], v[34:35], v[50:51] op_sel_hi:[1,0]
	v_pk_mul_f32 v[34:35], v[32:33], v[50:51] op_sel_hi:[1,0]
	v_cvt_pk_bf16_f32 v32, v36, v37
	v_cvt_pk_bf16_f32 v33, v38, v39
	s_nop 0
	v_cvt_pk_bf16_f32 v34, v34, v35
	v_cvt_pk_bf16_f32 v35, v40, v41
	global_store_dwordx4 v[48:49], v[32:35], off offset:256 nt
	s_nop 1
	v_mul_f32_e32 v33, 0x4b800000, v175
	v_cndmask_b32_e32 v33, v175, v33, vcc
	v_rsq_f32_e32 v34, v33
	v_add_u32_e32 v32, 0xa0, v144
	v_mad_i64_i32 v[32:33], s[0:1], v32, s52, v[146:147]
	v_mul_f32_e32 v35, 0x45800000, v34
	v_cndmask_b32_e32 v34, v34, v35, vcc
	v_lshl_add_u64 v[32:33], v[32:33], 0, v[148:149]
	v_pk_mul_f32 v[30:31], v[30:31], v[34:35] op_sel_hi:[1,0]
	v_pk_mul_f32 v[28:29], v[28:29], v[34:35] op_sel_hi:[1,0]
	v_pk_mul_f32 v[36:37], v[26:27], v[34:35] op_sel_hi:[1,0]
	v_pk_mul_f32 v[26:27], v[24:25], v[34:35] op_sel_hi:[1,0]
	v_cvt_pk_bf16_f32 v24, v28, v29
	v_cvt_pk_bf16_f32 v25, v30, v31
	v_pk_mul_f32 v[22:23], v[22:23], v[34:35] op_sel_hi:[1,0]
	v_cvt_pk_bf16_f32 v26, v26, v27
	v_cvt_pk_bf16_f32 v27, v36, v37
	global_store_dwordx4 v[32:33], v[24:27], off nt
	v_pk_mul_f32 v[20:21], v[20:21], v[34:35] op_sel_hi:[1,0]
	v_cmp_gt_f32_e32 vcc, s53, v169
	v_pk_mul_f32 v[24:25], v[18:19], v[34:35] op_sel_hi:[1,0]
	v_pk_mul_f32 v[18:19], v[16:17], v[34:35] op_sel_hi:[1,0]
	v_cvt_pk_bf16_f32 v16, v20, v21
	v_cvt_pk_bf16_f32 v17, v22, v23
	s_nop 0
	v_cvt_pk_bf16_f32 v18, v18, v19
	v_cvt_pk_bf16_f32 v19, v24, v25
	global_store_dwordx4 v[32:33], v[16:19], off offset:256 nt
	s_nop 1
	v_mul_f32_e32 v17, 0x4b800000, v169
	v_cndmask_b32_e32 v17, v169, v17, vcc
	v_rsq_f32_e32 v18, v17
	v_add_u32_e32 v16, 0xb0, v144
	v_mad_i64_i32 v[16:17], s[0:1], v16, s52, v[146:147]
	v_mul_f32_e32 v19, 0x45800000, v18
	v_cndmask_b32_e32 v18, v18, v19, vcc
	v_lshl_add_u64 v[16:17], v[16:17], 0, v[148:149]
	v_pk_mul_f32 v[14:15], v[14:15], v[18:19] op_sel_hi:[1,0]
	v_pk_mul_f32 v[12:13], v[12:13], v[18:19] op_sel_hi:[1,0]
	v_pk_mul_f32 v[20:21], v[10:11], v[18:19] op_sel_hi:[1,0]
	v_pk_mul_f32 v[10:11], v[8:9], v[18:19] op_sel_hi:[1,0]
	v_cvt_pk_bf16_f32 v8, v12, v13
	v_cvt_pk_bf16_f32 v9, v14, v15
	s_and_b64 vcc, exec, s[6:7]
	v_cvt_pk_bf16_f32 v10, v10, v11
	v_cvt_pk_bf16_f32 v11, v20, v21
	global_store_dwordx4 v[16:17], v[8:11], off nt
	s_mov_b32 s1, s20
	s_mov_b32 s0, s22
	v_pk_mul_f32 v[8:9], v[2:3], v[18:19] op_sel_hi:[1,0]
	v_pk_mul_f32 v[2:3], v[0:1], v[18:19] op_sel_hi:[1,0]
	v_pk_mul_f32 v[6:7], v[6:7], v[18:19] op_sel_hi:[1,0]
	v_pk_mul_f32 v[4:5], v[4:5], v[18:19] op_sel_hi:[1,0]
	s_nop 0
	v_cvt_pk_bf16_f32 v0, v4, v5
	v_cvt_pk_bf16_f32 v1, v6, v7
	v_cvt_pk_bf16_f32 v2, v2, v3
	v_cvt_pk_bf16_f32 v3, v8, v9
	global_store_dwordx4 v[16:17], v[0:3], off offset:256 nt
	s_cbranch_vccz .LBB0_943
	s_waitcnt vmcnt(0)
	s_cmpk_gt_u32 s33, 0xff
	s_cbranch_scc1 .LBB0_950
	s_barrier

.LBB0_1022:
	ds_read_b128 v[144:147], v178
	ds_read_b128 v[148:151], v178 offset:1024
	ds_read_b128 v[152:155], v178 offset:2048
	ds_read_b128 v[156:159], v178 offset:3072
	s_add_u32 s42, s40, 0xfffc0080
	s_addc_u32 s43, s41, -1
	s_cmp_eq_u32 s64, 12
	s_cselect_b32 s49, s29, s43
	s_cselect_b32 s48, s37, s42
	s_cselect_b32 s43, s27, s63
	s_cselect_b32 s42, s61, s62
	v_lshl_add_u64 v[172:173], s[40:41], 0, v[136:137]
	s_add_i32 m0, s39, 0xc000
	ds_read_b128 v[160:163], v179
	ds_read_b128 v[164:167], v179 offset:1024
	ds_read_b128 v[168:171], v179 offset:2048
	ds_read_b128 v[182:185], v179 offset:3072
	ds_read_b128 v[186:189], v179 offset:4096
	ds_read_b128 v[190:193], v179 offset:5120
	ds_read_b128 v[194:197], v179 offset:6144
	ds_read_b128 v[198:201], v179 offset:7168
	global_load_lds_dwordx4 v[172:173], off
	s_add_i32 m0, s39, 0xe000
	v_lshl_add_u64 v[172:173], s[40:41], 0, v[138:139]
	global_load_lds_dwordx4 v[172:173], off
	s_waitcnt lgkmcnt(8)
	s_setprio 1
	s_barrier
	s_waitcnt lgkmcnt(0)
	v_mfma_f32_16x16x32_bf16 v[124:127], v[144:147], v[160:163], v[124:127]
	v_mfma_f32_16x16x32_bf16 v[120:123], v[152:155], v[160:163], v[120:123]
	v_mfma_f32_16x16x32_bf16 v[108:111], v[144:147], v[168:171], v[108:111]
	v_mfma_f32_16x16x32_bf16 v[104:107], v[152:155], v[168:171], v[104:107]
	v_mfma_f32_16x16x32_bf16 v[96:99], v[144:147], v[186:189], v[96:99]
	v_mfma_f32_16x16x32_bf16 v[88:91], v[152:155], v[186:189], v[88:91]
	v_mfma_f32_16x16x32_bf16 v[80:83], v[144:147], v[194:197], v[80:83]
	v_mfma_f32_16x16x32_bf16 v[72:75], v[152:155], v[194:197], v[72:75]
	v_mfma_f32_16x16x32_bf16 v[124:127], v[148:151], v[164:167], v[124:127]
	v_mfma_f32_16x16x32_bf16 v[120:123], v[156:159], v[164:167], v[120:123]
	v_mfma_f32_16x16x32_bf16 v[108:111], v[148:151], v[182:185], v[108:111]
	v_mfma_f32_16x16x32_bf16 v[104:107], v[156:159], v[182:185], v[104:107]
	v_mfma_f32_16x16x32_bf16 v[96:99], v[148:151], v[190:193], v[96:99]
	v_mfma_f32_16x16x32_bf16 v[88:91], v[156:159], v[190:193], v[88:91]
	v_mfma_f32_16x16x32_bf16 v[80:83], v[148:151], v[198:201], v[80:83]
	v_mfma_f32_16x16x32_bf16 v[72:75], v[156:159], v[198:201], v[72:75]
	s_setprio 0
	s_barrier
	s_add_i32 s65, s59, s50
	v_lshl_add_u64 v[172:173], s[42:43], 0, v[130:131]
	s_mov_b32 m0, s65
	ds_read_b128 v[202:205], v180
	ds_read_b128 v[206:209], v180 offset:1024
	ds_read_b128 v[212:215], v180 offset:2048
	ds_read_b128 v[216:219], v180 offset:3072
	global_load_lds_dwordx4 v[172:173], off
	s_add_i32 m0, s65, 0x2000
	v_lshl_add_u64 v[220:221], s[42:43], 0, v[134:135]
	global_load_lds_dwordx4 v[220:221], off
	s_setprio 1
	s_barrier
	s_waitcnt lgkmcnt(0)
	v_mfma_f32_16x16x32_bf16 v[116:119], v[202:205], v[160:163], v[116:119]
	v_mfma_f32_16x16x32_bf16 v[112:115], v[212:215], v[160:163], v[112:115]
	v_mfma_f32_16x16x32_bf16 v[100:103], v[202:205], v[168:171], v[100:103]
	v_mfma_f32_16x16x32_bf16 v[92:95], v[212:215], v[168:171], v[92:95]
	v_mfma_f32_16x16x32_bf16 v[84:87], v[202:205], v[186:189], v[84:87]
	v_mfma_f32_16x16x32_bf16 v[76:79], v[212:215], v[186:189], v[76:79]
	v_mfma_f32_16x16x32_bf16 v[68:71], v[202:205], v[194:197], v[68:71]
	v_mfma_f32_16x16x32_bf16 v[64:67], v[212:215], v[194:197], v[64:67]
	v_mfma_f32_16x16x32_bf16 v[116:119], v[206:209], v[164:167], v[116:119]
	v_mfma_f32_16x16x32_bf16 v[112:115], v[216:219], v[164:167], v[112:115]
	v_mfma_f32_16x16x32_bf16 v[100:103], v[206:209], v[182:185], v[100:103]
	v_mfma_f32_16x16x32_bf16 v[92:95], v[216:219], v[182:185], v[92:95]
	v_mfma_f32_16x16x32_bf16 v[84:87], v[206:209], v[190:193], v[84:87]
	v_mfma_f32_16x16x32_bf16 v[76:79], v[216:219], v[190:193], v[76:79]
	v_mfma_f32_16x16x32_bf16 v[68:71], v[206:209], v[198:201], v[68:71]
	v_mfma_f32_16x16x32_bf16 v[64:67], v[216:219], v[198:201], v[64:67]
	s_setprio 0
	s_mov_b32 m0, s39
	v_lshl_add_u64 v[222:223], s[48:49], 0, v[128:129]
	s_barrier
	ds_read_b128 v[160:163], v179 offset:16384
	ds_read_b128 v[164:167], v179 offset:17408
	ds_read_b128 v[168:171], v179 offset:18432
	ds_read_b128 v[182:185], v179 offset:19456
	ds_read_b128 v[186:189], v179 offset:20480
	ds_read_b128 v[190:193], v179 offset:21504
	ds_read_b128 v[194:197], v179 offset:22528
	ds_read_b128 v[198:201], v179 offset:23552
	global_load_lds_dwordx4 v[222:223], off
	s_mov_b32 m0, s51
	v_lshl_add_u64 v[224:225], s[48:49], 0, v[132:133]
	global_load_lds_dwordx4 v[224:225], off
	s_setprio 1
	s_barrier
	s_waitcnt lgkmcnt(0)
	v_mfma_f32_16x16x32_bf16 v[60:63], v[144:147], v[160:163], v[60:63]
	v_mfma_f32_16x16x32_bf16 v[56:59], v[152:155], v[160:163], v[56:59]
	v_mfma_f32_16x16x32_bf16 v[44:47], v[144:147], v[168:171], v[44:47]
	v_mfma_f32_16x16x32_bf16 v[40:43], v[152:155], v[168:171], v[40:43]
	v_mfma_f32_16x16x32_bf16 v[32:35], v[144:147], v[186:189], v[32:35]
	v_mfma_f32_16x16x32_bf16 v[24:27], v[152:155], v[186:189], v[24:27]
	v_mfma_f32_16x16x32_bf16 v[16:19], v[144:147], v[194:197], v[16:19]
	v_mfma_f32_16x16x32_bf16 v[8:11], v[152:155], v[194:197], v[8:11]
	v_mfma_f32_16x16x32_bf16 v[60:63], v[148:151], v[164:167], v[60:63]
	v_mfma_f32_16x16x32_bf16 v[56:59], v[156:159], v[164:167], v[56:59]
	v_mfma_f32_16x16x32_bf16 v[44:47], v[148:151], v[182:185], v[44:47]
	v_mfma_f32_16x16x32_bf16 v[40:43], v[156:159], v[182:185], v[40:43]
	v_mfma_f32_16x16x32_bf16 v[32:35], v[148:151], v[190:193], v[32:35]
	v_mfma_f32_16x16x32_bf16 v[24:27], v[156:159], v[190:193], v[24:27]
	v_mfma_f32_16x16x32_bf16 v[16:19], v[148:151], v[198:201], v[16:19]
	v_mfma_f32_16x16x32_bf16 v[8:11], v[156:159], v[198:201], v[8:11]
	s_setprio 0
	s_barrier
	s_add_u32 s66, s42, 0x40000
	s_addc_u32 s67, s43, 0
	s_add_i32 s65, s60, s50
	s_mov_b32 m0, s65
	v_lshl_add_u64 v[144:145], s[66:67], 0, v[130:131]
	global_load_lds_dwordx4 v[144:145], off
	s_add_i32 m0, s65, 0x2000
	v_lshl_add_u64 v[144:145], s[66:67], 0, v[134:135]
	global_load_lds_dwordx4 v[144:145], off
	s_waitcnt vmcnt(6)
	s_setprio 1
	s_barrier
	v_mfma_f32_16x16x32_bf16 v[52:55], v[202:205], v[160:163], v[52:55]
	v_mfma_f32_16x16x32_bf16 v[48:51], v[212:215], v[160:163], v[48:51]
	v_mfma_f32_16x16x32_bf16 v[36:39], v[202:205], v[168:171], v[36:39]
	v_mfma_f32_16x16x32_bf16 v[28:31], v[212:215], v[168:171], v[28:31]
	v_mfma_f32_16x16x32_bf16 v[20:23], v[202:205], v[186:189], v[20:23]
	v_mfma_f32_16x16x32_bf16 v[12:15], v[212:215], v[186:189], v[12:15]
	v_mfma_f32_16x16x32_bf16 v[4:7], v[202:205], v[194:197], v[4:7]
	v_mfma_f32_16x16x32_bf16 v[0:3], v[212:215], v[194:197], v[0:3]
	v_mfma_f32_16x16x32_bf16 v[52:55], v[206:209], v[164:167], v[52:55]
	v_mfma_f32_16x16x32_bf16 v[48:51], v[216:219], v[164:167], v[48:51]
	v_mfma_f32_16x16x32_bf16 v[36:39], v[206:209], v[182:185], v[36:39]
	v_mfma_f32_16x16x32_bf16 v[28:31], v[216:219], v[182:185], v[28:31]
	v_mfma_f32_16x16x32_bf16 v[20:23], v[206:209], v[190:193], v[20:23]
	v_mfma_f32_16x16x32_bf16 v[12:15], v[216:219], v[190:193], v[12:15]
	v_mfma_f32_16x16x32_bf16 v[4:7], v[206:209], v[198:201], v[4:7]
	v_mfma_f32_16x16x32_bf16 v[0:3], v[216:219], v[198:201], v[0:3]
	s_setprio 0
	s_add_i32 s65, 0, 0x18000
	v_add_u32_e32 v156, s65, v176
	s_barrier
	ds_read_b128 v[144:147], v156
	ds_read_b128 v[148:151], v156 offset:1024
	ds_read_b128 v[152:155], v156 offset:2048
	ds_read_b128 v[156:159], v156 offset:3072
	s_add_u32 s48, s48, 0x40000
	s_addc_u32 s49, s49, 0
	s_mov_b32 m0, s52
	v_lshl_add_u64 v[202:203], s[48:49], 0, v[128:129]
	ds_read_b128 v[160:163], v179 offset:32768
	ds_read_b128 v[164:167], v179 offset:33792
	ds_read_b128 v[168:171], v179 offset:34816
	ds_read_b128 v[182:185], v179 offset:35840
	ds_read_b128 v[186:189], v179 offset:36864
	ds_read_b128 v[190:193], v179 offset:37888
	ds_read_b128 v[194:197], v179 offset:38912
	ds_read_b128 v[198:201], v179 offset:39936
	global_load_lds_dwordx4 v[202:203], off
	s_mov_b32 m0, s53
	v_lshl_add_u64 v[202:203], s[48:49], 0, v[132:133]
	global_load_lds_dwordx4 v[202:203], off
	s_waitcnt lgkmcnt(8)
	s_setprio 1
	s_barrier
	s_waitcnt lgkmcnt(0)
	v_mfma_f32_16x16x32_bf16 v[124:127], v[144:147], v[160:163], v[124:127]
	v_mfma_f32_16x16x32_bf16 v[120:123], v[152:155], v[160:163], v[120:123]
	v_mfma_f32_16x16x32_bf16 v[108:111], v[144:147], v[168:171], v[108:111]
	v_mfma_f32_16x16x32_bf16 v[104:107], v[152:155], v[168:171], v[104:107]
	v_mfma_f32_16x16x32_bf16 v[96:99], v[144:147], v[186:189], v[96:99]
	v_mfma_f32_16x16x32_bf16 v[88:91], v[152:155], v[186:189], v[88:91]
	v_mfma_f32_16x16x32_bf16 v[80:83], v[144:147], v[194:197], v[80:83]
	v_mfma_f32_16x16x32_bf16 v[72:75], v[152:155], v[194:197], v[72:75]
	v_mfma_f32_16x16x32_bf16 v[124:127], v[148:151], v[164:167], v[124:127]
	v_mfma_f32_16x16x32_bf16 v[120:123], v[156:159], v[164:167], v[120:123]
	v_mfma_f32_16x16x32_bf16 v[108:111], v[148:151], v[182:185], v[108:111]
	v_mfma_f32_16x16x32_bf16 v[104:107], v[156:159], v[182:185], v[104:107]
	v_mfma_f32_16x16x32_bf16 v[96:99], v[148:151], v[190:193], v[96:99]
	v_mfma_f32_16x16x32_bf16 v[88:91], v[156:159], v[190:193], v[88:91]
	v_mfma_f32_16x16x32_bf16 v[80:83], v[148:151], v[198:201], v[80:83]
	v_mfma_f32_16x16x32_bf16 v[72:75], v[156:159], v[198:201], v[72:75]
	s_setprio 0
	s_barrier
	s_add_i32 s48, 0, 0x1c000
	s_add_i32 s49, s65, s50
	v_add_u32_e32 v181, s48, v176
	v_lshl_add_u64 v[172:173], v[172:173], 0, s[2:3]
	s_mov_b32 m0, s49
	ds_read_b128 v[202:205], v181
	ds_read_b128 v[206:209], v181 offset:1024
	ds_read_b128 v[212:215], v181 offset:2048
	ds_read_b128 v[216:219], v181 offset:3072
	global_load_lds_dwordx4 v[172:173], off
	s_add_i32 m0, s49, 0x2000
	v_lshl_add_u64 v[172:173], v[220:221], 0, s[2:3]
	global_load_lds_dwordx4 v[172:173], off
	s_setprio 1
	s_barrier
	s_waitcnt lgkmcnt(0)
	v_mfma_f32_16x16x32_bf16 v[116:119], v[202:205], v[160:163], v[116:119]
	v_mfma_f32_16x16x32_bf16 v[112:115], v[212:215], v[160:163], v[112:115]
	v_mfma_f32_16x16x32_bf16 v[100:103], v[202:205], v[168:171], v[100:103]
	v_mfma_f32_16x16x32_bf16 v[92:95], v[212:215], v[168:171], v[92:95]
	v_mfma_f32_16x16x32_bf16 v[84:87], v[202:205], v[186:189], v[84:87]
	v_mfma_f32_16x16x32_bf16 v[76:79], v[212:215], v[186:189], v[76:79]
	v_mfma_f32_16x16x32_bf16 v[68:71], v[202:205], v[194:197], v[68:71]
	v_mfma_f32_16x16x32_bf16 v[64:67], v[212:215], v[194:197], v[64:67]
	v_mfma_f32_16x16x32_bf16 v[116:119], v[206:209], v[164:167], v[116:119]
	v_mfma_f32_16x16x32_bf16 v[112:115], v[216:219], v[164:167], v[112:115]
	v_mfma_f32_16x16x32_bf16 v[100:103], v[206:209], v[182:185], v[100:103]
	v_mfma_f32_16x16x32_bf16 v[92:95], v[216:219], v[182:185], v[92:95]
	v_mfma_f32_16x16x32_bf16 v[84:87], v[206:209], v[190:193], v[84:87]
	v_mfma_f32_16x16x32_bf16 v[76:79], v[216:219], v[190:193], v[76:79]
	v_mfma_f32_16x16x32_bf16 v[68:71], v[206:209], v[198:201], v[68:71]
	v_mfma_f32_16x16x32_bf16 v[64:67], v[216:219], v[198:201], v[64:67]
	s_setprio 0
	s_mov_b32 m0, s55
	v_lshl_add_u64 v[172:173], v[222:223], 0, s[2:3]
	s_barrier
	ds_read_b128 v[160:163], v179 offset:49152
	ds_read_b128 v[164:167], v179 offset:50176
	ds_read_b128 v[168:171], v179 offset:51200
	ds_read_b128 v[182:185], v179 offset:52224
	ds_read_b128 v[186:189], v179 offset:53248
	ds_read_b128 v[190:193], v179 offset:54272
	ds_read_b128 v[194:197], v179 offset:55296
	ds_read_b128 v[198:201], v179 offset:56320
	global_load_lds_dwordx4 v[172:173], off
	s_mov_b32 m0, s56
	v_lshl_add_u64 v[172:173], v[224:225], 0, s[2:3]
	global_load_lds_dwordx4 v[172:173], off
	s_setprio 1
	s_barrier
	s_waitcnt lgkmcnt(0)
	v_mfma_f32_16x16x32_bf16 v[60:63], v[144:147], v[160:163], v[60:63]
	v_mfma_f32_16x16x32_bf16 v[56:59], v[152:155], v[160:163], v[56:59]
	v_mfma_f32_16x16x32_bf16 v[44:47], v[144:147], v[168:171], v[44:47]
	v_mfma_f32_16x16x32_bf16 v[40:43], v[152:155], v[168:171], v[40:43]
	v_mfma_f32_16x16x32_bf16 v[32:35], v[144:147], v[186:189], v[32:35]
	v_mfma_f32_16x16x32_bf16 v[24:27], v[152:155], v[186:189], v[24:27]
	v_mfma_f32_16x16x32_bf16 v[16:19], v[144:147], v[194:197], v[16:19]
	v_mfma_f32_16x16x32_bf16 v[8:11], v[152:155], v[194:197], v[8:11]
	v_mfma_f32_16x16x32_bf16 v[60:63], v[148:151], v[164:167], v[60:63]
	v_mfma_f32_16x16x32_bf16 v[56:59], v[156:159], v[164:167], v[56:59]
	v_mfma_f32_16x16x32_bf16 v[44:47], v[148:151], v[182:185], v[44:47]
	v_mfma_f32_16x16x32_bf16 v[40:43], v[156:159], v[182:185], v[40:43]
	v_mfma_f32_16x16x32_bf16 v[32:35], v[148:151], v[190:193], v[32:35]
	v_mfma_f32_16x16x32_bf16 v[24:27], v[156:159], v[190:193], v[24:27]
	v_mfma_f32_16x16x32_bf16 v[16:19], v[148:151], v[198:201], v[16:19]
	v_mfma_f32_16x16x32_bf16 v[8:11], v[156:159], v[198:201], v[8:11]
	s_setprio 0
	s_barrier
	s_add_u32 s42, s42, 0x40080
	s_addc_u32 s43, s43, 0
	s_add_i32 s48, s48, s50
	s_mov_b32 m0, s48
	v_lshl_add_u64 v[144:145], s[42:43], 0, v[130:131]
	global_load_lds_dwordx4 v[144:145], off
	s_add_i32 m0, s48, 0x2000
	v_lshl_add_u64 v[144:145], s[42:43], 0, v[134:135]
	global_load_lds_dwordx4 v[144:145], off
	s_waitcnt vmcnt(6)
	s_setprio 1
	s_barrier
	v_mfma_f32_16x16x32_bf16 v[52:55], v[202:205], v[160:163], v[52:55]
	v_mfma_f32_16x16x32_bf16 v[48:51], v[212:215], v[160:163], v[48:51]
	v_mfma_f32_16x16x32_bf16 v[36:39], v[202:205], v[168:171], v[36:39]
	v_mfma_f32_16x16x32_bf16 v[28:31], v[212:215], v[168:171], v[28:31]
	v_mfma_f32_16x16x32_bf16 v[20:23], v[202:205], v[186:189], v[20:23]
	v_mfma_f32_16x16x32_bf16 v[12:15], v[212:215], v[186:189], v[12:15]
	v_mfma_f32_16x16x32_bf16 v[4:7], v[202:205], v[194:197], v[4:7]
	v_mfma_f32_16x16x32_bf16 v[0:3], v[212:215], v[194:197], v[0:3]
	v_mfma_f32_16x16x32_bf16 v[52:55], v[206:209], v[164:167], v[52:55]
	v_mfma_f32_16x16x32_bf16 v[48:51], v[216:219], v[164:167], v[48:51]
	v_mfma_f32_16x16x32_bf16 v[36:39], v[206:209], v[182:185], v[36:39]
	v_mfma_f32_16x16x32_bf16 v[28:31], v[216:219], v[182:185], v[28:31]
	v_mfma_f32_16x16x32_bf16 v[20:23], v[206:209], v[190:193], v[20:23]
	v_mfma_f32_16x16x32_bf16 v[12:15], v[216:219], v[190:193], v[12:15]
	v_mfma_f32_16x16x32_bf16 v[4:7], v[206:209], v[198:201], v[4:7]
	v_mfma_f32_16x16x32_bf16 v[0:3], v[216:219], v[198:201], v[0:3]
	s_setprio 0
	s_add_i32 s64, s64, 2
	s_add_u32 s40, s40, 0x100
	s_addc_u32 s41, s41, 0
	s_add_u32 s62, s62, 0x100
	s_addc_u32 s63, s63, 0
	s_cmp_gt_u32 s64, 13
	s_barrier
	s_cbranch_scc0 .LBB0_1022
	v_lshl_or_b32 v144, s38, 8, v177
	v_lshl_add_u32 v150, s36, 8, v175
	v_ashrrev_i32_e32 v145, 31, v144
	v_ashrrev_i32_e32 v151, 31, v150
	v_lshlrev_b64 v[144:145], 1, v[144:145]
	v_lshl_add_u64 v[146:147], s[10:11], 0, v[144:145]
	v_lshlrev_b64 v[148:149], 11, v[150:151]
	v_lshl_add_u64 v[152:153], v[146:147], 0, v[148:149]
	global_load_dwordx4 v[156:159], v[152:153], off
	global_load_dwordx4 v[160:163], v[152:153], off offset:256
	v_or_b32_e32 v152, 16, v150
	v_ashrrev_i32_e32 v153, 31, v152
	v_lshlrev_b64 v[170:171], 11, v[152:153]
	v_lshl_add_u64 v[152:153], v[146:147], 0, v[170:171]
	global_load_dwordx4 v[164:167], v[152:153], off
	global_load_dwordx4 v[182:185], v[152:153], off offset:256
	v_or_b32_e32 v152, 32, v150
	v_ashrrev_i32_e32 v153, 31, v152
	v_lshlrev_b64 v[154:155], 11, v[152:153]
	v_lshl_add_u64 v[152:153], v[146:147], 0, v[154:155]
	global_load_dwordx4 v[186:189], v[152:153], off
	global_load_dwordx4 v[190:193], v[152:153], off offset:256
	v_or_b32_e32 v152, 48, v150
	v_ashrrev_i32_e32 v153, 31, v152
	v_lshlrev_b64 v[152:153], 11, v[152:153]
	v_lshl_add_u64 v[168:169], v[146:147], 0, v[152:153]
	global_load_dwordx4 v[194:197], v[168:169], off
	global_load_dwordx4 v[198:201], v[168:169], off offset:256
	s_waitcnt vmcnt(0)
	v_lshlrev_b32_e32 v202, 16, v156
	v_and_b32_e32 v203, 0xffff0000, v156
	v_lshlrev_b32_e32 v204, 16, v157
	v_and_b32_e32 v205, 0xffff0000, v157
	v_lshlrev_b32_e32 v206, 16, v158
	v_and_b32_e32 v207, 0xffff0000, v158
	v_lshlrev_b32_e32 v208, 16, v159
	v_and_b32_e32 v209, 0xffff0000, v159
	v_pk_add_f32 v[126:127], v[126:127], v[204:205]
	v_pk_add_f32 v[124:125], v[124:125], v[202:203]
	v_lshlrev_b32_e32 v224, 16, v166
	v_and_b32_e32 v225, 0xffff0000, v166
	v_lshlrev_b32_e32 v226, 16, v167
	v_and_b32_e32 v227, 0xffff0000, v167
	v_lshlrev_b32_e32 v212, 16, v160
	v_lshlrev_b32_e32 v166, 16, v194
	v_and_b32_e32 v167, 0xffff0000, v194
	v_lshlrev_b32_e32 v172, 16, v195
	v_and_b32_e32 v173, 0xffff0000, v195
	v_pk_add_f32 v[194:195], v[122:123], v[208:209]
	v_pk_add_f32 v[122:123], v[120:121], v[206:207]
	v_mul_f32_e32 v120, v125, v125
	v_mul_f32_e32 v121, v127, v127
	v_fmac_f32_e32 v120, v124, v124
	v_fmac_f32_e32 v121, v126, v126
	v_add_f32_e32 v120, v120, v121
	v_mul_f32_e32 v121, v123, v123
	v_fmac_f32_e32 v121, v122, v122
	v_add_f32_e32 v120, v121, v120
	v_mul_f32_e32 v121, v195, v195
	v_fmac_f32_e32 v121, v194, v194
	v_and_b32_e32 v213, 0xffff0000, v160
	v_lshlrev_b32_e32 v214, 16, v161
	v_and_b32_e32 v215, 0xffff0000, v161
	v_add_f32_e32 v181, v121, v120
	v_cvt_pk_bf16_f32 v120, v124, v125
	v_lshl_add_u64 v[124:125], s[10:11], 0, v[148:149]
	v_lshlrev_b32_e32 v216, 16, v162
	v_and_b32_e32 v217, 0xffff0000, v162
	v_lshlrev_b32_e32 v218, 16, v163
	v_and_b32_e32 v219, 0xffff0000, v163
	v_cvt_pk_bf16_f32 v121, v126, v127
	v_lshl_add_u64 v[124:125], v[124:125], 0, v[144:145]
	v_pk_add_f32 v[118:119], v[118:119], v[214:215]
	v_pk_add_f32 v[116:117], v[116:117], v[212:213]
	v_cvt_pk_bf16_f32 v122, v122, v123
	v_cvt_pk_bf16_f32 v123, v194, v195
	global_store_dwordx4 v[124:125], v[120:123], off
	v_lshlrev_b32_e32 v220, 16, v164
	v_and_b32_e32 v221, 0xffff0000, v164
	v_pk_add_f32 v[120:121], v[114:115], v[218:219]
	v_pk_add_f32 v[114:115], v[112:113], v[216:217]
	v_mul_f32_e32 v112, v117, v117
	v_mul_f32_e32 v113, v119, v119
	v_fmac_f32_e32 v112, v116, v116
	v_fmac_f32_e32 v113, v118, v118
	v_add_f32_e32 v112, v112, v113
	v_mul_f32_e32 v113, v115, v115
	v_fmac_f32_e32 v113, v114, v114
	v_add_f32_e32 v112, v113, v112
	v_mul_f32_e32 v113, v121, v121
	v_fmac_f32_e32 v113, v120, v120
	v_add_f32_e32 v112, v113, v112
	v_lshlrev_b32_e32 v222, 16, v165
	v_and_b32_e32 v223, 0xffff0000, v165
	v_add_f32_e32 v126, v181, v112
	v_cvt_pk_bf16_f32 v112, v116, v117
	v_cvt_pk_bf16_f32 v113, v118, v119
	v_lshl_add_u64 v[116:117], s[10:11], 0, v[170:171]
	v_lshlrev_b32_e32 v230, 16, v184
	v_and_b32_e32 v231, 0xffff0000, v184
	v_lshlrev_b32_e32 v232, 16, v186
	v_and_b32_e32 v233, 0xffff0000, v186
	v_lshlrev_b32_e32 v186, 16, v187
	v_and_b32_e32 v187, 0xffff0000, v187
	v_cvt_pk_bf16_f32 v114, v114, v115
	v_cvt_pk_bf16_f32 v115, v120, v121
	global_store_dwordx4 v[124:125], v[112:115], off offset:256
	v_pk_add_f32 v[110:111], v[110:111], v[222:223]
	v_pk_add_f32 v[108:109], v[108:109], v[220:221]
	v_lshl_add_u64 v[118:119], v[116:117], 0, v[144:145]
	v_cvt_pk_bf16_f32 v112, v108, v109
	v_cvt_pk_bf16_f32 v113, v110, v111
	v_lshlrev_b32_e32 v228, 16, v182
	v_and_b32_e32 v229, 0xffff0000, v182
	v_lshlrev_b32_e32 v182, 16, v183
	v_and_b32_e32 v183, 0xffff0000, v183
	v_lshlrev_b32_e32 v184, 16, v185
	v_and_b32_e32 v185, 0xffff0000, v185
	v_lshlrev_b32_e32 v238, 16, v192
	v_and_b32_e32 v239, 0xffff0000, v192
	v_pk_add_f32 v[106:107], v[106:107], v[226:227]
	v_pk_add_f32 v[104:105], v[104:105], v[224:225]
	v_lshlrev_b32_e32 v156, 16, v200
	v_cvt_pk_bf16_f32 v114, v104, v105
	v_cvt_pk_bf16_f32 v115, v106, v107
	global_store_dwordx4 v[118:119], v[112:115], off
	v_and_b32_e32 v157, 0xffff0000, v200
	v_pk_add_f32 v[102:103], v[102:103], v[182:183]
	v_pk_add_f32 v[112:113], v[92:93], v[230:231]
	v_pk_add_f32 v[92:93], v[98:99], v[186:187]
	v_lshl_add_u64 v[98:99], s[10:11], 0, v[154:155]
	v_pk_add_f32 v[100:101], v[100:101], v[228:229]
	v_pk_add_f32 v[94:95], v[94:95], v[184:185]
	v_cvt_pk_bf16_f32 v114, v100, v101
	v_cvt_pk_bf16_f32 v115, v102, v103
	v_cvt_pk_bf16_f32 v116, v112, v113
	v_lshlrev_b32_e32 v234, 16, v188
	v_cvt_pk_bf16_f32 v117, v94, v95
	global_store_dwordx4 v[118:119], v[114:117], off offset:256
	v_lshl_add_u64 v[118:119], v[98:99], 0, v[144:145]
	v_pk_add_f32 v[98:99], v[76:77], v[238:239]
	v_pk_add_f32 v[76:77], v[82:83], v[172:173]
	v_lshl_add_u64 v[82:83], s[10:11], 0, v[152:153]
	v_lshl_add_u64 v[122:123], v[82:83], 0, v[144:145]
	v_pk_add_f32 v[82:83], v[64:65], v[156:157]
	v_and_b32_e32 v65, 64, v174
	v_and_b32_e32 v235, 0xffff0000, v188
	v_lshlrev_b32_e32 v188, 16, v189
	v_and_b32_e32 v189, 0xffff0000, v189
	v_lshlrev_b32_e32 v236, 16, v190
	v_and_b32_e32 v237, 0xffff0000, v190
	v_pk_add_f32 v[96:97], v[96:97], v[232:233]
	v_xor_b32_e32 v64, 16, v174
	v_cvt_pk_bf16_f32 v114, v96, v97
	v_add_u32_e32 v65, 64, v65
	v_lshlrev_b32_e32 v190, 16, v191
	v_and_b32_e32 v191, 0xffff0000, v191
	v_lshlrev_b32_e32 v192, 16, v193
	v_and_b32_e32 v193, 0xffff0000, v193
	v_pk_add_f32 v[90:91], v[90:91], v[188:189]
	v_pk_add_f32 v[88:89], v[88:89], v[234:235]
	v_cvt_pk_bf16_f32 v115, v92, v93
	v_pk_add_f32 v[84:85], v[84:85], v[236:237]
	v_cvt_pk_bf16_f32 v116, v88, v89
	v_cvt_pk_bf16_f32 v117, v90, v91
	global_store_dwordx4 v[118:119], v[114:117], off
	v_cmp_lt_i32_e32 vcc, v64, v65
	v_lshlrev_b32_e32 v164, 16, v196
	v_cvt_pk_bf16_f32 v114, v84, v85
	v_and_b32_e32 v165, 0xffff0000, v196
	v_lshlrev_b32_e32 v168, 16, v197
	v_and_b32_e32 v169, 0xffff0000, v197
	v_pk_add_f32 v[86:87], v[86:87], v[190:191]
	v_pk_add_f32 v[78:79], v[78:79], v[192:193]
	v_cvt_pk_bf16_f32 v115, v86, v87
	v_cvt_pk_bf16_f32 v116, v98, v99
	v_pk_add_f32 v[80:81], v[80:81], v[166:167]
	v_cvt_pk_bf16_f32 v117, v78, v79
	global_store_dwordx4 v[118:119], v[114:117], off offset:256
	v_cndmask_b32_e32 v64, v174, v64, vcc
	v_pk_add_f32 v[74:75], v[74:75], v[168:169]
	v_cvt_pk_bf16_f32 v114, v80, v81
	v_pk_add_f32 v[72:73], v[72:73], v[164:165]
	v_cvt_pk_bf16_f32 v115, v76, v77
	v_lshlrev_b32_e32 v158, 16, v198
	v_cvt_pk_bf16_f32 v116, v72, v73
	v_cvt_pk_bf16_f32 v117, v74, v75
	global_store_dwordx4 v[122:123], v[114:117], off
	v_and_b32_e32 v159, 0xffff0000, v198
	v_lshlrev_b32_e32 v162, 16, v199
	v_lshlrev_b32_e32 v114, 2, v64
	ds_bpermute_b32 v64, v114, v126
	v_xor_b32_e32 v115, 32, v174
	v_cmp_lt_i32_e32 vcc, v115, v65
	v_and_b32_e32 v163, 0xffff0000, v199
	v_lshlrev_b32_e32 v160, 16, v201
	v_cndmask_b32_e32 v65, v174, v115, vcc
	v_lshlrev_b32_e32 v115, 2, v65
	s_waitcnt lgkmcnt(0)
	v_add_f32_e32 v116, v126, v64
	ds_bpermute_b32 v117, v115, v116
	v_and_b32_e32 v161, 0xffff0000, v201
	v_pk_add_f32 v[70:71], v[70:71], v[162:163]
	v_pk_add_f32 v[68:69], v[68:69], v[158:159]
	v_pk_add_f32 v[66:67], v[66:67], v[160:161]
	v_lshl_add_u64 v[64:65], v[150:151], 2, s[18:19]
	v_cvt_pk_bf16_f32 v118, v68, v69
	v_cvt_pk_bf16_f32 v119, v70, v71
	v_cvt_pk_bf16_f32 v120, v82, v83
	v_cvt_pk_bf16_f32 v121, v66, v67
	global_store_dwordx4 v[122:123], v[118:121], off offset:256
	s_and_saveexec_b64 s[36:37], s[6:7]
	s_cbranch_execz .LBB0_1025
	s_waitcnt lgkmcnt(0)
	v_add_f32_e32 v116, v116, v117
	global_atomic_add_f32 v[64:65], v116, off

.LBB0_1080:
	ds_read_b128 v[144:147], v151
	ds_read_b128 v[156:159], v151 offset:1024
	ds_read_b128 v[160:163], v151 offset:2048
	ds_read_b128 v[164:167], v151 offset:3072
	s_add_u32 s36, s2, 0xfffc0080
	s_addc_u32 s37, s3, -1
	s_cmp_eq_u32 s67, 12
	s_cselect_b32 s39, s29, s37
	s_cselect_b32 s38, s63, s36
	s_cselect_b32 s37, s27, s66
	s_cselect_b32 s36, s64, s65
	v_lshl_add_u64 v[172:173], s[2:3], 0, v[136:137]
	s_add_i32 m0, s48, 0xc000
	ds_read_b128 v[168:171], v152
	ds_read_b128 v[176:179], v152 offset:1024
	ds_read_b128 v[180:183], v152 offset:2048
	ds_read_b128 v[184:187], v152 offset:3072
	ds_read_b128 v[188:191], v152 offset:4096
	ds_read_b128 v[192:195], v152 offset:5120
	ds_read_b128 v[196:199], v152 offset:6144
	ds_read_b128 v[200:203], v152 offset:7168
	global_load_lds_dwordx4 v[172:173], off
	s_add_i32 m0, s48, 0xe000
	v_lshl_add_u64 v[172:173], s[2:3], 0, v[138:139]
	global_load_lds_dwordx4 v[172:173], off
	s_waitcnt lgkmcnt(8)
	s_setprio 1
	s_barrier
	s_waitcnt lgkmcnt(0)
	v_mfma_f32_16x16x32_bf16 v[124:127], v[144:147], v[168:171], v[124:127]
	v_mfma_f32_16x16x32_bf16 v[120:123], v[160:163], v[168:171], v[120:123]
	v_mfma_f32_16x16x32_bf16 v[116:119], v[144:147], v[180:183], v[116:119]
	v_mfma_f32_16x16x32_bf16 v[112:115], v[160:163], v[180:183], v[112:115]
	v_mfma_f32_16x16x32_bf16 v[104:107], v[144:147], v[188:191], v[104:107]
	v_mfma_f32_16x16x32_bf16 v[96:99], v[160:163], v[188:191], v[96:99]
	v_mfma_f32_16x16x32_bf16 v[76:79], v[144:147], v[196:199], v[76:79]
	v_mfma_f32_16x16x32_bf16 v[72:75], v[160:163], v[196:199], v[72:75]
	v_mfma_f32_16x16x32_bf16 v[124:127], v[156:159], v[176:179], v[124:127]
	v_mfma_f32_16x16x32_bf16 v[120:123], v[164:167], v[176:179], v[120:123]
	v_mfma_f32_16x16x32_bf16 v[116:119], v[156:159], v[184:187], v[116:119]
	v_mfma_f32_16x16x32_bf16 v[112:115], v[164:167], v[184:187], v[112:115]
	v_mfma_f32_16x16x32_bf16 v[104:107], v[156:159], v[192:195], v[104:107]
	v_mfma_f32_16x16x32_bf16 v[96:99], v[164:167], v[192:195], v[96:99]
	v_mfma_f32_16x16x32_bf16 v[76:79], v[156:159], v[200:203], v[76:79]
	v_mfma_f32_16x16x32_bf16 v[72:75], v[164:167], v[200:203], v[72:75]
	s_setprio 0
	s_barrier
	s_add_i32 s68, s56, s43
	v_lshl_add_u64 v[172:173], s[36:37], 0, v[130:131]
	s_mov_b32 m0, s68
	ds_read_b128 v[204:207], v153
	ds_read_b128 v[212:215], v153 offset:1024
	ds_read_b128 v[216:219], v153 offset:2048
	ds_read_b128 v[220:223], v153 offset:3072
	global_load_lds_dwordx4 v[172:173], off
	s_add_i32 m0, s68, 0x2000
	v_lshl_add_u64 v[208:209], s[36:37], 0, v[134:135]
	global_load_lds_dwordx4 v[208:209], off
	s_setprio 1
	s_barrier
	s_waitcnt lgkmcnt(0)
	v_mfma_f32_16x16x32_bf16 v[108:111], v[204:207], v[168:171], v[108:111]
	v_mfma_f32_16x16x32_bf16 v[100:103], v[216:219], v[168:171], v[100:103]
	v_mfma_f32_16x16x32_bf16 v[92:95], v[204:207], v[180:183], v[92:95]
	v_mfma_f32_16x16x32_bf16 v[88:91], v[216:219], v[180:183], v[88:91]
	v_mfma_f32_16x16x32_bf16 v[84:87], v[204:207], v[188:191], v[84:87]
	v_mfma_f32_16x16x32_bf16 v[80:83], v[216:219], v[188:191], v[80:83]
	v_mfma_f32_16x16x32_bf16 v[68:71], v[204:207], v[196:199], v[68:71]
	v_mfma_f32_16x16x32_bf16 v[64:67], v[216:219], v[196:199], v[64:67]
	v_mfma_f32_16x16x32_bf16 v[108:111], v[212:215], v[176:179], v[108:111]
	v_mfma_f32_16x16x32_bf16 v[100:103], v[220:223], v[176:179], v[100:103]
	v_mfma_f32_16x16x32_bf16 v[92:95], v[212:215], v[184:187], v[92:95]
	v_mfma_f32_16x16x32_bf16 v[88:91], v[220:223], v[184:187], v[88:91]
	v_mfma_f32_16x16x32_bf16 v[84:87], v[212:215], v[192:195], v[84:87]
	v_mfma_f32_16x16x32_bf16 v[80:83], v[220:223], v[192:195], v[80:83]
	v_mfma_f32_16x16x32_bf16 v[68:71], v[212:215], v[200:203], v[68:71]
	v_mfma_f32_16x16x32_bf16 v[64:67], v[220:223], v[200:203], v[64:67]
	s_setprio 0
	s_mov_b32 m0, s48
	v_lshl_add_u64 v[224:225], s[38:39], 0, v[128:129]
	s_barrier
	ds_read_b128 v[168:171], v152 offset:16384
	ds_read_b128 v[176:179], v152 offset:17408
	ds_read_b128 v[180:183], v152 offset:18432
	ds_read_b128 v[184:187], v152 offset:19456
	ds_read_b128 v[188:191], v152 offset:20480
	ds_read_b128 v[192:195], v152 offset:21504
	ds_read_b128 v[196:199], v152 offset:22528
	ds_read_b128 v[200:203], v152 offset:23552
	global_load_lds_dwordx4 v[224:225], off
	s_mov_b32 m0, s49
	v_lshl_add_u64 v[226:227], s[38:39], 0, v[132:133]
	global_load_lds_dwordx4 v[226:227], off
	s_setprio 1
	s_barrier
	s_waitcnt lgkmcnt(0)
	v_mfma_f32_16x16x32_bf16 v[60:63], v[144:147], v[168:171], v[60:63]
	v_mfma_f32_16x16x32_bf16 v[56:59], v[160:163], v[168:171], v[56:59]
	v_mfma_f32_16x16x32_bf16 v[44:47], v[144:147], v[180:183], v[44:47]
	v_mfma_f32_16x16x32_bf16 v[40:43], v[160:163], v[180:183], v[40:43]
	v_mfma_f32_16x16x32_bf16 v[28:31], v[144:147], v[188:191], v[28:31]
	v_mfma_f32_16x16x32_bf16 v[24:27], v[160:163], v[188:191], v[24:27]
	v_mfma_f32_16x16x32_bf16 v[12:15], v[144:147], v[196:199], v[12:15]
	v_mfma_f32_16x16x32_bf16 v[8:11], v[160:163], v[196:199], v[8:11]
	v_mfma_f32_16x16x32_bf16 v[60:63], v[156:159], v[176:179], v[60:63]
	v_mfma_f32_16x16x32_bf16 v[56:59], v[164:167], v[176:179], v[56:59]
	v_mfma_f32_16x16x32_bf16 v[44:47], v[156:159], v[184:187], v[44:47]
	v_mfma_f32_16x16x32_bf16 v[40:43], v[164:167], v[184:187], v[40:43]
	v_mfma_f32_16x16x32_bf16 v[28:31], v[156:159], v[192:195], v[28:31]
	v_mfma_f32_16x16x32_bf16 v[24:27], v[164:167], v[192:195], v[24:27]
	v_mfma_f32_16x16x32_bf16 v[12:15], v[156:159], v[200:203], v[12:15]
	v_mfma_f32_16x16x32_bf16 v[8:11], v[164:167], v[200:203], v[8:11]
	s_setprio 0
	s_barrier
	s_add_u32 s68, s36, 0x40000
	s_addc_u32 s69, s37, 0
	s_add_i32 s70, s57, s43
	s_mov_b32 m0, s70
	v_lshl_add_u64 v[144:145], s[68:69], 0, v[130:131]
	global_load_lds_dwordx4 v[144:145], off
	s_add_i32 m0, s70, 0x2000
	v_lshl_add_u64 v[144:145], s[68:69], 0, v[134:135]
	global_load_lds_dwordx4 v[144:145], off
	s_waitcnt vmcnt(6)
	s_setprio 1
	s_barrier
	v_mfma_f32_16x16x32_bf16 v[52:55], v[204:207], v[168:171], v[52:55]
	v_mfma_f32_16x16x32_bf16 v[48:51], v[216:219], v[168:171], v[48:51]
	v_mfma_f32_16x16x32_bf16 v[36:39], v[204:207], v[180:183], v[36:39]
	v_mfma_f32_16x16x32_bf16 v[32:35], v[216:219], v[180:183], v[32:35]
	v_mfma_f32_16x16x32_bf16 v[20:23], v[204:207], v[188:191], v[20:23]
	v_mfma_f32_16x16x32_bf16 v[16:19], v[216:219], v[188:191], v[16:19]
	v_mfma_f32_16x16x32_bf16 v[4:7], v[204:207], v[196:199], v[4:7]
	v_mfma_f32_16x16x32_bf16 v[0:3], v[216:219], v[196:199], v[0:3]
	v_mfma_f32_16x16x32_bf16 v[52:55], v[212:215], v[176:179], v[52:55]
	v_mfma_f32_16x16x32_bf16 v[48:51], v[220:223], v[176:179], v[48:51]
	v_mfma_f32_16x16x32_bf16 v[36:39], v[212:215], v[184:187], v[36:39]
	v_mfma_f32_16x16x32_bf16 v[32:35], v[220:223], v[184:187], v[32:35]
	v_mfma_f32_16x16x32_bf16 v[20:23], v[212:215], v[192:195], v[20:23]
	v_mfma_f32_16x16x32_bf16 v[16:19], v[220:223], v[192:195], v[16:19]
	v_mfma_f32_16x16x32_bf16 v[4:7], v[212:215], v[200:203], v[4:7]
	v_mfma_f32_16x16x32_bf16 v[0:3], v[220:223], v[200:203], v[0:3]
	s_setprio 0
	s_add_i32 s68, 0, 0x18000
	v_add_u32_e32 v155, s68, v149
	s_barrier
	ds_read_b128 v[144:147], v155
	ds_read_b128 v[156:159], v155 offset:1024
	ds_read_b128 v[160:163], v155 offset:2048
	ds_read_b128 v[164:167], v155 offset:3072
	s_add_u32 s38, s38, 0x40000
	s_addc_u32 s39, s39, 0
	s_mov_b32 m0, s50
	v_lshl_add_u64 v[204:205], s[38:39], 0, v[128:129]
	ds_read_b128 v[168:171], v152 offset:32768
	ds_read_b128 v[176:179], v152 offset:33792
	ds_read_b128 v[180:183], v152 offset:34816
	ds_read_b128 v[184:187], v152 offset:35840
	ds_read_b128 v[188:191], v152 offset:36864
	ds_read_b128 v[192:195], v152 offset:37888
	ds_read_b128 v[196:199], v152 offset:38912
	ds_read_b128 v[200:203], v152 offset:39936
	global_load_lds_dwordx4 v[204:205], off
	s_mov_b32 m0, s51
	v_lshl_add_u64 v[204:205], s[38:39], 0, v[132:133]
	global_load_lds_dwordx4 v[204:205], off
	s_waitcnt lgkmcnt(8)
	s_setprio 1
	s_barrier
	s_waitcnt lgkmcnt(0)
	v_mfma_f32_16x16x32_bf16 v[124:127], v[144:147], v[168:171], v[124:127]
	v_mfma_f32_16x16x32_bf16 v[120:123], v[160:163], v[168:171], v[120:123]
	v_mfma_f32_16x16x32_bf16 v[116:119], v[144:147], v[180:183], v[116:119]
	v_mfma_f32_16x16x32_bf16 v[112:115], v[160:163], v[180:183], v[112:115]
	v_mfma_f32_16x16x32_bf16 v[104:107], v[144:147], v[188:191], v[104:107]
	v_mfma_f32_16x16x32_bf16 v[96:99], v[160:163], v[188:191], v[96:99]
	v_mfma_f32_16x16x32_bf16 v[76:79], v[144:147], v[196:199], v[76:79]
	v_mfma_f32_16x16x32_bf16 v[72:75], v[160:163], v[196:199], v[72:75]
	v_mfma_f32_16x16x32_bf16 v[124:127], v[156:159], v[176:179], v[124:127]
	v_mfma_f32_16x16x32_bf16 v[120:123], v[164:167], v[176:179], v[120:123]
	v_mfma_f32_16x16x32_bf16 v[116:119], v[156:159], v[184:187], v[116:119]
	v_mfma_f32_16x16x32_bf16 v[112:115], v[164:167], v[184:187], v[112:115]
	v_mfma_f32_16x16x32_bf16 v[104:107], v[156:159], v[192:195], v[104:107]
	v_mfma_f32_16x16x32_bf16 v[96:99], v[164:167], v[192:195], v[96:99]
	v_mfma_f32_16x16x32_bf16 v[76:79], v[156:159], v[200:203], v[76:79]
	v_mfma_f32_16x16x32_bf16 v[72:75], v[164:167], v[200:203], v[72:75]
	s_setprio 0
	s_barrier
	s_add_i32 s38, 0, 0x1c000
	s_add_i32 s39, s68, s43
	v_add_u32_e32 v155, s38, v149
	v_lshl_add_u64 v[172:173], v[172:173], 0, s[8:9]
	s_mov_b32 m0, s39
	ds_read_b128 v[204:207], v155
	ds_read_b128 v[212:215], v155 offset:1024
	ds_read_b128 v[216:219], v155 offset:2048
	ds_read_b128 v[220:223], v155 offset:3072
	global_load_lds_dwordx4 v[172:173], off
	s_add_i32 m0, s39, 0x2000
	v_lshl_add_u64 v[172:173], v[208:209], 0, s[8:9]
	global_load_lds_dwordx4 v[172:173], off
	s_setprio 1
	s_barrier
	s_waitcnt lgkmcnt(0)
	v_mfma_f32_16x16x32_bf16 v[108:111], v[204:207], v[168:171], v[108:111]
	v_mfma_f32_16x16x32_bf16 v[100:103], v[216:219], v[168:171], v[100:103]
	v_mfma_f32_16x16x32_bf16 v[92:95], v[204:207], v[180:183], v[92:95]
	v_mfma_f32_16x16x32_bf16 v[88:91], v[216:219], v[180:183], v[88:91]
	v_mfma_f32_16x16x32_bf16 v[84:87], v[204:207], v[188:191], v[84:87]
	v_mfma_f32_16x16x32_bf16 v[80:83], v[216:219], v[188:191], v[80:83]
	v_mfma_f32_16x16x32_bf16 v[68:71], v[204:207], v[196:199], v[68:71]
	v_mfma_f32_16x16x32_bf16 v[64:67], v[216:219], v[196:199], v[64:67]
	v_mfma_f32_16x16x32_bf16 v[108:111], v[212:215], v[176:179], v[108:111]
	v_mfma_f32_16x16x32_bf16 v[100:103], v[220:223], v[176:179], v[100:103]
	v_mfma_f32_16x16x32_bf16 v[92:95], v[212:215], v[184:187], v[92:95]
	v_mfma_f32_16x16x32_bf16 v[88:91], v[220:223], v[184:187], v[88:91]
	v_mfma_f32_16x16x32_bf16 v[84:87], v[212:215], v[192:195], v[84:87]
	v_mfma_f32_16x16x32_bf16 v[80:83], v[220:223], v[192:195], v[80:83]
	v_mfma_f32_16x16x32_bf16 v[68:71], v[212:215], v[200:203], v[68:71]
	v_mfma_f32_16x16x32_bf16 v[64:67], v[220:223], v[200:203], v[64:67]
	s_setprio 0
	s_mov_b32 m0, s53
	v_lshl_add_u64 v[172:173], v[224:225], 0, s[8:9]
	s_barrier
	ds_read_b128 v[168:171], v152 offset:49152
	ds_read_b128 v[176:179], v152 offset:50176
	ds_read_b128 v[180:183], v152 offset:51200
	ds_read_b128 v[184:187], v152 offset:52224
	ds_read_b128 v[188:191], v152 offset:53248
	ds_read_b128 v[192:195], v152 offset:54272
	ds_read_b128 v[196:199], v152 offset:55296
	ds_read_b128 v[200:203], v152 offset:56320
	global_load_lds_dwordx4 v[172:173], off
	s_mov_b32 m0, s54
	v_lshl_add_u64 v[172:173], v[226:227], 0, s[8:9]
	global_load_lds_dwordx4 v[172:173], off
	s_setprio 1
	s_barrier
	s_waitcnt lgkmcnt(0)
	v_mfma_f32_16x16x32_bf16 v[60:63], v[144:147], v[168:171], v[60:63]
	v_mfma_f32_16x16x32_bf16 v[56:59], v[160:163], v[168:171], v[56:59]
	v_mfma_f32_16x16x32_bf16 v[44:47], v[144:147], v[180:183], v[44:47]
	v_mfma_f32_16x16x32_bf16 v[40:43], v[160:163], v[180:183], v[40:43]
	v_mfma_f32_16x16x32_bf16 v[28:31], v[144:147], v[188:191], v[28:31]
	v_mfma_f32_16x16x32_bf16 v[24:27], v[160:163], v[188:191], v[24:27]
	v_mfma_f32_16x16x32_bf16 v[12:15], v[144:147], v[196:199], v[12:15]
	v_mfma_f32_16x16x32_bf16 v[8:11], v[160:163], v[196:199], v[8:11]
	v_mfma_f32_16x16x32_bf16 v[60:63], v[156:159], v[176:179], v[60:63]
	v_mfma_f32_16x16x32_bf16 v[56:59], v[164:167], v[176:179], v[56:59]
	v_mfma_f32_16x16x32_bf16 v[44:47], v[156:159], v[184:187], v[44:47]
	v_mfma_f32_16x16x32_bf16 v[40:43], v[164:167], v[184:187], v[40:43]
	v_mfma_f32_16x16x32_bf16 v[28:31], v[156:159], v[192:195], v[28:31]
	v_mfma_f32_16x16x32_bf16 v[24:27], v[164:167], v[192:195], v[24:27]
	v_mfma_f32_16x16x32_bf16 v[12:15], v[156:159], v[200:203], v[12:15]
	v_mfma_f32_16x16x32_bf16 v[8:11], v[164:167], v[200:203], v[8:11]
	s_setprio 0
	s_barrier
	s_add_u32 s36, s36, 0x40080
	s_addc_u32 s37, s37, 0
	s_add_i32 s38, s38, s43
	s_mov_b32 m0, s38
	v_lshl_add_u64 v[144:145], s[36:37], 0, v[130:131]
	global_load_lds_dwordx4 v[144:145], off
	s_add_i32 m0, s38, 0x2000
	v_lshl_add_u64 v[144:145], s[36:37], 0, v[134:135]
	global_load_lds_dwordx4 v[144:145], off
	s_waitcnt vmcnt(6)
	s_setprio 1
	s_barrier
	v_mfma_f32_16x16x32_bf16 v[52:55], v[204:207], v[168:171], v[52:55]
	v_mfma_f32_16x16x32_bf16 v[48:51], v[216:219], v[168:171], v[48:51]
	v_mfma_f32_16x16x32_bf16 v[36:39], v[204:207], v[180:183], v[36:39]
	v_mfma_f32_16x16x32_bf16 v[32:35], v[216:219], v[180:183], v[32:35]
	v_mfma_f32_16x16x32_bf16 v[20:23], v[204:207], v[188:191], v[20:23]
	v_mfma_f32_16x16x32_bf16 v[16:19], v[216:219], v[188:191], v[16:19]
	v_mfma_f32_16x16x32_bf16 v[4:7], v[204:207], v[196:199], v[4:7]
	v_mfma_f32_16x16x32_bf16 v[0:3], v[216:219], v[196:199], v[0:3]
	v_mfma_f32_16x16x32_bf16 v[52:55], v[212:215], v[176:179], v[52:55]
	v_mfma_f32_16x16x32_bf16 v[48:51], v[220:223], v[176:179], v[48:51]
	v_mfma_f32_16x16x32_bf16 v[36:39], v[212:215], v[184:187], v[36:39]
	v_mfma_f32_16x16x32_bf16 v[32:35], v[220:223], v[184:187], v[32:35]
	v_mfma_f32_16x16x32_bf16 v[20:23], v[212:215], v[192:195], v[20:23]
	v_mfma_f32_16x16x32_bf16 v[16:19], v[220:223], v[192:195], v[16:19]
	v_mfma_f32_16x16x32_bf16 v[4:7], v[212:215], v[200:203], v[4:7]
	v_mfma_f32_16x16x32_bf16 v[0:3], v[220:223], v[200:203], v[0:3]
	s_setprio 0
	s_add_i32 s67, s67, 2
	s_add_u32 s2, s2, 0x100
	s_addc_u32 s3, s3, 0
	s_add_u32 s65, s65, 0x100
	s_addc_u32 s66, s66, 0
	s_cmp_gt_u32 s67, 13
	s_barrier
	s_cbranch_scc0 .LBB0_1080
	v_lshl_add_u32 v146, s0, 8, v148
	v_ashrrev_i32_e32 v147, 31, v146
	v_lshl_add_u64 v[144:145], v[146:147], 2, s[18:19]
	global_load_dword v155, v[144:145], off
	global_load_dword v164, v[144:145], off offset:64
	global_load_dword v165, v[144:145], off offset:128
	global_load_dword v166, v[144:145], off offset:192
	global_load_dword v167, v[144:145], off offset:512
	global_load_dword v168, v[144:145], off offset:576
	global_load_dword v169, v[144:145], off offset:640
	global_load_dword v170, v[144:145], off offset:704
	v_lshl_or_b32 v144, s1, 8, v150
	v_ashrrev_i32_e32 v145, 31, v144
	v_lshlrev_b64 v[160:161], 10, v[146:147]
	v_lshlrev_b64 v[162:163], 1, v[144:145]
	v_lshl_add_u64 v[144:145], s[92:93], 0, v[160:161]
	v_or_b32_e32 v156, 16, v146
	v_ashrrev_i32_e32 v157, 31, v156
	v_or_b32_e32 v158, 32, v146
	v_lshlrev_b64 v[156:157], 10, v[156:157]
	v_lshl_add_u64 v[144:145], v[144:145], 0, v[162:163]
	v_ashrrev_i32_e32 v159, 31, v158
	v_lshl_add_u64 v[156:157], s[92:93], 0, v[156:157]
	v_lshlrev_b64 v[158:159], 10, v[158:159]
	v_lshl_add_u64 v[156:157], v[156:157], 0, v[162:163]
	v_lshl_add_u64 v[158:159], s[92:93], 0, v[158:159]
	v_lshl_add_u64 v[158:159], v[158:159], 0, v[162:163]
	s_mov_b64 s[36:37], s[34:35]
	s_waitcnt vmcnt(0)
	v_fmamk_f32 v147, v155, 0x3a800000, v154
	v_fmamk_f32 v155, v164, 0x3a800000, v154
	v_fmamk_f32 v160, v165, 0x3a800000, v154
	v_mul_f32_e32 v161, 0x4b800000, v147
	v_mul_f32_e32 v164, 0x4b800000, v155
	v_cmp_gt_f32_e32 vcc, s58, v147
	v_cmp_gt_f32_e64 s[0:1], s58, v155
	v_mul_f32_e32 v165, 0x4b800000, v160
	v_cndmask_b32_e32 v147, v147, v161, vcc
	v_cndmask_b32_e64 v155, v155, v164, s[0:1]
	v_cmp_gt_f32_e64 s[2:3], s58, v160
	v_rsq_f32_e32 v147, v147
	v_rsq_f32_e32 v155, v155
	v_cndmask_b32_e64 v160, v160, v165, s[2:3]
	v_rsq_f32_e32 v160, v160
	v_mul_f32_e32 v161, 0x45800000, v147
	v_mul_f32_e32 v164, 0x45800000, v155
	v_cndmask_b32_e32 v147, v147, v161, vcc
	v_mul_f32_e32 v165, 0x45800000, v160
	v_cndmask_b32_e64 v155, v155, v164, s[0:1]
	v_cndmask_b32_e64 v161, v160, v165, s[2:3]
	v_mul_f32_e32 v160, 0x3e0293ee, v147
	v_mul_f32_e32 v164, 0x3e0293ee, v155
	v_fmamk_f32 v171, v166, 0x3a800000, v154
	v_mul_f32_e32 v166, 0x3e0293ee, v161
	v_pk_mul_f32 v[126:127], v[126:127], v[160:161] op_sel_hi:[1,0]
	v_pk_mul_f32 v[124:125], v[124:125], v[160:161] op_sel_hi:[1,0]
	v_pk_mul_f32 v[122:123], v[122:123], v[160:161] op_sel_hi:[1,0]
	v_pk_mul_f32 v[120:121], v[120:121], v[160:161] op_sel_hi:[1,0]
	v_pk_mul_f32 v[110:111], v[110:111], v[160:161] op_sel_hi:[1,0]
	v_pk_mul_f32 v[108:109], v[108:109], v[160:161] op_sel_hi:[1,0]
	v_pk_mul_f32 v[102:103], v[102:103], v[160:161] op_sel_hi:[1,0]
	v_pk_mul_f32 v[100:101], v[100:101], v[160:161] op_sel_hi:[1,0]
	v_pk_mul_f32 v[118:119], v[118:119], v[164:165] op_sel_hi:[1,0]
	v_pk_mul_f32 v[116:117], v[116:117], v[164:165] op_sel_hi:[1,0]
	v_pk_mul_f32 v[114:115], v[114:115], v[164:165] op_sel_hi:[1,0]
	v_pk_mul_f32 v[112:113], v[112:113], v[164:165] op_sel_hi:[1,0]
	v_pk_mul_f32 v[94:95], v[94:95], v[164:165] op_sel_hi:[1,0]
	v_pk_mul_f32 v[92:93], v[92:93], v[164:165] op_sel_hi:[1,0]
	v_pk_mul_f32 v[160:161], v[90:91], v[164:165] op_sel_hi:[1,0]
	v_pk_mul_f32 v[164:165], v[88:89], v[164:165] op_sel_hi:[1,0]
	v_cvt_pk_bf16_f32 v88, v124, v125
	v_cvt_pk_bf16_f32 v89, v126, v127
	v_cvt_pk_bf16_f32 v90, v120, v121
	v_cvt_pk_bf16_f32 v91, v122, v123
	global_store_dwordx4 v[144:145], v[88:91], off
	v_fmamk_f32 v167, v167, 0x3a800000, v154
	v_pk_mul_f32 v[106:107], v[106:107], v[166:167] op_sel_hi:[1,0]
	v_cvt_pk_bf16_f32 v88, v108, v109
	v_cvt_pk_bf16_f32 v89, v110, v111
	v_cvt_pk_bf16_f32 v90, v100, v101
	v_cvt_pk_bf16_f32 v91, v102, v103
	global_store_dwordx4 v[144:145], v[88:91], off offset:256
	v_pk_mul_f32 v[104:105], v[104:105], v[166:167] op_sel_hi:[1,0]
	v_pk_mul_f32 v[98:99], v[98:99], v[166:167] op_sel_hi:[1,0]
	v_cvt_pk_bf16_f32 v88, v116, v117
	v_cvt_pk_bf16_f32 v89, v118, v119
	v_cvt_pk_bf16_f32 v90, v112, v113
	v_cvt_pk_bf16_f32 v91, v114, v115
	global_store_dwordx4 v[156:157], v[88:91], off
	v_pk_mul_f32 v[96:97], v[96:97], v[166:167] op_sel_hi:[1,0]
	v_pk_mul_f32 v[86:87], v[86:87], v[166:167] op_sel_hi:[1,0]
	v_cvt_pk_bf16_f32 v88, v92, v93
	v_cvt_pk_bf16_f32 v89, v94, v95
	v_cvt_pk_bf16_f32 v90, v164, v165
	v_cvt_pk_bf16_f32 v91, v160, v161
	global_store_dwordx4 v[156:157], v[88:91], off offset:256
	v_pk_mul_f32 v[84:85], v[84:85], v[166:167] op_sel_hi:[1,0]
	v_cmp_gt_f32_e32 vcc, s58, v171
	v_cvt_pk_bf16_f32 v88, v104, v105
	v_cvt_pk_bf16_f32 v89, v106, v107
	v_cvt_pk_bf16_f32 v90, v96, v97
	v_cvt_pk_bf16_f32 v91, v98, v99
	global_store_dwordx4 v[158:159], v[88:91], off
	v_fmamk_f32 v168, v168, 0x3a800000, v154
	v_fmamk_f32 v169, v169, 0x3a800000, v154
	v_pk_mul_f32 v[88:89], v[82:83], v[166:167] op_sel_hi:[1,0]
	v_pk_mul_f32 v[82:83], v[80:81], v[166:167] op_sel_hi:[1,0]
	v_cvt_pk_bf16_f32 v80, v84, v85
	v_cvt_pk_bf16_f32 v81, v86, v87
	v_fmamk_f32 v170, v170, 0x3a800000, v154
	v_cvt_pk_bf16_f32 v82, v82, v83
	v_cvt_pk_bf16_f32 v83, v88, v89
	global_store_dwordx4 v[158:159], v[80:83], off offset:256
	s_mov_b32 s1, s26
	s_mov_b32 s0, s28
	v_mul_f32_e32 v82, 0x4b800000, v171
	v_cndmask_b32_e32 v82, v171, v82, vcc
	v_rsq_f32_e32 v82, v82
	v_or_b32_e32 v80, 48, v146
	v_ashrrev_i32_e32 v81, 31, v80
	v_lshlrev_b64 v[80:81], 10, v[80:81]
	v_mul_f32_e32 v83, 0x45800000, v82
	v_cndmask_b32_e32 v82, v82, v83, vcc
	v_lshl_add_u64 v[80:81], s[92:93], 0, v[80:81]
	v_mul_f32_e32 v82, 0x3e0293ee, v82
	v_lshl_add_u64 v[80:81], v[80:81], 0, v[162:163]
	v_pk_mul_f32 v[78:79], v[78:79], v[82:83] op_sel_hi:[1,0]
	v_pk_mul_f32 v[76:77], v[76:77], v[82:83] op_sel_hi:[1,0]
	v_pk_mul_f32 v[84:85], v[74:75], v[82:83] op_sel_hi:[1,0]
	v_pk_mul_f32 v[74:75], v[72:73], v[82:83] op_sel_hi:[1,0]
	v_cvt_pk_bf16_f32 v72, v76, v77
	v_cvt_pk_bf16_f32 v73, v78, v79
	v_pk_mul_f32 v[70:71], v[70:71], v[82:83] op_sel_hi:[1,0]
	v_cvt_pk_bf16_f32 v74, v74, v75
	v_cvt_pk_bf16_f32 v75, v84, v85
	global_store_dwordx4 v[80:81], v[72:75], off
	v_pk_mul_f32 v[68:69], v[68:69], v[82:83] op_sel_hi:[1,0]
	v_cmp_gt_f32_e32 vcc, s58, v167
	v_pk_mul_f32 v[72:73], v[66:67], v[82:83] op_sel_hi:[1,0]
	v_pk_mul_f32 v[66:67], v[64:65], v[82:83] op_sel_hi:[1,0]
	v_cvt_pk_bf16_f32 v64, v68, v69
	v_cvt_pk_bf16_f32 v65, v70, v71
	s_mov_b64 s[2:3], s[30:31]
	v_cvt_pk_bf16_f32 v66, v66, v67
	v_mul_f32_e32 v67, 0x4b800000, v167
	v_cndmask_b32_e32 v67, v167, v67, vcc
	v_rsq_f32_e32 v68, v67
	v_cvt_pk_bf16_f32 v67, v72, v73
	global_store_dwordx4 v[80:81], v[64:67], off offset:256
	s_nop 1
	v_mul_f32_e32 v66, 0x45800000, v68
	v_cndmask_b32_e32 v66, v68, v66, vcc
	v_mul_f32_e32 v66, 0x3e0293ee, v66
	v_pk_mul_f32 v[60:61], v[60:61], v[66:67] op_sel_hi:[1,0]
	v_pk_mul_f32 v[68:69], v[58:59], v[66:67] op_sel_hi:[1,0]
	v_pk_mul_f32 v[58:59], v[56:57], v[66:67] op_sel_hi:[1,0]
	v_cvt_pk_bf16_f32 v56, v60, v61
	v_add_co_u32_e32 v60, vcc, s59, v144
	v_pk_mul_f32 v[62:63], v[62:63], v[66:67] op_sel_hi:[1,0]
	s_nop 0
	v_addc_co_u32_e32 v61, vcc, 0, v145, vcc
	v_cvt_pk_bf16_f32 v57, v62, v63
	v_cvt_pk_bf16_f32 v58, v58, v59
	v_cvt_pk_bf16_f32 v59, v68, v69
	global_store_dwordx4 v[60:61], v[56:59], off
	v_pk_mul_f32 v[54:55], v[54:55], v[66:67] op_sel_hi:[1,0]
	v_pk_mul_f32 v[52:53], v[52:53], v[66:67] op_sel_hi:[1,0]
	v_pk_mul_f32 v[56:57], v[50:51], v[66:67] op_sel_hi:[1,0]
	v_pk_mul_f32 v[50:51], v[48:49], v[66:67] op_sel_hi:[1,0]
	v_cvt_pk_bf16_f32 v48, v52, v53
	v_cvt_pk_bf16_f32 v49, v54, v55
	v_cmp_gt_f32_e32 vcc, s58, v168
	v_cvt_pk_bf16_f32 v50, v50, v51
	v_mul_f32_e32 v51, 0x4b800000, v168
	v_lshl_add_u64 v[64:65], v[144:145], 0, s[14:15]
	v_cndmask_b32_e32 v51, v168, v51, vcc
	v_rsq_f32_e32 v52, v51
	v_cvt_pk_bf16_f32 v51, v56, v57
	global_store_dwordx4 v[64:65], v[48:51], off offset:256
	s_nop 1
	v_mul_f32_e32 v50, 0x45800000, v52
	v_cndmask_b32_e32 v50, v52, v50, vcc
	v_mul_f32_e32 v50, 0x3e0293ee, v50
	v_pk_mul_f32 v[44:45], v[44:45], v[50:51] op_sel_hi:[1,0]
	v_pk_mul_f32 v[52:53], v[42:43], v[50:51] op_sel_hi:[1,0]
	v_pk_mul_f32 v[42:43], v[40:41], v[50:51] op_sel_hi:[1,0]
	v_cvt_pk_bf16_f32 v40, v44, v45
	v_add_co_u32_e32 v44, vcc, s60, v144
	v_pk_mul_f32 v[46:47], v[46:47], v[50:51] op_sel_hi:[1,0]
	s_nop 0
	v_addc_co_u32_e32 v45, vcc, 0, v145, vcc
	v_cvt_pk_bf16_f32 v41, v46, v47
	v_cvt_pk_bf16_f32 v42, v42, v43
	v_cvt_pk_bf16_f32 v43, v52, v53
	global_store_dwordx4 v[44:45], v[40:43], off
	v_pk_mul_f32 v[38:39], v[38:39], v[50:51] op_sel_hi:[1,0]
	v_pk_mul_f32 v[36:37], v[36:37], v[50:51] op_sel_hi:[1,0]
	v_pk_mul_f32 v[40:41], v[34:35], v[50:51] op_sel_hi:[1,0]
	v_pk_mul_f32 v[34:35], v[32:33], v[50:51] op_sel_hi:[1,0]
	v_cvt_pk_bf16_f32 v32, v36, v37
	v_cvt_pk_bf16_f32 v33, v38, v39
	v_cmp_gt_f32_e32 vcc, s58, v169
	v_cvt_pk_bf16_f32 v34, v34, v35
	v_mul_f32_e32 v35, 0x4b800000, v169
	v_lshl_add_u64 v[48:49], v[144:145], 0, s[20:21]
	v_cndmask_b32_e32 v35, v169, v35, vcc
	v_rsq_f32_e32 v36, v35
	v_cvt_pk_bf16_f32 v35, v40, v41
	global_store_dwordx4 v[48:49], v[32:35], off offset:256
	s_nop 1
	v_mul_f32_e32 v34, 0x45800000, v36
	v_cndmask_b32_e32 v34, v36, v34, vcc
	v_mul_f32_e32 v34, 0x3e0293ee, v34
	v_pk_mul_f32 v[28:29], v[28:29], v[34:35] op_sel_hi:[1,0]
	v_pk_mul_f32 v[36:37], v[26:27], v[34:35] op_sel_hi:[1,0]
	v_pk_mul_f32 v[26:27], v[24:25], v[34:35] op_sel_hi:[1,0]
	v_cvt_pk_bf16_f32 v24, v28, v29
	v_add_co_u32_e32 v28, vcc, s61, v144
	v_pk_mul_f32 v[30:31], v[30:31], v[34:35] op_sel_hi:[1,0]
	s_nop 0
	v_addc_co_u32_e32 v29, vcc, 0, v145, vcc
	v_cvt_pk_bf16_f32 v25, v30, v31
	v_cvt_pk_bf16_f32 v26, v26, v27
	v_cvt_pk_bf16_f32 v27, v36, v37
	global_store_dwordx4 v[28:29], v[24:27], off
	v_pk_mul_f32 v[22:23], v[22:23], v[34:35] op_sel_hi:[1,0]
	v_pk_mul_f32 v[20:21], v[20:21], v[34:35] op_sel_hi:[1,0]
	v_pk_mul_f32 v[24:25], v[18:19], v[34:35] op_sel_hi:[1,0]
	v_pk_mul_f32 v[18:19], v[16:17], v[34:35] op_sel_hi:[1,0]
	v_cvt_pk_bf16_f32 v16, v20, v21
	v_cvt_pk_bf16_f32 v17, v22, v23
	v_cmp_gt_f32_e32 vcc, s58, v170
	v_cvt_pk_bf16_f32 v18, v18, v19
	v_mul_f32_e32 v19, 0x4b800000, v170
	v_lshl_add_u64 v[32:33], v[144:145], 0, s[22:23]
	v_cndmask_b32_e32 v19, v170, v19, vcc
	v_rsq_f32_e32 v20, v19
	v_cvt_pk_bf16_f32 v19, v24, v25
	global_store_dwordx4 v[32:33], v[16:19], off offset:256
	s_nop 1
	v_mul_f32_e32 v18, 0x45800000, v20
	v_cndmask_b32_e32 v18, v20, v18, vcc
	v_mul_f32_e32 v18, 0x3e0293ee, v18
	v_pk_mul_f32 v[12:13], v[12:13], v[18:19] op_sel_hi:[1,0]
	v_pk_mul_f32 v[20:21], v[10:11], v[18:19] op_sel_hi:[1,0]
	v_pk_mul_f32 v[10:11], v[8:9], v[18:19] op_sel_hi:[1,0]
	v_cvt_pk_bf16_f32 v8, v12, v13
	v_add_co_u32_e32 v12, vcc, s62, v144
	v_pk_mul_f32 v[14:15], v[14:15], v[18:19] op_sel_hi:[1,0]
	s_nop 0
	v_addc_co_u32_e32 v13, vcc, 0, v145, vcc
	v_cvt_pk_bf16_f32 v9, v14, v15
	v_lshl_add_u64 v[16:17], v[144:145], 0, s[24:25]
	v_cvt_pk_bf16_f32 v10, v10, v11
	v_cvt_pk_bf16_f32 v11, v20, v21
	global_store_dwordx4 v[12:13], v[8:11], off
	s_and_b64 vcc, exec, s[6:7]
	v_pk_mul_f32 v[6:7], v[6:7], v[18:19] op_sel_hi:[1,0]
	v_pk_mul_f32 v[8:9], v[2:3], v[18:19] op_sel_hi:[1,0]
	v_pk_mul_f32 v[2:3], v[0:1], v[18:19] op_sel_hi:[1,0]
	v_pk_mul_f32 v[4:5], v[4:5], v[18:19] op_sel_hi:[1,0]
	s_nop 0
	v_cvt_pk_bf16_f32 v0, v4, v5
	v_cvt_pk_bf16_f32 v1, v6, v7
	v_cvt_pk_bf16_f32 v2, v2, v3
	v_cvt_pk_bf16_f32 v3, v8, v9
	global_store_dwordx4 v[16:17], v[0:3], off offset:256
	s_cbranch_vccz .LBB0_1073
	s_waitcnt vmcnt(0)
	s_cmpk_gt_u32 s33, 0xff
	s_cbranch_scc1 .LBB0_1084
	s_barrier

.LBB0_1160:
	ds_read_b128 v[144:147], v178
	ds_read_b128 v[148:151], v178 offset:1024
	ds_read_b128 v[152:155], v178 offset:2048
	ds_read_b128 v[156:159], v178 offset:3072
	s_add_u32 s38, s36, 0xfffe0080
	s_addc_u32 s39, s37, -1
	s_cmp_eq_u32 s62, 4
	s_cselect_b32 s41, s25, s39
	s_cselect_b32 s40, s31, s38
	s_cselect_b32 s39, s23, s61
	s_cselect_b32 s38, s59, s60
	v_lshl_add_u64 v[172:173], s[36:37], 0, v[136:137]
	s_add_i32 m0, s35, 0xc000
	ds_read_b128 v[160:163], v179
	ds_read_b128 v[164:167], v179 offset:1024
	ds_read_b128 v[168:171], v179 offset:2048
	ds_read_b128 v[182:185], v179 offset:3072
	ds_read_b128 v[186:189], v179 offset:4096
	ds_read_b128 v[190:193], v179 offset:5120
	ds_read_b128 v[194:197], v179 offset:6144
	ds_read_b128 v[198:201], v179 offset:7168
	global_load_lds_dwordx4 v[172:173], off
	s_add_i32 m0, s35, 0xe000
	v_lshl_add_u64 v[172:173], s[36:37], 0, v[138:139]
	global_load_lds_dwordx4 v[172:173], off
	s_waitcnt lgkmcnt(8)
	s_setprio 1
	s_barrier
	s_waitcnt lgkmcnt(0)
	v_mfma_f32_16x16x32_bf16 v[124:127], v[144:147], v[160:163], v[124:127]
	v_mfma_f32_16x16x32_bf16 v[120:123], v[152:155], v[160:163], v[120:123]
	v_mfma_f32_16x16x32_bf16 v[108:111], v[144:147], v[168:171], v[108:111]
	v_mfma_f32_16x16x32_bf16 v[104:107], v[152:155], v[168:171], v[104:107]
	v_mfma_f32_16x16x32_bf16 v[96:99], v[144:147], v[186:189], v[96:99]
	v_mfma_f32_16x16x32_bf16 v[88:91], v[152:155], v[186:189], v[88:91]
	v_mfma_f32_16x16x32_bf16 v[80:83], v[144:147], v[194:197], v[80:83]
	v_mfma_f32_16x16x32_bf16 v[72:75], v[152:155], v[194:197], v[72:75]
	v_mfma_f32_16x16x32_bf16 v[124:127], v[148:151], v[164:167], v[124:127]
	v_mfma_f32_16x16x32_bf16 v[120:123], v[156:159], v[164:167], v[120:123]
	v_mfma_f32_16x16x32_bf16 v[108:111], v[148:151], v[182:185], v[108:111]
	v_mfma_f32_16x16x32_bf16 v[104:107], v[156:159], v[182:185], v[104:107]
	v_mfma_f32_16x16x32_bf16 v[96:99], v[148:151], v[190:193], v[96:99]
	v_mfma_f32_16x16x32_bf16 v[88:91], v[156:159], v[190:193], v[88:91]
	v_mfma_f32_16x16x32_bf16 v[80:83], v[148:151], v[198:201], v[80:83]
	v_mfma_f32_16x16x32_bf16 v[72:75], v[156:159], v[198:201], v[72:75]
	s_setprio 0
	s_barrier
	s_add_i32 s63, s57, s48
	v_lshl_add_u64 v[172:173], s[38:39], 0, v[130:131]
	s_mov_b32 m0, s63
	ds_read_b128 v[202:205], v180
	ds_read_b128 v[206:209], v180 offset:1024
	ds_read_b128 v[212:215], v180 offset:2048
	ds_read_b128 v[216:219], v180 offset:3072
	global_load_lds_dwordx4 v[172:173], off
	s_add_i32 m0, s63, 0x2000
	v_lshl_add_u64 v[220:221], s[38:39], 0, v[134:135]
	global_load_lds_dwordx4 v[220:221], off
	s_setprio 1
	s_barrier
	s_waitcnt lgkmcnt(0)
	v_mfma_f32_16x16x32_bf16 v[116:119], v[202:205], v[160:163], v[116:119]
	v_mfma_f32_16x16x32_bf16 v[112:115], v[212:215], v[160:163], v[112:115]
	v_mfma_f32_16x16x32_bf16 v[100:103], v[202:205], v[168:171], v[100:103]
	v_mfma_f32_16x16x32_bf16 v[92:95], v[212:215], v[168:171], v[92:95]
	v_mfma_f32_16x16x32_bf16 v[84:87], v[202:205], v[186:189], v[84:87]
	v_mfma_f32_16x16x32_bf16 v[76:79], v[212:215], v[186:189], v[76:79]
	v_mfma_f32_16x16x32_bf16 v[68:71], v[202:205], v[194:197], v[68:71]
	v_mfma_f32_16x16x32_bf16 v[64:67], v[212:215], v[194:197], v[64:67]
	v_mfma_f32_16x16x32_bf16 v[116:119], v[206:209], v[164:167], v[116:119]
	v_mfma_f32_16x16x32_bf16 v[112:115], v[216:219], v[164:167], v[112:115]
	v_mfma_f32_16x16x32_bf16 v[100:103], v[206:209], v[182:185], v[100:103]
	v_mfma_f32_16x16x32_bf16 v[92:95], v[216:219], v[182:185], v[92:95]
	v_mfma_f32_16x16x32_bf16 v[84:87], v[206:209], v[190:193], v[84:87]
	v_mfma_f32_16x16x32_bf16 v[76:79], v[216:219], v[190:193], v[76:79]
	v_mfma_f32_16x16x32_bf16 v[68:71], v[206:209], v[198:201], v[68:71]
	v_mfma_f32_16x16x32_bf16 v[64:67], v[216:219], v[198:201], v[64:67]
	s_setprio 0
	s_mov_b32 m0, s35
	v_lshl_add_u64 v[222:223], s[40:41], 0, v[128:129]
	s_barrier
	ds_read_b128 v[160:163], v179 offset:16384
	ds_read_b128 v[164:167], v179 offset:17408
	ds_read_b128 v[168:171], v179 offset:18432
	ds_read_b128 v[182:185], v179 offset:19456
	ds_read_b128 v[186:189], v179 offset:20480
	ds_read_b128 v[190:193], v179 offset:21504
	ds_read_b128 v[194:197], v179 offset:22528
	ds_read_b128 v[198:201], v179 offset:23552
	global_load_lds_dwordx4 v[222:223], off
	s_mov_b32 m0, s49
	v_lshl_add_u64 v[224:225], s[40:41], 0, v[132:133]
	global_load_lds_dwordx4 v[224:225], off
	s_setprio 1
	s_barrier
	s_waitcnt lgkmcnt(0)
	v_mfma_f32_16x16x32_bf16 v[60:63], v[144:147], v[160:163], v[60:63]
	v_mfma_f32_16x16x32_bf16 v[56:59], v[152:155], v[160:163], v[56:59]
	v_mfma_f32_16x16x32_bf16 v[44:47], v[144:147], v[168:171], v[44:47]
	v_mfma_f32_16x16x32_bf16 v[40:43], v[152:155], v[168:171], v[40:43]
	v_mfma_f32_16x16x32_bf16 v[32:35], v[144:147], v[186:189], v[32:35]
	v_mfma_f32_16x16x32_bf16 v[24:27], v[152:155], v[186:189], v[24:27]
	v_mfma_f32_16x16x32_bf16 v[16:19], v[144:147], v[194:197], v[16:19]
	v_mfma_f32_16x16x32_bf16 v[8:11], v[152:155], v[194:197], v[8:11]
	v_mfma_f32_16x16x32_bf16 v[60:63], v[148:151], v[164:167], v[60:63]
	v_mfma_f32_16x16x32_bf16 v[56:59], v[156:159], v[164:167], v[56:59]
	v_mfma_f32_16x16x32_bf16 v[44:47], v[148:151], v[182:185], v[44:47]
	v_mfma_f32_16x16x32_bf16 v[40:43], v[156:159], v[182:185], v[40:43]
	v_mfma_f32_16x16x32_bf16 v[32:35], v[148:151], v[190:193], v[32:35]
	v_mfma_f32_16x16x32_bf16 v[24:27], v[156:159], v[190:193], v[24:27]
	v_mfma_f32_16x16x32_bf16 v[16:19], v[148:151], v[198:201], v[16:19]
	v_mfma_f32_16x16x32_bf16 v[8:11], v[156:159], v[198:201], v[8:11]
	s_setprio 0
	s_barrier
	s_add_u32 s64, s38, 0x20000
	s_addc_u32 s65, s39, 0
	s_add_i32 s63, s58, s48
	s_mov_b32 m0, s63
	v_lshl_add_u64 v[144:145], s[64:65], 0, v[130:131]
	global_load_lds_dwordx4 v[144:145], off
	s_add_i32 m0, s63, 0x2000
	v_lshl_add_u64 v[144:145], s[64:65], 0, v[134:135]
	global_load_lds_dwordx4 v[144:145], off
	s_waitcnt vmcnt(6)
	s_setprio 1
	s_barrier
	v_mfma_f32_16x16x32_bf16 v[52:55], v[202:205], v[160:163], v[52:55]
	v_mfma_f32_16x16x32_bf16 v[48:51], v[212:215], v[160:163], v[48:51]
	v_mfma_f32_16x16x32_bf16 v[36:39], v[202:205], v[168:171], v[36:39]
	v_mfma_f32_16x16x32_bf16 v[28:31], v[212:215], v[168:171], v[28:31]
	v_mfma_f32_16x16x32_bf16 v[20:23], v[202:205], v[186:189], v[20:23]
	v_mfma_f32_16x16x32_bf16 v[12:15], v[212:215], v[186:189], v[12:15]
	v_mfma_f32_16x16x32_bf16 v[4:7], v[202:205], v[194:197], v[4:7]
	v_mfma_f32_16x16x32_bf16 v[0:3], v[212:215], v[194:197], v[0:3]
	v_mfma_f32_16x16x32_bf16 v[52:55], v[206:209], v[164:167], v[52:55]
	v_mfma_f32_16x16x32_bf16 v[48:51], v[216:219], v[164:167], v[48:51]
	v_mfma_f32_16x16x32_bf16 v[36:39], v[206:209], v[182:185], v[36:39]
	v_mfma_f32_16x16x32_bf16 v[28:31], v[216:219], v[182:185], v[28:31]
	v_mfma_f32_16x16x32_bf16 v[20:23], v[206:209], v[190:193], v[20:23]
	v_mfma_f32_16x16x32_bf16 v[12:15], v[216:219], v[190:193], v[12:15]
	v_mfma_f32_16x16x32_bf16 v[4:7], v[206:209], v[198:201], v[4:7]
	v_mfma_f32_16x16x32_bf16 v[0:3], v[216:219], v[198:201], v[0:3]
	s_setprio 0
	s_add_i32 s63, 0, 0x18000
	v_add_u32_e32 v156, s63, v176
	s_barrier
	ds_read_b128 v[144:147], v156
	ds_read_b128 v[148:151], v156 offset:1024
	ds_read_b128 v[152:155], v156 offset:2048
	ds_read_b128 v[156:159], v156 offset:3072
	s_add_u32 s40, s40, 0x20000
	s_addc_u32 s41, s41, 0
	s_mov_b32 m0, s50
	v_lshl_add_u64 v[202:203], s[40:41], 0, v[128:129]
	ds_read_b128 v[160:163], v179 offset:32768
	ds_read_b128 v[164:167], v179 offset:33792
	ds_read_b128 v[168:171], v179 offset:34816
	ds_read_b128 v[182:185], v179 offset:35840
	ds_read_b128 v[186:189], v179 offset:36864
	ds_read_b128 v[190:193], v179 offset:37888
	ds_read_b128 v[194:197], v179 offset:38912
	ds_read_b128 v[198:201], v179 offset:39936
	global_load_lds_dwordx4 v[202:203], off
	s_mov_b32 m0, s51
	v_lshl_add_u64 v[202:203], s[40:41], 0, v[132:133]
	global_load_lds_dwordx4 v[202:203], off
	s_waitcnt lgkmcnt(8)
	s_setprio 1
	s_barrier
	s_waitcnt lgkmcnt(0)
	v_mfma_f32_16x16x32_bf16 v[124:127], v[144:147], v[160:163], v[124:127]
	v_mfma_f32_16x16x32_bf16 v[120:123], v[152:155], v[160:163], v[120:123]
	v_mfma_f32_16x16x32_bf16 v[108:111], v[144:147], v[168:171], v[108:111]
	v_mfma_f32_16x16x32_bf16 v[104:107], v[152:155], v[168:171], v[104:107]
	v_mfma_f32_16x16x32_bf16 v[96:99], v[144:147], v[186:189], v[96:99]
	v_mfma_f32_16x16x32_bf16 v[88:91], v[152:155], v[186:189], v[88:91]
	v_mfma_f32_16x16x32_bf16 v[80:83], v[144:147], v[194:197], v[80:83]
	v_mfma_f32_16x16x32_bf16 v[72:75], v[152:155], v[194:197], v[72:75]
	v_mfma_f32_16x16x32_bf16 v[124:127], v[148:151], v[164:167], v[124:127]
	v_mfma_f32_16x16x32_bf16 v[120:123], v[156:159], v[164:167], v[120:123]
	v_mfma_f32_16x16x32_bf16 v[108:111], v[148:151], v[182:185], v[108:111]
	v_mfma_f32_16x16x32_bf16 v[104:107], v[156:159], v[182:185], v[104:107]
	v_mfma_f32_16x16x32_bf16 v[96:99], v[148:151], v[190:193], v[96:99]
	v_mfma_f32_16x16x32_bf16 v[88:91], v[156:159], v[190:193], v[88:91]
	v_mfma_f32_16x16x32_bf16 v[80:83], v[148:151], v[198:201], v[80:83]
	v_mfma_f32_16x16x32_bf16 v[72:75], v[156:159], v[198:201], v[72:75]
	s_setprio 0
	s_barrier
	s_add_i32 s40, 0, 0x1c000
	s_add_i32 s41, s63, s48
	v_add_u32_e32 v181, s40, v176
	v_lshl_add_u64 v[172:173], v[172:173], 0, s[0:1]
	s_mov_b32 m0, s41
	ds_read_b128 v[202:205], v181
	ds_read_b128 v[206:209], v181 offset:1024
	ds_read_b128 v[212:215], v181 offset:2048
	ds_read_b128 v[216:219], v181 offset:3072
	global_load_lds_dwordx4 v[172:173], off
	s_add_i32 m0, s41, 0x2000
	v_lshl_add_u64 v[172:173], v[220:221], 0, s[0:1]
	global_load_lds_dwordx4 v[172:173], off
	s_setprio 1
	s_barrier
	s_waitcnt lgkmcnt(0)
	v_mfma_f32_16x16x32_bf16 v[116:119], v[202:205], v[160:163], v[116:119]
	v_mfma_f32_16x16x32_bf16 v[112:115], v[212:215], v[160:163], v[112:115]
	v_mfma_f32_16x16x32_bf16 v[100:103], v[202:205], v[168:171], v[100:103]
	v_mfma_f32_16x16x32_bf16 v[92:95], v[212:215], v[168:171], v[92:95]
	v_mfma_f32_16x16x32_bf16 v[84:87], v[202:205], v[186:189], v[84:87]
	v_mfma_f32_16x16x32_bf16 v[76:79], v[212:215], v[186:189], v[76:79]
	v_mfma_f32_16x16x32_bf16 v[68:71], v[202:205], v[194:197], v[68:71]
	v_mfma_f32_16x16x32_bf16 v[64:67], v[212:215], v[194:197], v[64:67]
	v_mfma_f32_16x16x32_bf16 v[116:119], v[206:209], v[164:167], v[116:119]
	v_mfma_f32_16x16x32_bf16 v[112:115], v[216:219], v[164:167], v[112:115]
	v_mfma_f32_16x16x32_bf16 v[100:103], v[206:209], v[182:185], v[100:103]
	v_mfma_f32_16x16x32_bf16 v[92:95], v[216:219], v[182:185], v[92:95]
	v_mfma_f32_16x16x32_bf16 v[84:87], v[206:209], v[190:193], v[84:87]
	v_mfma_f32_16x16x32_bf16 v[76:79], v[216:219], v[190:193], v[76:79]
	v_mfma_f32_16x16x32_bf16 v[68:71], v[206:209], v[198:201], v[68:71]
	v_mfma_f32_16x16x32_bf16 v[64:67], v[216:219], v[198:201], v[64:67]
	s_setprio 0
	s_mov_b32 m0, s53
	v_lshl_add_u64 v[172:173], v[222:223], 0, s[0:1]
	s_barrier
	ds_read_b128 v[160:163], v179 offset:49152
	ds_read_b128 v[164:167], v179 offset:50176
	ds_read_b128 v[168:171], v179 offset:51200
	ds_read_b128 v[182:185], v179 offset:52224
	ds_read_b128 v[186:189], v179 offset:53248
	ds_read_b128 v[190:193], v179 offset:54272
	ds_read_b128 v[194:197], v179 offset:55296
	ds_read_b128 v[198:201], v179 offset:56320
	global_load_lds_dwordx4 v[172:173], off
	s_mov_b32 m0, s54
	v_lshl_add_u64 v[172:173], v[224:225], 0, s[0:1]
	global_load_lds_dwordx4 v[172:173], off
	s_setprio 1
	s_barrier
	s_waitcnt lgkmcnt(0)
	v_mfma_f32_16x16x32_bf16 v[60:63], v[144:147], v[160:163], v[60:63]
	v_mfma_f32_16x16x32_bf16 v[56:59], v[152:155], v[160:163], v[56:59]
	v_mfma_f32_16x16x32_bf16 v[44:47], v[144:147], v[168:171], v[44:47]
	v_mfma_f32_16x16x32_bf16 v[40:43], v[152:155], v[168:171], v[40:43]
	v_mfma_f32_16x16x32_bf16 v[32:35], v[144:147], v[186:189], v[32:35]
	v_mfma_f32_16x16x32_bf16 v[24:27], v[152:155], v[186:189], v[24:27]
	v_mfma_f32_16x16x32_bf16 v[16:19], v[144:147], v[194:197], v[16:19]
	v_mfma_f32_16x16x32_bf16 v[8:11], v[152:155], v[194:197], v[8:11]
	v_mfma_f32_16x16x32_bf16 v[60:63], v[148:151], v[164:167], v[60:63]
	v_mfma_f32_16x16x32_bf16 v[56:59], v[156:159], v[164:167], v[56:59]
	v_mfma_f32_16x16x32_bf16 v[44:47], v[148:151], v[182:185], v[44:47]
	v_mfma_f32_16x16x32_bf16 v[40:43], v[156:159], v[182:185], v[40:43]
	v_mfma_f32_16x16x32_bf16 v[32:35], v[148:151], v[190:193], v[32:35]
	v_mfma_f32_16x16x32_bf16 v[24:27], v[156:159], v[190:193], v[24:27]
	v_mfma_f32_16x16x32_bf16 v[16:19], v[148:151], v[198:201], v[16:19]
	v_mfma_f32_16x16x32_bf16 v[8:11], v[156:159], v[198:201], v[8:11]
	s_setprio 0
	s_barrier
	s_add_u32 s38, s38, 0x20080
	s_addc_u32 s39, s39, 0
	s_add_i32 s40, s40, s48
	s_mov_b32 m0, s40
	v_lshl_add_u64 v[144:145], s[38:39], 0, v[130:131]
	global_load_lds_dwordx4 v[144:145], off
	s_add_i32 m0, s40, 0x2000
	v_lshl_add_u64 v[144:145], s[38:39], 0, v[134:135]
	global_load_lds_dwordx4 v[144:145], off
	s_waitcnt vmcnt(6)
	s_setprio 1
	s_barrier
	v_mfma_f32_16x16x32_bf16 v[52:55], v[202:205], v[160:163], v[52:55]
	v_mfma_f32_16x16x32_bf16 v[48:51], v[212:215], v[160:163], v[48:51]
	v_mfma_f32_16x16x32_bf16 v[36:39], v[202:205], v[168:171], v[36:39]
	v_mfma_f32_16x16x32_bf16 v[28:31], v[212:215], v[168:171], v[28:31]
	v_mfma_f32_16x16x32_bf16 v[20:23], v[202:205], v[186:189], v[20:23]
	v_mfma_f32_16x16x32_bf16 v[12:15], v[212:215], v[186:189], v[12:15]
	v_mfma_f32_16x16x32_bf16 v[4:7], v[202:205], v[194:197], v[4:7]
	v_mfma_f32_16x16x32_bf16 v[0:3], v[212:215], v[194:197], v[0:3]
	v_mfma_f32_16x16x32_bf16 v[52:55], v[206:209], v[164:167], v[52:55]
	v_mfma_f32_16x16x32_bf16 v[48:51], v[216:219], v[164:167], v[48:51]
	v_mfma_f32_16x16x32_bf16 v[36:39], v[206:209], v[182:185], v[36:39]
	v_mfma_f32_16x16x32_bf16 v[28:31], v[216:219], v[182:185], v[28:31]
	v_mfma_f32_16x16x32_bf16 v[20:23], v[206:209], v[190:193], v[20:23]
	v_mfma_f32_16x16x32_bf16 v[12:15], v[216:219], v[190:193], v[12:15]
	v_mfma_f32_16x16x32_bf16 v[4:7], v[206:209], v[198:201], v[4:7]
	v_mfma_f32_16x16x32_bf16 v[0:3], v[216:219], v[198:201], v[0:3]
	s_setprio 0
	s_add_i32 s62, s62, 2
	s_add_u32 s36, s36, 0x100
	s_addc_u32 s37, s37, 0
	s_add_u32 s60, s60, 0x100
	s_addc_u32 s61, s61, 0
	s_cmp_gt_u32 s62, 5
	s_barrier
	s_cbranch_scc0 .LBB0_1160
	v_lshl_or_b32 v144, s34, 8, v177
	v_lshl_add_u32 v150, s30, 8, v175
	v_ashrrev_i32_e32 v145, 31, v144
	v_ashrrev_i32_e32 v151, 31, v150
	v_lshlrev_b64 v[144:145], 1, v[144:145]
	v_lshl_add_u64 v[146:147], s[10:11], 0, v[144:145]
	v_lshlrev_b64 v[148:149], 11, v[150:151]
	v_lshl_add_u64 v[152:153], v[146:147], 0, v[148:149]
	global_load_dwordx4 v[156:159], v[152:153], off
	global_load_dwordx4 v[160:163], v[152:153], off offset:256
	v_or_b32_e32 v152, 16, v150
	v_ashrrev_i32_e32 v153, 31, v152
	v_lshlrev_b64 v[170:171], 11, v[152:153]
	v_lshl_add_u64 v[152:153], v[146:147], 0, v[170:171]
	global_load_dwordx4 v[164:167], v[152:153], off
	global_load_dwordx4 v[182:185], v[152:153], off offset:256
	v_or_b32_e32 v152, 32, v150
	v_ashrrev_i32_e32 v153, 31, v152
	v_lshlrev_b64 v[154:155], 11, v[152:153]
	v_lshl_add_u64 v[152:153], v[146:147], 0, v[154:155]
	global_load_dwordx4 v[186:189], v[152:153], off
	global_load_dwordx4 v[190:193], v[152:153], off offset:256
	v_or_b32_e32 v152, 48, v150
	v_ashrrev_i32_e32 v153, 31, v152
	v_lshlrev_b64 v[152:153], 11, v[152:153]
	v_lshl_add_u64 v[168:169], v[146:147], 0, v[152:153]
	global_load_dwordx4 v[194:197], v[168:169], off
	global_load_dwordx4 v[198:201], v[168:169], off offset:256
	s_waitcnt vmcnt(0)
	v_lshlrev_b32_e32 v202, 16, v156
	v_and_b32_e32 v203, 0xffff0000, v156
	v_lshlrev_b32_e32 v204, 16, v157
	v_and_b32_e32 v205, 0xffff0000, v157
	v_lshlrev_b32_e32 v206, 16, v158
	v_and_b32_e32 v207, 0xffff0000, v158
	v_lshlrev_b32_e32 v208, 16, v159
	v_and_b32_e32 v209, 0xffff0000, v159
	v_pk_add_f32 v[126:127], v[126:127], v[204:205]
	v_pk_add_f32 v[124:125], v[124:125], v[202:203]
	v_lshlrev_b32_e32 v224, 16, v166
	v_and_b32_e32 v225, 0xffff0000, v166
	v_lshlrev_b32_e32 v226, 16, v167
	v_and_b32_e32 v227, 0xffff0000, v167
	v_lshlrev_b32_e32 v212, 16, v160
	v_lshlrev_b32_e32 v166, 16, v194
	v_and_b32_e32 v167, 0xffff0000, v194
	v_lshlrev_b32_e32 v172, 16, v195
	v_and_b32_e32 v173, 0xffff0000, v195
	v_pk_add_f32 v[194:195], v[122:123], v[208:209]
	v_pk_add_f32 v[122:123], v[120:121], v[206:207]
	v_mul_f32_e32 v120, v125, v125
	v_mul_f32_e32 v121, v127, v127
	v_fmac_f32_e32 v120, v124, v124
	v_fmac_f32_e32 v121, v126, v126
	v_add_f32_e32 v120, v120, v121
	v_mul_f32_e32 v121, v123, v123
	v_fmac_f32_e32 v121, v122, v122
	v_add_f32_e32 v120, v121, v120
	v_mul_f32_e32 v121, v195, v195
	v_fmac_f32_e32 v121, v194, v194
	v_and_b32_e32 v213, 0xffff0000, v160
	v_lshlrev_b32_e32 v214, 16, v161
	v_and_b32_e32 v215, 0xffff0000, v161
	v_add_f32_e32 v181, v121, v120
	v_cvt_pk_bf16_f32 v120, v124, v125
	v_lshl_add_u64 v[124:125], s[90:91], 0, v[148:149]
	v_lshlrev_b32_e32 v216, 16, v162
	v_and_b32_e32 v217, 0xffff0000, v162
	v_lshlrev_b32_e32 v218, 16, v163
	v_and_b32_e32 v219, 0xffff0000, v163
	v_cvt_pk_bf16_f32 v121, v126, v127
	v_lshl_add_u64 v[124:125], v[124:125], 0, v[144:145]
	v_pk_add_f32 v[118:119], v[118:119], v[214:215]
	v_pk_add_f32 v[116:117], v[116:117], v[212:213]
	v_cvt_pk_bf16_f32 v122, v122, v123
	v_cvt_pk_bf16_f32 v123, v194, v195
	global_store_dwordx4 v[124:125], v[120:123], off
	v_lshlrev_b32_e32 v220, 16, v164
	v_and_b32_e32 v221, 0xffff0000, v164
	v_pk_add_f32 v[120:121], v[114:115], v[218:219]
	v_pk_add_f32 v[114:115], v[112:113], v[216:217]
	v_mul_f32_e32 v112, v117, v117
	v_mul_f32_e32 v113, v119, v119
	v_fmac_f32_e32 v112, v116, v116
	v_fmac_f32_e32 v113, v118, v118
	v_add_f32_e32 v112, v112, v113
	v_mul_f32_e32 v113, v115, v115
	v_fmac_f32_e32 v113, v114, v114
	v_add_f32_e32 v112, v113, v112
	v_mul_f32_e32 v113, v121, v121
	v_fmac_f32_e32 v113, v120, v120
	v_add_f32_e32 v112, v113, v112
	v_lshlrev_b32_e32 v222, 16, v165
	v_and_b32_e32 v223, 0xffff0000, v165
	v_add_f32_e32 v126, v181, v112
	v_cvt_pk_bf16_f32 v112, v116, v117
	v_cvt_pk_bf16_f32 v113, v118, v119
	v_lshl_add_u64 v[116:117], s[90:91], 0, v[170:171]
	v_lshlrev_b32_e32 v230, 16, v184
	v_and_b32_e32 v231, 0xffff0000, v184
	v_lshlrev_b32_e32 v232, 16, v186
	v_and_b32_e32 v233, 0xffff0000, v186
	v_lshlrev_b32_e32 v186, 16, v187
	v_and_b32_e32 v187, 0xffff0000, v187
	v_cvt_pk_bf16_f32 v114, v114, v115
	v_cvt_pk_bf16_f32 v115, v120, v121
	global_store_dwordx4 v[124:125], v[112:115], off offset:256
	v_pk_add_f32 v[110:111], v[110:111], v[222:223]
	v_pk_add_f32 v[108:109], v[108:109], v[220:221]
	v_lshl_add_u64 v[118:119], v[116:117], 0, v[144:145]
	v_cvt_pk_bf16_f32 v112, v108, v109
	v_cvt_pk_bf16_f32 v113, v110, v111
	v_lshlrev_b32_e32 v228, 16, v182
	v_and_b32_e32 v229, 0xffff0000, v182
	v_lshlrev_b32_e32 v182, 16, v183
	v_and_b32_e32 v183, 0xffff0000, v183
	v_lshlrev_b32_e32 v184, 16, v185
	v_and_b32_e32 v185, 0xffff0000, v185
	v_lshlrev_b32_e32 v238, 16, v192
	v_and_b32_e32 v239, 0xffff0000, v192
	v_pk_add_f32 v[106:107], v[106:107], v[226:227]
	v_pk_add_f32 v[104:105], v[104:105], v[224:225]
	v_lshlrev_b32_e32 v156, 16, v200
	v_cvt_pk_bf16_f32 v114, v104, v105
	v_cvt_pk_bf16_f32 v115, v106, v107
	global_store_dwordx4 v[118:119], v[112:115], off
	v_and_b32_e32 v157, 0xffff0000, v200
	v_pk_add_f32 v[102:103], v[102:103], v[182:183]
	v_pk_add_f32 v[112:113], v[92:93], v[230:231]
	v_pk_add_f32 v[92:93], v[98:99], v[186:187]
	v_lshl_add_u64 v[98:99], s[90:91], 0, v[154:155]
	v_pk_add_f32 v[100:101], v[100:101], v[228:229]
	v_pk_add_f32 v[94:95], v[94:95], v[184:185]
	v_cvt_pk_bf16_f32 v114, v100, v101
	v_cvt_pk_bf16_f32 v115, v102, v103
	v_cvt_pk_bf16_f32 v116, v112, v113
	v_lshlrev_b32_e32 v234, 16, v188
	v_cvt_pk_bf16_f32 v117, v94, v95
	global_store_dwordx4 v[118:119], v[114:117], off offset:256
	v_lshl_add_u64 v[118:119], v[98:99], 0, v[144:145]
	v_pk_add_f32 v[98:99], v[76:77], v[238:239]
	v_pk_add_f32 v[76:77], v[82:83], v[172:173]
	v_lshl_add_u64 v[82:83], s[90:91], 0, v[152:153]
	v_lshl_add_u64 v[122:123], v[82:83], 0, v[144:145]
	v_pk_add_f32 v[82:83], v[64:65], v[156:157]
	v_and_b32_e32 v65, 64, v174
	v_and_b32_e32 v235, 0xffff0000, v188
	v_lshlrev_b32_e32 v188, 16, v189
	v_and_b32_e32 v189, 0xffff0000, v189
	v_lshlrev_b32_e32 v236, 16, v190
	v_and_b32_e32 v237, 0xffff0000, v190
	v_pk_add_f32 v[96:97], v[96:97], v[232:233]
	v_xor_b32_e32 v64, 16, v174
	v_cvt_pk_bf16_f32 v114, v96, v97
	v_add_u32_e32 v65, 64, v65
	v_lshlrev_b32_e32 v190, 16, v191
	v_and_b32_e32 v191, 0xffff0000, v191
	v_lshlrev_b32_e32 v192, 16, v193
	v_and_b32_e32 v193, 0xffff0000, v193
	v_pk_add_f32 v[90:91], v[90:91], v[188:189]
	v_pk_add_f32 v[88:89], v[88:89], v[234:235]
	v_cvt_pk_bf16_f32 v115, v92, v93
	v_pk_add_f32 v[84:85], v[84:85], v[236:237]
	v_cvt_pk_bf16_f32 v116, v88, v89
	v_cvt_pk_bf16_f32 v117, v90, v91
	global_store_dwordx4 v[118:119], v[114:117], off
	v_cmp_lt_i32_e32 vcc, v64, v65
	v_lshlrev_b32_e32 v164, 16, v196
	v_cvt_pk_bf16_f32 v114, v84, v85
	v_and_b32_e32 v165, 0xffff0000, v196
	v_lshlrev_b32_e32 v168, 16, v197
	v_and_b32_e32 v169, 0xffff0000, v197
	v_pk_add_f32 v[86:87], v[86:87], v[190:191]
	v_pk_add_f32 v[78:79], v[78:79], v[192:193]
	v_cvt_pk_bf16_f32 v115, v86, v87
	v_cvt_pk_bf16_f32 v116, v98, v99
	v_pk_add_f32 v[80:81], v[80:81], v[166:167]
	v_cvt_pk_bf16_f32 v117, v78, v79
	global_store_dwordx4 v[118:119], v[114:117], off offset:256
	v_cndmask_b32_e32 v64, v174, v64, vcc
	v_pk_add_f32 v[74:75], v[74:75], v[168:169]
	v_cvt_pk_bf16_f32 v114, v80, v81
	v_pk_add_f32 v[72:73], v[72:73], v[164:165]
	v_cvt_pk_bf16_f32 v115, v76, v77
	v_lshlrev_b32_e32 v158, 16, v198
	v_cvt_pk_bf16_f32 v116, v72, v73
	v_cvt_pk_bf16_f32 v117, v74, v75
	global_store_dwordx4 v[122:123], v[114:117], off
	v_and_b32_e32 v159, 0xffff0000, v198
	v_lshlrev_b32_e32 v162, 16, v199
	v_lshlrev_b32_e32 v114, 2, v64
	ds_bpermute_b32 v64, v114, v126
	v_xor_b32_e32 v115, 32, v174
	v_cmp_lt_i32_e32 vcc, v115, v65
	v_and_b32_e32 v163, 0xffff0000, v199
	v_lshlrev_b32_e32 v160, 16, v201
	v_cndmask_b32_e32 v65, v174, v115, vcc
	v_lshlrev_b32_e32 v115, 2, v65
	s_waitcnt lgkmcnt(0)
	v_add_f32_e32 v116, v126, v64
	ds_bpermute_b32 v117, v115, v116
	v_and_b32_e32 v161, 0xffff0000, v201
	v_pk_add_f32 v[70:71], v[70:71], v[162:163]
	v_pk_add_f32 v[68:69], v[68:69], v[158:159]
	v_pk_add_f32 v[66:67], v[66:67], v[160:161]
	v_lshl_add_u64 v[64:65], v[150:151], 2, s[8:9]
	v_cvt_pk_bf16_f32 v118, v68, v69
	v_cvt_pk_bf16_f32 v119, v70, v71
	v_cvt_pk_bf16_f32 v120, v82, v83
	v_cvt_pk_bf16_f32 v121, v66, v67
	global_store_dwordx4 v[122:123], v[118:121], off offset:256
	s_and_saveexec_b64 s[30:31], s[2:3]
	s_cbranch_execz .LBB0_1163
	s_waitcnt lgkmcnt(0)
	v_add_f32_e32 v116, v116, v117
	global_atomic_add_f32 v[64:65], v116, off

.LBB0_1218:
	ds_read_b128 v[144:147], v151
	ds_read_b128 v[156:159], v151 offset:1024
	ds_read_b128 v[160:163], v151 offset:2048
	ds_read_b128 v[164:167], v151 offset:3072
	s_add_u32 s30, s28, 0xfffc0080
	s_addc_u32 s31, s29, -1
	s_cmp_eq_u32 s63, 12
	s_cselect_b32 s35, s23, s31
	s_cselect_b32 s34, s59, s30
	s_cselect_b32 s31, s21, s62
	s_cselect_b32 s30, s60, s61
	v_lshl_add_u64 v[172:173], s[28:29], 0, v[136:137]
	s_add_i32 m0, s40, 0xc000
	ds_read_b128 v[168:171], v152
	ds_read_b128 v[176:179], v152 offset:1024
	ds_read_b128 v[180:183], v152 offset:2048
	ds_read_b128 v[184:187], v152 offset:3072
	ds_read_b128 v[188:191], v152 offset:4096
	ds_read_b128 v[192:195], v152 offset:5120
	ds_read_b128 v[196:199], v152 offset:6144
	ds_read_b128 v[200:203], v152 offset:7168
	global_load_lds_dwordx4 v[172:173], off
	s_add_i32 m0, s40, 0xe000
	v_lshl_add_u64 v[172:173], s[28:29], 0, v[138:139]
	global_load_lds_dwordx4 v[172:173], off
	s_waitcnt lgkmcnt(8)
	s_setprio 1
	s_barrier
	s_waitcnt lgkmcnt(0)
	v_mfma_f32_16x16x32_bf16 v[124:127], v[144:147], v[168:171], v[124:127]
	v_mfma_f32_16x16x32_bf16 v[120:123], v[160:163], v[168:171], v[120:123]
	v_mfma_f32_16x16x32_bf16 v[116:119], v[144:147], v[180:183], v[116:119]
	v_mfma_f32_16x16x32_bf16 v[112:115], v[160:163], v[180:183], v[112:115]
	v_mfma_f32_16x16x32_bf16 v[92:95], v[144:147], v[188:191], v[92:95]
	v_mfma_f32_16x16x32_bf16 v[88:91], v[160:163], v[188:191], v[88:91]
	v_mfma_f32_16x16x32_bf16 v[76:79], v[144:147], v[196:199], v[76:79]
	v_mfma_f32_16x16x32_bf16 v[72:75], v[160:163], v[196:199], v[72:75]
	v_mfma_f32_16x16x32_bf16 v[124:127], v[156:159], v[176:179], v[124:127]
	v_mfma_f32_16x16x32_bf16 v[120:123], v[164:167], v[176:179], v[120:123]
	v_mfma_f32_16x16x32_bf16 v[116:119], v[156:159], v[184:187], v[116:119]
	v_mfma_f32_16x16x32_bf16 v[112:115], v[164:167], v[184:187], v[112:115]
	v_mfma_f32_16x16x32_bf16 v[92:95], v[156:159], v[192:195], v[92:95]
	v_mfma_f32_16x16x32_bf16 v[88:91], v[164:167], v[192:195], v[88:91]
	v_mfma_f32_16x16x32_bf16 v[76:79], v[156:159], v[200:203], v[76:79]
	v_mfma_f32_16x16x32_bf16 v[72:75], v[164:167], v[200:203], v[72:75]
	s_setprio 0
	s_barrier
	s_add_i32 s64, s52, s39
	v_lshl_add_u64 v[172:173], s[30:31], 0, v[130:131]
	s_mov_b32 m0, s64
	ds_read_b128 v[204:207], v153
	ds_read_b128 v[212:215], v153 offset:1024
	ds_read_b128 v[216:219], v153 offset:2048
	ds_read_b128 v[220:223], v153 offset:3072
	global_load_lds_dwordx4 v[172:173], off
	s_add_i32 m0, s64, 0x2000
	v_lshl_add_u64 v[208:209], s[30:31], 0, v[134:135]
	global_load_lds_dwordx4 v[208:209], off
	s_setprio 1
	s_barrier
	s_waitcnt lgkmcnt(0)
	v_mfma_f32_16x16x32_bf16 v[108:111], v[204:207], v[168:171], v[108:111]
	v_mfma_f32_16x16x32_bf16 v[104:107], v[216:219], v[168:171], v[104:107]
	v_mfma_f32_16x16x32_bf16 v[100:103], v[204:207], v[180:183], v[100:103]
	v_mfma_f32_16x16x32_bf16 v[96:99], v[216:219], v[180:183], v[96:99]
	v_mfma_f32_16x16x32_bf16 v[84:87], v[204:207], v[188:191], v[84:87]
	v_mfma_f32_16x16x32_bf16 v[80:83], v[216:219], v[188:191], v[80:83]
	v_mfma_f32_16x16x32_bf16 v[68:71], v[204:207], v[196:199], v[68:71]
	v_mfma_f32_16x16x32_bf16 v[64:67], v[216:219], v[196:199], v[64:67]
	v_mfma_f32_16x16x32_bf16 v[108:111], v[212:215], v[176:179], v[108:111]
	v_mfma_f32_16x16x32_bf16 v[104:107], v[220:223], v[176:179], v[104:107]
	v_mfma_f32_16x16x32_bf16 v[100:103], v[212:215], v[184:187], v[100:103]
	v_mfma_f32_16x16x32_bf16 v[96:99], v[220:223], v[184:187], v[96:99]
	v_mfma_f32_16x16x32_bf16 v[84:87], v[212:215], v[192:195], v[84:87]
	v_mfma_f32_16x16x32_bf16 v[80:83], v[220:223], v[192:195], v[80:83]
	v_mfma_f32_16x16x32_bf16 v[68:71], v[212:215], v[200:203], v[68:71]
	v_mfma_f32_16x16x32_bf16 v[64:67], v[220:223], v[200:203], v[64:67]
	s_setprio 0
	s_mov_b32 m0, s40
	v_lshl_add_u64 v[224:225], s[34:35], 0, v[128:129]
	s_barrier
	ds_read_b128 v[168:171], v152 offset:16384
	ds_read_b128 v[176:179], v152 offset:17408
	ds_read_b128 v[180:183], v152 offset:18432
	ds_read_b128 v[184:187], v152 offset:19456
	ds_read_b128 v[188:191], v152 offset:20480
	ds_read_b128 v[192:195], v152 offset:21504
	ds_read_b128 v[196:199], v152 offset:22528
	ds_read_b128 v[200:203], v152 offset:23552
	global_load_lds_dwordx4 v[224:225], off
	s_mov_b32 m0, s41
	v_lshl_add_u64 v[226:227], s[34:35], 0, v[132:133]
	global_load_lds_dwordx4 v[226:227], off
	s_setprio 1
	s_barrier
	s_waitcnt lgkmcnt(0)
	v_mfma_f32_16x16x32_bf16 v[60:63], v[144:147], v[168:171], v[60:63]
	v_mfma_f32_16x16x32_bf16 v[56:59], v[160:163], v[168:171], v[56:59]
	v_mfma_f32_16x16x32_bf16 v[44:47], v[144:147], v[180:183], v[44:47]
	v_mfma_f32_16x16x32_bf16 v[40:43], v[160:163], v[180:183], v[40:43]
	v_mfma_f32_16x16x32_bf16 v[28:31], v[144:147], v[188:191], v[28:31]
	v_mfma_f32_16x16x32_bf16 v[24:27], v[160:163], v[188:191], v[24:27]
	v_mfma_f32_16x16x32_bf16 v[12:15], v[144:147], v[196:199], v[12:15]
	v_mfma_f32_16x16x32_bf16 v[8:11], v[160:163], v[196:199], v[8:11]
	v_mfma_f32_16x16x32_bf16 v[60:63], v[156:159], v[176:179], v[60:63]
	v_mfma_f32_16x16x32_bf16 v[56:59], v[164:167], v[176:179], v[56:59]
	v_mfma_f32_16x16x32_bf16 v[44:47], v[156:159], v[184:187], v[44:47]
	v_mfma_f32_16x16x32_bf16 v[40:43], v[164:167], v[184:187], v[40:43]
	v_mfma_f32_16x16x32_bf16 v[28:31], v[156:159], v[192:195], v[28:31]
	v_mfma_f32_16x16x32_bf16 v[24:27], v[164:167], v[192:195], v[24:27]
	v_mfma_f32_16x16x32_bf16 v[12:15], v[156:159], v[200:203], v[12:15]
	v_mfma_f32_16x16x32_bf16 v[8:11], v[164:167], v[200:203], v[8:11]
	s_setprio 0
	s_barrier
	s_add_u32 s64, s30, 0x40000
	s_addc_u32 s65, s31, 0
	s_add_i32 s66, s53, s39
	s_mov_b32 m0, s66
	v_lshl_add_u64 v[144:145], s[64:65], 0, v[130:131]
	global_load_lds_dwordx4 v[144:145], off
	s_add_i32 m0, s66, 0x2000
	v_lshl_add_u64 v[144:145], s[64:65], 0, v[134:135]
	global_load_lds_dwordx4 v[144:145], off
	s_waitcnt vmcnt(6)
	s_setprio 1
	s_barrier
	v_mfma_f32_16x16x32_bf16 v[52:55], v[204:207], v[168:171], v[52:55]
	v_mfma_f32_16x16x32_bf16 v[48:51], v[216:219], v[168:171], v[48:51]
	v_mfma_f32_16x16x32_bf16 v[36:39], v[204:207], v[180:183], v[36:39]
	v_mfma_f32_16x16x32_bf16 v[32:35], v[216:219], v[180:183], v[32:35]
	v_mfma_f32_16x16x32_bf16 v[20:23], v[204:207], v[188:191], v[20:23]
	v_mfma_f32_16x16x32_bf16 v[16:19], v[216:219], v[188:191], v[16:19]
	v_mfma_f32_16x16x32_bf16 v[4:7], v[204:207], v[196:199], v[4:7]
	v_mfma_f32_16x16x32_bf16 v[0:3], v[216:219], v[196:199], v[0:3]
	v_mfma_f32_16x16x32_bf16 v[52:55], v[212:215], v[176:179], v[52:55]
	v_mfma_f32_16x16x32_bf16 v[48:51], v[220:223], v[176:179], v[48:51]
	v_mfma_f32_16x16x32_bf16 v[36:39], v[212:215], v[184:187], v[36:39]
	v_mfma_f32_16x16x32_bf16 v[32:35], v[220:223], v[184:187], v[32:35]
	v_mfma_f32_16x16x32_bf16 v[20:23], v[212:215], v[192:195], v[20:23]
	v_mfma_f32_16x16x32_bf16 v[16:19], v[220:223], v[192:195], v[16:19]
	v_mfma_f32_16x16x32_bf16 v[4:7], v[212:215], v[200:203], v[4:7]
	v_mfma_f32_16x16x32_bf16 v[0:3], v[220:223], v[200:203], v[0:3]
	s_setprio 0
	s_add_i32 s64, 0, 0x18000
	v_add_u32_e32 v155, s64, v149
	s_barrier
	ds_read_b128 v[144:147], v155
	ds_read_b128 v[156:159], v155 offset:1024
	ds_read_b128 v[160:163], v155 offset:2048
	ds_read_b128 v[164:167], v155 offset:3072
	s_add_u32 s34, s34, 0x40000
	s_addc_u32 s35, s35, 0
	s_mov_b32 m0, s42
	v_lshl_add_u64 v[204:205], s[34:35], 0, v[128:129]
	ds_read_b128 v[168:171], v152 offset:32768
	ds_read_b128 v[176:179], v152 offset:33792
	ds_read_b128 v[180:183], v152 offset:34816
	ds_read_b128 v[184:187], v152 offset:35840
	ds_read_b128 v[188:191], v152 offset:36864
	ds_read_b128 v[192:195], v152 offset:37888
	ds_read_b128 v[196:199], v152 offset:38912
	ds_read_b128 v[200:203], v152 offset:39936
	global_load_lds_dwordx4 v[204:205], off
	s_mov_b32 m0, s43
	v_lshl_add_u64 v[204:205], s[34:35], 0, v[132:133]
	global_load_lds_dwordx4 v[204:205], off
	s_waitcnt lgkmcnt(8)
	s_setprio 1
	s_barrier
	s_waitcnt lgkmcnt(0)
	v_mfma_f32_16x16x32_bf16 v[124:127], v[144:147], v[168:171], v[124:127]
	v_mfma_f32_16x16x32_bf16 v[120:123], v[160:163], v[168:171], v[120:123]
	v_mfma_f32_16x16x32_bf16 v[116:119], v[144:147], v[180:183], v[116:119]
	v_mfma_f32_16x16x32_bf16 v[112:115], v[160:163], v[180:183], v[112:115]
	v_mfma_f32_16x16x32_bf16 v[92:95], v[144:147], v[188:191], v[92:95]
	v_mfma_f32_16x16x32_bf16 v[88:91], v[160:163], v[188:191], v[88:91]
	v_mfma_f32_16x16x32_bf16 v[76:79], v[144:147], v[196:199], v[76:79]
	v_mfma_f32_16x16x32_bf16 v[72:75], v[160:163], v[196:199], v[72:75]
	v_mfma_f32_16x16x32_bf16 v[124:127], v[156:159], v[176:179], v[124:127]
	v_mfma_f32_16x16x32_bf16 v[120:123], v[164:167], v[176:179], v[120:123]
	v_mfma_f32_16x16x32_bf16 v[116:119], v[156:159], v[184:187], v[116:119]
	v_mfma_f32_16x16x32_bf16 v[112:115], v[164:167], v[184:187], v[112:115]
	v_mfma_f32_16x16x32_bf16 v[92:95], v[156:159], v[192:195], v[92:95]
	v_mfma_f32_16x16x32_bf16 v[88:91], v[164:167], v[192:195], v[88:91]
	v_mfma_f32_16x16x32_bf16 v[76:79], v[156:159], v[200:203], v[76:79]
	v_mfma_f32_16x16x32_bf16 v[72:75], v[164:167], v[200:203], v[72:75]
	s_setprio 0
	s_barrier
	s_add_i32 s34, 0, 0x1c000
	s_add_i32 s35, s64, s39
	v_add_u32_e32 v155, s34, v149
	v_lshl_add_u64 v[172:173], v[172:173], 0, s[6:7]
	s_mov_b32 m0, s35
	ds_read_b128 v[204:207], v155
	ds_read_b128 v[212:215], v155 offset:1024
	ds_read_b128 v[216:219], v155 offset:2048
	ds_read_b128 v[220:223], v155 offset:3072
	global_load_lds_dwordx4 v[172:173], off
	s_add_i32 m0, s35, 0x2000
	v_lshl_add_u64 v[172:173], v[208:209], 0, s[6:7]
	global_load_lds_dwordx4 v[172:173], off
	s_setprio 1
	s_barrier
	s_waitcnt lgkmcnt(0)
	v_mfma_f32_16x16x32_bf16 v[108:111], v[204:207], v[168:171], v[108:111]
	v_mfma_f32_16x16x32_bf16 v[104:107], v[216:219], v[168:171], v[104:107]
	v_mfma_f32_16x16x32_bf16 v[100:103], v[204:207], v[180:183], v[100:103]
	v_mfma_f32_16x16x32_bf16 v[96:99], v[216:219], v[180:183], v[96:99]
	v_mfma_f32_16x16x32_bf16 v[84:87], v[204:207], v[188:191], v[84:87]
	v_mfma_f32_16x16x32_bf16 v[80:83], v[216:219], v[188:191], v[80:83]
	v_mfma_f32_16x16x32_bf16 v[68:71], v[204:207], v[196:199], v[68:71]
	v_mfma_f32_16x16x32_bf16 v[64:67], v[216:219], v[196:199], v[64:67]
	v_mfma_f32_16x16x32_bf16 v[108:111], v[212:215], v[176:179], v[108:111]
	v_mfma_f32_16x16x32_bf16 v[104:107], v[220:223], v[176:179], v[104:107]
	v_mfma_f32_16x16x32_bf16 v[100:103], v[212:215], v[184:187], v[100:103]
	v_mfma_f32_16x16x32_bf16 v[96:99], v[220:223], v[184:187], v[96:99]
	v_mfma_f32_16x16x32_bf16 v[84:87], v[212:215], v[192:195], v[84:87]
	v_mfma_f32_16x16x32_bf16 v[80:83], v[220:223], v[192:195], v[80:83]
	v_mfma_f32_16x16x32_bf16 v[68:71], v[212:215], v[200:203], v[68:71]
	v_mfma_f32_16x16x32_bf16 v[64:67], v[220:223], v[200:203], v[64:67]
	s_setprio 0
	s_mov_b32 m0, s49
	v_lshl_add_u64 v[172:173], v[224:225], 0, s[6:7]
	s_barrier
	ds_read_b128 v[168:171], v152 offset:49152
	ds_read_b128 v[176:179], v152 offset:50176
	ds_read_b128 v[180:183], v152 offset:51200
	ds_read_b128 v[184:187], v152 offset:52224
	ds_read_b128 v[188:191], v152 offset:53248
	ds_read_b128 v[192:195], v152 offset:54272
	ds_read_b128 v[196:199], v152 offset:55296
	ds_read_b128 v[200:203], v152 offset:56320
	global_load_lds_dwordx4 v[172:173], off
	s_mov_b32 m0, s50
	v_lshl_add_u64 v[172:173], v[226:227], 0, s[6:7]
	global_load_lds_dwordx4 v[172:173], off
	s_setprio 1
	s_barrier
	s_waitcnt lgkmcnt(0)
	v_mfma_f32_16x16x32_bf16 v[60:63], v[144:147], v[168:171], v[60:63]
	v_mfma_f32_16x16x32_bf16 v[56:59], v[160:163], v[168:171], v[56:59]
	v_mfma_f32_16x16x32_bf16 v[44:47], v[144:147], v[180:183], v[44:47]
	v_mfma_f32_16x16x32_bf16 v[40:43], v[160:163], v[180:183], v[40:43]
	v_mfma_f32_16x16x32_bf16 v[28:31], v[144:147], v[188:191], v[28:31]
	v_mfma_f32_16x16x32_bf16 v[24:27], v[160:163], v[188:191], v[24:27]
	v_mfma_f32_16x16x32_bf16 v[12:15], v[144:147], v[196:199], v[12:15]
	v_mfma_f32_16x16x32_bf16 v[8:11], v[160:163], v[196:199], v[8:11]
	v_mfma_f32_16x16x32_bf16 v[60:63], v[156:159], v[176:179], v[60:63]
	v_mfma_f32_16x16x32_bf16 v[56:59], v[164:167], v[176:179], v[56:59]
	v_mfma_f32_16x16x32_bf16 v[44:47], v[156:159], v[184:187], v[44:47]
	v_mfma_f32_16x16x32_bf16 v[40:43], v[164:167], v[184:187], v[40:43]
	v_mfma_f32_16x16x32_bf16 v[28:31], v[156:159], v[192:195], v[28:31]
	v_mfma_f32_16x16x32_bf16 v[24:27], v[164:167], v[192:195], v[24:27]
	v_mfma_f32_16x16x32_bf16 v[12:15], v[156:159], v[200:203], v[12:15]
	v_mfma_f32_16x16x32_bf16 v[8:11], v[164:167], v[200:203], v[8:11]
	s_setprio 0
	s_barrier
	s_add_u32 s30, s30, 0x40080
	s_addc_u32 s31, s31, 0
	s_add_i32 s34, s34, s39
	s_mov_b32 m0, s34
	v_lshl_add_u64 v[144:145], s[30:31], 0, v[130:131]
	global_load_lds_dwordx4 v[144:145], off
	s_add_i32 m0, s34, 0x2000
	v_lshl_add_u64 v[144:145], s[30:31], 0, v[134:135]
	global_load_lds_dwordx4 v[144:145], off
	s_waitcnt vmcnt(6)
	s_setprio 1
	s_barrier
	v_mfma_f32_16x16x32_bf16 v[52:55], v[204:207], v[168:171], v[52:55]
	v_mfma_f32_16x16x32_bf16 v[48:51], v[216:219], v[168:171], v[48:51]
	v_mfma_f32_16x16x32_bf16 v[36:39], v[204:207], v[180:183], v[36:39]
	v_mfma_f32_16x16x32_bf16 v[32:35], v[216:219], v[180:183], v[32:35]
	v_mfma_f32_16x16x32_bf16 v[20:23], v[204:207], v[188:191], v[20:23]
	v_mfma_f32_16x16x32_bf16 v[16:19], v[216:219], v[188:191], v[16:19]
	v_mfma_f32_16x16x32_bf16 v[4:7], v[204:207], v[196:199], v[4:7]
	v_mfma_f32_16x16x32_bf16 v[0:3], v[216:219], v[196:199], v[0:3]
	v_mfma_f32_16x16x32_bf16 v[52:55], v[212:215], v[176:179], v[52:55]
	v_mfma_f32_16x16x32_bf16 v[48:51], v[220:223], v[176:179], v[48:51]
	v_mfma_f32_16x16x32_bf16 v[36:39], v[212:215], v[184:187], v[36:39]
	v_mfma_f32_16x16x32_bf16 v[32:35], v[220:223], v[184:187], v[32:35]
	v_mfma_f32_16x16x32_bf16 v[20:23], v[212:215], v[192:195], v[20:23]
	v_mfma_f32_16x16x32_bf16 v[16:19], v[220:223], v[192:195], v[16:19]
	v_mfma_f32_16x16x32_bf16 v[4:7], v[212:215], v[200:203], v[4:7]
	v_mfma_f32_16x16x32_bf16 v[0:3], v[220:223], v[200:203], v[0:3]
	s_setprio 0
	s_add_i32 s63, s63, 2
	s_add_u32 s28, s28, 0x100
	s_addc_u32 s29, s29, 0
	s_add_u32 s61, s61, 0x100
	s_addc_u32 s62, s62, 0
	s_cmp_gt_u32 s63, 13
	s_barrier
	s_cbranch_scc0 .LBB0_1218
	v_lshl_add_u32 v146, s0, 8, v148
	v_ashrrev_i32_e32 v147, 31, v146
	v_lshl_add_u64 v[144:145], v[146:147], 2, s[8:9]
	global_load_dword v155, v[144:145], off
	global_load_dword v162, v[144:145], off offset:64
	global_load_dword v163, v[144:145], off offset:128
	global_load_dword v164, v[144:145], off offset:192
	global_load_dword v165, v[144:145], off offset:512
	global_load_dword v166, v[144:145], off offset:576
	global_load_dword v167, v[144:145], off offset:640
	global_load_dword v168, v[144:145], off offset:704
	v_lshl_or_b32 v144, s1, 8, v150
	v_ashrrev_i32_e32 v145, 31, v144
	v_lshlrev_b64 v[158:159], 13, v[146:147]
	v_lshlrev_b64 v[160:161], 1, v[144:145]
	v_lshl_add_u64 v[144:145], s[92:93], 0, v[158:159]
	v_lshl_add_u64 v[144:145], v[144:145], 0, v[160:161]
	v_or_b32_e32 v156, 16, v146
	v_ashrrev_i32_e32 v157, 31, v156
	v_lshlrev_b64 v[156:157], 13, v[156:157]
	v_lshl_add_u64 v[156:157], s[92:93], 0, v[156:157]
	v_lshl_add_u64 v[156:157], v[156:157], 0, v[160:161]
	s_mov_b64 s[30:31], s[26:27]
	s_mov_b64 s[28:29], s[24:25]
	s_waitcnt vmcnt(0)
	v_fmamk_f32 v147, v155, 0x3a800000, v154
	v_mul_f32_e32 v158, 0x4b800000, v147
	v_cmp_gt_f32_e32 vcc, s54, v147
	v_fmamk_f32 v155, v162, 0x3a800000, v154
	v_mul_f32_e32 v162, 0x4b800000, v155
	v_cndmask_b32_e32 v147, v147, v158, vcc
	v_rsq_f32_e32 v158, v147
	v_cmp_gt_f32_e64 s[0:1], s54, v155
	v_fmamk_f32 v159, v163, 0x3a800000, v154
	v_fmamk_f32 v163, v164, 0x3a800000, v154
	v_cndmask_b32_e64 v155, v155, v162, s[0:1]
	v_rsq_f32_e32 v155, v155
	v_mul_f32_e32 v162, 0x45800000, v158
	v_cndmask_b32_e32 v158, v158, v162, vcc
	v_pk_mul_f32 v[124:125], v[124:125], v[158:159] op_sel_hi:[1,0]
	v_pk_mul_f32 v[104:105], v[104:105], v[158:159] op_sel_hi:[1,0]
	v_fmamk_f32 v164, v165, 0x3a800000, v154
	v_fmamk_f32 v165, v166, 0x3a800000, v154
	v_fmamk_f32 v166, v167, 0x3a800000, v154
	v_mul_f32_e32 v167, 0x45800000, v155
	v_pk_mul_f32 v[126:127], v[126:127], v[158:159] op_sel_hi:[1,0]
	v_pk_mul_f32 v[122:123], v[122:123], v[158:159] op_sel_hi:[1,0]
	v_pk_mul_f32 v[120:121], v[120:121], v[158:159] op_sel_hi:[1,0]
	v_pk_mul_f32 v[108:109], v[108:109], v[158:159] op_sel_hi:[1,0]
	v_pk_mul_f32 v[106:107], v[106:107], v[158:159] op_sel_hi:[1,0]
	v_max_f32_e32 v124, 0, v124
	v_max_f32_e32 v125, 0, v125
	v_max_f32_e32 v104, 0, v104
	v_cndmask_b32_e64 v162, v155, v167, s[0:1]
	v_pk_mul_f32 v[110:111], v[110:111], v[158:159] op_sel_hi:[1,0]
	v_max_f32_e32 v120, 0, v120
	v_max_f32_e32 v121, 0, v121
	v_max_f32_e32 v126, 0, v126
	v_max_f32_e32 v122, 0, v122
	v_max_f32_e32 v127, 0, v127
	v_max_f32_e32 v123, 0, v123
	v_max_f32_e32 v108, 0, v108
	v_max_f32_e32 v109, 0, v109
	v_max_f32_e32 v105, 0, v105
	v_max_f32_e32 v106, 0, v106
	v_max_f32_e32 v107, 0, v107
	v_mul_f32_e32 v124, v124, v124
	v_mul_f32_e32 v125, v125, v125
	v_mul_f32_e32 v155, v104, v104
	v_cvt_pk_bf16_f32 v104, v124, v125
	v_fmamk_f32 v147, v168, 0x3a800000, v154
	v_pk_mul_f32 v[112:113], v[112:113], v[162:163] op_sel_hi:[1,0]
	v_max_f32_e32 v110, 0, v110
	v_max_f32_e32 v111, 0, v111
	v_mul_f32_e32 v120, v120, v120
	v_mul_f32_e32 v121, v121, v121
	v_mul_f32_e32 v126, v126, v126
	v_mul_f32_e32 v122, v122, v122
	v_mul_f32_e32 v127, v127, v127
	v_mul_f32_e32 v123, v123, v123
	v_mul_f32_e32 v108, v108, v108
	v_mul_f32_e32 v109, v109, v109
	v_mul_f32_e32 v158, v105, v105
	v_mul_f32_e32 v167, v106, v106
	v_mul_f32_e32 v168, v107, v107
	v_cvt_pk_bf16_f32 v105, v126, v127
	v_cvt_pk_bf16_f32 v106, v120, v121
	v_cvt_pk_bf16_f32 v107, v122, v123
	global_store_dwordx4 v[144:145], v[104:107], off nt
	v_pk_mul_f32 v[116:117], v[116:117], v[162:163] op_sel_hi:[1,0]
	v_mul_f32_e32 v110, v110, v110
	v_cvt_pk_bf16_f32 v104, v108, v109
	v_mul_f32_e32 v111, v111, v111
	v_cvt_pk_bf16_f32 v105, v110, v111
	v_cvt_pk_bf16_f32 v106, v155, v158
	v_cvt_pk_bf16_f32 v107, v167, v168
	global_store_dwordx4 v[144:145], v[104:107], off offset:256 nt
	v_pk_mul_f32 v[118:119], v[118:119], v[162:163] op_sel_hi:[1,0]
	v_pk_mul_f32 v[114:115], v[114:115], v[162:163] op_sel_hi:[1,0]
	v_max_f32_e32 v104, 0, v112
	v_mul_f32_e32 v106, v104, v104
	v_max_f32_e32 v104, 0, v117
	v_max_f32_e32 v116, 0, v116
	v_max_f32_e32 v107, 0, v113
	v_mul_f32_e32 v104, v104, v104
	v_pk_mul_f32 v[98:99], v[98:99], v[162:163] op_sel_hi:[1,0]
	v_pk_mul_f32 v[96:97], v[96:97], v[162:163] op_sel_hi:[1,0]
	v_mul_f32_e32 v105, v116, v116
	v_mul_f32_e32 v107, v107, v107
	v_max_f32_e32 v108, 0, v118
	v_max_f32_e32 v109, 0, v114
	v_max_f32_e32 v110, 0, v119
	v_max_f32_e32 v111, 0, v115
	v_cvt_pk_bf16_f32 v104, v105, v104
	v_pk_mul_f32 v[102:103], v[102:103], v[162:163] op_sel_hi:[1,0]
	v_pk_mul_f32 v[100:101], v[100:101], v[162:163] op_sel_hi:[1,0]
	v_max_f32_e32 v96, 0, v96
	v_max_f32_e32 v97, 0, v97
	v_max_f32_e32 v98, 0, v98
	v_mul_f32_e32 v108, v108, v108
	v_mul_f32_e32 v109, v109, v109
	v_mul_f32_e32 v110, v110, v110
	v_mul_f32_e32 v111, v111, v111
	v_cvt_pk_bf16_f32 v105, v108, v110
	v_cvt_pk_bf16_f32 v106, v106, v107
	v_cvt_pk_bf16_f32 v107, v109, v111
	global_store_dwordx4 v[156:157], v[104:107], off nt
	v_max_f32_e32 v100, 0, v100
	v_max_f32_e32 v99, 0, v99
	v_mul_f32_e32 v104, v96, v96
	v_max_f32_e32 v96, 0, v101
	v_mul_f32_e32 v101, v97, v97
	v_max_f32_e32 v97, 0, v102
	v_mul_f32_e32 v102, v98, v98
	v_max_f32_e32 v98, 0, v103
	v_mul_f32_e32 v96, v96, v96
	v_mul_f32_e32 v97, v97, v97
	v_mul_f32_e32 v98, v98, v98
	v_mul_f32_e32 v100, v100, v100
	v_mul_f32_e32 v99, v99, v99
	v_cvt_pk_bf16_f32 v96, v100, v96
	v_cvt_pk_bf16_f32 v97, v97, v98
	v_cvt_pk_bf16_f32 v98, v104, v101
	v_cvt_pk_bf16_f32 v99, v102, v99
	global_store_dwordx4 v[156:157], v[96:99], off offset:256 nt
	v_cmp_gt_f32_e32 vcc, s54, v159
	s_mov_b32 s1, s20
	v_mul_f32_e32 v98, 0x4b800000, v159
	v_cndmask_b32_e32 v98, v159, v98, vcc
	v_rsq_f32_e32 v98, v98
	v_or_b32_e32 v96, 32, v146
	v_ashrrev_i32_e32 v97, 31, v96
	v_lshlrev_b64 v[96:97], 13, v[96:97]
	v_mul_f32_e32 v99, 0x45800000, v98
	v_cndmask_b32_e32 v98, v98, v99, vcc
	v_pk_mul_f32 v[88:89], v[88:89], v[98:99] op_sel_hi:[1,0]
	v_pk_mul_f32 v[92:93], v[92:93], v[98:99] op_sel_hi:[1,0]
	v_pk_mul_f32 v[90:91], v[90:91], v[98:99] op_sel_hi:[1,0]
	v_max_f32_e32 v88, 0, v88
	v_pk_mul_f32 v[94:95], v[94:95], v[98:99] op_sel_hi:[1,0]
	v_mul_f32_e32 v99, v88, v88
	v_max_f32_e32 v88, 0, v93
	v_max_f32_e32 v89, 0, v89
	v_max_f32_e32 v90, 0, v90
	v_lshl_add_u64 v[96:97], s[92:93], 0, v[96:97]
	v_max_f32_e32 v92, 0, v92
	v_mul_f32_e32 v88, v88, v88
	v_mul_f32_e32 v93, v89, v89
	v_max_f32_e32 v89, 0, v94
	v_mul_f32_e32 v94, v90, v90
	v_max_f32_e32 v90, 0, v95
	v_max_f32_e32 v91, 0, v91
	v_pk_mul_f32 v[82:83], v[82:83], v[98:99] op_sel_hi:[1,0]
	v_pk_mul_f32 v[80:81], v[80:81], v[98:99] op_sel_hi:[1,0]
	v_lshl_add_u64 v[96:97], v[96:97], 0, v[160:161]
	v_mul_f32_e32 v92, v92, v92
	v_mul_f32_e32 v89, v89, v89
	v_mul_f32_e32 v90, v90, v90
	v_mul_f32_e32 v91, v91, v91
	v_cvt_pk_bf16_f32 v88, v92, v88
	v_pk_mul_f32 v[86:87], v[86:87], v[98:99] op_sel_hi:[1,0]
	v_pk_mul_f32 v[84:85], v[84:85], v[98:99] op_sel_hi:[1,0]
	v_max_f32_e32 v80, 0, v80
	v_max_f32_e32 v81, 0, v81
	v_max_f32_e32 v82, 0, v82
	v_cvt_pk_bf16_f32 v89, v89, v90
	v_cvt_pk_bf16_f32 v90, v99, v93
	v_cvt_pk_bf16_f32 v91, v94, v91
	global_store_dwordx4 v[96:97], v[88:91], off nt
	v_max_f32_e32 v84, 0, v84
	v_max_f32_e32 v83, 0, v83
	v_mul_f32_e32 v88, v80, v80
	v_max_f32_e32 v80, 0, v85
	v_mul_f32_e32 v85, v81, v81
	v_max_f32_e32 v81, 0, v86
	v_mul_f32_e32 v86, v82, v82
	v_max_f32_e32 v82, 0, v87
	v_mul_f32_e32 v80, v80, v80
	v_mul_f32_e32 v81, v81, v81
	v_mul_f32_e32 v82, v82, v82
	v_mul_f32_e32 v84, v84, v84
	v_mul_f32_e32 v83, v83, v83
	v_cvt_pk_bf16_f32 v80, v84, v80
	v_cvt_pk_bf16_f32 v81, v81, v82
	v_cvt_pk_bf16_f32 v82, v88, v85
	v_cvt_pk_bf16_f32 v83, v86, v83
	global_store_dwordx4 v[96:97], v[80:83], off offset:256 nt
	v_cmp_gt_f32_e32 vcc, s54, v163
	s_mov_b32 s0, s22
	v_mul_f32_e32 v82, 0x4b800000, v163
	v_cndmask_b32_e32 v82, v163, v82, vcc
	v_rsq_f32_e32 v82, v82
	v_or_b32_e32 v80, 48, v146
	v_ashrrev_i32_e32 v81, 31, v80
	v_lshlrev_b64 v[80:81], 13, v[80:81]
	v_mul_f32_e32 v83, 0x45800000, v82
	v_cndmask_b32_e32 v82, v82, v83, vcc
	v_pk_mul_f32 v[72:73], v[72:73], v[82:83] op_sel_hi:[1,0]
	v_pk_mul_f32 v[76:77], v[76:77], v[82:83] op_sel_hi:[1,0]
	v_pk_mul_f32 v[74:75], v[74:75], v[82:83] op_sel_hi:[1,0]
	v_max_f32_e32 v72, 0, v72
	v_pk_mul_f32 v[78:79], v[78:79], v[82:83] op_sel_hi:[1,0]
	v_mul_f32_e32 v83, v72, v72
	v_max_f32_e32 v72, 0, v77
	v_max_f32_e32 v73, 0, v73
	v_max_f32_e32 v74, 0, v74
	v_lshl_add_u64 v[80:81], s[92:93], 0, v[80:81]
	v_max_f32_e32 v76, 0, v76
	v_mul_f32_e32 v72, v72, v72
	v_mul_f32_e32 v77, v73, v73
	v_max_f32_e32 v73, 0, v78
	v_mul_f32_e32 v78, v74, v74
	v_max_f32_e32 v74, 0, v79
	v_max_f32_e32 v75, 0, v75
	v_pk_mul_f32 v[64:65], v[64:65], v[82:83] op_sel_hi:[1,0]
	v_lshl_add_u64 v[80:81], v[80:81], 0, v[160:161]
	v_mul_f32_e32 v76, v76, v76
	v_mul_f32_e32 v73, v73, v73
	v_mul_f32_e32 v74, v74, v74
	v_mul_f32_e32 v75, v75, v75
	v_cvt_pk_bf16_f32 v72, v76, v72
	v_pk_mul_f32 v[68:69], v[68:69], v[82:83] op_sel_hi:[1,0]
	v_max_f32_e32 v64, 0, v64
	v_cvt_pk_bf16_f32 v73, v73, v74
	v_cvt_pk_bf16_f32 v74, v83, v77
	v_cvt_pk_bf16_f32 v75, v78, v75
	global_store_dwordx4 v[80:81], v[72:75], off nt
	v_max_f32_e32 v68, 0, v68
	v_mul_f32_e32 v68, v68, v68
	v_mul_f32_e32 v72, v64, v64
	v_max_f32_e32 v64, 0, v69
	v_mul_f32_e32 v64, v64, v64
	v_cvt_pk_bf16_f32 v64, v68, v64
	v_mul_f32_e32 v68, 0x4b800000, v164
	v_cmp_gt_f32_e32 vcc, s54, v164
	v_pk_mul_f32 v[66:67], v[66:67], v[82:83] op_sel_hi:[1,0]
	v_pk_mul_f32 v[70:71], v[70:71], v[82:83] op_sel_hi:[1,0]
	v_cndmask_b32_e32 v68, v164, v68, vcc
	v_max_f32_e32 v65, 0, v65
	v_max_f32_e32 v66, 0, v66
	v_rsq_f32_e32 v68, v68
	v_mul_f32_e32 v69, v65, v65
	v_max_f32_e32 v65, 0, v70
	v_mul_f32_e32 v70, v66, v66
	v_max_f32_e32 v66, 0, v71
	v_mul_f32_e32 v65, v65, v65
	v_max_f32_e32 v67, 0, v67
	v_mul_f32_e32 v66, v66, v66
	v_mul_f32_e32 v67, v67, v67
	v_cvt_pk_bf16_f32 v65, v65, v66
	v_cvt_pk_bf16_f32 v66, v72, v69
	v_cvt_pk_bf16_f32 v67, v70, v67
	global_store_dwordx4 v[80:81], v[64:67], off offset:256 nt
	s_nop 1
	v_mul_f32_e32 v66, 0x45800000, v68
	v_cndmask_b32_e32 v66, v68, v66, vcc
	v_pk_mul_f32 v[56:57], v[56:57], v[66:67] op_sel_hi:[1,0]
	v_pk_mul_f32 v[60:61], v[60:61], v[66:67] op_sel_hi:[1,0]
	v_pk_mul_f32 v[58:59], v[58:59], v[66:67] op_sel_hi:[1,0]
	v_max_f32_e32 v56, 0, v56
	v_pk_mul_f32 v[62:63], v[62:63], v[66:67] op_sel_hi:[1,0]
	v_max_f32_e32 v60, 0, v60
	v_mul_f32_e32 v67, v56, v56
	v_max_f32_e32 v56, 0, v61
	v_max_f32_e32 v57, 0, v57
	v_max_f32_e32 v58, 0, v58
	v_mul_f32_e32 v60, v60, v60
	v_mul_f32_e32 v56, v56, v56
	v_mul_f32_e32 v61, v57, v57
	v_max_f32_e32 v57, 0, v62
	v_mul_f32_e32 v62, v58, v58
	v_max_f32_e32 v58, 0, v63
	v_mul_f32_e32 v57, v57, v57
	v_max_f32_e32 v59, 0, v59
	v_mul_f32_e32 v58, v58, v58
	v_cvt_pk_bf16_f32 v56, v60, v56
	v_add_co_u32_e32 v60, vcc, s55, v144
	v_pk_mul_f32 v[48:49], v[48:49], v[66:67] op_sel_hi:[1,0]
	v_mul_f32_e32 v59, v59, v59
	v_cvt_pk_bf16_f32 v57, v57, v58
	v_cvt_pk_bf16_f32 v58, v67, v61
	v_addc_co_u32_e32 v61, vcc, 0, v145, vcc
	v_pk_mul_f32 v[52:53], v[52:53], v[66:67] op_sel_hi:[1,0]
	v_max_f32_e32 v48, 0, v48
	v_cvt_pk_bf16_f32 v59, v62, v59
	global_store_dwordx4 v[60:61], v[56:59], off nt
	v_max_f32_e32 v52, 0, v52
	v_mul_f32_e32 v52, v52, v52
	v_mul_f32_e32 v56, v48, v48
	v_max_f32_e32 v48, 0, v53
	v_mul_f32_e32 v48, v48, v48
	v_cvt_pk_bf16_f32 v48, v52, v48
	v_mul_f32_e32 v52, 0x4b800000, v165
	v_cmp_gt_f32_e32 vcc, s54, v165
	v_pk_mul_f32 v[50:51], v[50:51], v[66:67] op_sel_hi:[1,0]
	v_pk_mul_f32 v[54:55], v[54:55], v[66:67] op_sel_hi:[1,0]
	v_cndmask_b32_e32 v52, v165, v52, vcc
	v_max_f32_e32 v49, 0, v49
	v_max_f32_e32 v50, 0, v50
	v_rsq_f32_e32 v52, v52
	v_mul_f32_e32 v53, v49, v49
	v_max_f32_e32 v49, 0, v54
	v_mul_f32_e32 v54, v50, v50
	v_max_f32_e32 v50, 0, v55
	v_mul_f32_e32 v49, v49, v49
	v_max_f32_e32 v51, 0, v51
	v_mul_f32_e32 v50, v50, v50
	v_lshl_add_u64 v[64:65], v[144:145], 0, s[12:13]
	v_mul_f32_e32 v51, v51, v51
	v_cvt_pk_bf16_f32 v49, v49, v50
	v_cvt_pk_bf16_f32 v50, v56, v53
	v_cvt_pk_bf16_f32 v51, v54, v51
	global_store_dwordx4 v[64:65], v[48:51], off offset:256 nt
	s_nop 1
	v_mul_f32_e32 v50, 0x45800000, v52
	v_cndmask_b32_e32 v50, v52, v50, vcc
	v_pk_mul_f32 v[40:41], v[40:41], v[50:51] op_sel_hi:[1,0]
	v_pk_mul_f32 v[44:45], v[44:45], v[50:51] op_sel_hi:[1,0]
	v_pk_mul_f32 v[42:43], v[42:43], v[50:51] op_sel_hi:[1,0]
	v_max_f32_e32 v40, 0, v40
	v_pk_mul_f32 v[46:47], v[46:47], v[50:51] op_sel_hi:[1,0]
	v_max_f32_e32 v44, 0, v44
	v_mul_f32_e32 v51, v40, v40
	v_max_f32_e32 v40, 0, v45
	v_max_f32_e32 v41, 0, v41
	v_max_f32_e32 v42, 0, v42
	v_mul_f32_e32 v44, v44, v44
	v_mul_f32_e32 v40, v40, v40
	v_mul_f32_e32 v45, v41, v41
	v_max_f32_e32 v41, 0, v46
	v_mul_f32_e32 v46, v42, v42
	v_max_f32_e32 v42, 0, v47
	v_mul_f32_e32 v41, v41, v41
	v_max_f32_e32 v43, 0, v43
	v_mul_f32_e32 v42, v42, v42
	v_cvt_pk_bf16_f32 v40, v44, v40
	v_add_co_u32_e32 v44, vcc, s56, v144
	v_pk_mul_f32 v[32:33], v[32:33], v[50:51] op_sel_hi:[1,0]
	v_mul_f32_e32 v43, v43, v43
	v_cvt_pk_bf16_f32 v41, v41, v42
	v_cvt_pk_bf16_f32 v42, v51, v45
	v_addc_co_u32_e32 v45, vcc, 0, v145, vcc
	v_pk_mul_f32 v[36:37], v[36:37], v[50:51] op_sel_hi:[1,0]
	v_max_f32_e32 v32, 0, v32
	v_cvt_pk_bf16_f32 v43, v46, v43
	global_store_dwordx4 v[44:45], v[40:43], off nt
	v_max_f32_e32 v36, 0, v36
	v_mul_f32_e32 v36, v36, v36
	v_mul_f32_e32 v40, v32, v32
	v_max_f32_e32 v32, 0, v37
	v_mul_f32_e32 v32, v32, v32
	v_cvt_pk_bf16_f32 v32, v36, v32
	v_mul_f32_e32 v36, 0x4b800000, v166
	v_cmp_gt_f32_e32 vcc, s54, v166
	v_pk_mul_f32 v[34:35], v[34:35], v[50:51] op_sel_hi:[1,0]
	v_pk_mul_f32 v[38:39], v[38:39], v[50:51] op_sel_hi:[1,0]
	v_cndmask_b32_e32 v36, v166, v36, vcc
	v_max_f32_e32 v33, 0, v33
	v_max_f32_e32 v34, 0, v34
	v_rsq_f32_e32 v36, v36
	v_mul_f32_e32 v37, v33, v33
	v_max_f32_e32 v33, 0, v38
	v_mul_f32_e32 v38, v34, v34
	v_max_f32_e32 v34, 0, v39
	v_mul_f32_e32 v33, v33, v33
	v_max_f32_e32 v35, 0, v35
	v_mul_f32_e32 v34, v34, v34
	v_lshl_add_u64 v[48:49], v[144:145], 0, s[14:15]
	v_mul_f32_e32 v35, v35, v35
	v_cvt_pk_bf16_f32 v33, v33, v34
	v_cvt_pk_bf16_f32 v34, v40, v37
	v_cvt_pk_bf16_f32 v35, v38, v35
	global_store_dwordx4 v[48:49], v[32:35], off offset:256 nt
	s_nop 1
	v_mul_f32_e32 v34, 0x45800000, v36
	v_cndmask_b32_e32 v34, v36, v34, vcc
	v_pk_mul_f32 v[24:25], v[24:25], v[34:35] op_sel_hi:[1,0]
	v_pk_mul_f32 v[28:29], v[28:29], v[34:35] op_sel_hi:[1,0]
	v_pk_mul_f32 v[26:27], v[26:27], v[34:35] op_sel_hi:[1,0]
	v_max_f32_e32 v24, 0, v24
	v_pk_mul_f32 v[30:31], v[30:31], v[34:35] op_sel_hi:[1,0]
	v_max_f32_e32 v28, 0, v28
	v_mul_f32_e32 v35, v24, v24
	v_max_f32_e32 v24, 0, v29
	v_max_f32_e32 v25, 0, v25
	v_max_f32_e32 v26, 0, v26
	v_mul_f32_e32 v28, v28, v28
	v_mul_f32_e32 v24, v24, v24
	v_mul_f32_e32 v29, v25, v25
	v_max_f32_e32 v25, 0, v30
	v_mul_f32_e32 v30, v26, v26
	v_max_f32_e32 v26, 0, v31
	v_mul_f32_e32 v25, v25, v25
	v_max_f32_e32 v27, 0, v27
	v_mul_f32_e32 v26, v26, v26
	v_cvt_pk_bf16_f32 v24, v28, v24
	v_add_co_u32_e32 v28, vcc, s57, v144
	v_pk_mul_f32 v[16:17], v[16:17], v[34:35] op_sel_hi:[1,0]
	v_mul_f32_e32 v27, v27, v27
	v_cvt_pk_bf16_f32 v25, v25, v26
	v_cvt_pk_bf16_f32 v26, v35, v29
	v_addc_co_u32_e32 v29, vcc, 0, v145, vcc
	v_pk_mul_f32 v[20:21], v[20:21], v[34:35] op_sel_hi:[1,0]
	v_max_f32_e32 v16, 0, v16
	v_cvt_pk_bf16_f32 v27, v30, v27
	global_store_dwordx4 v[28:29], v[24:27], off nt
	v_max_f32_e32 v20, 0, v20
	v_mul_f32_e32 v20, v20, v20
	v_mul_f32_e32 v24, v16, v16
	v_max_f32_e32 v16, 0, v21
	v_mul_f32_e32 v16, v16, v16
	v_cvt_pk_bf16_f32 v16, v20, v16
	v_mul_f32_e32 v20, 0x4b800000, v147
	v_cmp_gt_f32_e32 vcc, s54, v147
	v_pk_mul_f32 v[18:19], v[18:19], v[34:35] op_sel_hi:[1,0]
	v_pk_mul_f32 v[22:23], v[22:23], v[34:35] op_sel_hi:[1,0]
	v_cndmask_b32_e32 v20, v147, v20, vcc
	v_max_f32_e32 v17, 0, v17
	v_max_f32_e32 v18, 0, v18
	v_rsq_f32_e32 v20, v20
	v_mul_f32_e32 v21, v17, v17
	v_max_f32_e32 v17, 0, v22
	v_mul_f32_e32 v22, v18, v18
	v_max_f32_e32 v18, 0, v23
	v_mul_f32_e32 v17, v17, v17
	v_max_f32_e32 v19, 0, v19
	v_mul_f32_e32 v18, v18, v18
	v_lshl_add_u64 v[32:33], v[144:145], 0, s[16:17]
	v_mul_f32_e32 v19, v19, v19
	v_cvt_pk_bf16_f32 v17, v17, v18
	v_cvt_pk_bf16_f32 v18, v24, v21
	v_cvt_pk_bf16_f32 v19, v22, v19
	global_store_dwordx4 v[32:33], v[16:19], off offset:256 nt
	s_nop 1
	v_mul_f32_e32 v18, 0x45800000, v20
	v_cndmask_b32_e32 v18, v20, v18, vcc
	v_pk_mul_f32 v[8:9], v[8:9], v[18:19] op_sel_hi:[1,0]
	v_pk_mul_f32 v[12:13], v[12:13], v[18:19] op_sel_hi:[1,0]
	v_pk_mul_f32 v[10:11], v[10:11], v[18:19] op_sel_hi:[1,0]
	v_max_f32_e32 v8, 0, v8
	v_pk_mul_f32 v[14:15], v[14:15], v[18:19] op_sel_hi:[1,0]
	v_max_f32_e32 v12, 0, v12
	v_mul_f32_e32 v19, v8, v8
	v_max_f32_e32 v8, 0, v13
	v_max_f32_e32 v9, 0, v9
	v_max_f32_e32 v10, 0, v10
	v_mul_f32_e32 v12, v12, v12
	v_mul_f32_e32 v8, v8, v8
	v_mul_f32_e32 v13, v9, v9
	v_max_f32_e32 v9, 0, v14
	v_mul_f32_e32 v14, v10, v10
	v_max_f32_e32 v10, 0, v15
	v_mul_f32_e32 v9, v9, v9
	v_max_f32_e32 v11, 0, v11
	v_mul_f32_e32 v10, v10, v10
	v_cvt_pk_bf16_f32 v8, v12, v8
	v_add_co_u32_e32 v12, vcc, s58, v144
	v_pk_mul_f32 v[2:3], v[2:3], v[18:19] op_sel_hi:[1,0]
	v_pk_mul_f32 v[0:1], v[0:1], v[18:19] op_sel_hi:[1,0]
	v_mul_f32_e32 v11, v11, v11
	v_cvt_pk_bf16_f32 v9, v9, v10
	v_cvt_pk_bf16_f32 v10, v19, v13
	v_addc_co_u32_e32 v13, vcc, 0, v145, vcc
	v_pk_mul_f32 v[6:7], v[6:7], v[18:19] op_sel_hi:[1,0]
	v_pk_mul_f32 v[4:5], v[4:5], v[18:19] op_sel_hi:[1,0]
	v_max_f32_e32 v0, 0, v0
	v_max_f32_e32 v1, 0, v1
	v_max_f32_e32 v2, 0, v2
	v_cvt_pk_bf16_f32 v11, v14, v11
	global_store_dwordx4 v[12:13], v[8:11], off nt
	v_max_f32_e32 v3, 0, v3
	v_lshl_add_u64 v[16:17], v[144:145], 0, s[18:19]
	v_mul_f32_e32 v8, v0, v0
	v_max_f32_e32 v0, 0, v5
	v_mul_f32_e32 v5, v1, v1
	v_max_f32_e32 v1, 0, v6
	v_mul_f32_e32 v6, v2, v2
	v_max_f32_e32 v2, 0, v7
	v_max_f32_e32 v4, 0, v4
	v_mul_f32_e32 v0, v0, v0
	v_mul_f32_e32 v1, v1, v1
	v_mul_f32_e32 v2, v2, v2
	v_mul_f32_e32 v3, v3, v3
	s_and_b64 vcc, exec, s[2:3]
	v_mul_f32_e32 v4, v4, v4
	v_cvt_pk_bf16_f32 v0, v4, v0
	v_cvt_pk_bf16_f32 v1, v1, v2
	v_cvt_pk_bf16_f32 v2, v8, v5
	v_cvt_pk_bf16_f32 v3, v6, v3
	global_store_dwordx4 v[16:17], v[0:3], off offset:256 nt
	s_cbranch_vccz .LBB0_1211
	s_waitcnt vmcnt(0)
	s_cmpk_gt_u32 s33, 0xff
	s_cbranch_scc1 .LBB0_1222
	s_barrier

.LBB0_1264:
	ds_read_b128 v[144:147], v178
	ds_read_b128 v[148:151], v178 offset:1024
	ds_read_b128 v[152:155], v178 offset:2048
	ds_read_b128 v[156:159], v178 offset:3072
	s_add_u32 s34, s30, 0xfff00080
	s_addc_u32 s35, s31, -1
	s_cmp_eq_u32 s58, 60
	s_cselect_b32 s37, s21, s35
	s_cselect_b32 s36, s27, s34
	s_cselect_b32 s35, s19, s57
	s_cselect_b32 s34, s55, s56
	v_lshl_add_u64 v[172:173], s[30:31], 0, v[136:137]
	s_add_i32 m0, s29, 0xc000
	ds_read_b128 v[160:163], v179
	ds_read_b128 v[164:167], v179 offset:1024
	ds_read_b128 v[168:171], v179 offset:2048
	ds_read_b128 v[182:185], v179 offset:3072
	ds_read_b128 v[186:189], v179 offset:4096
	ds_read_b128 v[190:193], v179 offset:5120
	ds_read_b128 v[194:197], v179 offset:6144
	ds_read_b128 v[198:201], v179 offset:7168
	global_load_lds_dwordx4 v[172:173], off
	s_add_i32 m0, s29, 0xe000
	v_lshl_add_u64 v[172:173], s[30:31], 0, v[138:139]
	global_load_lds_dwordx4 v[172:173], off
	s_waitcnt lgkmcnt(8)
	s_setprio 1
	s_barrier
	s_waitcnt lgkmcnt(0)
	v_mfma_f32_16x16x32_bf16 v[124:127], v[144:147], v[160:163], v[124:127]
	v_mfma_f32_16x16x32_bf16 v[120:123], v[152:155], v[160:163], v[120:123]
	v_mfma_f32_16x16x32_bf16 v[108:111], v[144:147], v[168:171], v[108:111]
	v_mfma_f32_16x16x32_bf16 v[104:107], v[152:155], v[168:171], v[104:107]
	v_mfma_f32_16x16x32_bf16 v[96:99], v[144:147], v[186:189], v[96:99]
	v_mfma_f32_16x16x32_bf16 v[88:91], v[152:155], v[186:189], v[88:91]
	v_mfma_f32_16x16x32_bf16 v[80:83], v[144:147], v[194:197], v[80:83]
	v_mfma_f32_16x16x32_bf16 v[72:75], v[152:155], v[194:197], v[72:75]
	v_mfma_f32_16x16x32_bf16 v[124:127], v[148:151], v[164:167], v[124:127]
	v_mfma_f32_16x16x32_bf16 v[120:123], v[156:159], v[164:167], v[120:123]
	v_mfma_f32_16x16x32_bf16 v[108:111], v[148:151], v[182:185], v[108:111]
	v_mfma_f32_16x16x32_bf16 v[104:107], v[156:159], v[182:185], v[104:107]
	v_mfma_f32_16x16x32_bf16 v[96:99], v[148:151], v[190:193], v[96:99]
	v_mfma_f32_16x16x32_bf16 v[88:91], v[156:159], v[190:193], v[88:91]
	v_mfma_f32_16x16x32_bf16 v[80:83], v[148:151], v[198:201], v[80:83]
	v_mfma_f32_16x16x32_bf16 v[72:75], v[156:159], v[198:201], v[72:75]
	s_setprio 0
	s_barrier
	s_add_i32 s59, s53, s40
	v_lshl_add_u64 v[172:173], s[34:35], 0, v[130:131]
	s_mov_b32 m0, s59
	ds_read_b128 v[202:205], v180
	ds_read_b128 v[206:209], v180 offset:1024
	ds_read_b128 v[212:215], v180 offset:2048
	ds_read_b128 v[216:219], v180 offset:3072
	global_load_lds_dwordx4 v[172:173], off
	s_add_i32 m0, s59, 0x2000
	v_lshl_add_u64 v[220:221], s[34:35], 0, v[134:135]
	global_load_lds_dwordx4 v[220:221], off
	s_setprio 1
	s_barrier
	s_waitcnt lgkmcnt(0)
	v_mfma_f32_16x16x32_bf16 v[116:119], v[202:205], v[160:163], v[116:119]
	v_mfma_f32_16x16x32_bf16 v[112:115], v[212:215], v[160:163], v[112:115]
	v_mfma_f32_16x16x32_bf16 v[100:103], v[202:205], v[168:171], v[100:103]
	v_mfma_f32_16x16x32_bf16 v[92:95], v[212:215], v[168:171], v[92:95]
	v_mfma_f32_16x16x32_bf16 v[84:87], v[202:205], v[186:189], v[84:87]
	v_mfma_f32_16x16x32_bf16 v[76:79], v[212:215], v[186:189], v[76:79]
	v_mfma_f32_16x16x32_bf16 v[68:71], v[202:205], v[194:197], v[68:71]
	v_mfma_f32_16x16x32_bf16 v[64:67], v[212:215], v[194:197], v[64:67]
	v_mfma_f32_16x16x32_bf16 v[116:119], v[206:209], v[164:167], v[116:119]
	v_mfma_f32_16x16x32_bf16 v[112:115], v[216:219], v[164:167], v[112:115]
	v_mfma_f32_16x16x32_bf16 v[100:103], v[206:209], v[182:185], v[100:103]
	v_mfma_f32_16x16x32_bf16 v[92:95], v[216:219], v[182:185], v[92:95]
	v_mfma_f32_16x16x32_bf16 v[84:87], v[206:209], v[190:193], v[84:87]
	v_mfma_f32_16x16x32_bf16 v[76:79], v[216:219], v[190:193], v[76:79]
	v_mfma_f32_16x16x32_bf16 v[68:71], v[206:209], v[198:201], v[68:71]
	v_mfma_f32_16x16x32_bf16 v[64:67], v[216:219], v[198:201], v[64:67]
	s_setprio 0
	s_mov_b32 m0, s29
	v_lshl_add_u64 v[222:223], s[36:37], 0, v[128:129]
	s_barrier
	ds_read_b128 v[160:163], v179 offset:16384
	ds_read_b128 v[164:167], v179 offset:17408
	ds_read_b128 v[168:171], v179 offset:18432
	ds_read_b128 v[182:185], v179 offset:19456
	ds_read_b128 v[186:189], v179 offset:20480
	ds_read_b128 v[190:193], v179 offset:21504
	ds_read_b128 v[194:197], v179 offset:22528
	ds_read_b128 v[198:201], v179 offset:23552
	global_load_lds_dwordx4 v[222:223], off
	s_mov_b32 m0, s41
	v_lshl_add_u64 v[224:225], s[36:37], 0, v[132:133]
	global_load_lds_dwordx4 v[224:225], off
	s_setprio 1
	s_barrier
	s_waitcnt lgkmcnt(0)
	v_mfma_f32_16x16x32_bf16 v[60:63], v[144:147], v[160:163], v[60:63]
	v_mfma_f32_16x16x32_bf16 v[56:59], v[152:155], v[160:163], v[56:59]
	v_mfma_f32_16x16x32_bf16 v[44:47], v[144:147], v[168:171], v[44:47]
	v_mfma_f32_16x16x32_bf16 v[40:43], v[152:155], v[168:171], v[40:43]
	v_mfma_f32_16x16x32_bf16 v[32:35], v[144:147], v[186:189], v[32:35]
	v_mfma_f32_16x16x32_bf16 v[24:27], v[152:155], v[186:189], v[24:27]
	v_mfma_f32_16x16x32_bf16 v[16:19], v[144:147], v[194:197], v[16:19]
	v_mfma_f32_16x16x32_bf16 v[8:11], v[152:155], v[194:197], v[8:11]
	v_mfma_f32_16x16x32_bf16 v[60:63], v[148:151], v[164:167], v[60:63]
	v_mfma_f32_16x16x32_bf16 v[56:59], v[156:159], v[164:167], v[56:59]
	v_mfma_f32_16x16x32_bf16 v[44:47], v[148:151], v[182:185], v[44:47]
	v_mfma_f32_16x16x32_bf16 v[40:43], v[156:159], v[182:185], v[40:43]
	v_mfma_f32_16x16x32_bf16 v[32:35], v[148:151], v[190:193], v[32:35]
	v_mfma_f32_16x16x32_bf16 v[24:27], v[156:159], v[190:193], v[24:27]
	v_mfma_f32_16x16x32_bf16 v[16:19], v[148:151], v[198:201], v[16:19]
	v_mfma_f32_16x16x32_bf16 v[8:11], v[156:159], v[198:201], v[8:11]
	s_setprio 0
	s_barrier
	s_add_u32 s60, s34, 0x100000
	s_addc_u32 s61, s35, 0
	s_add_i32 s59, s54, s40
	s_mov_b32 m0, s59
	v_lshl_add_u64 v[144:145], s[60:61], 0, v[130:131]
	global_load_lds_dwordx4 v[144:145], off
	s_add_i32 m0, s59, 0x2000
	v_lshl_add_u64 v[144:145], s[60:61], 0, v[134:135]
	global_load_lds_dwordx4 v[144:145], off
	s_waitcnt vmcnt(6)
	s_setprio 1
	s_barrier
	v_mfma_f32_16x16x32_bf16 v[52:55], v[202:205], v[160:163], v[52:55]
	v_mfma_f32_16x16x32_bf16 v[48:51], v[212:215], v[160:163], v[48:51]
	v_mfma_f32_16x16x32_bf16 v[36:39], v[202:205], v[168:171], v[36:39]
	v_mfma_f32_16x16x32_bf16 v[28:31], v[212:215], v[168:171], v[28:31]
	v_mfma_f32_16x16x32_bf16 v[20:23], v[202:205], v[186:189], v[20:23]
	v_mfma_f32_16x16x32_bf16 v[12:15], v[212:215], v[186:189], v[12:15]
	v_mfma_f32_16x16x32_bf16 v[4:7], v[202:205], v[194:197], v[4:7]
	v_mfma_f32_16x16x32_bf16 v[0:3], v[212:215], v[194:197], v[0:3]
	v_mfma_f32_16x16x32_bf16 v[52:55], v[206:209], v[164:167], v[52:55]
	v_mfma_f32_16x16x32_bf16 v[48:51], v[216:219], v[164:167], v[48:51]
	v_mfma_f32_16x16x32_bf16 v[36:39], v[206:209], v[182:185], v[36:39]
	v_mfma_f32_16x16x32_bf16 v[28:31], v[216:219], v[182:185], v[28:31]
	v_mfma_f32_16x16x32_bf16 v[20:23], v[206:209], v[190:193], v[20:23]
	v_mfma_f32_16x16x32_bf16 v[12:15], v[216:219], v[190:193], v[12:15]
	v_mfma_f32_16x16x32_bf16 v[4:7], v[206:209], v[198:201], v[4:7]
	v_mfma_f32_16x16x32_bf16 v[0:3], v[216:219], v[198:201], v[0:3]
	s_setprio 0
	s_add_i32 s59, 0, 0x18000
	v_add_u32_e32 v156, s59, v176
	s_barrier
	ds_read_b128 v[144:147], v156
	ds_read_b128 v[148:151], v156 offset:1024
	ds_read_b128 v[152:155], v156 offset:2048
	ds_read_b128 v[156:159], v156 offset:3072
	s_add_u32 s36, s36, 0x100000
	s_addc_u32 s37, s37, 0
	s_mov_b32 m0, s42
	v_lshl_add_u64 v[202:203], s[36:37], 0, v[128:129]
	ds_read_b128 v[160:163], v179 offset:32768
	ds_read_b128 v[164:167], v179 offset:33792
	ds_read_b128 v[168:171], v179 offset:34816
	ds_read_b128 v[182:185], v179 offset:35840
	ds_read_b128 v[186:189], v179 offset:36864
	ds_read_b128 v[190:193], v179 offset:37888
	ds_read_b128 v[194:197], v179 offset:38912
	ds_read_b128 v[198:201], v179 offset:39936
	global_load_lds_dwordx4 v[202:203], off
	s_mov_b32 m0, s43
	v_lshl_add_u64 v[202:203], s[36:37], 0, v[132:133]
	global_load_lds_dwordx4 v[202:203], off
	s_waitcnt lgkmcnt(8)
	s_setprio 1
	s_barrier
	s_waitcnt lgkmcnt(0)
	v_mfma_f32_16x16x32_bf16 v[124:127], v[144:147], v[160:163], v[124:127]
	v_mfma_f32_16x16x32_bf16 v[120:123], v[152:155], v[160:163], v[120:123]
	v_mfma_f32_16x16x32_bf16 v[108:111], v[144:147], v[168:171], v[108:111]
	v_mfma_f32_16x16x32_bf16 v[104:107], v[152:155], v[168:171], v[104:107]
	v_mfma_f32_16x16x32_bf16 v[96:99], v[144:147], v[186:189], v[96:99]
	v_mfma_f32_16x16x32_bf16 v[88:91], v[152:155], v[186:189], v[88:91]
	v_mfma_f32_16x16x32_bf16 v[80:83], v[144:147], v[194:197], v[80:83]
	v_mfma_f32_16x16x32_bf16 v[72:75], v[152:155], v[194:197], v[72:75]
	v_mfma_f32_16x16x32_bf16 v[124:127], v[148:151], v[164:167], v[124:127]
	v_mfma_f32_16x16x32_bf16 v[120:123], v[156:159], v[164:167], v[120:123]
	v_mfma_f32_16x16x32_bf16 v[108:111], v[148:151], v[182:185], v[108:111]
	v_mfma_f32_16x16x32_bf16 v[104:107], v[156:159], v[182:185], v[104:107]
	v_mfma_f32_16x16x32_bf16 v[96:99], v[148:151], v[190:193], v[96:99]
	v_mfma_f32_16x16x32_bf16 v[88:91], v[156:159], v[190:193], v[88:91]
	v_mfma_f32_16x16x32_bf16 v[80:83], v[148:151], v[198:201], v[80:83]
	v_mfma_f32_16x16x32_bf16 v[72:75], v[156:159], v[198:201], v[72:75]
	s_setprio 0
	s_barrier
	s_add_i32 s36, 0, 0x1c000
	s_add_i32 s37, s59, s40
	v_add_u32_e32 v181, s36, v176
	v_lshl_add_u64 v[172:173], v[172:173], 0, s[0:1]
	s_mov_b32 m0, s37
	ds_read_b128 v[202:205], v181
	ds_read_b128 v[206:209], v181 offset:1024
	ds_read_b128 v[212:215], v181 offset:2048
	ds_read_b128 v[216:219], v181 offset:3072
	global_load_lds_dwordx4 v[172:173], off
	s_add_i32 m0, s37, 0x2000
	v_lshl_add_u64 v[172:173], v[220:221], 0, s[0:1]
	global_load_lds_dwordx4 v[172:173], off
	s_setprio 1
	s_barrier
	s_waitcnt lgkmcnt(0)
	v_mfma_f32_16x16x32_bf16 v[116:119], v[202:205], v[160:163], v[116:119]
	v_mfma_f32_16x16x32_bf16 v[112:115], v[212:215], v[160:163], v[112:115]
	v_mfma_f32_16x16x32_bf16 v[100:103], v[202:205], v[168:171], v[100:103]
	v_mfma_f32_16x16x32_bf16 v[92:95], v[212:215], v[168:171], v[92:95]
	v_mfma_f32_16x16x32_bf16 v[84:87], v[202:205], v[186:189], v[84:87]
	v_mfma_f32_16x16x32_bf16 v[76:79], v[212:215], v[186:189], v[76:79]
	v_mfma_f32_16x16x32_bf16 v[68:71], v[202:205], v[194:197], v[68:71]
	v_mfma_f32_16x16x32_bf16 v[64:67], v[212:215], v[194:197], v[64:67]
	v_mfma_f32_16x16x32_bf16 v[116:119], v[206:209], v[164:167], v[116:119]
	v_mfma_f32_16x16x32_bf16 v[112:115], v[216:219], v[164:167], v[112:115]
	v_mfma_f32_16x16x32_bf16 v[100:103], v[206:209], v[182:185], v[100:103]
	v_mfma_f32_16x16x32_bf16 v[92:95], v[216:219], v[182:185], v[92:95]
	v_mfma_f32_16x16x32_bf16 v[84:87], v[206:209], v[190:193], v[84:87]
	v_mfma_f32_16x16x32_bf16 v[76:79], v[216:219], v[190:193], v[76:79]
	v_mfma_f32_16x16x32_bf16 v[68:71], v[206:209], v[198:201], v[68:71]
	v_mfma_f32_16x16x32_bf16 v[64:67], v[216:219], v[198:201], v[64:67]
	s_setprio 0
	s_mov_b32 m0, s49
	v_lshl_add_u64 v[172:173], v[222:223], 0, s[0:1]
	s_barrier
	ds_read_b128 v[160:163], v179 offset:49152
	ds_read_b128 v[164:167], v179 offset:50176
	ds_read_b128 v[168:171], v179 offset:51200
	ds_read_b128 v[182:185], v179 offset:52224
	ds_read_b128 v[186:189], v179 offset:53248
	ds_read_b128 v[190:193], v179 offset:54272
	ds_read_b128 v[194:197], v179 offset:55296
	ds_read_b128 v[198:201], v179 offset:56320
	global_load_lds_dwordx4 v[172:173], off
	s_mov_b32 m0, s50
	v_lshl_add_u64 v[172:173], v[224:225], 0, s[0:1]
	global_load_lds_dwordx4 v[172:173], off
	s_setprio 1
	s_barrier
	s_waitcnt lgkmcnt(0)
	v_mfma_f32_16x16x32_bf16 v[60:63], v[144:147], v[160:163], v[60:63]
	v_mfma_f32_16x16x32_bf16 v[56:59], v[152:155], v[160:163], v[56:59]
	v_mfma_f32_16x16x32_bf16 v[44:47], v[144:147], v[168:171], v[44:47]
	v_mfma_f32_16x16x32_bf16 v[40:43], v[152:155], v[168:171], v[40:43]
	v_mfma_f32_16x16x32_bf16 v[32:35], v[144:147], v[186:189], v[32:35]
	v_mfma_f32_16x16x32_bf16 v[24:27], v[152:155], v[186:189], v[24:27]
	v_mfma_f32_16x16x32_bf16 v[16:19], v[144:147], v[194:197], v[16:19]
	v_mfma_f32_16x16x32_bf16 v[8:11], v[152:155], v[194:197], v[8:11]
	v_mfma_f32_16x16x32_bf16 v[60:63], v[148:151], v[164:167], v[60:63]
	v_mfma_f32_16x16x32_bf16 v[56:59], v[156:159], v[164:167], v[56:59]
	v_mfma_f32_16x16x32_bf16 v[44:47], v[148:151], v[182:185], v[44:47]
	v_mfma_f32_16x16x32_bf16 v[40:43], v[156:159], v[182:185], v[40:43]
	v_mfma_f32_16x16x32_bf16 v[32:35], v[148:151], v[190:193], v[32:35]
	v_mfma_f32_16x16x32_bf16 v[24:27], v[156:159], v[190:193], v[24:27]
	v_mfma_f32_16x16x32_bf16 v[16:19], v[148:151], v[198:201], v[16:19]
	v_mfma_f32_16x16x32_bf16 v[8:11], v[156:159], v[198:201], v[8:11]
	s_setprio 0
	s_barrier
	s_add_u32 s34, s34, 0x100080
	s_addc_u32 s35, s35, 0
	s_add_i32 s36, s36, s40
	s_mov_b32 m0, s36
	v_lshl_add_u64 v[144:145], s[34:35], 0, v[130:131]
	global_load_lds_dwordx4 v[144:145], off
	s_add_i32 m0, s36, 0x2000
	v_lshl_add_u64 v[144:145], s[34:35], 0, v[134:135]
	global_load_lds_dwordx4 v[144:145], off
	s_waitcnt vmcnt(6)
	s_setprio 1
	s_barrier
	v_mfma_f32_16x16x32_bf16 v[52:55], v[202:205], v[160:163], v[52:55]
	v_mfma_f32_16x16x32_bf16 v[48:51], v[212:215], v[160:163], v[48:51]
	v_mfma_f32_16x16x32_bf16 v[36:39], v[202:205], v[168:171], v[36:39]
	v_mfma_f32_16x16x32_bf16 v[28:31], v[212:215], v[168:171], v[28:31]
	v_mfma_f32_16x16x32_bf16 v[20:23], v[202:205], v[186:189], v[20:23]
	v_mfma_f32_16x16x32_bf16 v[12:15], v[212:215], v[186:189], v[12:15]
	v_mfma_f32_16x16x32_bf16 v[4:7], v[202:205], v[194:197], v[4:7]
	v_mfma_f32_16x16x32_bf16 v[0:3], v[212:215], v[194:197], v[0:3]
	v_mfma_f32_16x16x32_bf16 v[52:55], v[206:209], v[164:167], v[52:55]
	v_mfma_f32_16x16x32_bf16 v[48:51], v[216:219], v[164:167], v[48:51]
	v_mfma_f32_16x16x32_bf16 v[36:39], v[206:209], v[182:185], v[36:39]
	v_mfma_f32_16x16x32_bf16 v[28:31], v[216:219], v[182:185], v[28:31]
	v_mfma_f32_16x16x32_bf16 v[20:23], v[206:209], v[190:193], v[20:23]
	v_mfma_f32_16x16x32_bf16 v[12:15], v[216:219], v[190:193], v[12:15]
	v_mfma_f32_16x16x32_bf16 v[4:7], v[206:209], v[198:201], v[4:7]
	v_mfma_f32_16x16x32_bf16 v[0:3], v[216:219], v[198:201], v[0:3]
	s_setprio 0
	s_add_i32 s58, s58, 2
	s_add_u32 s30, s30, 0x100
	s_addc_u32 s31, s31, 0
	s_add_u32 s56, s56, 0x100
	s_addc_u32 s57, s57, 0
	s_cmp_gt_u32 s58, 61
	s_barrier
	s_cbranch_scc0 .LBB0_1264
	v_lshl_or_b32 v144, s28, 8, v177
	v_lshl_add_u32 v150, s26, 8, v175
	v_ashrrev_i32_e32 v145, 31, v144
	v_ashrrev_i32_e32 v151, 31, v150
	v_lshlrev_b64 v[144:145], 1, v[144:145]
	v_lshl_add_u64 v[146:147], s[90:91], 0, v[144:145]
	v_lshlrev_b64 v[148:149], 11, v[150:151]
	v_lshl_add_u64 v[152:153], v[146:147], 0, v[148:149]
	global_load_dwordx4 v[156:159], v[152:153], off
	global_load_dwordx4 v[160:163], v[152:153], off offset:256
	v_or_b32_e32 v152, 16, v150
	v_ashrrev_i32_e32 v153, 31, v152
	v_lshlrev_b64 v[170:171], 11, v[152:153]
	v_lshl_add_u64 v[152:153], v[146:147], 0, v[170:171]
	global_load_dwordx4 v[164:167], v[152:153], off
	global_load_dwordx4 v[182:185], v[152:153], off offset:256
	v_or_b32_e32 v152, 32, v150
	v_ashrrev_i32_e32 v153, 31, v152
	v_lshlrev_b64 v[154:155], 11, v[152:153]
	v_lshl_add_u64 v[152:153], v[146:147], 0, v[154:155]
	global_load_dwordx4 v[186:189], v[152:153], off
	global_load_dwordx4 v[190:193], v[152:153], off offset:256
	v_or_b32_e32 v152, 48, v150
	v_ashrrev_i32_e32 v153, 31, v152
	v_lshlrev_b64 v[152:153], 11, v[152:153]
	v_lshl_add_u64 v[168:169], v[146:147], 0, v[152:153]
	global_load_dwordx4 v[194:197], v[168:169], off
	global_load_dwordx4 v[198:201], v[168:169], off offset:256
	s_waitcnt vmcnt(0)
	v_lshlrev_b32_e32 v202, 16, v156
	v_and_b32_e32 v203, 0xffff0000, v156
	v_lshlrev_b32_e32 v204, 16, v157
	v_and_b32_e32 v205, 0xffff0000, v157
	v_lshlrev_b32_e32 v206, 16, v158
	v_and_b32_e32 v207, 0xffff0000, v158
	v_lshlrev_b32_e32 v208, 16, v159
	v_and_b32_e32 v209, 0xffff0000, v159
	v_pk_add_f32 v[126:127], v[126:127], v[204:205]
	v_pk_add_f32 v[124:125], v[124:125], v[202:203]
	v_lshlrev_b32_e32 v224, 16, v166
	v_and_b32_e32 v225, 0xffff0000, v166
	v_lshlrev_b32_e32 v226, 16, v167
	v_and_b32_e32 v227, 0xffff0000, v167
	v_lshlrev_b32_e32 v212, 16, v160
	v_lshlrev_b32_e32 v166, 16, v194
	v_and_b32_e32 v167, 0xffff0000, v194
	v_lshlrev_b32_e32 v172, 16, v195
	v_and_b32_e32 v173, 0xffff0000, v195
	v_pk_add_f32 v[194:195], v[122:123], v[208:209]
	v_pk_add_f32 v[122:123], v[120:121], v[206:207]
	v_mul_f32_e32 v120, v125, v125
	v_mul_f32_e32 v121, v127, v127
	v_fmac_f32_e32 v120, v124, v124
	v_fmac_f32_e32 v121, v126, v126
	v_add_f32_e32 v120, v120, v121
	v_mul_f32_e32 v121, v123, v123
	v_fmac_f32_e32 v121, v122, v122
	v_add_f32_e32 v120, v121, v120
	v_mul_f32_e32 v121, v195, v195
	v_fmac_f32_e32 v121, v194, v194
	v_and_b32_e32 v213, 0xffff0000, v160
	v_lshlrev_b32_e32 v214, 16, v161
	v_and_b32_e32 v215, 0xffff0000, v161
	v_add_f32_e32 v181, v121, v120
	v_cvt_pk_bf16_f32 v120, v124, v125
	v_lshl_add_u64 v[124:125], s[10:11], 0, v[148:149]
	v_lshlrev_b32_e32 v216, 16, v162
	v_and_b32_e32 v217, 0xffff0000, v162
	v_lshlrev_b32_e32 v218, 16, v163
	v_and_b32_e32 v219, 0xffff0000, v163
	v_cvt_pk_bf16_f32 v121, v126, v127
	v_lshl_add_u64 v[124:125], v[124:125], 0, v[144:145]
	v_pk_add_f32 v[118:119], v[118:119], v[214:215]
	v_pk_add_f32 v[116:117], v[116:117], v[212:213]
	v_cvt_pk_bf16_f32 v122, v122, v123
	v_cvt_pk_bf16_f32 v123, v194, v195
	global_store_dwordx4 v[124:125], v[120:123], off
	v_lshlrev_b32_e32 v220, 16, v164
	v_and_b32_e32 v221, 0xffff0000, v164
	v_pk_add_f32 v[120:121], v[114:115], v[218:219]
	v_pk_add_f32 v[114:115], v[112:113], v[216:217]
	v_mul_f32_e32 v112, v117, v117
	v_mul_f32_e32 v113, v119, v119
	v_fmac_f32_e32 v112, v116, v116
	v_fmac_f32_e32 v113, v118, v118
	v_add_f32_e32 v112, v112, v113
	v_mul_f32_e32 v113, v115, v115
	v_fmac_f32_e32 v113, v114, v114
	v_add_f32_e32 v112, v113, v112
	v_mul_f32_e32 v113, v121, v121
	v_fmac_f32_e32 v113, v120, v120
	v_add_f32_e32 v112, v113, v112
	v_lshlrev_b32_e32 v222, 16, v165
	v_and_b32_e32 v223, 0xffff0000, v165
	v_add_f32_e32 v126, v181, v112
	v_cvt_pk_bf16_f32 v112, v116, v117
	v_cvt_pk_bf16_f32 v113, v118, v119
	v_lshl_add_u64 v[116:117], s[10:11], 0, v[170:171]
	v_lshlrev_b32_e32 v230, 16, v184
	v_and_b32_e32 v231, 0xffff0000, v184
	v_lshlrev_b32_e32 v232, 16, v186
	v_and_b32_e32 v233, 0xffff0000, v186
	v_lshlrev_b32_e32 v186, 16, v187
	v_and_b32_e32 v187, 0xffff0000, v187
	v_cvt_pk_bf16_f32 v114, v114, v115
	v_cvt_pk_bf16_f32 v115, v120, v121
	global_store_dwordx4 v[124:125], v[112:115], off offset:256
	v_pk_add_f32 v[110:111], v[110:111], v[222:223]
	v_pk_add_f32 v[108:109], v[108:109], v[220:221]
	v_lshl_add_u64 v[118:119], v[116:117], 0, v[144:145]
	v_cvt_pk_bf16_f32 v112, v108, v109
	v_cvt_pk_bf16_f32 v113, v110, v111
	v_lshlrev_b32_e32 v228, 16, v182
	v_and_b32_e32 v229, 0xffff0000, v182
	v_lshlrev_b32_e32 v182, 16, v183
	v_and_b32_e32 v183, 0xffff0000, v183
	v_lshlrev_b32_e32 v184, 16, v185
	v_and_b32_e32 v185, 0xffff0000, v185
	v_lshlrev_b32_e32 v238, 16, v192
	v_and_b32_e32 v239, 0xffff0000, v192
	v_pk_add_f32 v[106:107], v[106:107], v[226:227]
	v_pk_add_f32 v[104:105], v[104:105], v[224:225]
	v_lshlrev_b32_e32 v156, 16, v200
	v_cvt_pk_bf16_f32 v114, v104, v105
	v_cvt_pk_bf16_f32 v115, v106, v107
	global_store_dwordx4 v[118:119], v[112:115], off
	v_and_b32_e32 v157, 0xffff0000, v200
	v_pk_add_f32 v[102:103], v[102:103], v[182:183]
	v_pk_add_f32 v[112:113], v[92:93], v[230:231]
	v_pk_add_f32 v[92:93], v[98:99], v[186:187]
	v_lshl_add_u64 v[98:99], s[10:11], 0, v[154:155]
	v_pk_add_f32 v[100:101], v[100:101], v[228:229]
	v_pk_add_f32 v[94:95], v[94:95], v[184:185]
	v_cvt_pk_bf16_f32 v114, v100, v101
	v_cvt_pk_bf16_f32 v115, v102, v103
	v_cvt_pk_bf16_f32 v116, v112, v113
	v_lshlrev_b32_e32 v234, 16, v188
	v_cvt_pk_bf16_f32 v117, v94, v95
	global_store_dwordx4 v[118:119], v[114:117], off offset:256
	v_lshl_add_u64 v[118:119], v[98:99], 0, v[144:145]
	v_pk_add_f32 v[98:99], v[76:77], v[238:239]
	v_pk_add_f32 v[76:77], v[82:83], v[172:173]
	v_lshl_add_u64 v[82:83], s[10:11], 0, v[152:153]
	v_lshl_add_u64 v[122:123], v[82:83], 0, v[144:145]
	v_pk_add_f32 v[82:83], v[64:65], v[156:157]
	v_and_b32_e32 v65, 64, v174
	v_and_b32_e32 v235, 0xffff0000, v188
	v_lshlrev_b32_e32 v188, 16, v189
	v_and_b32_e32 v189, 0xffff0000, v189
	v_lshlrev_b32_e32 v236, 16, v190
	v_and_b32_e32 v237, 0xffff0000, v190
	v_pk_add_f32 v[96:97], v[96:97], v[232:233]
	v_xor_b32_e32 v64, 16, v174
	v_cvt_pk_bf16_f32 v114, v96, v97
	v_add_u32_e32 v65, 64, v65
	v_lshlrev_b32_e32 v190, 16, v191
	v_and_b32_e32 v191, 0xffff0000, v191
	v_lshlrev_b32_e32 v192, 16, v193
	v_and_b32_e32 v193, 0xffff0000, v193
	v_pk_add_f32 v[90:91], v[90:91], v[188:189]
	v_pk_add_f32 v[88:89], v[88:89], v[234:235]
	v_cvt_pk_bf16_f32 v115, v92, v93
	v_pk_add_f32 v[84:85], v[84:85], v[236:237]
	v_cvt_pk_bf16_f32 v116, v88, v89
	v_cvt_pk_bf16_f32 v117, v90, v91
	global_store_dwordx4 v[118:119], v[114:117], off
	v_cmp_lt_i32_e32 vcc, v64, v65
	v_lshlrev_b32_e32 v164, 16, v196
	v_cvt_pk_bf16_f32 v114, v84, v85
	v_and_b32_e32 v165, 0xffff0000, v196
	v_lshlrev_b32_e32 v168, 16, v197
	v_and_b32_e32 v169, 0xffff0000, v197
	v_pk_add_f32 v[86:87], v[86:87], v[190:191]
	v_pk_add_f32 v[78:79], v[78:79], v[192:193]
	v_cvt_pk_bf16_f32 v115, v86, v87
	v_cvt_pk_bf16_f32 v116, v98, v99
	v_pk_add_f32 v[80:81], v[80:81], v[166:167]
	v_cvt_pk_bf16_f32 v117, v78, v79
	global_store_dwordx4 v[118:119], v[114:117], off offset:256
	v_cndmask_b32_e32 v64, v174, v64, vcc
	v_pk_add_f32 v[74:75], v[74:75], v[168:169]
	v_cvt_pk_bf16_f32 v114, v80, v81
	v_pk_add_f32 v[72:73], v[72:73], v[164:165]
	v_cvt_pk_bf16_f32 v115, v76, v77
	v_lshlrev_b32_e32 v158, 16, v198
	v_cvt_pk_bf16_f32 v116, v72, v73
	v_cvt_pk_bf16_f32 v117, v74, v75
	global_store_dwordx4 v[122:123], v[114:117], off
	v_and_b32_e32 v159, 0xffff0000, v198
	v_lshlrev_b32_e32 v162, 16, v199
	v_lshlrev_b32_e32 v114, 2, v64
	ds_bpermute_b32 v64, v114, v126
	v_xor_b32_e32 v115, 32, v174
	v_cmp_lt_i32_e32 vcc, v115, v65
	v_and_b32_e32 v163, 0xffff0000, v199
	v_lshlrev_b32_e32 v160, 16, v201
	v_cndmask_b32_e32 v65, v174, v115, vcc
	v_lshlrev_b32_e32 v115, 2, v65
	s_waitcnt lgkmcnt(0)
	v_add_f32_e32 v116, v126, v64
	ds_bpermute_b32 v117, v115, v116
	v_and_b32_e32 v161, 0xffff0000, v201
	v_pk_add_f32 v[70:71], v[70:71], v[162:163]
	v_pk_add_f32 v[68:69], v[68:69], v[158:159]
	v_pk_add_f32 v[66:67], v[66:67], v[160:161]
	v_lshl_add_u64 v[64:65], v[150:151], 2, s[6:7]
	v_cvt_pk_bf16_f32 v118, v68, v69
	v_cvt_pk_bf16_f32 v119, v70, v71
	v_cvt_pk_bf16_f32 v120, v82, v83
	v_cvt_pk_bf16_f32 v121, v66, v67
	global_store_dwordx4 v[122:123], v[118:121], off offset:256
	s_and_saveexec_b64 s[26:27], s[2:3]
	s_cbranch_execz .LBB0_1267
	s_waitcnt lgkmcnt(0)
	v_add_f32_e32 v116, v116, v117
	global_atomic_add_f32 v[64:65], v116, off
